# speedup vs baseline: 1.0091x; 1.0091x over previous
;   __device__ __forceinline__ void tile(const float* reg, int row0, int col0, int lane) const {
;     rows4(reg, lane, [&](int it, int rr, int c4, float4 v) {
;       int row = row0 + rr, idx = row * 1024 + col0 + c4;
;       float4 xo = *(const float4*)(xold + idx);
;       v.x = fmaf(coef, v.x, xo.x); v.y = fmaf(coef, v.y, xo.y); v.z = fmaf(coef, v.z, xo.z); v.w = fmaf(coef, v.w, xo.w);
;       *(float4*)(xnew + idx) = v;
;       *(bf16x4*)(xb + idx) = pack4(v.x, v.y, v.z, v.w);
;       float s = row16_sum(v.x * v.x + v.y * v.y + v.z * v.z + v.w * v.w);
;       if ((lane & 15) == 0) atomicAdd(ssqn + row, s);
;     });
; template <int MF, class Epi>
; __device__ __forceinline__ void staged_epilogue(f32x4 (&acc)[MF][4], int row0, int col0, const Epi& epi) {
;   const int lane = tidx() & 63, wid = tidx() >> 6, fr = lane & 15, fq = lane >> 4;
;   float* reg = (float*)(g_shm + 65536 + wid * 8704);
; #pragma unroll
;   for (int mp = 0; mp < MF / 2; ++mp) {
;     __builtin_amdgcn_sched_barrier(0);
; #pragma unroll
;     for (int mm = 0; mm < 2; ++mm)
; #pragma unroll
;       for (int n = 0; n < 4; ++n)
; #pragma unroll
;         for (int j = 0; j < 4; ++j) reg[(mm * 16 + fq * 4 + j) * 68 + n * 16 + fr] = acc[mp * 2 + mm][n][j];
;     __builtin_amdgcn_fence(__ATOMIC_ACQ_REL, "wavefront");
;     epi.tile(reg, row0 + mp * 32, col0, lane);
.LBB0_122:
	v_mov_b32_e32 v131, v204
	v_mov_b32_e32 v130, v204
	s_nop 0
	v_lshrrev_b32_e32 v130, 6, v130
	v_mul_lo_u32 v130, v130, s47
	v_add_u32_e32 v136, 0x10000, v130
	v_lshrrev_b32_e32 v130, 2, v131
	v_and_b32_e32 v137, 15, v131
	v_and_b32_e32 v138, 12, v130
	v_bfe_u32 v130, v131, 4, 2
	v_lshlrev_b32_e32 v131, 2, v131
	v_and_b32_e32 v131, 60, v131
	v_lshl_or_b32 v139, v137, 2, v136
	v_lshl_or_b32 v136, v131, 2, v136
	v_add_u32_e32 v128, v131, v128
	v_cmp_eq_u32_e32 vcc, 0, v137
	v_mad_u32_u24 v140, v130, s50, v136
	v_mad_u32_u24 v131, v138, s50, v139
	ds_write2_b32 v131, v120, v124 offset1:16
	ds_write2_b32 v131, v121, v125 offset0:68 offset1:84
	ds_write2_b32 v131, v122, v126 offset0:136 offset1:152
	ds_write2_b32 v131, v123, v127 offset0:204 offset1:220
	ds_write2_b32 v131, v112, v116 offset0:32 offset1:48
	ds_write2_b32 v131, v113, v117 offset0:100 offset1:116
	ds_write2_b32 v131, v114, v118 offset0:168 offset1:184
	ds_write2_b32 v131, v115, v119 offset0:236 offset1:252
	v_add_u32_e32 v112, 0x1000, v131
	ds_write2_b32 v112, v104, v108 offset0:64 offset1:80
	ds_write2_b32 v112, v105, v109 offset0:132 offset1:148
	ds_write2_b32 v112, v106, v110 offset0:200 offset1:216
	v_add_u32_e32 v104, 0x1400, v131
	ds_write2_b32 v104, v107, v111 offset0:12 offset1:28
	ds_write2_b32 v112, v96, v100 offset0:96 offset1:112
	ds_write2_b32 v112, v97, v101 offset0:164 offset1:180
	ds_write2_b32 v112, v98, v102 offset0:232 offset1:248
	ds_write2_b32 v104, v99, v103 offset0:44 offset1:60
	v_add_u32_e32 v184, v130, v129
	v_lshl_add_u32 v178, v184, 10, v128
	v_ashrrev_i32_e32 v179, 31, v178
	v_lshlrev_b64 v[180:181], 2, v[178:179]
	v_lshl_add_u64 v[176:177], s[4:5], 0, v[180:181]
	global_load_dwordx4 v[144:147], v[176:177], off
	v_or_b32_e32 v185, 4, v130
	v_add_u32_e32 v184, v185, v129
	v_lshl_add_u32 v178, v184, 10, v128
	v_ashrrev_i32_e32 v179, 31, v178
	v_lshlrev_b64 v[180:181], 2, v[178:179]
	v_lshl_add_u64 v[176:177], s[4:5], 0, v[180:181]
	global_load_dwordx4 v[148:151], v[176:177], off
	v_or_b32_e32 v185, 8, v130
	v_add_u32_e32 v184, v185, v129
	v_lshl_add_u32 v178, v184, 10, v128
	v_ashrrev_i32_e32 v179, 31, v178
	v_lshlrev_b64 v[180:181], 2, v[178:179]
	v_lshl_add_u64 v[176:177], s[4:5], 0, v[180:181]
	global_load_dwordx4 v[152:155], v[176:177], off
	v_or_b32_e32 v185, 12, v130
	v_add_u32_e32 v184, v185, v129
	v_lshl_add_u32 v176, v184, 10, v128
	v_ashrrev_i32_e32 v177, 31, v176
	v_lshlrev_b64 v[178:179], 2, v[176:177]
	v_lshl_add_u64 v[180:181], s[4:5], 0, v[178:179]
	global_load_dwordx4 v[156:159], v[180:181], off
	v_or_b32_e32 v185, 16, v130
	v_add_u32_e32 v184, v185, v129
	v_lshl_add_u32 v176, v184, 10, v128
	v_ashrrev_i32_e32 v177, 31, v176
	v_lshlrev_b64 v[178:179], 2, v[176:177]
	v_lshl_add_u64 v[180:181], s[4:5], 0, v[178:179]
	global_load_dwordx4 v[160:163], v[180:181], off
	v_or_b32_e32 v185, 20, v130
	v_add_u32_e32 v184, v185, v129
	v_lshl_add_u32 v176, v184, 10, v128
	v_ashrrev_i32_e32 v177, 31, v176
	v_lshlrev_b64 v[180:181], 2, v[176:177]
	v_lshl_add_u64 v[178:179], s[4:5], 0, v[180:181]
	global_load_dwordx4 v[164:167], v[178:179], off
	v_or_b32_e32 v185, 24, v130
	v_add_u32_e32 v184, v185, v129
	v_lshl_add_u32 v176, v184, 10, v128
	v_ashrrev_i32_e32 v177, 31, v176
	v_lshlrev_b64 v[180:181], 2, v[176:177]
	v_lshl_add_u64 v[178:179], s[4:5], 0, v[180:181]
	global_load_dwordx4 v[168:171], v[178:179], off
	v_or_b32_e32 v185, 28, v130
	v_add_u32_e32 v184, v185, v129
	v_lshl_add_u32 v176, v184, 10, v128
	v_ashrrev_i32_e32 v177, 31, v176
	v_lshlrev_b64 v[180:181], 2, v[176:177]
	v_lshl_add_u64 v[178:179], s[4:5], 0, v[180:181]
	global_load_dwordx4 v[172:175], v[178:179], off
	v_add_u32_e32 v96, v130, v129
	v_lshl_add_u32 v102, v96, 10, v128
	v_ashrrev_i32_e32 v103, 31, v102
	v_lshlrev_b64 v[110:111], 2, v[102:103]
	v_lshl_add_u64 v[98:99], s[4:5], 0, v[110:111]
	s_waitcnt vmcnt(7)
	v_mov_b32_e32 v98, v144
	v_mov_b32_e32 v99, v145
	v_mov_b32_e32 v100, v146
	v_mov_b32_e32 v101, v147
	ds_read_b128 v[106:109], v140
	v_lshl_add_u64 v[110:111], s[8:9], 0, v[110:111]
	v_lshl_add_u64 v[102:103], v[102:103], 1, s[10:11]
	s_waitcnt lgkmcnt(0)
	v_pk_fma_f32 v[98:99], v[106:107], 0.5, v[98:99] op_sel_hi:[1,0,1]
	v_pk_fma_f32 v[100:101], v[108:109], 0.5, v[100:101] op_sel_hi:[1,0,1]
	global_store_dwordx4 v[110:111], v[98:101], off
	v_cvt_pk_bf16_f32 v106, v98, v99
	v_cvt_pk_bf16_f32 v107, v100, v101
	v_pk_mul_f32 v[98:99], v[98:99], v[98:99]
	v_pk_mul_f32 v[100:101], v[100:101], v[100:101]
	v_add_f32_e32 v97, v98, v99
	v_add_f32_e32 v97, v100, v97
	v_add_f32_e32 v97, v101, v97
	v_mov_b32_e32 v98, 0
	global_store_dwordx2 v[102:103], v[106:107], off
	v_add_f32_dpp v97, v97, v97 quad_perm:[1,0,3,2] row_mask:0xf bank_mask:0xf bound_ctrl:1
	s_nop 1
	v_add_f32_dpp v97, v97, v97 quad_perm:[2,3,0,1] row_mask:0xf bank_mask:0xf bound_ctrl:1
	s_nop 1
	v_add_f32_dpp v97, v97, v97 row_half_mirror row_mask:0xf bank_mask:0xf bound_ctrl:1
	s_nop 1
	v_mov_b32_dpp v98, v97 row_mirror row_mask:0xf bank_mask:0xf
	s_and_saveexec_b64 s[0:1], vcc
	s_cbranch_execz .LBB0_124
	v_add_f32_e32 v98, v97, v98
	v_ashrrev_i32_e32 v97, 31, v96
	v_lshl_add_u64 v[96:97], v[96:97], 2, s[12:13]
	global_atomic_add_f32 v[96:97], v98, off
;   __device__ __forceinline__ void tile(const float* reg, int row0, int col0, int lane) const {
;     rows4(reg, lane, [&](int it, int rr, int c4, float4 v) {
;       int row = row0 + rr, idx = row * 1024 + col0 + c4;
;       float4 xo = *(const float4*)(xold + idx);
;       v.x = fmaf(coef, v.x, xo.x); v.y = fmaf(coef, v.y, xo.y); v.z = fmaf(coef, v.z, xo.z); v.w = fmaf(coef, v.w, xo.w);
;       *(float4*)(xnew + idx) = v;
;       *(bf16x4*)(xb + idx) = pack4(v.x, v.y, v.z, v.w);
;       float s = row16_sum(v.x * v.x + v.y * v.y + v.z * v.z + v.w * v.w);
;       if ((lane & 15) == 0) atomicAdd(ssqn + row, s);
;     });
.LBB0_124:
	s_or_b64 exec, exec, s[0:1]
	v_or_b32_e32 v99, 4, v130
	v_add_u32_e32 v96, v99, v129
	v_lshl_add_u32 v102, v96, 10, v128
	v_ashrrev_i32_e32 v103, 31, v102
	v_lshlrev_b64 v[106:107], 2, v[102:103]
	v_lshl_add_u64 v[100:101], s[4:5], 0, v[106:107]
	v_mul_u32_u24_e32 v109, 0x110, v130
	v_add_u32_e32 v98, 0x440, v109
	v_add_u32_e32 v100, v136, v98
	ds_read_b128 v[118:121], v100
	v_lshl_add_u64 v[106:107], s[8:9], 0, v[106:107]
	v_mov_b32_e32 v101, 0
	v_lshl_add_u64 v[102:103], v[102:103], 1, s[10:11]
	s_waitcnt vmcnt(9) lgkmcnt(0)
	v_mov_b32_e32 v114, v148
	v_mov_b32_e32 v115, v149
	v_mov_b32_e32 v116, v150
	v_mov_b32_e32 v117, v151
	v_pk_fma_f32 v[114:115], v[118:119], 0.5, v[114:115] op_sel_hi:[1,0,1]
	v_pk_fma_f32 v[116:117], v[120:121], 0.5, v[116:117] op_sel_hi:[1,0,1]
	v_pk_mul_f32 v[110:111], v[114:115], v[114:115]
	global_store_dwordx4 v[106:107], v[114:117], off
	v_cvt_pk_bf16_f32 v106, v114, v115
	v_add_f32_e32 v97, v110, v111
	v_pk_mul_f32 v[114:115], v[116:117], v[116:117]
	v_cvt_pk_bf16_f32 v107, v116, v117
	v_add_f32_e32 v97, v114, v97
	v_add_f32_e32 v97, v115, v97
	global_store_dwordx2 v[102:103], v[106:107], off
	s_nop 0
	v_add_f32_dpp v97, v97, v97 quad_perm:[1,0,3,2] row_mask:0xf bank_mask:0xf bound_ctrl:1
	s_nop 1
	v_add_f32_dpp v97, v97, v97 quad_perm:[2,3,0,1] row_mask:0xf bank_mask:0xf bound_ctrl:1
	s_nop 1
	v_add_f32_dpp v97, v97, v97 row_half_mirror row_mask:0xf bank_mask:0xf bound_ctrl:1
	s_nop 1
	v_mov_b32_dpp v101, v97 row_mirror row_mask:0xf bank_mask:0xf
	s_and_saveexec_b64 s[0:1], vcc
	s_cbranch_execz .LBB0_126
	v_add_f32_e32 v101, v97, v101
	v_ashrrev_i32_e32 v97, 31, v96
	v_lshl_add_u64 v[96:97], v[96:97], 2, s[12:13]
	global_atomic_add_f32 v[96:97], v101, off
.LBB0_126:
	s_or_b64 exec, exec, s[0:1]
	v_or_b32_e32 v101, 8, v130
	v_add_u32_e32 v96, v101, v129
	v_lshl_add_u32 v106, v96, 10, v128
	v_ashrrev_i32_e32 v107, 31, v106
	v_lshlrev_b64 v[110:111], 2, v[106:107]
	v_lshl_add_u64 v[102:103], s[4:5], 0, v[110:111]
	v_add_u32_e32 v98, 0x440, v98
	v_add_u32_e32 v102, v136, v98
	ds_read_b128 v[118:121], v102
	v_lshl_add_u64 v[110:111], s[8:9], 0, v[110:111]
	v_mov_b32_e32 v103, 0
	v_lshl_add_u64 v[106:107], v[106:107], 1, s[10:11]
	s_waitcnt vmcnt(11) lgkmcnt(0)
	v_mov_b32_e32 v114, v152
	v_mov_b32_e32 v115, v153
	v_mov_b32_e32 v116, v154
	v_mov_b32_e32 v117, v155
	v_pk_fma_f32 v[114:115], v[118:119], 0.5, v[114:115] op_sel_hi:[1,0,1]
	v_pk_fma_f32 v[116:117], v[120:121], 0.5, v[116:117] op_sel_hi:[1,0,1]
	global_store_dwordx4 v[110:111], v[114:117], off
	v_cvt_pk_bf16_f32 v110, v114, v115
	v_cvt_pk_bf16_f32 v111, v116, v117
	v_pk_mul_f32 v[114:115], v[114:115], v[114:115]
	v_pk_mul_f32 v[116:117], v[116:117], v[116:117]
	v_add_f32_e32 v97, v114, v115
	v_add_f32_e32 v97, v116, v97
	v_add_f32_e32 v97, v117, v97
	global_store_dwordx2 v[106:107], v[110:111], off
	s_nop 0
	v_add_f32_dpp v97, v97, v97 quad_perm:[1,0,3,2] row_mask:0xf bank_mask:0xf bound_ctrl:1
	s_nop 1
	v_add_f32_dpp v97, v97, v97 quad_perm:[2,3,0,1] row_mask:0xf bank_mask:0xf bound_ctrl:1
	s_nop 1
	v_add_f32_dpp v97, v97, v97 row_half_mirror row_mask:0xf bank_mask:0xf bound_ctrl:1
	s_nop 1
	v_mov_b32_dpp v103, v97 row_mirror row_mask:0xf bank_mask:0xf
	s_and_saveexec_b64 s[0:1], vcc
	s_cbranch_execz .LBB0_128
	v_add_f32_e32 v103, v97, v103
	v_ashrrev_i32_e32 v97, 31, v96
	v_lshl_add_u64 v[96:97], v[96:97], 2, s[12:13]
	global_atomic_add_f32 v[96:97], v103, off
.LBB0_128:
	s_or_b64 exec, exec, s[0:1]
	v_or_b32_e32 v103, 12, v130
	v_add_u32_e32 v96, v103, v129
	v_lshl_add_u32 v106, v96, 10, v128
	v_ashrrev_i32_e32 v107, 31, v106
	v_lshlrev_b64 v[110:111], 2, v[106:107]
	v_lshl_add_u64 v[114:115], s[4:5], 0, v[110:111]
	v_add_u32_e32 v97, 0x440, v98
	v_add_u32_e32 v98, v136, v97
	ds_read_b128 v[118:121], v98
	v_lshl_add_u64 v[110:111], s[8:9], 0, v[110:111]
	v_mov_b32_e32 v105, 0
	v_lshl_add_u64 v[106:107], v[106:107], 1, s[10:11]
	s_waitcnt vmcnt(13) lgkmcnt(0)
	v_mov_b32_e32 v114, v156
	v_mov_b32_e32 v115, v157
	v_mov_b32_e32 v116, v158
	v_mov_b32_e32 v117, v159
	v_pk_fma_f32 v[114:115], v[118:119], 0.5, v[114:115] op_sel_hi:[1,0,1]
	v_pk_fma_f32 v[116:117], v[120:121], 0.5, v[116:117] op_sel_hi:[1,0,1]
	global_store_dwordx4 v[110:111], v[114:117], off
	v_cvt_pk_bf16_f32 v110, v114, v115
	v_cvt_pk_bf16_f32 v111, v116, v117
	v_pk_mul_f32 v[114:115], v[114:115], v[114:115]
	v_pk_mul_f32 v[116:117], v[116:117], v[116:117]
	v_add_f32_e32 v97, v114, v115
	v_add_f32_e32 v97, v116, v97
	v_add_f32_e32 v97, v117, v97
	global_store_dwordx2 v[106:107], v[110:111], off
	s_nop 0
	v_add_f32_dpp v97, v97, v97 quad_perm:[1,0,3,2] row_mask:0xf bank_mask:0xf bound_ctrl:1
	s_nop 1
	v_add_f32_dpp v97, v97, v97 quad_perm:[2,3,0,1] row_mask:0xf bank_mask:0xf bound_ctrl:1
	s_nop 1
	v_add_f32_dpp v97, v97, v97 row_half_mirror row_mask:0xf bank_mask:0xf bound_ctrl:1
	s_nop 1
	v_mov_b32_dpp v105, v97 row_mirror row_mask:0xf bank_mask:0xf
	s_and_saveexec_b64 s[0:1], vcc
	s_cbranch_execz .LBB0_130
	v_add_f32_e32 v105, v97, v105
	v_ashrrev_i32_e32 v97, 31, v96
	v_lshl_add_u64 v[96:97], v[96:97], 2, s[12:13]
	global_atomic_add_f32 v[96:97], v105, off
;   __device__ __forceinline__ void tile(const float* reg, int row0, int col0, int lane) const {
;     rows4(reg, lane, [&](int it, int rr, int c4, float4 v) {
;       int row = row0 + rr, idx = row * 1024 + col0 + c4;
;       float4 xo = *(const float4*)(xold + idx);
;       v.x = fmaf(coef, v.x, xo.x); v.y = fmaf(coef, v.y, xo.y); v.z = fmaf(coef, v.z, xo.z); v.w = fmaf(coef, v.w, xo.w);
;       *(float4*)(xnew + idx) = v;
;       *(bf16x4*)(xb + idx) = pack4(v.x, v.y, v.z, v.w);
;       float s = row16_sum(v.x * v.x + v.y * v.y + v.z * v.z + v.w * v.w);
;       if ((lane & 15) == 0) atomicAdd(ssqn + row, s);
;     });
.LBB0_130:
	s_or_b64 exec, exec, s[0:1]
	v_or_b32_e32 v105, 16, v130
	v_add_u32_e32 v96, v105, v129
	v_lshl_add_u32 v106, v96, 10, v128
	v_ashrrev_i32_e32 v107, 31, v106
	v_lshlrev_b64 v[110:111], 2, v[106:107]
	v_lshl_add_u64 v[114:115], s[4:5], 0, v[110:111]
	ds_read_b128 v[118:121], v98 offset:1088
	v_lshl_add_u64 v[110:111], s[8:9], 0, v[110:111]
	v_lshl_add_u64 v[106:107], v[106:107], 1, s[10:11]
	s_waitcnt vmcnt(15) lgkmcnt(0)
	v_mov_b32_e32 v114, v160
	v_mov_b32_e32 v115, v161
	v_mov_b32_e32 v116, v162
	v_mov_b32_e32 v117, v163
	v_pk_fma_f32 v[114:115], v[118:119], 0.5, v[114:115] op_sel_hi:[1,0,1]
	v_pk_fma_f32 v[116:117], v[120:121], 0.5, v[116:117] op_sel_hi:[1,0,1]
	global_store_dwordx4 v[110:111], v[114:117], off
	v_cvt_pk_bf16_f32 v110, v114, v115
	v_cvt_pk_bf16_f32 v111, v116, v117
	v_pk_mul_f32 v[114:115], v[114:115], v[114:115]
	v_pk_mul_f32 v[116:117], v[116:117], v[116:117]
	v_add_f32_e32 v97, v114, v115
	v_add_f32_e32 v97, v116, v97
	v_add_f32_e32 v97, v117, v97
	global_store_dwordx2 v[106:107], v[110:111], off
	v_mov_b32_e32 v106, 0
	v_add_f32_dpp v97, v97, v97 quad_perm:[1,0,3,2] row_mask:0xf bank_mask:0xf bound_ctrl:1
	s_nop 1
	v_add_f32_dpp v97, v97, v97 quad_perm:[2,3,0,1] row_mask:0xf bank_mask:0xf bound_ctrl:1
	s_nop 1
	v_add_f32_dpp v97, v97, v97 row_half_mirror row_mask:0xf bank_mask:0xf bound_ctrl:1
	s_nop 1
	v_mov_b32_dpp v106, v97 row_mirror row_mask:0xf bank_mask:0xf
	s_and_saveexec_b64 s[0:1], vcc
	s_cbranch_execz .LBB0_132
	v_add_f32_e32 v106, v97, v106
	v_ashrrev_i32_e32 v97, 31, v96
	v_lshl_add_u64 v[96:97], v[96:97], 2, s[12:13]
	global_atomic_add_f32 v[96:97], v106, off
.LBB0_132:
	s_or_b64 exec, exec, s[0:1]
	v_or_b32_e32 v106, 20, v130
	v_add_u32_e32 v96, v106, v129
	v_lshl_add_u32 v110, v96, 10, v128
	v_ashrrev_i32_e32 v111, 31, v110
	v_lshlrev_b64 v[122:123], 2, v[110:111]
	v_lshl_add_u64 v[114:115], s[4:5], 0, v[122:123]
	ds_read_b128 v[118:121], v98 offset:2176
	v_lshl_add_u64 v[122:123], s[8:9], 0, v[122:123]
	v_mov_b32_e32 v107, 0
	v_lshl_add_u64 v[110:111], v[110:111], 1, s[10:11]
	s_waitcnt vmcnt(17) lgkmcnt(0)
	v_mov_b32_e32 v114, v164
	v_mov_b32_e32 v115, v165
	v_mov_b32_e32 v116, v166
	v_mov_b32_e32 v117, v167
	v_pk_fma_f32 v[114:115], v[118:119], 0.5, v[114:115] op_sel_hi:[1,0,1]
	v_pk_fma_f32 v[116:117], v[120:121], 0.5, v[116:117] op_sel_hi:[1,0,1]
	global_store_dwordx4 v[122:123], v[114:117], off
	v_cvt_pk_bf16_f32 v118, v114, v115
	v_cvt_pk_bf16_f32 v119, v116, v117
	v_pk_mul_f32 v[114:115], v[114:115], v[114:115]
	v_pk_mul_f32 v[116:117], v[116:117], v[116:117]
	v_add_f32_e32 v97, v114, v115
	v_add_f32_e32 v97, v116, v97
	v_add_f32_e32 v97, v117, v97
	global_store_dwordx2 v[110:111], v[118:119], off
	s_nop 0
	v_add_f32_dpp v97, v97, v97 quad_perm:[1,0,3,2] row_mask:0xf bank_mask:0xf bound_ctrl:1
	s_nop 1
	v_add_f32_dpp v97, v97, v97 quad_perm:[2,3,0,1] row_mask:0xf bank_mask:0xf bound_ctrl:1
	s_nop 1
	v_add_f32_dpp v97, v97, v97 row_half_mirror row_mask:0xf bank_mask:0xf bound_ctrl:1
	s_nop 1
	v_mov_b32_dpp v107, v97 row_mirror row_mask:0xf bank_mask:0xf
	s_and_saveexec_b64 s[0:1], vcc
	s_cbranch_execz .LBB0_134
	v_add_f32_e32 v107, v97, v107
	v_ashrrev_i32_e32 v97, 31, v96
	v_lshl_add_u64 v[96:97], v[96:97], 2, s[12:13]
	global_atomic_add_f32 v[96:97], v107, off
.LBB0_134:
	s_or_b64 exec, exec, s[0:1]
	v_or_b32_e32 v107, 24, v130
	v_add_u32_e32 v96, v107, v129
	v_lshl_add_u32 v110, v96, 10, v128
	v_ashrrev_i32_e32 v111, 31, v110
	v_lshlrev_b64 v[122:123], 2, v[110:111]
	v_lshl_add_u64 v[114:115], s[4:5], 0, v[122:123]
	ds_read_b128 v[118:121], v98 offset:3264
	v_lshl_add_u64 v[122:123], s[8:9], 0, v[122:123]
	v_mov_b32_e32 v108, 0
	v_lshl_add_u64 v[110:111], v[110:111], 1, s[10:11]
	s_waitcnt vmcnt(19) lgkmcnt(0)
	v_mov_b32_e32 v114, v168
	v_mov_b32_e32 v115, v169
	v_mov_b32_e32 v116, v170
	v_mov_b32_e32 v117, v171
	v_pk_fma_f32 v[114:115], v[118:119], 0.5, v[114:115] op_sel_hi:[1,0,1]
	v_pk_fma_f32 v[116:117], v[120:121], 0.5, v[116:117] op_sel_hi:[1,0,1]
	global_store_dwordx4 v[122:123], v[114:117], off
	v_cvt_pk_bf16_f32 v118, v114, v115
	v_cvt_pk_bf16_f32 v119, v116, v117
	v_pk_mul_f32 v[114:115], v[114:115], v[114:115]
	v_pk_mul_f32 v[116:117], v[116:117], v[116:117]
	v_add_f32_e32 v97, v114, v115
	v_add_f32_e32 v97, v116, v97
	v_add_f32_e32 v97, v117, v97
	global_store_dwordx2 v[110:111], v[118:119], off
	s_nop 0
	v_add_f32_dpp v97, v97, v97 quad_perm:[1,0,3,2] row_mask:0xf bank_mask:0xf bound_ctrl:1
	s_nop 1
	v_add_f32_dpp v97, v97, v97 quad_perm:[2,3,0,1] row_mask:0xf bank_mask:0xf bound_ctrl:1
	s_nop 1
	v_add_f32_dpp v97, v97, v97 row_half_mirror row_mask:0xf bank_mask:0xf bound_ctrl:1
	s_nop 1
	v_mov_b32_dpp v108, v97 row_mirror row_mask:0xf bank_mask:0xf
	s_and_saveexec_b64 s[0:1], vcc
	s_cbranch_execz .LBB0_136
	v_add_f32_e32 v108, v97, v108
	v_ashrrev_i32_e32 v97, 31, v96
	v_lshl_add_u64 v[96:97], v[96:97], 2, s[12:13]
	global_atomic_add_f32 v[96:97], v108, off
;   __device__ __forceinline__ void tile(const float* reg, int row0, int col0, int lane) const {
;     rows4(reg, lane, [&](int it, int rr, int c4, float4 v) {
;       int row = row0 + rr, idx = row * 1024 + col0 + c4;
;       float4 xo = *(const float4*)(xold + idx);
;       v.x = fmaf(coef, v.x, xo.x); v.y = fmaf(coef, v.y, xo.y); v.z = fmaf(coef, v.z, xo.z); v.w = fmaf(coef, v.w, xo.w);
;       *(float4*)(xnew + idx) = v;
;       *(bf16x4*)(xb + idx) = pack4(v.x, v.y, v.z, v.w);
;       float s = row16_sum(v.x * v.x + v.y * v.y + v.z * v.z + v.w * v.w);
;       if ((lane & 15) == 0) atomicAdd(ssqn + row, s);
;     });
; template <int MF, class Epi>
; __device__ __forceinline__ void staged_epilogue(f32x4 (&acc)[MF][4], int row0, int col0, const Epi& epi) {
;     ...
;         for (int j = 0; j < 4; ++j) reg[(mm * 16 + fq * 4 + j) * 68 + n * 16 + fr] = acc[mp * 2 + mm][n][j];
.LBB0_136:
	s_or_b64 exec, exec, s[0:1]
	v_or_b32_e32 v108, 28, v130
	v_add_u32_e32 v96, v108, v129
	v_lshl_add_u32 v110, v96, 10, v128
	v_ashrrev_i32_e32 v111, 31, v110
	v_lshlrev_b64 v[122:123], 2, v[110:111]
	v_lshl_add_u64 v[114:115], s[4:5], 0, v[122:123]
	ds_read_b128 v[118:121], v98 offset:4352
	v_lshl_add_u64 v[122:123], s[8:9], 0, v[122:123]
	v_lshl_add_u64 v[110:111], v[110:111], 1, s[10:11]
	s_waitcnt vmcnt(21) lgkmcnt(0)
	v_mov_b32_e32 v114, v172
	v_mov_b32_e32 v115, v173
	v_mov_b32_e32 v116, v174
	v_mov_b32_e32 v117, v175
	v_pk_fma_f32 v[114:115], v[118:119], 0.5, v[114:115] op_sel_hi:[1,0,1]
	v_pk_fma_f32 v[116:117], v[120:121], 0.5, v[116:117] op_sel_hi:[1,0,1]
	global_store_dwordx4 v[122:123], v[114:117], off
	v_cvt_pk_bf16_f32 v118, v114, v115
	v_cvt_pk_bf16_f32 v119, v116, v117
	v_pk_mul_f32 v[114:115], v[114:115], v[114:115]
	v_pk_mul_f32 v[116:117], v[116:117], v[116:117]
	v_add_f32_e32 v97, v114, v115
	v_add_f32_e32 v97, v116, v97
	v_add_f32_e32 v97, v117, v97
	global_store_dwordx2 v[110:111], v[118:119], off
	v_mov_b32_e32 v110, 0
	v_add_f32_dpp v97, v97, v97 quad_perm:[1,0,3,2] row_mask:0xf bank_mask:0xf bound_ctrl:1
	s_nop 1
	v_add_f32_dpp v97, v97, v97 quad_perm:[2,3,0,1] row_mask:0xf bank_mask:0xf bound_ctrl:1
	s_nop 1
	v_add_f32_dpp v97, v97, v97 row_half_mirror row_mask:0xf bank_mask:0xf bound_ctrl:1
	s_nop 1
	v_mov_b32_dpp v110, v97 row_mirror row_mask:0xf bank_mask:0xf
	s_and_saveexec_b64 s[0:1], vcc
	s_cbranch_execz .LBB0_138
	v_add_f32_e32 v110, v97, v110
	v_ashrrev_i32_e32 v97, 31, v96
	v_lshl_add_u64 v[96:97], v[96:97], 2, s[12:13]
	global_atomic_add_f32 v[96:97], v110, off
.LBB0_138:
	s_or_b64 exec, exec, s[0:1]
	ds_write2_b32 v131, v88, v92 offset1:16
	ds_write2_b32 v131, v89, v93 offset0:68 offset1:84
	ds_write2_b32 v131, v90, v94 offset0:136 offset1:152
	ds_write2_b32 v131, v91, v95 offset0:204 offset1:220
	ds_write2_b32 v131, v80, v84 offset0:32 offset1:48
	ds_write2_b32 v131, v81, v85 offset0:100 offset1:116
	ds_write2_b32 v131, v82, v86 offset0:168 offset1:184
	ds_write2_b32 v131, v83, v87 offset0:236 offset1:252
	ds_write2_b32 v112, v72, v76 offset0:64 offset1:80
	ds_write2_b32 v112, v73, v77 offset0:132 offset1:148
	ds_write2_b32 v112, v74, v78 offset0:200 offset1:216
	ds_write2_b32 v104, v75, v79 offset0:12 offset1:28
	ds_write2_b32 v112, v64, v68 offset0:96 offset1:112
	ds_write2_b32 v112, v65, v69 offset0:164 offset1:180
	ds_write2_b32 v112, v66, v70 offset0:232 offset1:248
	ds_write2_b32 v104, v67, v71 offset0:44 offset1:60
	v_add_u32_e32 v185, 32, v129
	v_add_u32_e32 v184, v130, v185
	v_lshl_add_u32 v178, v184, 10, v128
	v_ashrrev_i32_e32 v179, 31, v178
	v_lshlrev_b64 v[180:181], 2, v[178:179]
	v_lshl_add_u64 v[176:177], s[4:5], 0, v[180:181]
	global_load_dwordx4 v[144:147], v[176:177], off
	v_add_u32_e32 v185, 32, v129
	v_add_u32_e32 v184, v99, v185
	v_lshl_add_u32 v178, v184, 10, v128
	v_ashrrev_i32_e32 v179, 31, v178
	v_lshlrev_b64 v[180:181], 2, v[178:179]
	v_lshl_add_u64 v[176:177], s[4:5], 0, v[180:181]
	global_load_dwordx4 v[148:151], v[176:177], off
	v_add_u32_e32 v185, 32, v129
	v_add_u32_e32 v184, v101, v185
	v_lshl_add_u32 v178, v184, 10, v128
	v_ashrrev_i32_e32 v179, 31, v178
	v_lshlrev_b64 v[180:181], 2, v[178:179]
	v_lshl_add_u64 v[176:177], s[4:5], 0, v[180:181]
	global_load_dwordx4 v[152:155], v[176:177], off
	v_add_u32_e32 v185, 32, v129
	v_add_u32_e32 v184, v103, v185
	v_lshl_add_u32 v178, v184, 10, v128
	v_ashrrev_i32_e32 v179, 31, v178
	v_lshlrev_b64 v[180:181], 2, v[178:179]
	v_lshl_add_u64 v[176:177], s[4:5], 0, v[180:181]
	global_load_dwordx4 v[156:159], v[176:177], off
	v_add_u32_e32 v185, 32, v129
	v_add_u32_e32 v184, v105, v185
	v_lshl_add_u32 v178, v184, 10, v128
	v_ashrrev_i32_e32 v179, 31, v178
	v_lshlrev_b64 v[180:181], 2, v[178:179]
	v_lshl_add_u64 v[176:177], s[4:5], 0, v[180:181]
	global_load_dwordx4 v[160:163], v[176:177], off
	v_add_u32_e32 v185, 32, v129
	v_add_u32_e32 v184, v106, v185
	v_lshl_add_u32 v178, v184, 10, v128
	v_ashrrev_i32_e32 v179, 31, v178
	v_lshlrev_b64 v[180:181], 2, v[178:179]
	v_lshl_add_u64 v[176:177], s[4:5], 0, v[180:181]
	global_load_dwordx4 v[164:167], v[176:177], off
	v_add_u32_e32 v185, 32, v129
	v_add_u32_e32 v184, v107, v185
	v_lshl_add_u32 v178, v184, 10, v128
	v_ashrrev_i32_e32 v179, 31, v178
	v_lshlrev_b64 v[180:181], 2, v[178:179]
	v_lshl_add_u64 v[176:177], s[4:5], 0, v[180:181]
	global_load_dwordx4 v[168:171], v[176:177], off
	v_add_u32_e32 v185, 32, v129
	v_add_u32_e32 v184, v108, v185
	v_lshl_add_u32 v178, v184, 10, v128
	v_ashrrev_i32_e32 v179, 31, v178
	v_lshlrev_b64 v[180:181], 2, v[178:179]
	v_lshl_add_u64 v[176:177], s[4:5], 0, v[180:181]
	global_load_dwordx4 v[172:175], v[176:177], off
	v_add_u32_e32 v67, 32, v129
	v_add_u32_e32 v64, v130, v67
	v_lshl_add_u32 v76, v64, 10, v128
	v_ashrrev_i32_e32 v77, 31, v76
	v_lshlrev_b64 v[78:79], 2, v[76:77]
	v_lshl_add_u64 v[68:69], s[4:5], 0, v[78:79]
	v_add_u32_e32 v66, v136, v109
	ds_read_b128 v[72:75], v66
	v_lshl_add_u64 v[78:79], s[8:9], 0, v[78:79]
	v_lshl_add_u64 v[76:77], v[76:77], 1, s[10:11]
	s_waitcnt vmcnt(7) lgkmcnt(0)
	v_mov_b32_e32 v68, v144
	v_mov_b32_e32 v69, v145
	v_mov_b32_e32 v70, v146
	v_mov_b32_e32 v71, v147
	v_pk_fma_f32 v[68:69], v[72:73], 0.5, v[68:69] op_sel_hi:[1,0,1]
	v_pk_fma_f32 v[70:71], v[74:75], 0.5, v[70:71] op_sel_hi:[1,0,1]
	global_store_dwordx4 v[78:79], v[68:71], off
	v_cvt_pk_bf16_f32 v72, v68, v69
	v_cvt_pk_bf16_f32 v73, v70, v71
	v_pk_mul_f32 v[68:69], v[68:69], v[68:69]
	v_pk_mul_f32 v[70:71], v[70:71], v[70:71]
	v_add_f32_e32 v65, v68, v69
	v_add_f32_e32 v65, v70, v65
	v_add_f32_e32 v65, v71, v65
	v_mov_b32_e32 v68, 0
	global_store_dwordx2 v[76:77], v[72:73], off
	v_add_f32_dpp v65, v65, v65 quad_perm:[1,0,3,2] row_mask:0xf bank_mask:0xf bound_ctrl:1
	s_nop 1
	v_add_f32_dpp v65, v65, v65 quad_perm:[2,3,0,1] row_mask:0xf bank_mask:0xf bound_ctrl:1
	s_nop 1
	v_add_f32_dpp v65, v65, v65 row_half_mirror row_mask:0xf bank_mask:0xf bound_ctrl:1
	s_nop 1
	v_mov_b32_dpp v68, v65 row_mirror row_mask:0xf bank_mask:0xf
	s_and_saveexec_b64 s[0:1], vcc
	s_cbranch_execz .LBB0_140
	v_add_f32_e32 v68, v65, v68
	v_ashrrev_i32_e32 v65, 31, v64
	v_lshl_add_u64 v[64:65], v[64:65], 2, s[12:13]
	global_atomic_add_f32 v[64:65], v68, off
;   __device__ __forceinline__ void tile(const float* reg, int row0, int col0, int lane) const {
;     rows4(reg, lane, [&](int it, int rr, int c4, float4 v) {
;       int row = row0 + rr, idx = row * 1024 + col0 + c4;
;       float4 xo = *(const float4*)(xold + idx);
;       v.x = fmaf(coef, v.x, xo.x); v.y = fmaf(coef, v.y, xo.y); v.z = fmaf(coef, v.z, xo.z); v.w = fmaf(coef, v.w, xo.w);
;       *(float4*)(xnew + idx) = v;
;       *(bf16x4*)(xb + idx) = pack4(v.x, v.y, v.z, v.w);
;       float s = row16_sum(v.x * v.x + v.y * v.y + v.z * v.z + v.w * v.w);
;       if ((lane & 15) == 0) atomicAdd(ssqn + row, s);
;     });
.LBB0_140:
	s_or_b64 exec, exec, s[0:1]
	v_add_u32_e32 v64, v99, v67
	v_lshl_add_u32 v76, v64, 10, v128
	v_ashrrev_i32_e32 v77, 31, v76
	v_lshlrev_b64 v[78:79], 2, v[76:77]
	v_lshl_add_u64 v[68:69], s[4:5], 0, v[78:79]
	ds_read_b128 v[72:75], v100
	v_lshl_add_u64 v[78:79], s[8:9], 0, v[78:79]
	v_lshl_add_u64 v[76:77], v[76:77], 1, s[10:11]
	s_waitcnt vmcnt(9) lgkmcnt(0)
	v_mov_b32_e32 v68, v148
	v_mov_b32_e32 v69, v149
	v_mov_b32_e32 v70, v150
	v_mov_b32_e32 v71, v151
	v_pk_fma_f32 v[68:69], v[72:73], 0.5, v[68:69] op_sel_hi:[1,0,1]
	v_pk_fma_f32 v[70:71], v[74:75], 0.5, v[70:71] op_sel_hi:[1,0,1]
	global_store_dwordx4 v[78:79], v[68:71], off
	v_cvt_pk_bf16_f32 v72, v68, v69
	v_cvt_pk_bf16_f32 v73, v70, v71
	v_pk_mul_f32 v[68:69], v[68:69], v[68:69]
	v_pk_mul_f32 v[70:71], v[70:71], v[70:71]
	v_add_f32_e32 v65, v68, v69
	v_add_f32_e32 v65, v70, v65
	v_add_f32_e32 v65, v71, v65
	v_mov_b32_e32 v68, 0
	global_store_dwordx2 v[76:77], v[72:73], off
	v_add_f32_dpp v65, v65, v65 quad_perm:[1,0,3,2] row_mask:0xf bank_mask:0xf bound_ctrl:1
	s_nop 1
	v_add_f32_dpp v65, v65, v65 quad_perm:[2,3,0,1] row_mask:0xf bank_mask:0xf bound_ctrl:1
	s_nop 1
	v_add_f32_dpp v65, v65, v65 row_half_mirror row_mask:0xf bank_mask:0xf bound_ctrl:1
	s_nop 1
	v_mov_b32_dpp v68, v65 row_mirror row_mask:0xf bank_mask:0xf
	s_and_saveexec_b64 s[0:1], vcc
	s_cbranch_execz .LBB0_142
	v_add_f32_e32 v68, v65, v68
	v_ashrrev_i32_e32 v65, 31, v64
	v_lshl_add_u64 v[64:65], v[64:65], 2, s[12:13]
	global_atomic_add_f32 v[64:65], v68, off
.LBB0_142:
	s_or_b64 exec, exec, s[0:1]
	v_add_u32_e32 v64, v101, v67
	v_lshl_add_u32 v76, v64, 10, v128
	v_ashrrev_i32_e32 v77, 31, v76
	v_lshlrev_b64 v[78:79], 2, v[76:77]
	v_lshl_add_u64 v[68:69], s[4:5], 0, v[78:79]
	ds_read_b128 v[72:75], v102
	v_lshl_add_u64 v[78:79], s[8:9], 0, v[78:79]
	v_lshl_add_u64 v[76:77], v[76:77], 1, s[10:11]
	s_waitcnt vmcnt(11) lgkmcnt(0)
	v_mov_b32_e32 v68, v152
	v_mov_b32_e32 v69, v153
	v_mov_b32_e32 v70, v154
	v_mov_b32_e32 v71, v155
	v_pk_fma_f32 v[68:69], v[72:73], 0.5, v[68:69] op_sel_hi:[1,0,1]
	v_pk_fma_f32 v[70:71], v[74:75], 0.5, v[70:71] op_sel_hi:[1,0,1]
	global_store_dwordx4 v[78:79], v[68:71], off
	v_cvt_pk_bf16_f32 v72, v68, v69
	v_cvt_pk_bf16_f32 v73, v70, v71
	v_pk_mul_f32 v[68:69], v[68:69], v[68:69]
	v_pk_mul_f32 v[70:71], v[70:71], v[70:71]
	v_add_f32_e32 v65, v68, v69
	v_add_f32_e32 v65, v70, v65
	v_add_f32_e32 v65, v71, v65
	v_mov_b32_e32 v68, 0
	global_store_dwordx2 v[76:77], v[72:73], off
	v_add_f32_dpp v65, v65, v65 quad_perm:[1,0,3,2] row_mask:0xf bank_mask:0xf bound_ctrl:1
	s_nop 1
	v_add_f32_dpp v65, v65, v65 quad_perm:[2,3,0,1] row_mask:0xf bank_mask:0xf bound_ctrl:1
	s_nop 1
	v_add_f32_dpp v65, v65, v65 row_half_mirror row_mask:0xf bank_mask:0xf bound_ctrl:1
	s_nop 1
	v_mov_b32_dpp v68, v65 row_mirror row_mask:0xf bank_mask:0xf
	s_and_saveexec_b64 s[0:1], vcc
	s_cbranch_execz .LBB0_144
	v_add_f32_e32 v68, v65, v68
	v_ashrrev_i32_e32 v65, 31, v64
	v_lshl_add_u64 v[64:65], v[64:65], 2, s[12:13]
	global_atomic_add_f32 v[64:65], v68, off
.LBB0_144:
	s_or_b64 exec, exec, s[0:1]
	v_add_u32_e32 v64, v103, v67
	v_lshl_add_u32 v76, v64, 10, v128
	v_ashrrev_i32_e32 v77, 31, v76
	v_lshlrev_b64 v[78:79], 2, v[76:77]
	v_lshl_add_u64 v[68:69], s[4:5], 0, v[78:79]
	ds_read_b128 v[72:75], v98
	v_lshl_add_u64 v[78:79], s[8:9], 0, v[78:79]
	v_lshl_add_u64 v[76:77], v[76:77], 1, s[10:11]
	s_waitcnt vmcnt(13) lgkmcnt(0)
	v_mov_b32_e32 v68, v156
	v_mov_b32_e32 v69, v157
	v_mov_b32_e32 v70, v158
	v_mov_b32_e32 v71, v159
	v_pk_fma_f32 v[68:69], v[72:73], 0.5, v[68:69] op_sel_hi:[1,0,1]
	v_pk_fma_f32 v[70:71], v[74:75], 0.5, v[70:71] op_sel_hi:[1,0,1]
	global_store_dwordx4 v[78:79], v[68:71], off
	v_cvt_pk_bf16_f32 v72, v68, v69
	v_cvt_pk_bf16_f32 v73, v70, v71
	v_pk_mul_f32 v[68:69], v[68:69], v[68:69]
	v_pk_mul_f32 v[70:71], v[70:71], v[70:71]
	v_add_f32_e32 v65, v68, v69
	v_add_f32_e32 v65, v70, v65
	v_add_f32_e32 v65, v71, v65
	v_mov_b32_e32 v68, 0
	global_store_dwordx2 v[76:77], v[72:73], off
	v_add_f32_dpp v65, v65, v65 quad_perm:[1,0,3,2] row_mask:0xf bank_mask:0xf bound_ctrl:1
	s_nop 1
	v_add_f32_dpp v65, v65, v65 quad_perm:[2,3,0,1] row_mask:0xf bank_mask:0xf bound_ctrl:1
	s_nop 1
	v_add_f32_dpp v65, v65, v65 row_half_mirror row_mask:0xf bank_mask:0xf bound_ctrl:1
	s_nop 1
	v_mov_b32_dpp v68, v65 row_mirror row_mask:0xf bank_mask:0xf
	s_and_saveexec_b64 s[0:1], vcc
	s_cbranch_execz .LBB0_146
	v_add_f32_e32 v68, v65, v68
	v_ashrrev_i32_e32 v65, 31, v64
	v_lshl_add_u64 v[64:65], v[64:65], 2, s[12:13]
	global_atomic_add_f32 v[64:65], v68, off
.LBB0_146:
	s_or_b64 exec, exec, s[0:1]
	v_add_u32_e32 v64, v105, v67
	v_lshl_add_u32 v76, v64, 10, v128
	v_ashrrev_i32_e32 v77, 31, v76
	v_lshlrev_b64 v[78:79], 2, v[76:77]
	v_lshl_add_u64 v[68:69], s[4:5], 0, v[78:79]
	ds_read_b128 v[72:75], v98 offset:1088
	v_lshl_add_u64 v[78:79], s[8:9], 0, v[78:79]
	v_lshl_add_u64 v[76:77], v[76:77], 1, s[10:11]
	s_waitcnt vmcnt(15) lgkmcnt(0)
	v_mov_b32_e32 v68, v160
	v_mov_b32_e32 v69, v161
	v_mov_b32_e32 v70, v162
	v_mov_b32_e32 v71, v163
	v_pk_fma_f32 v[68:69], v[72:73], 0.5, v[68:69] op_sel_hi:[1,0,1]
	v_pk_fma_f32 v[70:71], v[74:75], 0.5, v[70:71] op_sel_hi:[1,0,1]
	global_store_dwordx4 v[78:79], v[68:71], off
	v_cvt_pk_bf16_f32 v72, v68, v69
	v_cvt_pk_bf16_f32 v73, v70, v71
	v_pk_mul_f32 v[68:69], v[68:69], v[68:69]
	v_pk_mul_f32 v[70:71], v[70:71], v[70:71]
	v_add_f32_e32 v65, v68, v69
	v_add_f32_e32 v65, v70, v65
	v_add_f32_e32 v65, v71, v65
	v_mov_b32_e32 v68, 0
	global_store_dwordx2 v[76:77], v[72:73], off
	v_add_f32_dpp v65, v65, v65 quad_perm:[1,0,3,2] row_mask:0xf bank_mask:0xf bound_ctrl:1
	s_nop 1
	v_add_f32_dpp v65, v65, v65 quad_perm:[2,3,0,1] row_mask:0xf bank_mask:0xf bound_ctrl:1
	s_nop 1
	v_add_f32_dpp v65, v65, v65 row_half_mirror row_mask:0xf bank_mask:0xf bound_ctrl:1
	s_nop 1
	v_mov_b32_dpp v68, v65 row_mirror row_mask:0xf bank_mask:0xf
	s_and_saveexec_b64 s[0:1], vcc
	s_cbranch_execz .LBB0_148
	v_add_f32_e32 v68, v65, v68
	v_ashrrev_i32_e32 v65, 31, v64
	v_lshl_add_u64 v[64:65], v[64:65], 2, s[12:13]
	global_atomic_add_f32 v[64:65], v68, off
;   __device__ __forceinline__ void tile(const float* reg, int row0, int col0, int lane) const {
;     rows4(reg, lane, [&](int it, int rr, int c4, float4 v) {
;       int row = row0 + rr, idx = row * 1024 + col0 + c4;
;       float4 xo = *(const float4*)(xold + idx);
;       v.x = fmaf(coef, v.x, xo.x); v.y = fmaf(coef, v.y, xo.y); v.z = fmaf(coef, v.z, xo.z); v.w = fmaf(coef, v.w, xo.w);
;       *(float4*)(xnew + idx) = v;
;       *(bf16x4*)(xb + idx) = pack4(v.x, v.y, v.z, v.w);
;       float s = row16_sum(v.x * v.x + v.y * v.y + v.z * v.z + v.w * v.w);
;       if ((lane & 15) == 0) atomicAdd(ssqn + row, s);
;     });
.LBB0_148:
	s_or_b64 exec, exec, s[0:1]
	v_add_u32_e32 v64, v106, v67
	v_lshl_add_u32 v76, v64, 10, v128
	v_ashrrev_i32_e32 v77, 31, v76
	v_lshlrev_b64 v[78:79], 2, v[76:77]
	v_lshl_add_u64 v[68:69], s[4:5], 0, v[78:79]
	ds_read_b128 v[72:75], v98 offset:2176
	v_lshl_add_u64 v[78:79], s[8:9], 0, v[78:79]
	v_lshl_add_u64 v[76:77], v[76:77], 1, s[10:11]
	s_waitcnt vmcnt(17) lgkmcnt(0)
	v_mov_b32_e32 v68, v164
	v_mov_b32_e32 v69, v165
	v_mov_b32_e32 v70, v166
	v_mov_b32_e32 v71, v167
	v_pk_fma_f32 v[68:69], v[72:73], 0.5, v[68:69] op_sel_hi:[1,0,1]
	v_pk_fma_f32 v[70:71], v[74:75], 0.5, v[70:71] op_sel_hi:[1,0,1]
	global_store_dwordx4 v[78:79], v[68:71], off
	v_cvt_pk_bf16_f32 v72, v68, v69
	v_cvt_pk_bf16_f32 v73, v70, v71
	v_pk_mul_f32 v[68:69], v[68:69], v[68:69]
	v_pk_mul_f32 v[70:71], v[70:71], v[70:71]
	v_add_f32_e32 v65, v68, v69
	v_add_f32_e32 v65, v70, v65
	v_add_f32_e32 v65, v71, v65
	v_mov_b32_e32 v68, 0
	global_store_dwordx2 v[76:77], v[72:73], off
	v_add_f32_dpp v65, v65, v65 quad_perm:[1,0,3,2] row_mask:0xf bank_mask:0xf bound_ctrl:1
	s_nop 1
	v_add_f32_dpp v65, v65, v65 quad_perm:[2,3,0,1] row_mask:0xf bank_mask:0xf bound_ctrl:1
	s_nop 1
	v_add_f32_dpp v65, v65, v65 row_half_mirror row_mask:0xf bank_mask:0xf bound_ctrl:1
	s_nop 1
	v_mov_b32_dpp v68, v65 row_mirror row_mask:0xf bank_mask:0xf
	s_and_saveexec_b64 s[0:1], vcc
	s_cbranch_execz .LBB0_150
	v_add_f32_e32 v68, v65, v68
	v_ashrrev_i32_e32 v65, 31, v64
	v_lshl_add_u64 v[64:65], v[64:65], 2, s[12:13]
	global_atomic_add_f32 v[64:65], v68, off
.LBB0_150:
	s_or_b64 exec, exec, s[0:1]
	v_add_u32_e32 v64, v107, v67
	v_lshl_add_u32 v76, v64, 10, v128
	v_ashrrev_i32_e32 v77, 31, v76
	v_lshlrev_b64 v[78:79], 2, v[76:77]
	v_lshl_add_u64 v[68:69], s[4:5], 0, v[78:79]
	ds_read_b128 v[72:75], v98 offset:3264
	v_lshl_add_u64 v[78:79], s[8:9], 0, v[78:79]
	v_lshl_add_u64 v[76:77], v[76:77], 1, s[10:11]
	s_waitcnt vmcnt(19) lgkmcnt(0)
	v_mov_b32_e32 v68, v168
	v_mov_b32_e32 v69, v169
	v_mov_b32_e32 v70, v170
	v_mov_b32_e32 v71, v171
	v_pk_fma_f32 v[68:69], v[72:73], 0.5, v[68:69] op_sel_hi:[1,0,1]
	v_pk_fma_f32 v[70:71], v[74:75], 0.5, v[70:71] op_sel_hi:[1,0,1]
	global_store_dwordx4 v[78:79], v[68:71], off
	v_cvt_pk_bf16_f32 v72, v68, v69
	v_cvt_pk_bf16_f32 v73, v70, v71
	v_pk_mul_f32 v[68:69], v[68:69], v[68:69]
	v_pk_mul_f32 v[70:71], v[70:71], v[70:71]
	v_add_f32_e32 v65, v68, v69
	v_add_f32_e32 v65, v70, v65
	v_add_f32_e32 v65, v71, v65
	v_mov_b32_e32 v68, 0
	global_store_dwordx2 v[76:77], v[72:73], off
	v_add_f32_dpp v65, v65, v65 quad_perm:[1,0,3,2] row_mask:0xf bank_mask:0xf bound_ctrl:1
	s_nop 1
	v_add_f32_dpp v65, v65, v65 quad_perm:[2,3,0,1] row_mask:0xf bank_mask:0xf bound_ctrl:1
	s_nop 1
	v_add_f32_dpp v65, v65, v65 row_half_mirror row_mask:0xf bank_mask:0xf bound_ctrl:1
	s_nop 1
	v_mov_b32_dpp v68, v65 row_mirror row_mask:0xf bank_mask:0xf
	s_and_saveexec_b64 s[0:1], vcc
	s_cbranch_execz .LBB0_152
	v_add_f32_e32 v68, v65, v68
	v_ashrrev_i32_e32 v65, 31, v64
	v_lshl_add_u64 v[64:65], v[64:65], 2, s[12:13]
	global_atomic_add_f32 v[64:65], v68, off
.LBB0_152:
	s_or_b64 exec, exec, s[0:1]
	v_add_u32_e32 v64, v108, v67
	v_lshl_add_u32 v76, v64, 10, v128
	v_ashrrev_i32_e32 v77, 31, v76
	v_lshlrev_b64 v[78:79], 2, v[76:77]
	v_lshl_add_u64 v[68:69], s[4:5], 0, v[78:79]
	ds_read_b128 v[72:75], v98 offset:4352
	v_lshl_add_u64 v[78:79], s[8:9], 0, v[78:79]
	v_mov_b32_e32 v67, 0
	v_lshl_add_u64 v[76:77], v[76:77], 1, s[10:11]
	s_waitcnt vmcnt(21) lgkmcnt(0)
	v_mov_b32_e32 v68, v172
	v_mov_b32_e32 v69, v173
	v_mov_b32_e32 v70, v174
	v_mov_b32_e32 v71, v175
	v_pk_fma_f32 v[68:69], v[72:73], 0.5, v[68:69] op_sel_hi:[1,0,1]
	v_pk_fma_f32 v[70:71], v[74:75], 0.5, v[70:71] op_sel_hi:[1,0,1]
	global_store_dwordx4 v[78:79], v[68:71], off
	v_cvt_pk_bf16_f32 v72, v68, v69
	v_cvt_pk_bf16_f32 v73, v70, v71
	v_pk_mul_f32 v[68:69], v[68:69], v[68:69]
	v_pk_mul_f32 v[70:71], v[70:71], v[70:71]
	v_add_f32_e32 v65, v68, v69
	v_add_f32_e32 v65, v70, v65
	v_add_f32_e32 v65, v71, v65
	global_store_dwordx2 v[76:77], v[72:73], off
	s_nop 0
	v_add_f32_dpp v65, v65, v65 quad_perm:[1,0,3,2] row_mask:0xf bank_mask:0xf bound_ctrl:1
	s_nop 1
	v_add_f32_dpp v65, v65, v65 quad_perm:[2,3,0,1] row_mask:0xf bank_mask:0xf bound_ctrl:1
	s_nop 1
	v_add_f32_dpp v65, v65, v65 row_half_mirror row_mask:0xf bank_mask:0xf bound_ctrl:1
	s_nop 1
	v_mov_b32_dpp v67, v65 row_mirror row_mask:0xf bank_mask:0xf
	s_and_saveexec_b64 s[0:1], vcc
	s_cbranch_execz .LBB0_154
	v_add_f32_e32 v67, v65, v67
	v_ashrrev_i32_e32 v65, 31, v64
	v_lshl_add_u64 v[64:65], v[64:65], 2, s[12:13]
	global_atomic_add_f32 v[64:65], v67, off
;   __device__ __forceinline__ void tile(const float* reg, int row0, int col0, int lane) const {
;     rows4(reg, lane, [&](int it, int rr, int c4, float4 v) {
;       int row = row0 + rr, idx = row * 1024 + col0 + c4;
;       float4 xo = *(const float4*)(xold + idx);
;       v.x = fmaf(coef, v.x, xo.x); v.y = fmaf(coef, v.y, xo.y); v.z = fmaf(coef, v.z, xo.z); v.w = fmaf(coef, v.w, xo.w);
;       *(float4*)(xnew + idx) = v;
;       *(bf16x4*)(xb + idx) = pack4(v.x, v.y, v.z, v.w);
;       float s = row16_sum(v.x * v.x + v.y * v.y + v.z * v.z + v.w * v.w);
;       if ((lane & 15) == 0) atomicAdd(ssqn + row, s);
;     });
; template <int MF, class Epi>
; __device__ __forceinline__ void staged_epilogue(f32x4 (&acc)[MF][4], int row0, int col0, const Epi& epi) {
;     ...
;         for (int j = 0; j < 4; ++j) reg[(mm * 16 + fq * 4 + j) * 68 + n * 16 + fr] = acc[mp * 2 + mm][n][j];
.LBB0_154:
	s_or_b64 exec, exec, s[0:1]
	ds_write2_b32 v131, v56, v60 offset1:16
	ds_write2_b32 v131, v57, v61 offset0:68 offset1:84
	ds_write2_b32 v131, v58, v62 offset0:136 offset1:152
	ds_write2_b32 v131, v59, v63 offset0:204 offset1:220
	ds_write2_b32 v131, v48, v52 offset0:32 offset1:48
	ds_write2_b32 v131, v49, v53 offset0:100 offset1:116
	ds_write2_b32 v131, v50, v54 offset0:168 offset1:184
	ds_write2_b32 v131, v51, v55 offset0:236 offset1:252
	ds_write2_b32 v112, v40, v44 offset0:64 offset1:80
	ds_write2_b32 v112, v41, v45 offset0:132 offset1:148
	ds_write2_b32 v112, v42, v46 offset0:200 offset1:216
	ds_write2_b32 v104, v43, v47 offset0:12 offset1:28
	ds_write2_b32 v112, v32, v36 offset0:96 offset1:112
	ds_write2_b32 v112, v33, v37 offset0:164 offset1:180
	ds_write2_b32 v112, v34, v38 offset0:232 offset1:248
	ds_write2_b32 v104, v35, v39 offset0:44 offset1:60
	v_add_u32_e32 v185, 64, v129
	v_add_u32_e32 v184, v130, v185
	v_lshl_add_u32 v178, v184, 10, v128
	v_ashrrev_i32_e32 v179, 31, v178
	v_lshlrev_b64 v[180:181], 2, v[178:179]
	v_lshl_add_u64 v[176:177], s[4:5], 0, v[180:181]
	global_load_dwordx4 v[144:147], v[176:177], off
	v_add_u32_e32 v185, 64, v129
	v_add_u32_e32 v184, v99, v185
	v_lshl_add_u32 v178, v184, 10, v128
	v_ashrrev_i32_e32 v179, 31, v178
	v_lshlrev_b64 v[180:181], 2, v[178:179]
	v_lshl_add_u64 v[176:177], s[4:5], 0, v[180:181]
	global_load_dwordx4 v[148:151], v[176:177], off
	v_add_u32_e32 v185, 64, v129
	v_add_u32_e32 v184, v101, v185
	v_lshl_add_u32 v178, v184, 10, v128
	v_ashrrev_i32_e32 v179, 31, v178
	v_lshlrev_b64 v[180:181], 2, v[178:179]
	v_lshl_add_u64 v[176:177], s[4:5], 0, v[180:181]
	global_load_dwordx4 v[152:155], v[176:177], off
	v_add_u32_e32 v185, 64, v129
	v_add_u32_e32 v184, v103, v185
	v_lshl_add_u32 v178, v184, 10, v128
	v_ashrrev_i32_e32 v179, 31, v178
	v_lshlrev_b64 v[180:181], 2, v[178:179]
	v_lshl_add_u64 v[176:177], s[4:5], 0, v[180:181]
	global_load_dwordx4 v[156:159], v[176:177], off
	v_add_u32_e32 v185, 64, v129
	v_add_u32_e32 v184, v105, v185
	v_lshl_add_u32 v178, v184, 10, v128
	v_ashrrev_i32_e32 v179, 31, v178
	v_lshlrev_b64 v[180:181], 2, v[178:179]
	v_lshl_add_u64 v[176:177], s[4:5], 0, v[180:181]
	global_load_dwordx4 v[160:163], v[176:177], off
	v_add_u32_e32 v185, 64, v129
	v_add_u32_e32 v184, v106, v185
	v_lshl_add_u32 v178, v184, 10, v128
	v_ashrrev_i32_e32 v179, 31, v178
	v_lshlrev_b64 v[180:181], 2, v[178:179]
	v_lshl_add_u64 v[176:177], s[4:5], 0, v[180:181]
	global_load_dwordx4 v[164:167], v[176:177], off
	v_add_u32_e32 v185, 64, v129
	v_add_u32_e32 v184, v107, v185
	v_lshl_add_u32 v178, v184, 10, v128
	v_ashrrev_i32_e32 v179, 31, v178
	v_lshlrev_b64 v[180:181], 2, v[178:179]
	v_lshl_add_u64 v[176:177], s[4:5], 0, v[180:181]
	global_load_dwordx4 v[168:171], v[176:177], off
	v_add_u32_e32 v176, 64, v129
	v_add_u32_e32 v184, v108, v176
	v_lshl_add_u32 v178, v184, 10, v128
	v_ashrrev_i32_e32 v179, 31, v178
	v_lshlrev_b64 v[180:181], 2, v[178:179]
	v_lshl_add_u64 v[176:177], s[4:5], 0, v[180:181]
	global_load_dwordx4 v[172:175], v[176:177], off
	v_add_u32_e32 v34, 64, v129
	v_add_u32_e32 v32, v130, v34
	v_lshl_add_u32 v44, v32, 10, v128
	v_ashrrev_i32_e32 v45, 31, v44
	v_lshlrev_b64 v[46:47], 2, v[44:45]
	v_lshl_add_u64 v[36:37], s[4:5], 0, v[46:47]
	ds_read_b128 v[40:43], v66
	v_lshl_add_u64 v[46:47], s[8:9], 0, v[46:47]
	v_mov_b32_e32 v35, 0
	v_lshl_add_u64 v[44:45], v[44:45], 1, s[10:11]
	s_waitcnt vmcnt(7) lgkmcnt(0)
	v_mov_b32_e32 v36, v144
	v_mov_b32_e32 v37, v145
	v_mov_b32_e32 v38, v146
	v_mov_b32_e32 v39, v147
	v_pk_fma_f32 v[36:37], v[40:41], 0.5, v[36:37] op_sel_hi:[1,0,1]
	v_pk_fma_f32 v[38:39], v[42:43], 0.5, v[38:39] op_sel_hi:[1,0,1]
	global_store_dwordx4 v[46:47], v[36:39], off
	v_cvt_pk_bf16_f32 v40, v36, v37
	v_cvt_pk_bf16_f32 v41, v38, v39
	v_pk_mul_f32 v[36:37], v[36:37], v[36:37]
	v_pk_mul_f32 v[38:39], v[38:39], v[38:39]
	v_add_f32_e32 v33, v36, v37
	v_add_f32_e32 v33, v38, v33
	v_add_f32_e32 v33, v39, v33
	global_store_dwordx2 v[44:45], v[40:41], off
	s_nop 0
	v_add_f32_dpp v33, v33, v33 quad_perm:[1,0,3,2] row_mask:0xf bank_mask:0xf bound_ctrl:1
	s_nop 1
	v_add_f32_dpp v33, v33, v33 quad_perm:[2,3,0,1] row_mask:0xf bank_mask:0xf bound_ctrl:1
	s_nop 1
	v_add_f32_dpp v33, v33, v33 row_half_mirror row_mask:0xf bank_mask:0xf bound_ctrl:1
	s_nop 1
	v_mov_b32_dpp v35, v33 row_mirror row_mask:0xf bank_mask:0xf
	s_and_saveexec_b64 s[0:1], vcc
	s_cbranch_execz .LBB0_156
	v_add_f32_e32 v35, v33, v35
	v_ashrrev_i32_e32 v33, 31, v32
	v_lshl_add_u64 v[32:33], v[32:33], 2, s[12:13]
	global_atomic_add_f32 v[32:33], v35, off
.LBB0_156:
	s_or_b64 exec, exec, s[0:1]
	v_add_u32_e32 v32, v99, v34
	v_lshl_add_u32 v44, v32, 10, v128
	v_ashrrev_i32_e32 v45, 31, v44
	v_lshlrev_b64 v[46:47], 2, v[44:45]
	v_lshl_add_u64 v[36:37], s[4:5], 0, v[46:47]
	ds_read_b128 v[40:43], v100
	v_lshl_add_u64 v[46:47], s[8:9], 0, v[46:47]
	v_mov_b32_e32 v35, 0
	v_lshl_add_u64 v[44:45], v[44:45], 1, s[10:11]
	s_waitcnt vmcnt(9) lgkmcnt(0)
	v_mov_b32_e32 v36, v148
	v_mov_b32_e32 v37, v149
	v_mov_b32_e32 v38, v150
	v_mov_b32_e32 v39, v151
	v_pk_fma_f32 v[36:37], v[40:41], 0.5, v[36:37] op_sel_hi:[1,0,1]
	v_pk_fma_f32 v[38:39], v[42:43], 0.5, v[38:39] op_sel_hi:[1,0,1]
	global_store_dwordx4 v[46:47], v[36:39], off
	v_cvt_pk_bf16_f32 v40, v36, v37
	v_cvt_pk_bf16_f32 v41, v38, v39
	v_pk_mul_f32 v[36:37], v[36:37], v[36:37]
	v_pk_mul_f32 v[38:39], v[38:39], v[38:39]
	v_add_f32_e32 v33, v36, v37
	v_add_f32_e32 v33, v38, v33
	v_add_f32_e32 v33, v39, v33
	global_store_dwordx2 v[44:45], v[40:41], off
	s_nop 0
	v_add_f32_dpp v33, v33, v33 quad_perm:[1,0,3,2] row_mask:0xf bank_mask:0xf bound_ctrl:1
	s_nop 1
	v_add_f32_dpp v33, v33, v33 quad_perm:[2,3,0,1] row_mask:0xf bank_mask:0xf bound_ctrl:1
	s_nop 1
	v_add_f32_dpp v33, v33, v33 row_half_mirror row_mask:0xf bank_mask:0xf bound_ctrl:1
	s_nop 1
	v_mov_b32_dpp v35, v33 row_mirror row_mask:0xf bank_mask:0xf
	s_and_saveexec_b64 s[0:1], vcc
	s_cbranch_execz .LBB0_158
	v_add_f32_e32 v35, v33, v35
	v_ashrrev_i32_e32 v33, 31, v32
	v_lshl_add_u64 v[32:33], v[32:33], 2, s[12:13]
	global_atomic_add_f32 v[32:33], v35, off
;   __device__ __forceinline__ void tile(const float* reg, int row0, int col0, int lane) const {
;     rows4(reg, lane, [&](int it, int rr, int c4, float4 v) {
;       int row = row0 + rr, idx = row * 1024 + col0 + c4;
;       float4 xo = *(const float4*)(xold + idx);
;       v.x = fmaf(coef, v.x, xo.x); v.y = fmaf(coef, v.y, xo.y); v.z = fmaf(coef, v.z, xo.z); v.w = fmaf(coef, v.w, xo.w);
;       *(float4*)(xnew + idx) = v;
;       *(bf16x4*)(xb + idx) = pack4(v.x, v.y, v.z, v.w);
;       float s = row16_sum(v.x * v.x + v.y * v.y + v.z * v.z + v.w * v.w);
;       if ((lane & 15) == 0) atomicAdd(ssqn + row, s);
;     });
.LBB0_158:
	s_or_b64 exec, exec, s[0:1]
	v_add_u32_e32 v32, v101, v34
	v_lshl_add_u32 v44, v32, 10, v128
	v_ashrrev_i32_e32 v45, 31, v44
	v_lshlrev_b64 v[46:47], 2, v[44:45]
	v_lshl_add_u64 v[36:37], s[4:5], 0, v[46:47]
	ds_read_b128 v[40:43], v102
	v_lshl_add_u64 v[46:47], s[8:9], 0, v[46:47]
	v_mov_b32_e32 v35, 0
	v_lshl_add_u64 v[44:45], v[44:45], 1, s[10:11]
	s_waitcnt vmcnt(11) lgkmcnt(0)
	v_mov_b32_e32 v36, v152
	v_mov_b32_e32 v37, v153
	v_mov_b32_e32 v38, v154
	v_mov_b32_e32 v39, v155
	v_pk_fma_f32 v[36:37], v[40:41], 0.5, v[36:37] op_sel_hi:[1,0,1]
	v_pk_fma_f32 v[38:39], v[42:43], 0.5, v[38:39] op_sel_hi:[1,0,1]
	global_store_dwordx4 v[46:47], v[36:39], off
	v_cvt_pk_bf16_f32 v40, v36, v37
	v_cvt_pk_bf16_f32 v41, v38, v39
	v_pk_mul_f32 v[36:37], v[36:37], v[36:37]
	v_pk_mul_f32 v[38:39], v[38:39], v[38:39]
	v_add_f32_e32 v33, v36, v37
	v_add_f32_e32 v33, v38, v33
	v_add_f32_e32 v33, v39, v33
	global_store_dwordx2 v[44:45], v[40:41], off
	s_nop 0
	v_add_f32_dpp v33, v33, v33 quad_perm:[1,0,3,2] row_mask:0xf bank_mask:0xf bound_ctrl:1
	s_nop 1
	v_add_f32_dpp v33, v33, v33 quad_perm:[2,3,0,1] row_mask:0xf bank_mask:0xf bound_ctrl:1
	s_nop 1
	v_add_f32_dpp v33, v33, v33 row_half_mirror row_mask:0xf bank_mask:0xf bound_ctrl:1
	s_nop 1
	v_mov_b32_dpp v35, v33 row_mirror row_mask:0xf bank_mask:0xf
	s_and_saveexec_b64 s[0:1], vcc
	s_cbranch_execz .LBB0_160
	v_add_f32_e32 v35, v33, v35
	v_ashrrev_i32_e32 v33, 31, v32
	v_lshl_add_u64 v[32:33], v[32:33], 2, s[12:13]
	global_atomic_add_f32 v[32:33], v35, off
.LBB0_160:
	s_or_b64 exec, exec, s[0:1]
	v_add_u32_e32 v32, v103, v34
	v_lshl_add_u32 v44, v32, 10, v128
	v_ashrrev_i32_e32 v45, 31, v44
	v_lshlrev_b64 v[46:47], 2, v[44:45]
	v_lshl_add_u64 v[36:37], s[4:5], 0, v[46:47]
	ds_read_b128 v[40:43], v98
	v_lshl_add_u64 v[46:47], s[8:9], 0, v[46:47]
	v_mov_b32_e32 v35, 0
	v_lshl_add_u64 v[44:45], v[44:45], 1, s[10:11]
	s_waitcnt vmcnt(13) lgkmcnt(0)
	v_mov_b32_e32 v36, v156
	v_mov_b32_e32 v37, v157
	v_mov_b32_e32 v38, v158
	v_mov_b32_e32 v39, v159
	v_pk_fma_f32 v[36:37], v[40:41], 0.5, v[36:37] op_sel_hi:[1,0,1]
	v_pk_fma_f32 v[38:39], v[42:43], 0.5, v[38:39] op_sel_hi:[1,0,1]
	global_store_dwordx4 v[46:47], v[36:39], off
	v_cvt_pk_bf16_f32 v40, v36, v37
	v_cvt_pk_bf16_f32 v41, v38, v39
	v_pk_mul_f32 v[36:37], v[36:37], v[36:37]
	v_pk_mul_f32 v[38:39], v[38:39], v[38:39]
	v_add_f32_e32 v33, v36, v37
	v_add_f32_e32 v33, v38, v33
	v_add_f32_e32 v33, v39, v33
	global_store_dwordx2 v[44:45], v[40:41], off
	s_nop 0
	v_add_f32_dpp v33, v33, v33 quad_perm:[1,0,3,2] row_mask:0xf bank_mask:0xf bound_ctrl:1
	s_nop 1
	v_add_f32_dpp v33, v33, v33 quad_perm:[2,3,0,1] row_mask:0xf bank_mask:0xf bound_ctrl:1
	s_nop 1
	v_add_f32_dpp v33, v33, v33 row_half_mirror row_mask:0xf bank_mask:0xf bound_ctrl:1
	s_nop 1
	v_mov_b32_dpp v35, v33 row_mirror row_mask:0xf bank_mask:0xf
	s_and_saveexec_b64 s[0:1], vcc
	s_cbranch_execz .LBB0_162
	v_add_f32_e32 v35, v33, v35
	v_ashrrev_i32_e32 v33, 31, v32
	v_lshl_add_u64 v[32:33], v[32:33], 2, s[12:13]
	global_atomic_add_f32 v[32:33], v35, off
.LBB0_162:
	s_or_b64 exec, exec, s[0:1]
	v_add_u32_e32 v32, v105, v34
	v_lshl_add_u32 v44, v32, 10, v128
	v_ashrrev_i32_e32 v45, 31, v44
	v_lshlrev_b64 v[46:47], 2, v[44:45]
	v_lshl_add_u64 v[36:37], s[4:5], 0, v[46:47]
	ds_read_b128 v[40:43], v98 offset:1088
	v_lshl_add_u64 v[46:47], s[8:9], 0, v[46:47]
	v_mov_b32_e32 v35, 0
	v_lshl_add_u64 v[44:45], v[44:45], 1, s[10:11]
	s_waitcnt vmcnt(15) lgkmcnt(0)
	v_mov_b32_e32 v36, v160
	v_mov_b32_e32 v37, v161
	v_mov_b32_e32 v38, v162
	v_mov_b32_e32 v39, v163
	v_pk_fma_f32 v[36:37], v[40:41], 0.5, v[36:37] op_sel_hi:[1,0,1]
	v_pk_fma_f32 v[38:39], v[42:43], 0.5, v[38:39] op_sel_hi:[1,0,1]
	global_store_dwordx4 v[46:47], v[36:39], off
	v_cvt_pk_bf16_f32 v40, v36, v37
	v_cvt_pk_bf16_f32 v41, v38, v39
	v_pk_mul_f32 v[36:37], v[36:37], v[36:37]
	v_pk_mul_f32 v[38:39], v[38:39], v[38:39]
	v_add_f32_e32 v33, v36, v37
	v_add_f32_e32 v33, v38, v33
	v_add_f32_e32 v33, v39, v33
	global_store_dwordx2 v[44:45], v[40:41], off
	s_nop 0
	v_add_f32_dpp v33, v33, v33 quad_perm:[1,0,3,2] row_mask:0xf bank_mask:0xf bound_ctrl:1
	s_nop 1
	v_add_f32_dpp v33, v33, v33 quad_perm:[2,3,0,1] row_mask:0xf bank_mask:0xf bound_ctrl:1
	s_nop 1
	v_add_f32_dpp v33, v33, v33 row_half_mirror row_mask:0xf bank_mask:0xf bound_ctrl:1
	s_nop 1
	v_mov_b32_dpp v35, v33 row_mirror row_mask:0xf bank_mask:0xf
	s_and_saveexec_b64 s[0:1], vcc
	s_cbranch_execz .LBB0_164
	v_add_f32_e32 v35, v33, v35
	v_ashrrev_i32_e32 v33, 31, v32
	v_lshl_add_u64 v[32:33], v[32:33], 2, s[12:13]
	global_atomic_add_f32 v[32:33], v35, off
.LBB0_164:
	s_or_b64 exec, exec, s[0:1]
	v_add_u32_e32 v32, v106, v34
	v_lshl_add_u32 v44, v32, 10, v128
	v_ashrrev_i32_e32 v45, 31, v44
	v_lshlrev_b64 v[46:47], 2, v[44:45]
	v_lshl_add_u64 v[36:37], s[4:5], 0, v[46:47]
	ds_read_b128 v[40:43], v98 offset:2176
	v_lshl_add_u64 v[46:47], s[8:9], 0, v[46:47]
	v_mov_b32_e32 v35, 0
	v_lshl_add_u64 v[44:45], v[44:45], 1, s[10:11]
	s_waitcnt vmcnt(17) lgkmcnt(0)
	v_mov_b32_e32 v36, v164
	v_mov_b32_e32 v37, v165
	v_mov_b32_e32 v38, v166
	v_mov_b32_e32 v39, v167
	v_pk_fma_f32 v[36:37], v[40:41], 0.5, v[36:37] op_sel_hi:[1,0,1]
	v_pk_fma_f32 v[38:39], v[42:43], 0.5, v[38:39] op_sel_hi:[1,0,1]
	global_store_dwordx4 v[46:47], v[36:39], off
	v_cvt_pk_bf16_f32 v40, v36, v37
	v_cvt_pk_bf16_f32 v41, v38, v39
	v_pk_mul_f32 v[36:37], v[36:37], v[36:37]
	v_pk_mul_f32 v[38:39], v[38:39], v[38:39]
	v_add_f32_e32 v33, v36, v37
	v_add_f32_e32 v33, v38, v33
	v_add_f32_e32 v33, v39, v33
	global_store_dwordx2 v[44:45], v[40:41], off
	s_nop 0
	v_add_f32_dpp v33, v33, v33 quad_perm:[1,0,3,2] row_mask:0xf bank_mask:0xf bound_ctrl:1
	s_nop 1
	v_add_f32_dpp v33, v33, v33 quad_perm:[2,3,0,1] row_mask:0xf bank_mask:0xf bound_ctrl:1
	s_nop 1
	v_add_f32_dpp v33, v33, v33 row_half_mirror row_mask:0xf bank_mask:0xf bound_ctrl:1
	s_nop 1
	v_mov_b32_dpp v35, v33 row_mirror row_mask:0xf bank_mask:0xf
	s_and_saveexec_b64 s[0:1], vcc
	s_cbranch_execz .LBB0_166
	v_add_f32_e32 v35, v33, v35
	v_ashrrev_i32_e32 v33, 31, v32
	v_lshl_add_u64 v[32:33], v[32:33], 2, s[12:13]
	global_atomic_add_f32 v[32:33], v35, off
;   __device__ __forceinline__ void tile(const float* reg, int row0, int col0, int lane) const {
;     rows4(reg, lane, [&](int it, int rr, int c4, float4 v) {
;       int row = row0 + rr, idx = row * 1024 + col0 + c4;
;       float4 xo = *(const float4*)(xold + idx);
;       v.x = fmaf(coef, v.x, xo.x); v.y = fmaf(coef, v.y, xo.y); v.z = fmaf(coef, v.z, xo.z); v.w = fmaf(coef, v.w, xo.w);
;       *(float4*)(xnew + idx) = v;
;       *(bf16x4*)(xb + idx) = pack4(v.x, v.y, v.z, v.w);
;       float s = row16_sum(v.x * v.x + v.y * v.y + v.z * v.z + v.w * v.w);
;       if ((lane & 15) == 0) atomicAdd(ssqn + row, s);
;     });
; template <int MF, class Epi>
; __device__ __forceinline__ void staged_epilogue(f32x4 (&acc)[MF][4], int row0, int col0, const Epi& epi) {
;     ...
;         for (int j = 0; j < 4; ++j) reg[(mm * 16 + fq * 4 + j) * 68 + n * 16 + fr] = acc[mp * 2 + mm][n][j];
.LBB0_166:
	s_or_b64 exec, exec, s[0:1]
	v_add_u32_e32 v32, v107, v34
	v_lshl_add_u32 v44, v32, 10, v128
	v_ashrrev_i32_e32 v45, 31, v44
	v_lshlrev_b64 v[46:47], 2, v[44:45]
	v_lshl_add_u64 v[36:37], s[4:5], 0, v[46:47]
	ds_read_b128 v[40:43], v98 offset:3264
	v_lshl_add_u64 v[46:47], s[8:9], 0, v[46:47]
	v_mov_b32_e32 v35, 0
	v_lshl_add_u64 v[44:45], v[44:45], 1, s[10:11]
	s_waitcnt vmcnt(19) lgkmcnt(0)
	v_mov_b32_e32 v36, v168
	v_mov_b32_e32 v37, v169
	v_mov_b32_e32 v38, v170
	v_mov_b32_e32 v39, v171
	v_pk_fma_f32 v[36:37], v[40:41], 0.5, v[36:37] op_sel_hi:[1,0,1]
	v_pk_fma_f32 v[38:39], v[42:43], 0.5, v[38:39] op_sel_hi:[1,0,1]
	global_store_dwordx4 v[46:47], v[36:39], off
	v_cvt_pk_bf16_f32 v40, v36, v37
	v_cvt_pk_bf16_f32 v41, v38, v39
	v_pk_mul_f32 v[36:37], v[36:37], v[36:37]
	v_pk_mul_f32 v[38:39], v[38:39], v[38:39]
	v_add_f32_e32 v33, v36, v37
	v_add_f32_e32 v33, v38, v33
	v_add_f32_e32 v33, v39, v33
	global_store_dwordx2 v[44:45], v[40:41], off
	s_nop 0
	v_add_f32_dpp v33, v33, v33 quad_perm:[1,0,3,2] row_mask:0xf bank_mask:0xf bound_ctrl:1
	s_nop 1
	v_add_f32_dpp v33, v33, v33 quad_perm:[2,3,0,1] row_mask:0xf bank_mask:0xf bound_ctrl:1
	s_nop 1
	v_add_f32_dpp v33, v33, v33 row_half_mirror row_mask:0xf bank_mask:0xf bound_ctrl:1
	s_nop 1
	v_mov_b32_dpp v35, v33 row_mirror row_mask:0xf bank_mask:0xf
	s_and_saveexec_b64 s[0:1], vcc
	s_cbranch_execz .LBB0_168
	v_add_f32_e32 v35, v33, v35
	v_ashrrev_i32_e32 v33, 31, v32
	v_lshl_add_u64 v[32:33], v[32:33], 2, s[12:13]
	global_atomic_add_f32 v[32:33], v35, off
.LBB0_168:
	s_or_b64 exec, exec, s[0:1]
	v_add_u32_e32 v32, v108, v34
	v_lshl_add_u32 v42, v32, 10, v128
	v_ashrrev_i32_e32 v43, 31, v42
	v_lshlrev_b64 v[44:45], 2, v[42:43]
	v_lshl_add_u64 v[34:35], s[4:5], 0, v[44:45]
	ds_read_b128 v[38:41], v98 offset:4352
	v_lshl_add_u64 v[44:45], s[8:9], 0, v[44:45]
	v_lshl_add_u64 v[42:43], v[42:43], 1, s[10:11]
	s_waitcnt vmcnt(21) lgkmcnt(0)
	v_mov_b32_e32 v34, v172
	v_mov_b32_e32 v35, v173
	v_mov_b32_e32 v36, v174
	v_mov_b32_e32 v37, v175
	v_pk_fma_f32 v[34:35], v[38:39], 0.5, v[34:35] op_sel_hi:[1,0,1]
	v_pk_fma_f32 v[36:37], v[40:41], 0.5, v[36:37] op_sel_hi:[1,0,1]
	global_store_dwordx4 v[44:45], v[34:37], off
	v_cvt_pk_bf16_f32 v38, v34, v35
	v_cvt_pk_bf16_f32 v39, v36, v37
	v_pk_mul_f32 v[34:35], v[34:35], v[34:35]
	v_pk_mul_f32 v[36:37], v[36:37], v[36:37]
	v_add_f32_e32 v33, v34, v35
	v_add_f32_e32 v33, v36, v33
	v_add_f32_e32 v33, v37, v33
	v_mov_b32_e32 v34, 0
	global_store_dwordx2 v[42:43], v[38:39], off
	v_add_f32_dpp v33, v33, v33 quad_perm:[1,0,3,2] row_mask:0xf bank_mask:0xf bound_ctrl:1
	s_nop 1
	v_add_f32_dpp v33, v33, v33 quad_perm:[2,3,0,1] row_mask:0xf bank_mask:0xf bound_ctrl:1
	s_nop 1
	v_add_f32_dpp v33, v33, v33 row_half_mirror row_mask:0xf bank_mask:0xf bound_ctrl:1
	s_nop 1
	v_mov_b32_dpp v34, v33 row_mirror row_mask:0xf bank_mask:0xf
	s_and_saveexec_b64 s[0:1], vcc
	s_cbranch_execz .LBB0_170
	v_add_f32_e32 v34, v33, v34
	v_ashrrev_i32_e32 v33, 31, v32
	v_lshl_add_u64 v[32:33], v[32:33], 2, s[12:13]
	global_atomic_add_f32 v[32:33], v34, off
.LBB0_170:
	s_or_b64 exec, exec, s[0:1]
	ds_write2_b32 v131, v24, v28 offset1:16
	ds_write2_b32 v131, v25, v29 offset0:68 offset1:84
	ds_write2_b32 v131, v26, v30 offset0:136 offset1:152
	ds_write2_b32 v131, v27, v31 offset0:204 offset1:220
	ds_write2_b32 v131, v16, v20 offset0:32 offset1:48
	ds_write2_b32 v131, v17, v21 offset0:100 offset1:116
	ds_write2_b32 v131, v18, v22 offset0:168 offset1:184
	ds_write2_b32 v131, v19, v23 offset0:236 offset1:252
	ds_write2_b32 v112, v4, v8 offset0:64 offset1:80
	ds_write2_b32 v112, v5, v9 offset0:132 offset1:148
	ds_write2_b32 v112, v6, v10 offset0:200 offset1:216
	ds_write2_b32 v104, v7, v11 offset0:12 offset1:28
	ds_write2_b32 v112, v0, v12 offset0:96 offset1:112
	ds_write2_b32 v112, v1, v13 offset0:164 offset1:180
	ds_write2_b32 v112, v2, v14 offset0:232 offset1:248
	ds_write2_b32 v104, v3, v15 offset0:44 offset1:60
	v_add_u32_e32 v185, 0x60, v129
	v_add_u32_e32 v184, v130, v185
	v_lshl_add_u32 v178, v184, 10, v128
	v_ashrrev_i32_e32 v179, 31, v178
	v_lshlrev_b64 v[180:181], 2, v[178:179]
	v_lshl_add_u64 v[176:177], s[4:5], 0, v[180:181]
	global_load_dwordx4 v[144:147], v[176:177], off
	v_add_u32_e32 v185, 0x60, v129
	v_add_u32_e32 v184, v99, v185
	v_lshl_add_u32 v178, v184, 10, v128
	v_ashrrev_i32_e32 v179, 31, v178
	v_lshlrev_b64 v[180:181], 2, v[178:179]
	v_lshl_add_u64 v[176:177], s[4:5], 0, v[180:181]
	global_load_dwordx4 v[148:151], v[176:177], off
	v_add_u32_e32 v185, 0x60, v129
	v_add_u32_e32 v184, v101, v185
	v_lshl_add_u32 v178, v184, 10, v128
	v_ashrrev_i32_e32 v179, 31, v178
	v_lshlrev_b64 v[180:181], 2, v[178:179]
	v_lshl_add_u64 v[176:177], s[4:5], 0, v[180:181]
	global_load_dwordx4 v[152:155], v[176:177], off
	v_add_u32_e32 v185, 0x60, v129
	v_add_u32_e32 v184, v103, v185
	v_lshl_add_u32 v178, v184, 10, v128
	v_ashrrev_i32_e32 v179, 31, v178
	v_lshlrev_b64 v[180:181], 2, v[178:179]
	v_lshl_add_u64 v[176:177], s[4:5], 0, v[180:181]
	global_load_dwordx4 v[156:159], v[176:177], off
	v_add_u32_e32 v185, 0x60, v129
	v_add_u32_e32 v184, v105, v185
	v_lshl_add_u32 v178, v184, 10, v128
	v_ashrrev_i32_e32 v179, 31, v178
	v_lshlrev_b64 v[180:181], 2, v[178:179]
	v_lshl_add_u64 v[176:177], s[4:5], 0, v[180:181]
	global_load_dwordx4 v[160:163], v[176:177], off
	v_add_u32_e32 v185, 0x60, v129
	v_add_u32_e32 v184, v106, v185
	v_lshl_add_u32 v178, v184, 10, v128
	v_ashrrev_i32_e32 v179, 31, v178
	v_lshlrev_b64 v[180:181], 2, v[178:179]
	v_lshl_add_u64 v[176:177], s[4:5], 0, v[180:181]
	global_load_dwordx4 v[164:167], v[176:177], off
	v_add_u32_e32 v185, 0x60, v129
	v_add_u32_e32 v184, v107, v185
	v_lshl_add_u32 v178, v184, 10, v128
	v_ashrrev_i32_e32 v179, 31, v178
	v_lshlrev_b64 v[180:181], 2, v[178:179]
	v_lshl_add_u64 v[176:177], s[4:5], 0, v[180:181]
	global_load_dwordx4 v[168:171], v[176:177], off
	v_add_u32_e32 v176, 0x60, v129
	v_add_u32_e32 v184, v108, v176
	v_lshl_add_u32 v178, v184, 10, v128
	v_ashrrev_i32_e32 v179, 31, v178
	v_lshlrev_b64 v[180:181], 2, v[178:179]
	v_lshl_add_u64 v[176:177], s[4:5], 0, v[180:181]
	global_load_dwordx4 v[172:175], v[176:177], off
	v_add_u32_e32 v2, 0x60, v129
	v_add_u32_e32 v0, v130, v2
	v_lshl_add_u32 v12, v0, 10, v128
	v_ashrrev_i32_e32 v13, 31, v12
	v_lshlrev_b64 v[14:15], 2, v[12:13]
	v_lshl_add_u64 v[4:5], s[4:5], 0, v[14:15]
	ds_read_b128 v[8:11], v66
	v_lshl_add_u64 v[14:15], s[8:9], 0, v[14:15]
	v_mov_b32_e32 v3, 0
	v_lshl_add_u64 v[12:13], v[12:13], 1, s[10:11]
	s_waitcnt vmcnt(7) lgkmcnt(0)
;   __device__ __forceinline__ void tile(const float* reg, int row0, int col0, int lane) const {
;     rows4(reg, lane, [&](int it, int rr, int c4, float4 v) {
;       int row = row0 + rr, idx = row * 1024 + col0 + c4;
;       float4 xo = *(const float4*)(xold + idx);
;       v.x = fmaf(coef, v.x, xo.x); v.y = fmaf(coef, v.y, xo.y); v.z = fmaf(coef, v.z, xo.z); v.w = fmaf(coef, v.w, xo.w);
;       *(float4*)(xnew + idx) = v;
;       *(bf16x4*)(xb + idx) = pack4(v.x, v.y, v.z, v.w);
;       float s = row16_sum(v.x * v.x + v.y * v.y + v.z * v.z + v.w * v.w);
;       if ((lane & 15) == 0) atomicAdd(ssqn + row, s);
;     });
	v_mov_b32_e32 v4, v144
	v_mov_b32_e32 v5, v145
	v_mov_b32_e32 v6, v146
	v_mov_b32_e32 v7, v147
	v_pk_fma_f32 v[4:5], v[8:9], 0.5, v[4:5] op_sel_hi:[1,0,1]
	v_pk_fma_f32 v[6:7], v[10:11], 0.5, v[6:7] op_sel_hi:[1,0,1]
	global_store_dwordx4 v[14:15], v[4:7], off
	v_cvt_pk_bf16_f32 v8, v4, v5
	v_cvt_pk_bf16_f32 v9, v6, v7
	v_pk_mul_f32 v[4:5], v[4:5], v[4:5]
	v_pk_mul_f32 v[6:7], v[6:7], v[6:7]
	v_add_f32_e32 v1, v4, v5
	v_add_f32_e32 v1, v6, v1
	v_add_f32_e32 v1, v7, v1
	global_store_dwordx2 v[12:13], v[8:9], off
	s_nop 0
	v_add_f32_dpp v1, v1, v1 quad_perm:[1,0,3,2] row_mask:0xf bank_mask:0xf bound_ctrl:1
	s_nop 1
	v_add_f32_dpp v1, v1, v1 quad_perm:[2,3,0,1] row_mask:0xf bank_mask:0xf bound_ctrl:1
	s_nop 1
	v_add_f32_dpp v1, v1, v1 row_half_mirror row_mask:0xf bank_mask:0xf bound_ctrl:1
	s_nop 1
	v_mov_b32_dpp v3, v1 row_mirror row_mask:0xf bank_mask:0xf
	s_and_saveexec_b64 s[0:1], vcc
	s_cbranch_execz .LBB0_172
	v_add_f32_e32 v3, v1, v3
	v_ashrrev_i32_e32 v1, 31, v0
	v_lshl_add_u64 v[0:1], v[0:1], 2, s[12:13]
	global_atomic_add_f32 v[0:1], v3, off
.LBB0_172:
	s_or_b64 exec, exec, s[0:1]
	v_add_u32_e32 v0, v99, v2
	v_lshl_add_u32 v12, v0, 10, v128
	v_ashrrev_i32_e32 v13, 31, v12
	v_lshlrev_b64 v[14:15], 2, v[12:13]
	v_lshl_add_u64 v[4:5], s[4:5], 0, v[14:15]
	ds_read_b128 v[8:11], v100
	v_lshl_add_u64 v[14:15], s[8:9], 0, v[14:15]
	v_mov_b32_e32 v3, 0
	v_lshl_add_u64 v[12:13], v[12:13], 1, s[10:11]
	s_waitcnt vmcnt(9) lgkmcnt(0)
	v_mov_b32_e32 v4, v148
	v_mov_b32_e32 v5, v149
	v_mov_b32_e32 v6, v150
	v_mov_b32_e32 v7, v151
	v_pk_fma_f32 v[4:5], v[8:9], 0.5, v[4:5] op_sel_hi:[1,0,1]
	v_pk_fma_f32 v[6:7], v[10:11], 0.5, v[6:7] op_sel_hi:[1,0,1]
	global_store_dwordx4 v[14:15], v[4:7], off
	v_cvt_pk_bf16_f32 v8, v4, v5
	v_cvt_pk_bf16_f32 v9, v6, v7
	v_pk_mul_f32 v[4:5], v[4:5], v[4:5]
	v_pk_mul_f32 v[6:7], v[6:7], v[6:7]
	v_add_f32_e32 v1, v4, v5
	v_add_f32_e32 v1, v6, v1
	v_add_f32_e32 v1, v7, v1
	global_store_dwordx2 v[12:13], v[8:9], off
	s_nop 0
	v_add_f32_dpp v1, v1, v1 quad_perm:[1,0,3,2] row_mask:0xf bank_mask:0xf bound_ctrl:1
	s_nop 1
	v_add_f32_dpp v1, v1, v1 quad_perm:[2,3,0,1] row_mask:0xf bank_mask:0xf bound_ctrl:1
	s_nop 1
	v_add_f32_dpp v1, v1, v1 row_half_mirror row_mask:0xf bank_mask:0xf bound_ctrl:1
	s_nop 1
	v_mov_b32_dpp v3, v1 row_mirror row_mask:0xf bank_mask:0xf
	s_and_saveexec_b64 s[0:1], vcc
	s_cbranch_execz .LBB0_174
	v_add_f32_e32 v3, v1, v3
	v_ashrrev_i32_e32 v1, 31, v0
	v_lshl_add_u64 v[0:1], v[0:1], 2, s[12:13]
	global_atomic_add_f32 v[0:1], v3, off
.LBB0_174:
	s_or_b64 exec, exec, s[0:1]
	v_add_u32_e32 v0, v101, v2
	v_lshl_add_u32 v12, v0, 10, v128
	v_ashrrev_i32_e32 v13, 31, v12
	v_lshlrev_b64 v[14:15], 2, v[12:13]
	v_lshl_add_u64 v[4:5], s[4:5], 0, v[14:15]
	ds_read_b128 v[8:11], v102
	v_lshl_add_u64 v[14:15], s[8:9], 0, v[14:15]
	v_mov_b32_e32 v3, 0
	v_lshl_add_u64 v[12:13], v[12:13], 1, s[10:11]
	s_waitcnt vmcnt(11) lgkmcnt(0)
	v_mov_b32_e32 v4, v152
	v_mov_b32_e32 v5, v153
	v_mov_b32_e32 v6, v154
	v_mov_b32_e32 v7, v155
	v_pk_fma_f32 v[4:5], v[8:9], 0.5, v[4:5] op_sel_hi:[1,0,1]
	v_pk_fma_f32 v[6:7], v[10:11], 0.5, v[6:7] op_sel_hi:[1,0,1]
	global_store_dwordx4 v[14:15], v[4:7], off
	v_cvt_pk_bf16_f32 v8, v4, v5
	v_cvt_pk_bf16_f32 v9, v6, v7
	v_pk_mul_f32 v[4:5], v[4:5], v[4:5]
	v_pk_mul_f32 v[6:7], v[6:7], v[6:7]
	v_add_f32_e32 v1, v4, v5
	v_add_f32_e32 v1, v6, v1
	v_add_f32_e32 v1, v7, v1
	global_store_dwordx2 v[12:13], v[8:9], off
	s_nop 0
	v_add_f32_dpp v1, v1, v1 quad_perm:[1,0,3,2] row_mask:0xf bank_mask:0xf bound_ctrl:1
	s_nop 1
	v_add_f32_dpp v1, v1, v1 quad_perm:[2,3,0,1] row_mask:0xf bank_mask:0xf bound_ctrl:1
	s_nop 1
	v_add_f32_dpp v1, v1, v1 row_half_mirror row_mask:0xf bank_mask:0xf bound_ctrl:1
	s_nop 1
	v_mov_b32_dpp v3, v1 row_mirror row_mask:0xf bank_mask:0xf
	s_and_saveexec_b64 s[0:1], vcc
	s_cbranch_execz .LBB0_176
	v_add_f32_e32 v3, v1, v3
	v_ashrrev_i32_e32 v1, 31, v0
	v_lshl_add_u64 v[0:1], v[0:1], 2, s[12:13]
	global_atomic_add_f32 v[0:1], v3, off
.LBB0_176:
	s_or_b64 exec, exec, s[0:1]
	v_add_u32_e32 v0, v103, v2
	v_lshl_add_u32 v12, v0, 10, v128
	v_ashrrev_i32_e32 v13, 31, v12
	v_lshlrev_b64 v[14:15], 2, v[12:13]
	v_lshl_add_u64 v[4:5], s[4:5], 0, v[14:15]
	ds_read_b128 v[8:11], v98
	v_lshl_add_u64 v[14:15], s[8:9], 0, v[14:15]
	v_mov_b32_e32 v3, 0
	v_lshl_add_u64 v[12:13], v[12:13], 1, s[10:11]
	s_waitcnt vmcnt(13) lgkmcnt(0)
	v_mov_b32_e32 v4, v156
	v_mov_b32_e32 v5, v157
	v_mov_b32_e32 v6, v158
	v_mov_b32_e32 v7, v159
	v_pk_fma_f32 v[4:5], v[8:9], 0.5, v[4:5] op_sel_hi:[1,0,1]
	v_pk_fma_f32 v[6:7], v[10:11], 0.5, v[6:7] op_sel_hi:[1,0,1]
	global_store_dwordx4 v[14:15], v[4:7], off
	v_cvt_pk_bf16_f32 v8, v4, v5
	v_cvt_pk_bf16_f32 v9, v6, v7
	v_pk_mul_f32 v[4:5], v[4:5], v[4:5]
	v_pk_mul_f32 v[6:7], v[6:7], v[6:7]
	v_add_f32_e32 v1, v4, v5
	v_add_f32_e32 v1, v6, v1
	v_add_f32_e32 v1, v7, v1
	global_store_dwordx2 v[12:13], v[8:9], off
	s_nop 0
	v_add_f32_dpp v1, v1, v1 quad_perm:[1,0,3,2] row_mask:0xf bank_mask:0xf bound_ctrl:1
	s_nop 1
	v_add_f32_dpp v1, v1, v1 quad_perm:[2,3,0,1] row_mask:0xf bank_mask:0xf bound_ctrl:1
	s_nop 1
	v_add_f32_dpp v1, v1, v1 row_half_mirror row_mask:0xf bank_mask:0xf bound_ctrl:1
	s_nop 1
	v_mov_b32_dpp v3, v1 row_mirror row_mask:0xf bank_mask:0xf
	s_and_saveexec_b64 s[0:1], vcc
	s_cbranch_execz .LBB0_178
	v_add_f32_e32 v3, v1, v3
	v_ashrrev_i32_e32 v1, 31, v0
	v_lshl_add_u64 v[0:1], v[0:1], 2, s[12:13]
	global_atomic_add_f32 v[0:1], v3, off
;   __device__ __forceinline__ void tile(const float* reg, int row0, int col0, int lane) const {
;     rows4(reg, lane, [&](int it, int rr, int c4, float4 v) {
;       int row = row0 + rr, idx = row * 1024 + col0 + c4;
;       float4 xo = *(const float4*)(xold + idx);
;       v.x = fmaf(coef, v.x, xo.x); v.y = fmaf(coef, v.y, xo.y); v.z = fmaf(coef, v.z, xo.z); v.w = fmaf(coef, v.w, xo.w);
;       *(float4*)(xnew + idx) = v;
;       *(bf16x4*)(xb + idx) = pack4(v.x, v.y, v.z, v.w);
;       float s = row16_sum(v.x * v.x + v.y * v.y + v.z * v.z + v.w * v.w);
;       if ((lane & 15) == 0) atomicAdd(ssqn + row, s);
;     });
.LBB0_178:
	s_or_b64 exec, exec, s[0:1]
	v_add_u32_e32 v0, v105, v2
	v_lshl_add_u32 v12, v0, 10, v128
	v_ashrrev_i32_e32 v13, 31, v12
	v_lshlrev_b64 v[14:15], 2, v[12:13]
	v_lshl_add_u64 v[4:5], s[4:5], 0, v[14:15]
	ds_read_b128 v[8:11], v98 offset:1088
	v_lshl_add_u64 v[14:15], s[8:9], 0, v[14:15]
	v_mov_b32_e32 v3, 0
	v_lshl_add_u64 v[12:13], v[12:13], 1, s[10:11]
	s_waitcnt vmcnt(15) lgkmcnt(0)
	v_mov_b32_e32 v4, v160
	v_mov_b32_e32 v5, v161
	v_mov_b32_e32 v6, v162
	v_mov_b32_e32 v7, v163
	v_pk_fma_f32 v[4:5], v[8:9], 0.5, v[4:5] op_sel_hi:[1,0,1]
	v_pk_fma_f32 v[6:7], v[10:11], 0.5, v[6:7] op_sel_hi:[1,0,1]
	global_store_dwordx4 v[14:15], v[4:7], off
	v_cvt_pk_bf16_f32 v8, v4, v5
	v_cvt_pk_bf16_f32 v9, v6, v7
	v_pk_mul_f32 v[4:5], v[4:5], v[4:5]
	v_pk_mul_f32 v[6:7], v[6:7], v[6:7]
	v_add_f32_e32 v1, v4, v5
	v_add_f32_e32 v1, v6, v1
	v_add_f32_e32 v1, v7, v1
	global_store_dwordx2 v[12:13], v[8:9], off
	s_nop 0
	v_add_f32_dpp v1, v1, v1 quad_perm:[1,0,3,2] row_mask:0xf bank_mask:0xf bound_ctrl:1
	s_nop 1
	v_add_f32_dpp v1, v1, v1 quad_perm:[2,3,0,1] row_mask:0xf bank_mask:0xf bound_ctrl:1
	s_nop 1
	v_add_f32_dpp v1, v1, v1 row_half_mirror row_mask:0xf bank_mask:0xf bound_ctrl:1
	s_nop 1
	v_mov_b32_dpp v3, v1 row_mirror row_mask:0xf bank_mask:0xf
	s_and_saveexec_b64 s[0:1], vcc
	s_cbranch_execz .LBB0_180
	v_add_f32_e32 v3, v1, v3
	v_ashrrev_i32_e32 v1, 31, v0
	v_lshl_add_u64 v[0:1], v[0:1], 2, s[12:13]
	global_atomic_add_f32 v[0:1], v3, off
.LBB0_180:
	s_or_b64 exec, exec, s[0:1]
	v_add_u32_e32 v0, v106, v2
	v_lshl_add_u32 v12, v0, 10, v128
	v_ashrrev_i32_e32 v13, 31, v12
	v_lshlrev_b64 v[14:15], 2, v[12:13]
	v_lshl_add_u64 v[4:5], s[4:5], 0, v[14:15]
	ds_read_b128 v[8:11], v98 offset:2176
	v_lshl_add_u64 v[14:15], s[8:9], 0, v[14:15]
	v_mov_b32_e32 v3, 0
	v_lshl_add_u64 v[12:13], v[12:13], 1, s[10:11]
	s_waitcnt vmcnt(17) lgkmcnt(0)
	v_mov_b32_e32 v4, v164
	v_mov_b32_e32 v5, v165
	v_mov_b32_e32 v6, v166
	v_mov_b32_e32 v7, v167
	v_pk_fma_f32 v[4:5], v[8:9], 0.5, v[4:5] op_sel_hi:[1,0,1]
	v_pk_fma_f32 v[6:7], v[10:11], 0.5, v[6:7] op_sel_hi:[1,0,1]
	global_store_dwordx4 v[14:15], v[4:7], off
	v_cvt_pk_bf16_f32 v8, v4, v5
	v_cvt_pk_bf16_f32 v9, v6, v7
	v_pk_mul_f32 v[4:5], v[4:5], v[4:5]
	v_pk_mul_f32 v[6:7], v[6:7], v[6:7]
	v_add_f32_e32 v1, v4, v5
	v_add_f32_e32 v1, v6, v1
	v_add_f32_e32 v1, v7, v1
	global_store_dwordx2 v[12:13], v[8:9], off
	s_nop 0
	v_add_f32_dpp v1, v1, v1 quad_perm:[1,0,3,2] row_mask:0xf bank_mask:0xf bound_ctrl:1
	s_nop 1
	v_add_f32_dpp v1, v1, v1 quad_perm:[2,3,0,1] row_mask:0xf bank_mask:0xf bound_ctrl:1
	s_nop 1
	v_add_f32_dpp v1, v1, v1 row_half_mirror row_mask:0xf bank_mask:0xf bound_ctrl:1
	s_nop 1
	v_mov_b32_dpp v3, v1 row_mirror row_mask:0xf bank_mask:0xf
	s_and_saveexec_b64 s[0:1], vcc
	s_cbranch_execz .LBB0_182
	v_add_f32_e32 v3, v1, v3
	v_ashrrev_i32_e32 v1, 31, v0
	v_lshl_add_u64 v[0:1], v[0:1], 2, s[12:13]
	global_atomic_add_f32 v[0:1], v3, off
.LBB0_182:
	s_or_b64 exec, exec, s[0:1]
	v_add_u32_e32 v0, v107, v2
	v_lshl_add_u32 v12, v0, 10, v128
	v_ashrrev_i32_e32 v13, 31, v12
	v_lshlrev_b64 v[14:15], 2, v[12:13]
	v_lshl_add_u64 v[4:5], s[4:5], 0, v[14:15]
	ds_read_b128 v[8:11], v98 offset:3264
	v_lshl_add_u64 v[14:15], s[8:9], 0, v[14:15]
	v_mov_b32_e32 v3, 0
	v_lshl_add_u64 v[12:13], v[12:13], 1, s[10:11]
	s_waitcnt vmcnt(19) lgkmcnt(0)
	v_mov_b32_e32 v4, v168
	v_mov_b32_e32 v5, v169
	v_mov_b32_e32 v6, v170
	v_mov_b32_e32 v7, v171
	v_pk_fma_f32 v[4:5], v[8:9], 0.5, v[4:5] op_sel_hi:[1,0,1]
	v_pk_fma_f32 v[6:7], v[10:11], 0.5, v[6:7] op_sel_hi:[1,0,1]
	global_store_dwordx4 v[14:15], v[4:7], off
	v_cvt_pk_bf16_f32 v8, v4, v5
	v_cvt_pk_bf16_f32 v9, v6, v7
	v_pk_mul_f32 v[4:5], v[4:5], v[4:5]
	v_pk_mul_f32 v[6:7], v[6:7], v[6:7]
	v_add_f32_e32 v1, v4, v5
	v_add_f32_e32 v1, v6, v1
	v_add_f32_e32 v1, v7, v1
	global_store_dwordx2 v[12:13], v[8:9], off
	s_nop 0
	v_add_f32_dpp v1, v1, v1 quad_perm:[1,0,3,2] row_mask:0xf bank_mask:0xf bound_ctrl:1
	s_nop 1
	v_add_f32_dpp v1, v1, v1 quad_perm:[2,3,0,1] row_mask:0xf bank_mask:0xf bound_ctrl:1
	s_nop 1
	v_add_f32_dpp v1, v1, v1 row_half_mirror row_mask:0xf bank_mask:0xf bound_ctrl:1
	s_nop 1
	v_mov_b32_dpp v3, v1 row_mirror row_mask:0xf bank_mask:0xf
	s_and_saveexec_b64 s[0:1], vcc
	s_cbranch_execz .LBB0_184
	v_add_f32_e32 v3, v1, v3
	v_ashrrev_i32_e32 v1, 31, v0
	v_lshl_add_u64 v[0:1], v[0:1], 2, s[12:13]
	global_atomic_add_f32 v[0:1], v3, off
.LBB0_184:
	s_or_b64 exec, exec, s[0:1]
	v_add_u32_e32 v0, v108, v2
	v_lshl_add_u32 v10, v0, 10, v128
	v_ashrrev_i32_e32 v11, 31, v10
	v_lshlrev_b64 v[12:13], 2, v[10:11]
	v_lshl_add_u64 v[2:3], s[4:5], 0, v[12:13]
	ds_read_b128 v[6:9], v98 offset:4352
	v_lshl_add_u64 v[12:13], s[8:9], 0, v[12:13]
	v_lshl_add_u64 v[10:11], v[10:11], 1, s[10:11]
	s_waitcnt vmcnt(21) lgkmcnt(0)
	v_mov_b32_e32 v2, v172
	v_mov_b32_e32 v3, v173
	v_mov_b32_e32 v4, v174
	v_mov_b32_e32 v5, v175
	v_pk_fma_f32 v[2:3], v[6:7], 0.5, v[2:3] op_sel_hi:[1,0,1]
	v_pk_fma_f32 v[4:5], v[8:9], 0.5, v[4:5] op_sel_hi:[1,0,1]
	global_store_dwordx4 v[12:13], v[2:5], off
	v_cvt_pk_bf16_f32 v6, v2, v3
	v_cvt_pk_bf16_f32 v7, v4, v5
	v_pk_mul_f32 v[2:3], v[2:3], v[2:3]
	v_pk_mul_f32 v[4:5], v[4:5], v[4:5]
	v_add_f32_e32 v1, v2, v3
	v_add_f32_e32 v1, v4, v1
	v_add_f32_e32 v1, v5, v1
	v_mov_b32_e32 v2, 0
	global_store_dwordx2 v[10:11], v[6:7], off
	v_add_f32_dpp v1, v1, v1 quad_perm:[1,0,3,2] row_mask:0xf bank_mask:0xf bound_ctrl:1
	s_nop 1
	v_add_f32_dpp v1, v1, v1 quad_perm:[2,3,0,1] row_mask:0xf bank_mask:0xf bound_ctrl:1
	s_nop 1
	v_add_f32_dpp v1, v1, v1 row_half_mirror row_mask:0xf bank_mask:0xf bound_ctrl:1
	s_nop 1
	v_mov_b32_dpp v2, v1 row_mirror row_mask:0xf bank_mask:0xf
	s_and_saveexec_b64 s[0:1], vcc
	s_cbranch_execz .LBB0_117
	v_add_f32_e32 v2, v1, v2
	v_ashrrev_i32_e32 v1, 31, v0
	v_lshl_add_u64 v[0:1], v[0:1], 2, s[12:13]
	global_atomic_add_f32 v[0:1], v2, off
	s_branch .LBB0_117

;   __device__ __forceinline__ void tile(const float* reg, int row0, int col0, int lane) const {
;     rows4(reg, lane, [&](int it, int rr, int c4, float4 v) {
;       int row = row0 + rr, idx = row * 1024 + col0 + c4;
;       float4 xo = *(const float4*)(xold + idx);
;       v.x = fmaf(coef, v.x, xo.x); v.y = fmaf(coef, v.y, xo.y); v.z = fmaf(coef, v.z, xo.z); v.w = fmaf(coef, v.w, xo.w);
;       *(float4*)(xnew + idx) = v;
;       *(bf16x4*)(xb + idx) = pack4(v.x, v.y, v.z, v.w);
;       float s = row16_sum(v.x * v.x + v.y * v.y + v.z * v.z + v.w * v.w);
;       if ((lane & 15) == 0) atomicAdd(ssqn + row, s);
;     });
; template <int MF, class Epi>
; __device__ __forceinline__ void staged_epilogue(f32x4 (&acc)[MF][4], int row0, int col0, const Epi& epi) {
;   const int lane = tidx() & 63, wid = tidx() >> 6, fr = lane & 15, fq = lane >> 4;
;   float* reg = (float*)(g_shm + 65536 + wid * 8704);
; #pragma unroll
;   for (int mp = 0; mp < MF / 2; ++mp) {
;     __builtin_amdgcn_sched_barrier(0);
; #pragma unroll
;     for (int mm = 0; mm < 2; ++mm)
; #pragma unroll
;       for (int n = 0; n < 4; ++n)
; #pragma unroll
;         for (int j = 0; j < 4; ++j) reg[(mm * 16 + fq * 4 + j) * 68 + n * 16 + fr] = acc[mp * 2 + mm][n][j];
;     __builtin_amdgcn_fence(__ATOMIC_ACQ_REL, "wavefront");
;     epi.tile(reg, row0 + mp * 32, col0, lane);
.LBB0_1409:
	v_mov_b32_e32 v131, v204
	v_mov_b32_e32 v130, v204
	s_nop 0
	v_lshrrev_b32_e32 v130, 6, v130
	v_mul_lo_u32 v130, v130, s52
	v_add_u32_e32 v135, 0x10000, v130
	v_lshrrev_b32_e32 v130, 2, v131
	v_and_b32_e32 v136, 15, v131
	v_and_b32_e32 v137, 12, v130
	v_bfe_u32 v130, v131, 4, 2
	v_lshlrev_b32_e32 v131, 2, v131
	v_and_b32_e32 v131, 60, v131
	v_lshl_or_b32 v138, v136, 2, v135
	v_lshl_or_b32 v135, v131, 2, v135
	v_add_u32_e32 v128, v131, v128
	v_cmp_eq_u32_e32 vcc, 0, v136
	v_mad_u32_u24 v139, v130, s53, v135
	v_mad_u32_u24 v131, v137, s53, v138
	ds_write2_b32 v131, v120, v124 offset1:16
	ds_write2_b32 v131, v121, v125 offset0:68 offset1:84
	ds_write2_b32 v131, v122, v126 offset0:136 offset1:152
	ds_write2_b32 v131, v123, v127 offset0:204 offset1:220
	ds_write2_b32 v131, v112, v116 offset0:32 offset1:48
	ds_write2_b32 v131, v113, v117 offset0:100 offset1:116
	ds_write2_b32 v131, v114, v118 offset0:168 offset1:184
	ds_write2_b32 v131, v115, v119 offset0:236 offset1:252
	v_add_u32_e32 v112, 0x1000, v131
	ds_write2_b32 v112, v104, v108 offset0:64 offset1:80
	ds_write2_b32 v112, v105, v109 offset0:132 offset1:148
	ds_write2_b32 v112, v106, v110 offset0:200 offset1:216
	v_add_u32_e32 v104, 0x1400, v131
	ds_write2_b32 v104, v107, v111 offset0:12 offset1:28
	ds_write2_b32 v112, v96, v100 offset0:96 offset1:112
	ds_write2_b32 v112, v97, v101 offset0:164 offset1:180
	ds_write2_b32 v112, v98, v102 offset0:232 offset1:248
	ds_write2_b32 v104, v99, v103 offset0:44 offset1:60
	v_add_u32_e32 v184, v130, v129
	v_lshl_add_u32 v176, v184, 10, v128
	v_ashrrev_i32_e32 v177, 31, v176
	v_lshl_add_u64 v[178:179], v[176:177], 2, s[12:13]
	global_load_dwordx4 v[144:147], v[178:179], off
	v_or_b32_e32 v185, 4, v130
	v_add_u32_e32 v184, v185, v129
	v_lshl_add_u32 v176, v184, 10, v128
	v_ashrrev_i32_e32 v177, 31, v176
	v_lshl_add_u64 v[178:179], v[176:177], 2, s[12:13]
	global_load_dwordx4 v[148:151], v[178:179], off
	v_or_b32_e32 v185, 8, v130
	v_add_u32_e32 v184, v185, v129
	v_lshl_add_u32 v176, v184, 10, v128
	v_ashrrev_i32_e32 v177, 31, v176
	v_lshl_add_u64 v[178:179], v[176:177], 2, s[12:13]
	global_load_dwordx4 v[152:155], v[178:179], off
	v_or_b32_e32 v185, 12, v130
	v_add_u32_e32 v184, v185, v129
	v_lshl_add_u32 v176, v184, 10, v128
	v_ashrrev_i32_e32 v177, 31, v176
	v_lshl_add_u64 v[178:179], v[176:177], 2, s[12:13]
	global_load_dwordx4 v[156:159], v[178:179], off
	v_or_b32_e32 v185, 16, v130
	v_add_u32_e32 v184, v185, v129
	v_lshl_add_u32 v176, v184, 10, v128
	v_ashrrev_i32_e32 v177, 31, v176
	v_lshl_add_u64 v[178:179], v[176:177], 2, s[12:13]
	global_load_dwordx4 v[160:163], v[178:179], off
	v_or_b32_e32 v185, 20, v130
	v_add_u32_e32 v184, v185, v129
	v_lshl_add_u32 v176, v184, 10, v128
	v_ashrrev_i32_e32 v177, 31, v176
	v_lshl_add_u64 v[178:179], v[176:177], 2, s[12:13]
	global_load_dwordx4 v[164:167], v[178:179], off
	v_or_b32_e32 v185, 24, v130
	v_add_u32_e32 v184, v185, v129
	v_lshl_add_u32 v176, v184, 10, v128
	v_ashrrev_i32_e32 v177, 31, v176
	v_lshl_add_u64 v[178:179], v[176:177], 2, s[12:13]
	global_load_dwordx4 v[168:171], v[178:179], off
	v_or_b32_e32 v185, 28, v130
	v_add_u32_e32 v184, v185, v129
	v_lshl_add_u32 v176, v184, 10, v128
	v_ashrrev_i32_e32 v177, 31, v176
	v_lshl_add_u64 v[178:179], v[176:177], 2, s[12:13]
	global_load_dwordx4 v[172:175], v[178:179], off
	v_add_u32_e32 v96, v130, v129
	v_lshl_add_u32 v102, v96, 10, v128
	v_ashrrev_i32_e32 v103, 31, v102
	v_lshl_add_u64 v[110:111], v[102:103], 2, s[12:13]
	s_waitcnt vmcnt(7)
	v_mov_b32_e32 v98, v144
	v_mov_b32_e32 v99, v145
	v_mov_b32_e32 v100, v146
	v_mov_b32_e32 v101, v147
	ds_read_b128 v[106:109], v139
	v_lshl_add_u64 v[102:103], v[102:103], 1, s[14:15]
	s_waitcnt lgkmcnt(0)
	v_pk_add_f32 v[98:99], v[106:107], v[98:99]
	v_pk_add_f32 v[100:101], v[108:109], v[100:101]
	global_store_dwordx4 v[110:111], v[98:101], off
	v_cvt_pk_bf16_f32 v106, v98, v99
	v_cvt_pk_bf16_f32 v107, v100, v101
	v_pk_mul_f32 v[98:99], v[98:99], v[98:99]
	v_pk_mul_f32 v[100:101], v[100:101], v[100:101]
	v_add_f32_e32 v97, v98, v99
	v_add_f32_e32 v97, v100, v97
	v_add_f32_e32 v97, v101, v97
	v_mov_b32_e32 v98, 0
	global_store_dwordx2 v[102:103], v[106:107], off
	v_add_f32_dpp v97, v97, v97 quad_perm:[1,0,3,2] row_mask:0xf bank_mask:0xf bound_ctrl:1
	s_nop 1
	v_add_f32_dpp v97, v97, v97 quad_perm:[2,3,0,1] row_mask:0xf bank_mask:0xf bound_ctrl:1
	s_nop 1
	v_add_f32_dpp v97, v97, v97 row_half_mirror row_mask:0xf bank_mask:0xf bound_ctrl:1
	s_nop 1
	v_mov_b32_dpp v98, v97 row_mirror row_mask:0xf bank_mask:0xf
	s_and_saveexec_b64 s[0:1], vcc
	s_cbranch_execz .LBB0_1411
	v_add_f32_e32 v98, v97, v98
	v_ashrrev_i32_e32 v97, 31, v96
	v_lshl_add_u64 v[96:97], v[96:97], 2, s[18:19]
	global_atomic_add_f32 v[96:97], v98, off
.LBB0_1411:
	s_or_b64 exec, exec, s[0:1]
	v_or_b32_e32 v99, 4, v130
	v_add_u32_e32 v96, v99, v129
	v_lshl_add_u32 v102, v96, 10, v128
	v_ashrrev_i32_e32 v103, 31, v102
	v_lshl_add_u64 v[106:107], v[102:103], 2, s[12:13]
	v_mul_u32_u24_e32 v109, 0x110, v130
	v_add_u32_e32 v98, 0x440, v109
	v_add_u32_e32 v100, v135, v98
	ds_read_b128 v[118:121], v100
	v_mov_b32_e32 v101, 0
	v_lshl_add_u64 v[102:103], v[102:103], 1, s[14:15]
	s_waitcnt vmcnt(9) lgkmcnt(0)
	v_mov_b32_e32 v114, v148
	v_mov_b32_e32 v115, v149
	v_mov_b32_e32 v116, v150
	v_mov_b32_e32 v117, v151
	v_pk_add_f32 v[114:115], v[118:119], v[114:115]
	v_pk_add_f32 v[116:117], v[120:121], v[116:117]
	v_pk_mul_f32 v[110:111], v[114:115], v[114:115]
	global_store_dwordx4 v[106:107], v[114:117], off
	v_cvt_pk_bf16_f32 v106, v114, v115
	v_add_f32_e32 v97, v110, v111
	v_pk_mul_f32 v[114:115], v[116:117], v[116:117]
	v_cvt_pk_bf16_f32 v107, v116, v117
	v_add_f32_e32 v97, v114, v97
	v_add_f32_e32 v97, v115, v97
	global_store_dwordx2 v[102:103], v[106:107], off
	s_nop 0
	v_add_f32_dpp v97, v97, v97 quad_perm:[1,0,3,2] row_mask:0xf bank_mask:0xf bound_ctrl:1
	s_nop 1
	v_add_f32_dpp v97, v97, v97 quad_perm:[2,3,0,1] row_mask:0xf bank_mask:0xf bound_ctrl:1
	s_nop 1
	v_add_f32_dpp v97, v97, v97 row_half_mirror row_mask:0xf bank_mask:0xf bound_ctrl:1
	s_nop 1
	v_mov_b32_dpp v101, v97 row_mirror row_mask:0xf bank_mask:0xf
	s_and_saveexec_b64 s[0:1], vcc
	s_cbranch_execz .LBB0_1413
	v_add_f32_e32 v101, v97, v101
	v_ashrrev_i32_e32 v97, 31, v96
	v_lshl_add_u64 v[96:97], v[96:97], 2, s[18:19]
	global_atomic_add_f32 v[96:97], v101, off
;   __device__ __forceinline__ void tile(const float* reg, int row0, int col0, int lane) const {
;     rows4(reg, lane, [&](int it, int rr, int c4, float4 v) {
;       int row = row0 + rr, idx = row * 1024 + col0 + c4;
;       float4 xo = *(const float4*)(xold + idx);
;       v.x = fmaf(coef, v.x, xo.x); v.y = fmaf(coef, v.y, xo.y); v.z = fmaf(coef, v.z, xo.z); v.w = fmaf(coef, v.w, xo.w);
;       *(float4*)(xnew + idx) = v;
;       *(bf16x4*)(xb + idx) = pack4(v.x, v.y, v.z, v.w);
;       float s = row16_sum(v.x * v.x + v.y * v.y + v.z * v.z + v.w * v.w);
;       if ((lane & 15) == 0) atomicAdd(ssqn + row, s);
;     });
.LBB0_1413:
	s_or_b64 exec, exec, s[0:1]
	v_or_b32_e32 v101, 8, v130
	v_add_u32_e32 v96, v101, v129
	v_lshl_add_u32 v106, v96, 10, v128
	v_ashrrev_i32_e32 v107, 31, v106
	v_lshl_add_u64 v[110:111], v[106:107], 2, s[12:13]
	v_add_u32_e32 v98, 0x440, v98
	v_add_u32_e32 v102, v135, v98
	ds_read_b128 v[118:121], v102
	v_mov_b32_e32 v103, 0
	v_lshl_add_u64 v[106:107], v[106:107], 1, s[14:15]
	s_waitcnt vmcnt(11) lgkmcnt(0)
	v_mov_b32_e32 v114, v152
	v_mov_b32_e32 v115, v153
	v_mov_b32_e32 v116, v154
	v_mov_b32_e32 v117, v155
	v_pk_add_f32 v[114:115], v[118:119], v[114:115]
	v_pk_add_f32 v[116:117], v[120:121], v[116:117]
	global_store_dwordx4 v[110:111], v[114:117], off
	v_cvt_pk_bf16_f32 v110, v114, v115
	v_cvt_pk_bf16_f32 v111, v116, v117
	v_pk_mul_f32 v[114:115], v[114:115], v[114:115]
	v_pk_mul_f32 v[116:117], v[116:117], v[116:117]
	v_add_f32_e32 v97, v114, v115
	v_add_f32_e32 v97, v116, v97
	v_add_f32_e32 v97, v117, v97
	global_store_dwordx2 v[106:107], v[110:111], off
	s_nop 0
	v_add_f32_dpp v97, v97, v97 quad_perm:[1,0,3,2] row_mask:0xf bank_mask:0xf bound_ctrl:1
	s_nop 1
	v_add_f32_dpp v97, v97, v97 quad_perm:[2,3,0,1] row_mask:0xf bank_mask:0xf bound_ctrl:1
	s_nop 1
	v_add_f32_dpp v97, v97, v97 row_half_mirror row_mask:0xf bank_mask:0xf bound_ctrl:1
	s_nop 1
	v_mov_b32_dpp v103, v97 row_mirror row_mask:0xf bank_mask:0xf
	s_and_saveexec_b64 s[0:1], vcc
	s_cbranch_execz .LBB0_1415
	v_add_f32_e32 v103, v97, v103
	v_ashrrev_i32_e32 v97, 31, v96
	v_lshl_add_u64 v[96:97], v[96:97], 2, s[18:19]
	global_atomic_add_f32 v[96:97], v103, off
.LBB0_1415:
	s_or_b64 exec, exec, s[0:1]
	v_or_b32_e32 v103, 12, v130
	v_add_u32_e32 v96, v103, v129
	v_lshl_add_u32 v106, v96, 10, v128
	v_ashrrev_i32_e32 v107, 31, v106
	v_lshl_add_u64 v[110:111], v[106:107], 2, s[12:13]
	v_add_u32_e32 v97, 0x440, v98
	v_add_u32_e32 v98, v135, v97
	ds_read_b128 v[118:121], v98
	v_mov_b32_e32 v105, 0
	v_lshl_add_u64 v[106:107], v[106:107], 1, s[14:15]
	s_waitcnt vmcnt(13) lgkmcnt(0)
	v_mov_b32_e32 v114, v156
	v_mov_b32_e32 v115, v157
	v_mov_b32_e32 v116, v158
	v_mov_b32_e32 v117, v159
	v_pk_add_f32 v[114:115], v[118:119], v[114:115]
	v_pk_add_f32 v[116:117], v[120:121], v[116:117]
	global_store_dwordx4 v[110:111], v[114:117], off
	v_cvt_pk_bf16_f32 v110, v114, v115
	v_cvt_pk_bf16_f32 v111, v116, v117
	v_pk_mul_f32 v[114:115], v[114:115], v[114:115]
	v_pk_mul_f32 v[116:117], v[116:117], v[116:117]
	v_add_f32_e32 v97, v114, v115
	v_add_f32_e32 v97, v116, v97
	v_add_f32_e32 v97, v117, v97
	global_store_dwordx2 v[106:107], v[110:111], off
	s_nop 0
	v_add_f32_dpp v97, v97, v97 quad_perm:[1,0,3,2] row_mask:0xf bank_mask:0xf bound_ctrl:1
	s_nop 1
	v_add_f32_dpp v97, v97, v97 quad_perm:[2,3,0,1] row_mask:0xf bank_mask:0xf bound_ctrl:1
	s_nop 1
	v_add_f32_dpp v97, v97, v97 row_half_mirror row_mask:0xf bank_mask:0xf bound_ctrl:1
	s_nop 1
	v_mov_b32_dpp v105, v97 row_mirror row_mask:0xf bank_mask:0xf
	s_and_saveexec_b64 s[0:1], vcc
	s_cbranch_execz .LBB0_1417
	v_add_f32_e32 v105, v97, v105
	v_ashrrev_i32_e32 v97, 31, v96
	v_lshl_add_u64 v[96:97], v[96:97], 2, s[18:19]
	global_atomic_add_f32 v[96:97], v105, off
.LBB0_1417:
	s_or_b64 exec, exec, s[0:1]
	v_or_b32_e32 v105, 16, v130
	v_add_u32_e32 v96, v105, v129
	v_lshl_add_u32 v106, v96, 10, v128
	v_ashrrev_i32_e32 v107, 31, v106
	v_lshl_add_u64 v[110:111], v[106:107], 2, s[12:13]
	ds_read_b128 v[118:121], v98 offset:1088
	v_lshl_add_u64 v[106:107], v[106:107], 1, s[14:15]
	s_waitcnt vmcnt(15) lgkmcnt(0)
	v_mov_b32_e32 v114, v160
	v_mov_b32_e32 v115, v161
	v_mov_b32_e32 v116, v162
	v_mov_b32_e32 v117, v163
	v_pk_add_f32 v[114:115], v[118:119], v[114:115]
	v_pk_add_f32 v[116:117], v[120:121], v[116:117]
	global_store_dwordx4 v[110:111], v[114:117], off
	v_cvt_pk_bf16_f32 v110, v114, v115
	v_cvt_pk_bf16_f32 v111, v116, v117
	v_pk_mul_f32 v[114:115], v[114:115], v[114:115]
	v_pk_mul_f32 v[116:117], v[116:117], v[116:117]
	v_add_f32_e32 v97, v114, v115
	v_add_f32_e32 v97, v116, v97
	v_add_f32_e32 v97, v117, v97
	global_store_dwordx2 v[106:107], v[110:111], off
	v_mov_b32_e32 v106, 0
	v_add_f32_dpp v97, v97, v97 quad_perm:[1,0,3,2] row_mask:0xf bank_mask:0xf bound_ctrl:1
	s_nop 1
	v_add_f32_dpp v97, v97, v97 quad_perm:[2,3,0,1] row_mask:0xf bank_mask:0xf bound_ctrl:1
	s_nop 1
	v_add_f32_dpp v97, v97, v97 row_half_mirror row_mask:0xf bank_mask:0xf bound_ctrl:1
	s_nop 1
	v_mov_b32_dpp v106, v97 row_mirror row_mask:0xf bank_mask:0xf
	s_and_saveexec_b64 s[0:1], vcc
	s_cbranch_execz .LBB0_1419
	v_add_f32_e32 v106, v97, v106
	v_ashrrev_i32_e32 v97, 31, v96
	v_lshl_add_u64 v[96:97], v[96:97], 2, s[18:19]
	global_atomic_add_f32 v[96:97], v106, off
.LBB0_1419:
	s_or_b64 exec, exec, s[0:1]
	v_or_b32_e32 v106, 20, v130
	v_add_u32_e32 v96, v106, v129
	v_lshl_add_u32 v110, v96, 10, v128
	v_ashrrev_i32_e32 v111, 31, v110
	v_lshl_add_u64 v[122:123], v[110:111], 2, s[12:13]
	ds_read_b128 v[118:121], v98 offset:2176
	v_mov_b32_e32 v107, 0
	v_lshl_add_u64 v[110:111], v[110:111], 1, s[14:15]
	s_waitcnt vmcnt(17) lgkmcnt(0)
	v_mov_b32_e32 v114, v164
	v_mov_b32_e32 v115, v165
	v_mov_b32_e32 v116, v166
	v_mov_b32_e32 v117, v167
	v_pk_add_f32 v[114:115], v[118:119], v[114:115]
	v_pk_add_f32 v[116:117], v[120:121], v[116:117]
	global_store_dwordx4 v[122:123], v[114:117], off
	v_cvt_pk_bf16_f32 v118, v114, v115
	v_cvt_pk_bf16_f32 v119, v116, v117
	v_pk_mul_f32 v[114:115], v[114:115], v[114:115]
	v_pk_mul_f32 v[116:117], v[116:117], v[116:117]
	v_add_f32_e32 v97, v114, v115
	v_add_f32_e32 v97, v116, v97
	v_add_f32_e32 v97, v117, v97
	global_store_dwordx2 v[110:111], v[118:119], off
	s_nop 0
	v_add_f32_dpp v97, v97, v97 quad_perm:[1,0,3,2] row_mask:0xf bank_mask:0xf bound_ctrl:1
	s_nop 1
	v_add_f32_dpp v97, v97, v97 quad_perm:[2,3,0,1] row_mask:0xf bank_mask:0xf bound_ctrl:1
	s_nop 1
	v_add_f32_dpp v97, v97, v97 row_half_mirror row_mask:0xf bank_mask:0xf bound_ctrl:1
	s_nop 1
	v_mov_b32_dpp v107, v97 row_mirror row_mask:0xf bank_mask:0xf
	s_and_saveexec_b64 s[0:1], vcc
	s_cbranch_execz .LBB0_1421
	v_add_f32_e32 v107, v97, v107
	v_ashrrev_i32_e32 v97, 31, v96
	v_lshl_add_u64 v[96:97], v[96:97], 2, s[18:19]
	global_atomic_add_f32 v[96:97], v107, off
;   __device__ __forceinline__ void tile(const float* reg, int row0, int col0, int lane) const {
;     rows4(reg, lane, [&](int it, int rr, int c4, float4 v) {
;       int row = row0 + rr, idx = row * 1024 + col0 + c4;
;       float4 xo = *(const float4*)(xold + idx);
;       v.x = fmaf(coef, v.x, xo.x); v.y = fmaf(coef, v.y, xo.y); v.z = fmaf(coef, v.z, xo.z); v.w = fmaf(coef, v.w, xo.w);
;       *(float4*)(xnew + idx) = v;
;       *(bf16x4*)(xb + idx) = pack4(v.x, v.y, v.z, v.w);
;       float s = row16_sum(v.x * v.x + v.y * v.y + v.z * v.z + v.w * v.w);
;       if ((lane & 15) == 0) atomicAdd(ssqn + row, s);
;     });
; template <int MF, class Epi>
; __device__ __forceinline__ void staged_epilogue(f32x4 (&acc)[MF][4], int row0, int col0, const Epi& epi) {
;     ...
;         for (int j = 0; j < 4; ++j) reg[(mm * 16 + fq * 4 + j) * 68 + n * 16 + fr] = acc[mp * 2 + mm][n][j];
.LBB0_1421:
	s_or_b64 exec, exec, s[0:1]
	v_or_b32_e32 v107, 24, v130
	v_add_u32_e32 v96, v107, v129
	v_lshl_add_u32 v110, v96, 10, v128
	v_ashrrev_i32_e32 v111, 31, v110
	v_lshl_add_u64 v[122:123], v[110:111], 2, s[12:13]
	ds_read_b128 v[118:121], v98 offset:3264
	v_mov_b32_e32 v108, 0
	v_lshl_add_u64 v[110:111], v[110:111], 1, s[14:15]
	s_waitcnt vmcnt(19) lgkmcnt(0)
	v_mov_b32_e32 v114, v168
	v_mov_b32_e32 v115, v169
	v_mov_b32_e32 v116, v170
	v_mov_b32_e32 v117, v171
	v_pk_add_f32 v[114:115], v[118:119], v[114:115]
	v_pk_add_f32 v[116:117], v[120:121], v[116:117]
	global_store_dwordx4 v[122:123], v[114:117], off
	v_cvt_pk_bf16_f32 v118, v114, v115
	v_cvt_pk_bf16_f32 v119, v116, v117
	v_pk_mul_f32 v[114:115], v[114:115], v[114:115]
	v_pk_mul_f32 v[116:117], v[116:117], v[116:117]
	v_add_f32_e32 v97, v114, v115
	v_add_f32_e32 v97, v116, v97
	v_add_f32_e32 v97, v117, v97
	global_store_dwordx2 v[110:111], v[118:119], off
	s_nop 0
	v_add_f32_dpp v97, v97, v97 quad_perm:[1,0,3,2] row_mask:0xf bank_mask:0xf bound_ctrl:1
	s_nop 1
	v_add_f32_dpp v97, v97, v97 quad_perm:[2,3,0,1] row_mask:0xf bank_mask:0xf bound_ctrl:1
	s_nop 1
	v_add_f32_dpp v97, v97, v97 row_half_mirror row_mask:0xf bank_mask:0xf bound_ctrl:1
	s_nop 1
	v_mov_b32_dpp v108, v97 row_mirror row_mask:0xf bank_mask:0xf
	s_and_saveexec_b64 s[0:1], vcc
	s_cbranch_execz .LBB0_1423
	v_add_f32_e32 v108, v97, v108
	v_ashrrev_i32_e32 v97, 31, v96
	v_lshl_add_u64 v[96:97], v[96:97], 2, s[18:19]
	global_atomic_add_f32 v[96:97], v108, off
.LBB0_1423:
	s_or_b64 exec, exec, s[0:1]
	v_or_b32_e32 v108, 28, v130
	v_add_u32_e32 v96, v108, v129
	v_lshl_add_u32 v110, v96, 10, v128
	v_ashrrev_i32_e32 v111, 31, v110
	v_lshl_add_u64 v[122:123], v[110:111], 2, s[12:13]
	ds_read_b128 v[118:121], v98 offset:4352
	v_lshl_add_u64 v[110:111], v[110:111], 1, s[14:15]
	s_waitcnt vmcnt(21) lgkmcnt(0)
	v_mov_b32_e32 v114, v172
	v_mov_b32_e32 v115, v173
	v_mov_b32_e32 v116, v174
	v_mov_b32_e32 v117, v175
	v_pk_add_f32 v[114:115], v[118:119], v[114:115]
	v_pk_add_f32 v[116:117], v[120:121], v[116:117]
	global_store_dwordx4 v[122:123], v[114:117], off
	v_cvt_pk_bf16_f32 v118, v114, v115
	v_cvt_pk_bf16_f32 v119, v116, v117
	v_pk_mul_f32 v[114:115], v[114:115], v[114:115]
	v_pk_mul_f32 v[116:117], v[116:117], v[116:117]
	v_add_f32_e32 v97, v114, v115
	v_add_f32_e32 v97, v116, v97
	v_add_f32_e32 v97, v117, v97
	global_store_dwordx2 v[110:111], v[118:119], off
	v_mov_b32_e32 v110, 0
	v_add_f32_dpp v97, v97, v97 quad_perm:[1,0,3,2] row_mask:0xf bank_mask:0xf bound_ctrl:1
	s_nop 1
	v_add_f32_dpp v97, v97, v97 quad_perm:[2,3,0,1] row_mask:0xf bank_mask:0xf bound_ctrl:1
	s_nop 1
	v_add_f32_dpp v97, v97, v97 row_half_mirror row_mask:0xf bank_mask:0xf bound_ctrl:1
	s_nop 1
	v_mov_b32_dpp v110, v97 row_mirror row_mask:0xf bank_mask:0xf
	s_and_saveexec_b64 s[0:1], vcc
	s_cbranch_execz .LBB0_1425
	v_add_f32_e32 v110, v97, v110
	v_ashrrev_i32_e32 v97, 31, v96
	v_lshl_add_u64 v[96:97], v[96:97], 2, s[18:19]
	global_atomic_add_f32 v[96:97], v110, off
.LBB0_1425:
	s_or_b64 exec, exec, s[0:1]
	ds_write2_b32 v131, v88, v92 offset1:16
	ds_write2_b32 v131, v89, v93 offset0:68 offset1:84
	ds_write2_b32 v131, v90, v94 offset0:136 offset1:152
	ds_write2_b32 v131, v91, v95 offset0:204 offset1:220
	ds_write2_b32 v131, v80, v84 offset0:32 offset1:48
	ds_write2_b32 v131, v81, v85 offset0:100 offset1:116
	ds_write2_b32 v131, v82, v86 offset0:168 offset1:184
	ds_write2_b32 v131, v83, v87 offset0:236 offset1:252
	ds_write2_b32 v112, v72, v76 offset0:64 offset1:80
	ds_write2_b32 v112, v73, v77 offset0:132 offset1:148
	ds_write2_b32 v112, v74, v78 offset0:200 offset1:216
	ds_write2_b32 v104, v75, v79 offset0:12 offset1:28
	ds_write2_b32 v112, v64, v68 offset0:96 offset1:112
	ds_write2_b32 v112, v65, v69 offset0:164 offset1:180
	ds_write2_b32 v112, v66, v70 offset0:232 offset1:248
	ds_write2_b32 v104, v67, v71 offset0:44 offset1:60
	v_add_u32_e32 v185, 32, v129
	v_add_u32_e32 v184, v130, v185
	v_lshl_add_u32 v176, v184, 10, v128
	v_ashrrev_i32_e32 v177, 31, v176
	v_lshl_add_u64 v[178:179], v[176:177], 2, s[12:13]
	global_load_dwordx4 v[144:147], v[178:179], off
	v_add_u32_e32 v185, 32, v129
	v_add_u32_e32 v184, v99, v185
	v_lshl_add_u32 v176, v184, 10, v128
	v_ashrrev_i32_e32 v177, 31, v176
	v_lshl_add_u64 v[178:179], v[176:177], 2, s[12:13]
	global_load_dwordx4 v[148:151], v[178:179], off
	v_add_u32_e32 v185, 32, v129
	v_add_u32_e32 v184, v101, v185
	v_lshl_add_u32 v176, v184, 10, v128
	v_ashrrev_i32_e32 v177, 31, v176
	v_lshl_add_u64 v[178:179], v[176:177], 2, s[12:13]
	global_load_dwordx4 v[152:155], v[178:179], off
	v_add_u32_e32 v185, 32, v129
	v_add_u32_e32 v184, v103, v185
	v_lshl_add_u32 v176, v184, 10, v128
	v_ashrrev_i32_e32 v177, 31, v176
	v_lshl_add_u64 v[178:179], v[176:177], 2, s[12:13]
	global_load_dwordx4 v[156:159], v[178:179], off
	v_add_u32_e32 v185, 32, v129
	v_add_u32_e32 v184, v105, v185
	v_lshl_add_u32 v176, v184, 10, v128
	v_ashrrev_i32_e32 v177, 31, v176
	v_lshl_add_u64 v[178:179], v[176:177], 2, s[12:13]
	global_load_dwordx4 v[160:163], v[178:179], off
	v_add_u32_e32 v185, 32, v129
	v_add_u32_e32 v184, v106, v185
	v_lshl_add_u32 v176, v184, 10, v128
	v_ashrrev_i32_e32 v177, 31, v176
	v_lshl_add_u64 v[178:179], v[176:177], 2, s[12:13]
	global_load_dwordx4 v[164:167], v[178:179], off
	v_add_u32_e32 v185, 32, v129
	v_add_u32_e32 v184, v107, v185
	v_lshl_add_u32 v176, v184, 10, v128
	v_ashrrev_i32_e32 v177, 31, v176
	v_lshl_add_u64 v[178:179], v[176:177], 2, s[12:13]
	global_load_dwordx4 v[168:171], v[178:179], off
	v_add_u32_e32 v185, 32, v129
	v_add_u32_e32 v184, v108, v185
	v_lshl_add_u32 v176, v184, 10, v128
	v_ashrrev_i32_e32 v177, 31, v176
	v_lshl_add_u64 v[178:179], v[176:177], 2, s[12:13]
	global_load_dwordx4 v[172:175], v[178:179], off
	v_add_u32_e32 v67, 32, v129
	v_add_u32_e32 v64, v130, v67
	v_lshl_add_u32 v76, v64, 10, v128
	v_ashrrev_i32_e32 v77, 31, v76
	v_lshl_add_u64 v[78:79], v[76:77], 2, s[12:13]
	v_add_u32_e32 v66, v135, v109
	ds_read_b128 v[72:75], v66
	v_lshl_add_u64 v[76:77], v[76:77], 1, s[14:15]
	s_waitcnt vmcnt(7) lgkmcnt(0)
	v_mov_b32_e32 v68, v144
	v_mov_b32_e32 v69, v145
	v_mov_b32_e32 v70, v146
	v_mov_b32_e32 v71, v147
	v_pk_add_f32 v[68:69], v[72:73], v[68:69]
	v_pk_add_f32 v[70:71], v[74:75], v[70:71]
	global_store_dwordx4 v[78:79], v[68:71], off
	v_cvt_pk_bf16_f32 v72, v68, v69
	v_cvt_pk_bf16_f32 v73, v70, v71
	v_pk_mul_f32 v[68:69], v[68:69], v[68:69]
	v_pk_mul_f32 v[70:71], v[70:71], v[70:71]
	v_add_f32_e32 v65, v68, v69
	v_add_f32_e32 v65, v70, v65
	v_add_f32_e32 v65, v71, v65
	v_mov_b32_e32 v68, 0
	global_store_dwordx2 v[76:77], v[72:73], off
	v_add_f32_dpp v65, v65, v65 quad_perm:[1,0,3,2] row_mask:0xf bank_mask:0xf bound_ctrl:1
	s_nop 1
	v_add_f32_dpp v65, v65, v65 quad_perm:[2,3,0,1] row_mask:0xf bank_mask:0xf bound_ctrl:1
	s_nop 1
	v_add_f32_dpp v65, v65, v65 row_half_mirror row_mask:0xf bank_mask:0xf bound_ctrl:1
	s_nop 1
	v_mov_b32_dpp v68, v65 row_mirror row_mask:0xf bank_mask:0xf
	s_and_saveexec_b64 s[0:1], vcc
	s_cbranch_execz .LBB0_1427
;   __device__ __forceinline__ void tile(const float* reg, int row0, int col0, int lane) const {
;     rows4(reg, lane, [&](int it, int rr, int c4, float4 v) {
;       int row = row0 + rr, idx = row * 1024 + col0 + c4;
;       float4 xo = *(const float4*)(xold + idx);
;       v.x = fmaf(coef, v.x, xo.x); v.y = fmaf(coef, v.y, xo.y); v.z = fmaf(coef, v.z, xo.z); v.w = fmaf(coef, v.w, xo.w);
;       *(float4*)(xnew + idx) = v;
;       *(bf16x4*)(xb + idx) = pack4(v.x, v.y, v.z, v.w);
;       float s = row16_sum(v.x * v.x + v.y * v.y + v.z * v.z + v.w * v.w);
;       if ((lane & 15) == 0) atomicAdd(ssqn + row, s);
;     });
	v_add_f32_e32 v68, v65, v68
	v_ashrrev_i32_e32 v65, 31, v64
	v_lshl_add_u64 v[64:65], v[64:65], 2, s[18:19]
	global_atomic_add_f32 v[64:65], v68, off
.LBB0_1427:
	s_or_b64 exec, exec, s[0:1]
	v_add_u32_e32 v64, v99, v67
	v_lshl_add_u32 v76, v64, 10, v128
	v_ashrrev_i32_e32 v77, 31, v76
	v_lshl_add_u64 v[78:79], v[76:77], 2, s[12:13]
	ds_read_b128 v[72:75], v100
	v_lshl_add_u64 v[76:77], v[76:77], 1, s[14:15]
	s_waitcnt vmcnt(9) lgkmcnt(0)
	v_mov_b32_e32 v68, v148
	v_mov_b32_e32 v69, v149
	v_mov_b32_e32 v70, v150
	v_mov_b32_e32 v71, v151
	v_pk_add_f32 v[68:69], v[72:73], v[68:69]
	v_pk_add_f32 v[70:71], v[74:75], v[70:71]
	global_store_dwordx4 v[78:79], v[68:71], off
	v_cvt_pk_bf16_f32 v72, v68, v69
	v_cvt_pk_bf16_f32 v73, v70, v71
	v_pk_mul_f32 v[68:69], v[68:69], v[68:69]
	v_pk_mul_f32 v[70:71], v[70:71], v[70:71]
	v_add_f32_e32 v65, v68, v69
	v_add_f32_e32 v65, v70, v65
	v_add_f32_e32 v65, v71, v65
	v_mov_b32_e32 v68, 0
	global_store_dwordx2 v[76:77], v[72:73], off
	v_add_f32_dpp v65, v65, v65 quad_perm:[1,0,3,2] row_mask:0xf bank_mask:0xf bound_ctrl:1
	s_nop 1
	v_add_f32_dpp v65, v65, v65 quad_perm:[2,3,0,1] row_mask:0xf bank_mask:0xf bound_ctrl:1
	s_nop 1
	v_add_f32_dpp v65, v65, v65 row_half_mirror row_mask:0xf bank_mask:0xf bound_ctrl:1
	s_nop 1
	v_mov_b32_dpp v68, v65 row_mirror row_mask:0xf bank_mask:0xf
	s_and_saveexec_b64 s[0:1], vcc
	s_cbranch_execz .LBB0_1429
	v_add_f32_e32 v68, v65, v68
	v_ashrrev_i32_e32 v65, 31, v64
	v_lshl_add_u64 v[64:65], v[64:65], 2, s[18:19]
	global_atomic_add_f32 v[64:65], v68, off
.LBB0_1429:
	s_or_b64 exec, exec, s[0:1]
	v_add_u32_e32 v64, v101, v67
	v_lshl_add_u32 v76, v64, 10, v128
	v_ashrrev_i32_e32 v77, 31, v76
	v_lshl_add_u64 v[78:79], v[76:77], 2, s[12:13]
	ds_read_b128 v[72:75], v102
	v_lshl_add_u64 v[76:77], v[76:77], 1, s[14:15]
	s_waitcnt vmcnt(11) lgkmcnt(0)
	v_mov_b32_e32 v68, v152
	v_mov_b32_e32 v69, v153
	v_mov_b32_e32 v70, v154
	v_mov_b32_e32 v71, v155
	v_pk_add_f32 v[68:69], v[72:73], v[68:69]
	v_pk_add_f32 v[70:71], v[74:75], v[70:71]
	global_store_dwordx4 v[78:79], v[68:71], off
	v_cvt_pk_bf16_f32 v72, v68, v69
	v_cvt_pk_bf16_f32 v73, v70, v71
	v_pk_mul_f32 v[68:69], v[68:69], v[68:69]
	v_pk_mul_f32 v[70:71], v[70:71], v[70:71]
	v_add_f32_e32 v65, v68, v69
	v_add_f32_e32 v65, v70, v65
	v_add_f32_e32 v65, v71, v65
	v_mov_b32_e32 v68, 0
	global_store_dwordx2 v[76:77], v[72:73], off
	v_add_f32_dpp v65, v65, v65 quad_perm:[1,0,3,2] row_mask:0xf bank_mask:0xf bound_ctrl:1
	s_nop 1
	v_add_f32_dpp v65, v65, v65 quad_perm:[2,3,0,1] row_mask:0xf bank_mask:0xf bound_ctrl:1
	s_nop 1
	v_add_f32_dpp v65, v65, v65 row_half_mirror row_mask:0xf bank_mask:0xf bound_ctrl:1
	s_nop 1
	v_mov_b32_dpp v68, v65 row_mirror row_mask:0xf bank_mask:0xf
	s_and_saveexec_b64 s[0:1], vcc
	s_cbranch_execz .LBB0_1431
	v_add_f32_e32 v68, v65, v68
	v_ashrrev_i32_e32 v65, 31, v64
	v_lshl_add_u64 v[64:65], v[64:65], 2, s[18:19]
	global_atomic_add_f32 v[64:65], v68, off
.LBB0_1431:
	s_or_b64 exec, exec, s[0:1]
	v_add_u32_e32 v64, v103, v67
	v_lshl_add_u32 v76, v64, 10, v128
	v_ashrrev_i32_e32 v77, 31, v76
	v_lshl_add_u64 v[78:79], v[76:77], 2, s[12:13]
	ds_read_b128 v[72:75], v98
	v_lshl_add_u64 v[76:77], v[76:77], 1, s[14:15]
	s_waitcnt vmcnt(13) lgkmcnt(0)
	v_mov_b32_e32 v68, v156
	v_mov_b32_e32 v69, v157
	v_mov_b32_e32 v70, v158
	v_mov_b32_e32 v71, v159
	v_pk_add_f32 v[68:69], v[72:73], v[68:69]
	v_pk_add_f32 v[70:71], v[74:75], v[70:71]
	global_store_dwordx4 v[78:79], v[68:71], off
	v_cvt_pk_bf16_f32 v72, v68, v69
	v_cvt_pk_bf16_f32 v73, v70, v71
	v_pk_mul_f32 v[68:69], v[68:69], v[68:69]
	v_pk_mul_f32 v[70:71], v[70:71], v[70:71]
	v_add_f32_e32 v65, v68, v69
	v_add_f32_e32 v65, v70, v65
	v_add_f32_e32 v65, v71, v65
	v_mov_b32_e32 v68, 0
	global_store_dwordx2 v[76:77], v[72:73], off
	v_add_f32_dpp v65, v65, v65 quad_perm:[1,0,3,2] row_mask:0xf bank_mask:0xf bound_ctrl:1
	s_nop 1
	v_add_f32_dpp v65, v65, v65 quad_perm:[2,3,0,1] row_mask:0xf bank_mask:0xf bound_ctrl:1
	s_nop 1
	v_add_f32_dpp v65, v65, v65 row_half_mirror row_mask:0xf bank_mask:0xf bound_ctrl:1
	s_nop 1
	v_mov_b32_dpp v68, v65 row_mirror row_mask:0xf bank_mask:0xf
	s_and_saveexec_b64 s[0:1], vcc
	s_cbranch_execz .LBB0_1433
	v_add_f32_e32 v68, v65, v68
	v_ashrrev_i32_e32 v65, 31, v64
	v_lshl_add_u64 v[64:65], v[64:65], 2, s[18:19]
	global_atomic_add_f32 v[64:65], v68, off
.LBB0_1433:
	s_or_b64 exec, exec, s[0:1]
	v_add_u32_e32 v64, v105, v67
	v_lshl_add_u32 v76, v64, 10, v128
	v_ashrrev_i32_e32 v77, 31, v76
	v_lshl_add_u64 v[78:79], v[76:77], 2, s[12:13]
	ds_read_b128 v[72:75], v98 offset:1088
	v_lshl_add_u64 v[76:77], v[76:77], 1, s[14:15]
	s_waitcnt vmcnt(15) lgkmcnt(0)
	v_mov_b32_e32 v68, v160
	v_mov_b32_e32 v69, v161
	v_mov_b32_e32 v70, v162
	v_mov_b32_e32 v71, v163
	v_pk_add_f32 v[68:69], v[72:73], v[68:69]
	v_pk_add_f32 v[70:71], v[74:75], v[70:71]
	global_store_dwordx4 v[78:79], v[68:71], off
	v_cvt_pk_bf16_f32 v72, v68, v69
	v_cvt_pk_bf16_f32 v73, v70, v71
	v_pk_mul_f32 v[68:69], v[68:69], v[68:69]
	v_pk_mul_f32 v[70:71], v[70:71], v[70:71]
	v_add_f32_e32 v65, v68, v69
	v_add_f32_e32 v65, v70, v65
	v_add_f32_e32 v65, v71, v65
	v_mov_b32_e32 v68, 0
	global_store_dwordx2 v[76:77], v[72:73], off
	v_add_f32_dpp v65, v65, v65 quad_perm:[1,0,3,2] row_mask:0xf bank_mask:0xf bound_ctrl:1
	s_nop 1
	v_add_f32_dpp v65, v65, v65 quad_perm:[2,3,0,1] row_mask:0xf bank_mask:0xf bound_ctrl:1
	s_nop 1
	v_add_f32_dpp v65, v65, v65 row_half_mirror row_mask:0xf bank_mask:0xf bound_ctrl:1
	s_nop 1
	v_mov_b32_dpp v68, v65 row_mirror row_mask:0xf bank_mask:0xf
	s_and_saveexec_b64 s[0:1], vcc
	s_cbranch_execz .LBB0_1435
	v_add_f32_e32 v68, v65, v68
	v_ashrrev_i32_e32 v65, 31, v64
	v_lshl_add_u64 v[64:65], v[64:65], 2, s[18:19]
	global_atomic_add_f32 v[64:65], v68, off
;   __device__ __forceinline__ void tile(const float* reg, int row0, int col0, int lane) const {
;     rows4(reg, lane, [&](int it, int rr, int c4, float4 v) {
;       int row = row0 + rr, idx = row * 1024 + col0 + c4;
;       float4 xo = *(const float4*)(xold + idx);
;       v.x = fmaf(coef, v.x, xo.x); v.y = fmaf(coef, v.y, xo.y); v.z = fmaf(coef, v.z, xo.z); v.w = fmaf(coef, v.w, xo.w);
;       *(float4*)(xnew + idx) = v;
;       *(bf16x4*)(xb + idx) = pack4(v.x, v.y, v.z, v.w);
;       float s = row16_sum(v.x * v.x + v.y * v.y + v.z * v.z + v.w * v.w);
;       if ((lane & 15) == 0) atomicAdd(ssqn + row, s);
;     });
.LBB0_1435:
	s_or_b64 exec, exec, s[0:1]
	v_add_u32_e32 v64, v106, v67
	v_lshl_add_u32 v76, v64, 10, v128
	v_ashrrev_i32_e32 v77, 31, v76
	v_lshl_add_u64 v[78:79], v[76:77], 2, s[12:13]
	ds_read_b128 v[72:75], v98 offset:2176
	v_lshl_add_u64 v[76:77], v[76:77], 1, s[14:15]
	s_waitcnt vmcnt(17) lgkmcnt(0)
	v_mov_b32_e32 v68, v164
	v_mov_b32_e32 v69, v165
	v_mov_b32_e32 v70, v166
	v_mov_b32_e32 v71, v167
	v_pk_add_f32 v[68:69], v[72:73], v[68:69]
	v_pk_add_f32 v[70:71], v[74:75], v[70:71]
	global_store_dwordx4 v[78:79], v[68:71], off
	v_cvt_pk_bf16_f32 v72, v68, v69
	v_cvt_pk_bf16_f32 v73, v70, v71
	v_pk_mul_f32 v[68:69], v[68:69], v[68:69]
	v_pk_mul_f32 v[70:71], v[70:71], v[70:71]
	v_add_f32_e32 v65, v68, v69
	v_add_f32_e32 v65, v70, v65
	v_add_f32_e32 v65, v71, v65
	v_mov_b32_e32 v68, 0
	global_store_dwordx2 v[76:77], v[72:73], off
	v_add_f32_dpp v65, v65, v65 quad_perm:[1,0,3,2] row_mask:0xf bank_mask:0xf bound_ctrl:1
	s_nop 1
	v_add_f32_dpp v65, v65, v65 quad_perm:[2,3,0,1] row_mask:0xf bank_mask:0xf bound_ctrl:1
	s_nop 1
	v_add_f32_dpp v65, v65, v65 row_half_mirror row_mask:0xf bank_mask:0xf bound_ctrl:1
	s_nop 1
	v_mov_b32_dpp v68, v65 row_mirror row_mask:0xf bank_mask:0xf
	s_and_saveexec_b64 s[0:1], vcc
	s_cbranch_execz .LBB0_1437
	v_add_f32_e32 v68, v65, v68
	v_ashrrev_i32_e32 v65, 31, v64
	v_lshl_add_u64 v[64:65], v[64:65], 2, s[18:19]
	global_atomic_add_f32 v[64:65], v68, off
.LBB0_1437:
	s_or_b64 exec, exec, s[0:1]
	v_add_u32_e32 v64, v107, v67
	v_lshl_add_u32 v76, v64, 10, v128
	v_ashrrev_i32_e32 v77, 31, v76
	v_lshl_add_u64 v[78:79], v[76:77], 2, s[12:13]
	ds_read_b128 v[72:75], v98 offset:3264
	v_lshl_add_u64 v[76:77], v[76:77], 1, s[14:15]
	s_waitcnt vmcnt(19) lgkmcnt(0)
	v_mov_b32_e32 v68, v168
	v_mov_b32_e32 v69, v169
	v_mov_b32_e32 v70, v170
	v_mov_b32_e32 v71, v171
	v_pk_add_f32 v[68:69], v[72:73], v[68:69]
	v_pk_add_f32 v[70:71], v[74:75], v[70:71]
	global_store_dwordx4 v[78:79], v[68:71], off
	v_cvt_pk_bf16_f32 v72, v68, v69
	v_cvt_pk_bf16_f32 v73, v70, v71
	v_pk_mul_f32 v[68:69], v[68:69], v[68:69]
	v_pk_mul_f32 v[70:71], v[70:71], v[70:71]
	v_add_f32_e32 v65, v68, v69
	v_add_f32_e32 v65, v70, v65
	v_add_f32_e32 v65, v71, v65
	v_mov_b32_e32 v68, 0
	global_store_dwordx2 v[76:77], v[72:73], off
	v_add_f32_dpp v65, v65, v65 quad_perm:[1,0,3,2] row_mask:0xf bank_mask:0xf bound_ctrl:1
	s_nop 1
	v_add_f32_dpp v65, v65, v65 quad_perm:[2,3,0,1] row_mask:0xf bank_mask:0xf bound_ctrl:1
	s_nop 1
	v_add_f32_dpp v65, v65, v65 row_half_mirror row_mask:0xf bank_mask:0xf bound_ctrl:1
	s_nop 1
	v_mov_b32_dpp v68, v65 row_mirror row_mask:0xf bank_mask:0xf
	s_and_saveexec_b64 s[0:1], vcc
	s_cbranch_execz .LBB0_1439
	v_add_f32_e32 v68, v65, v68
	v_ashrrev_i32_e32 v65, 31, v64
	v_lshl_add_u64 v[64:65], v[64:65], 2, s[18:19]
	global_atomic_add_f32 v[64:65], v68, off
.LBB0_1439:
	s_or_b64 exec, exec, s[0:1]
	v_add_u32_e32 v64, v108, v67
	v_lshl_add_u32 v76, v64, 10, v128
	v_ashrrev_i32_e32 v77, 31, v76
	v_lshl_add_u64 v[78:79], v[76:77], 2, s[12:13]
	ds_read_b128 v[72:75], v98 offset:4352
	v_mov_b32_e32 v67, 0
	v_lshl_add_u64 v[76:77], v[76:77], 1, s[14:15]
	s_waitcnt vmcnt(21) lgkmcnt(0)
	v_mov_b32_e32 v68, v172
	v_mov_b32_e32 v69, v173
	v_mov_b32_e32 v70, v174
	v_mov_b32_e32 v71, v175
	v_pk_add_f32 v[68:69], v[72:73], v[68:69]
	v_pk_add_f32 v[70:71], v[74:75], v[70:71]
	global_store_dwordx4 v[78:79], v[68:71], off
	v_cvt_pk_bf16_f32 v72, v68, v69
	v_cvt_pk_bf16_f32 v73, v70, v71
	v_pk_mul_f32 v[68:69], v[68:69], v[68:69]
	v_pk_mul_f32 v[70:71], v[70:71], v[70:71]
	v_add_f32_e32 v65, v68, v69
	v_add_f32_e32 v65, v70, v65
	v_add_f32_e32 v65, v71, v65
	global_store_dwordx2 v[76:77], v[72:73], off
	s_nop 0
	v_add_f32_dpp v65, v65, v65 quad_perm:[1,0,3,2] row_mask:0xf bank_mask:0xf bound_ctrl:1
	s_nop 1
	v_add_f32_dpp v65, v65, v65 quad_perm:[2,3,0,1] row_mask:0xf bank_mask:0xf bound_ctrl:1
	s_nop 1
	v_add_f32_dpp v65, v65, v65 row_half_mirror row_mask:0xf bank_mask:0xf bound_ctrl:1
	s_nop 1
	v_mov_b32_dpp v67, v65 row_mirror row_mask:0xf bank_mask:0xf
	s_and_saveexec_b64 s[0:1], vcc
	s_cbranch_execz .LBB0_1441
	v_add_f32_e32 v67, v65, v67
	v_ashrrev_i32_e32 v65, 31, v64
	v_lshl_add_u64 v[64:65], v[64:65], 2, s[18:19]
	global_atomic_add_f32 v[64:65], v67, off
;   __device__ __forceinline__ void tile(const float* reg, int row0, int col0, int lane) const {
;     rows4(reg, lane, [&](int it, int rr, int c4, float4 v) {
;       int row = row0 + rr, idx = row * 1024 + col0 + c4;
;       float4 xo = *(const float4*)(xold + idx);
;       v.x = fmaf(coef, v.x, xo.x); v.y = fmaf(coef, v.y, xo.y); v.z = fmaf(coef, v.z, xo.z); v.w = fmaf(coef, v.w, xo.w);
;       *(float4*)(xnew + idx) = v;
;       *(bf16x4*)(xb + idx) = pack4(v.x, v.y, v.z, v.w);
;       float s = row16_sum(v.x * v.x + v.y * v.y + v.z * v.z + v.w * v.w);
;       if ((lane & 15) == 0) atomicAdd(ssqn + row, s);
;     });
; template <int MF, class Epi>
; __device__ __forceinline__ void staged_epilogue(f32x4 (&acc)[MF][4], int row0, int col0, const Epi& epi) {
;     ...
;         for (int j = 0; j < 4; ++j) reg[(mm * 16 + fq * 4 + j) * 68 + n * 16 + fr] = acc[mp * 2 + mm][n][j];
.LBB0_1441:
	s_or_b64 exec, exec, s[0:1]
	ds_write2_b32 v131, v56, v60 offset1:16
	ds_write2_b32 v131, v57, v61 offset0:68 offset1:84
	ds_write2_b32 v131, v58, v62 offset0:136 offset1:152
	ds_write2_b32 v131, v59, v63 offset0:204 offset1:220
	ds_write2_b32 v131, v48, v52 offset0:32 offset1:48
	ds_write2_b32 v131, v49, v53 offset0:100 offset1:116
	ds_write2_b32 v131, v50, v54 offset0:168 offset1:184
	ds_write2_b32 v131, v51, v55 offset0:236 offset1:252
	ds_write2_b32 v112, v40, v44 offset0:64 offset1:80
	ds_write2_b32 v112, v41, v45 offset0:132 offset1:148
	ds_write2_b32 v112, v42, v46 offset0:200 offset1:216
	ds_write2_b32 v104, v43, v47 offset0:12 offset1:28
	ds_write2_b32 v112, v32, v36 offset0:96 offset1:112
	ds_write2_b32 v112, v33, v37 offset0:164 offset1:180
	ds_write2_b32 v112, v34, v38 offset0:232 offset1:248
	ds_write2_b32 v104, v35, v39 offset0:44 offset1:60
	v_add_u32_e32 v185, 64, v129
	v_add_u32_e32 v184, v130, v185
	v_lshl_add_u32 v176, v184, 10, v128
	v_ashrrev_i32_e32 v177, 31, v176
	v_lshl_add_u64 v[178:179], v[176:177], 2, s[12:13]
	global_load_dwordx4 v[144:147], v[178:179], off
	v_add_u32_e32 v185, 64, v129
	v_add_u32_e32 v184, v99, v185
	v_lshl_add_u32 v176, v184, 10, v128
	v_ashrrev_i32_e32 v177, 31, v176
	v_lshl_add_u64 v[178:179], v[176:177], 2, s[12:13]
	global_load_dwordx4 v[148:151], v[178:179], off
	v_add_u32_e32 v185, 64, v129
	v_add_u32_e32 v184, v101, v185
	v_lshl_add_u32 v176, v184, 10, v128
	v_ashrrev_i32_e32 v177, 31, v176
	v_lshl_add_u64 v[178:179], v[176:177], 2, s[12:13]
	global_load_dwordx4 v[152:155], v[178:179], off
	v_add_u32_e32 v185, 64, v129
	v_add_u32_e32 v184, v103, v185
	v_lshl_add_u32 v176, v184, 10, v128
	v_ashrrev_i32_e32 v177, 31, v176
	v_lshl_add_u64 v[178:179], v[176:177], 2, s[12:13]
	global_load_dwordx4 v[156:159], v[178:179], off
	v_add_u32_e32 v185, 64, v129
	v_add_u32_e32 v184, v105, v185
	v_lshl_add_u32 v176, v184, 10, v128
	v_ashrrev_i32_e32 v177, 31, v176
	v_lshl_add_u64 v[178:179], v[176:177], 2, s[12:13]
	global_load_dwordx4 v[160:163], v[178:179], off
	v_add_u32_e32 v185, 64, v129
	v_add_u32_e32 v184, v106, v185
	v_lshl_add_u32 v176, v184, 10, v128
	v_ashrrev_i32_e32 v177, 31, v176
	v_lshl_add_u64 v[178:179], v[176:177], 2, s[12:13]
	global_load_dwordx4 v[164:167], v[178:179], off
	v_add_u32_e32 v185, 64, v129
	v_add_u32_e32 v184, v107, v185
	v_lshl_add_u32 v176, v184, 10, v128
	v_ashrrev_i32_e32 v177, 31, v176
	v_lshl_add_u64 v[178:179], v[176:177], 2, s[12:13]
	global_load_dwordx4 v[168:171], v[178:179], off
	v_add_u32_e32 v185, 64, v129
	v_add_u32_e32 v184, v108, v185
	v_lshl_add_u32 v176, v184, 10, v128
	v_ashrrev_i32_e32 v177, 31, v176
	v_lshl_add_u64 v[178:179], v[176:177], 2, s[12:13]
	global_load_dwordx4 v[172:175], v[178:179], off
	v_add_u32_e32 v34, 64, v129
	v_add_u32_e32 v32, v130, v34
	v_lshl_add_u32 v44, v32, 10, v128
	v_ashrrev_i32_e32 v45, 31, v44
	v_lshl_add_u64 v[46:47], v[44:45], 2, s[12:13]
	ds_read_b128 v[40:43], v66
	v_mov_b32_e32 v35, 0
	v_lshl_add_u64 v[44:45], v[44:45], 1, s[14:15]
	s_waitcnt vmcnt(7) lgkmcnt(0)
	v_mov_b32_e32 v36, v144
	v_mov_b32_e32 v37, v145
	v_mov_b32_e32 v38, v146
	v_mov_b32_e32 v39, v147
	v_pk_add_f32 v[36:37], v[40:41], v[36:37]
	v_pk_add_f32 v[38:39], v[42:43], v[38:39]
	global_store_dwordx4 v[46:47], v[36:39], off
	v_cvt_pk_bf16_f32 v40, v36, v37
	v_cvt_pk_bf16_f32 v41, v38, v39
	v_pk_mul_f32 v[36:37], v[36:37], v[36:37]
	v_pk_mul_f32 v[38:39], v[38:39], v[38:39]
	v_add_f32_e32 v33, v36, v37
	v_add_f32_e32 v33, v38, v33
	v_add_f32_e32 v33, v39, v33
	global_store_dwordx2 v[44:45], v[40:41], off
	s_nop 0
	v_add_f32_dpp v33, v33, v33 quad_perm:[1,0,3,2] row_mask:0xf bank_mask:0xf bound_ctrl:1
	s_nop 1
	v_add_f32_dpp v33, v33, v33 quad_perm:[2,3,0,1] row_mask:0xf bank_mask:0xf bound_ctrl:1
	s_nop 1
	v_add_f32_dpp v33, v33, v33 row_half_mirror row_mask:0xf bank_mask:0xf bound_ctrl:1
	s_nop 1
	v_mov_b32_dpp v35, v33 row_mirror row_mask:0xf bank_mask:0xf
	s_and_saveexec_b64 s[0:1], vcc
	s_cbranch_execz .LBB0_1443
	v_add_f32_e32 v35, v33, v35
	v_ashrrev_i32_e32 v33, 31, v32
	v_lshl_add_u64 v[32:33], v[32:33], 2, s[18:19]
	global_atomic_add_f32 v[32:33], v35, off
.LBB0_1443:
	s_or_b64 exec, exec, s[0:1]
	v_add_u32_e32 v32, v99, v34
	v_lshl_add_u32 v44, v32, 10, v128
	v_ashrrev_i32_e32 v45, 31, v44
	v_lshl_add_u64 v[46:47], v[44:45], 2, s[12:13]
	ds_read_b128 v[40:43], v100
	v_mov_b32_e32 v35, 0
	v_lshl_add_u64 v[44:45], v[44:45], 1, s[14:15]
	s_waitcnt vmcnt(9) lgkmcnt(0)
	v_mov_b32_e32 v36, v148
	v_mov_b32_e32 v37, v149
	v_mov_b32_e32 v38, v150
	v_mov_b32_e32 v39, v151
	v_pk_add_f32 v[36:37], v[40:41], v[36:37]
	v_pk_add_f32 v[38:39], v[42:43], v[38:39]
	global_store_dwordx4 v[46:47], v[36:39], off
	v_cvt_pk_bf16_f32 v40, v36, v37
	v_cvt_pk_bf16_f32 v41, v38, v39
	v_pk_mul_f32 v[36:37], v[36:37], v[36:37]
	v_pk_mul_f32 v[38:39], v[38:39], v[38:39]
	v_add_f32_e32 v33, v36, v37
	v_add_f32_e32 v33, v38, v33
	v_add_f32_e32 v33, v39, v33
	global_store_dwordx2 v[44:45], v[40:41], off
	s_nop 0
	v_add_f32_dpp v33, v33, v33 quad_perm:[1,0,3,2] row_mask:0xf bank_mask:0xf bound_ctrl:1
	s_nop 1
	v_add_f32_dpp v33, v33, v33 quad_perm:[2,3,0,1] row_mask:0xf bank_mask:0xf bound_ctrl:1
	s_nop 1
	v_add_f32_dpp v33, v33, v33 row_half_mirror row_mask:0xf bank_mask:0xf bound_ctrl:1
	s_nop 1
	v_mov_b32_dpp v35, v33 row_mirror row_mask:0xf bank_mask:0xf
	s_and_saveexec_b64 s[0:1], vcc
	s_cbranch_execz .LBB0_1445
	v_add_f32_e32 v35, v33, v35
	v_ashrrev_i32_e32 v33, 31, v32
	v_lshl_add_u64 v[32:33], v[32:33], 2, s[18:19]
	global_atomic_add_f32 v[32:33], v35, off
;   __device__ __forceinline__ void tile(const float* reg, int row0, int col0, int lane) const {
;     rows4(reg, lane, [&](int it, int rr, int c4, float4 v) {
;       int row = row0 + rr, idx = row * 1024 + col0 + c4;
;       float4 xo = *(const float4*)(xold + idx);
;       v.x = fmaf(coef, v.x, xo.x); v.y = fmaf(coef, v.y, xo.y); v.z = fmaf(coef, v.z, xo.z); v.w = fmaf(coef, v.w, xo.w);
;       *(float4*)(xnew + idx) = v;
;       *(bf16x4*)(xb + idx) = pack4(v.x, v.y, v.z, v.w);
;       float s = row16_sum(v.x * v.x + v.y * v.y + v.z * v.z + v.w * v.w);
;       if ((lane & 15) == 0) atomicAdd(ssqn + row, s);
;     });
.LBB0_1445:
	s_or_b64 exec, exec, s[0:1]
	v_add_u32_e32 v32, v101, v34
	v_lshl_add_u32 v44, v32, 10, v128
	v_ashrrev_i32_e32 v45, 31, v44
	v_lshl_add_u64 v[46:47], v[44:45], 2, s[12:13]
	ds_read_b128 v[40:43], v102
	v_mov_b32_e32 v35, 0
	v_lshl_add_u64 v[44:45], v[44:45], 1, s[14:15]
	s_waitcnt vmcnt(11) lgkmcnt(0)
	v_mov_b32_e32 v36, v152
	v_mov_b32_e32 v37, v153
	v_mov_b32_e32 v38, v154
	v_mov_b32_e32 v39, v155
	v_pk_add_f32 v[36:37], v[40:41], v[36:37]
	v_pk_add_f32 v[38:39], v[42:43], v[38:39]
	global_store_dwordx4 v[46:47], v[36:39], off
	v_cvt_pk_bf16_f32 v40, v36, v37
	v_cvt_pk_bf16_f32 v41, v38, v39
	v_pk_mul_f32 v[36:37], v[36:37], v[36:37]
	v_pk_mul_f32 v[38:39], v[38:39], v[38:39]
	v_add_f32_e32 v33, v36, v37
	v_add_f32_e32 v33, v38, v33
	v_add_f32_e32 v33, v39, v33
	global_store_dwordx2 v[44:45], v[40:41], off
	s_nop 0
	v_add_f32_dpp v33, v33, v33 quad_perm:[1,0,3,2] row_mask:0xf bank_mask:0xf bound_ctrl:1
	s_nop 1
	v_add_f32_dpp v33, v33, v33 quad_perm:[2,3,0,1] row_mask:0xf bank_mask:0xf bound_ctrl:1
	s_nop 1
	v_add_f32_dpp v33, v33, v33 row_half_mirror row_mask:0xf bank_mask:0xf bound_ctrl:1
	s_nop 1
	v_mov_b32_dpp v35, v33 row_mirror row_mask:0xf bank_mask:0xf
	s_and_saveexec_b64 s[0:1], vcc
	s_cbranch_execz .LBB0_1447
	v_add_f32_e32 v35, v33, v35
	v_ashrrev_i32_e32 v33, 31, v32
	v_lshl_add_u64 v[32:33], v[32:33], 2, s[18:19]
	global_atomic_add_f32 v[32:33], v35, off
.LBB0_1447:
	s_or_b64 exec, exec, s[0:1]
	v_add_u32_e32 v32, v103, v34
	v_lshl_add_u32 v44, v32, 10, v128
	v_ashrrev_i32_e32 v45, 31, v44
	v_lshl_add_u64 v[46:47], v[44:45], 2, s[12:13]
	ds_read_b128 v[40:43], v98
	v_mov_b32_e32 v35, 0
	v_lshl_add_u64 v[44:45], v[44:45], 1, s[14:15]
	s_waitcnt vmcnt(13) lgkmcnt(0)
	v_mov_b32_e32 v36, v156
	v_mov_b32_e32 v37, v157
	v_mov_b32_e32 v38, v158
	v_mov_b32_e32 v39, v159
	v_pk_add_f32 v[36:37], v[40:41], v[36:37]
	v_pk_add_f32 v[38:39], v[42:43], v[38:39]
	global_store_dwordx4 v[46:47], v[36:39], off
	v_cvt_pk_bf16_f32 v40, v36, v37
	v_cvt_pk_bf16_f32 v41, v38, v39
	v_pk_mul_f32 v[36:37], v[36:37], v[36:37]
	v_pk_mul_f32 v[38:39], v[38:39], v[38:39]
	v_add_f32_e32 v33, v36, v37
	v_add_f32_e32 v33, v38, v33
	v_add_f32_e32 v33, v39, v33
	global_store_dwordx2 v[44:45], v[40:41], off
	s_nop 0
	v_add_f32_dpp v33, v33, v33 quad_perm:[1,0,3,2] row_mask:0xf bank_mask:0xf bound_ctrl:1
	s_nop 1
	v_add_f32_dpp v33, v33, v33 quad_perm:[2,3,0,1] row_mask:0xf bank_mask:0xf bound_ctrl:1
	s_nop 1
	v_add_f32_dpp v33, v33, v33 row_half_mirror row_mask:0xf bank_mask:0xf bound_ctrl:1
	s_nop 1
	v_mov_b32_dpp v35, v33 row_mirror row_mask:0xf bank_mask:0xf
	s_and_saveexec_b64 s[0:1], vcc
	s_cbranch_execz .LBB0_1449
	v_add_f32_e32 v35, v33, v35
	v_ashrrev_i32_e32 v33, 31, v32
	v_lshl_add_u64 v[32:33], v[32:33], 2, s[18:19]
	global_atomic_add_f32 v[32:33], v35, off
.LBB0_1449:
	s_or_b64 exec, exec, s[0:1]
	v_add_u32_e32 v32, v105, v34
	v_lshl_add_u32 v44, v32, 10, v128
	v_ashrrev_i32_e32 v45, 31, v44
	v_lshl_add_u64 v[46:47], v[44:45], 2, s[12:13]
	ds_read_b128 v[40:43], v98 offset:1088
	v_mov_b32_e32 v35, 0
	v_lshl_add_u64 v[44:45], v[44:45], 1, s[14:15]
	s_waitcnt vmcnt(15) lgkmcnt(0)
	v_mov_b32_e32 v36, v160
	v_mov_b32_e32 v37, v161
	v_mov_b32_e32 v38, v162
	v_mov_b32_e32 v39, v163
	v_pk_add_f32 v[36:37], v[40:41], v[36:37]
	v_pk_add_f32 v[38:39], v[42:43], v[38:39]
	global_store_dwordx4 v[46:47], v[36:39], off
	v_cvt_pk_bf16_f32 v40, v36, v37
	v_cvt_pk_bf16_f32 v41, v38, v39
	v_pk_mul_f32 v[36:37], v[36:37], v[36:37]
	v_pk_mul_f32 v[38:39], v[38:39], v[38:39]
	v_add_f32_e32 v33, v36, v37
	v_add_f32_e32 v33, v38, v33
	v_add_f32_e32 v33, v39, v33
	global_store_dwordx2 v[44:45], v[40:41], off
	s_nop 0
	v_add_f32_dpp v33, v33, v33 quad_perm:[1,0,3,2] row_mask:0xf bank_mask:0xf bound_ctrl:1
	s_nop 1
	v_add_f32_dpp v33, v33, v33 quad_perm:[2,3,0,1] row_mask:0xf bank_mask:0xf bound_ctrl:1
	s_nop 1
	v_add_f32_dpp v33, v33, v33 row_half_mirror row_mask:0xf bank_mask:0xf bound_ctrl:1
	s_nop 1
	v_mov_b32_dpp v35, v33 row_mirror row_mask:0xf bank_mask:0xf
	s_and_saveexec_b64 s[0:1], vcc
	s_cbranch_execz .LBB0_1451
	v_add_f32_e32 v35, v33, v35
	v_ashrrev_i32_e32 v33, 31, v32
	v_lshl_add_u64 v[32:33], v[32:33], 2, s[18:19]
	global_atomic_add_f32 v[32:33], v35, off
.LBB0_1451:
	s_or_b64 exec, exec, s[0:1]
	v_add_u32_e32 v32, v106, v34
	v_lshl_add_u32 v44, v32, 10, v128
	v_ashrrev_i32_e32 v45, 31, v44
	v_lshl_add_u64 v[46:47], v[44:45], 2, s[12:13]
	ds_read_b128 v[40:43], v98 offset:2176
	v_mov_b32_e32 v35, 0
	v_lshl_add_u64 v[44:45], v[44:45], 1, s[14:15]
	s_waitcnt vmcnt(17) lgkmcnt(0)
	v_mov_b32_e32 v36, v164
	v_mov_b32_e32 v37, v165
	v_mov_b32_e32 v38, v166
	v_mov_b32_e32 v39, v167
	v_pk_add_f32 v[36:37], v[40:41], v[36:37]
	v_pk_add_f32 v[38:39], v[42:43], v[38:39]
	global_store_dwordx4 v[46:47], v[36:39], off
	v_cvt_pk_bf16_f32 v40, v36, v37
	v_cvt_pk_bf16_f32 v41, v38, v39
	v_pk_mul_f32 v[36:37], v[36:37], v[36:37]
	v_pk_mul_f32 v[38:39], v[38:39], v[38:39]
	v_add_f32_e32 v33, v36, v37
	v_add_f32_e32 v33, v38, v33
	v_add_f32_e32 v33, v39, v33
	global_store_dwordx2 v[44:45], v[40:41], off
	s_nop 0
	v_add_f32_dpp v33, v33, v33 quad_perm:[1,0,3,2] row_mask:0xf bank_mask:0xf bound_ctrl:1
	s_nop 1
	v_add_f32_dpp v33, v33, v33 quad_perm:[2,3,0,1] row_mask:0xf bank_mask:0xf bound_ctrl:1
	s_nop 1
	v_add_f32_dpp v33, v33, v33 row_half_mirror row_mask:0xf bank_mask:0xf bound_ctrl:1
	s_nop 1
	v_mov_b32_dpp v35, v33 row_mirror row_mask:0xf bank_mask:0xf
	s_and_saveexec_b64 s[0:1], vcc
	s_cbranch_execz .LBB0_1453
	v_add_f32_e32 v35, v33, v35
	v_ashrrev_i32_e32 v33, 31, v32
	v_lshl_add_u64 v[32:33], v[32:33], 2, s[18:19]
	global_atomic_add_f32 v[32:33], v35, off
;   __device__ __forceinline__ void tile(const float* reg, int row0, int col0, int lane) const {
;     rows4(reg, lane, [&](int it, int rr, int c4, float4 v) {
;       int row = row0 + rr, idx = row * 1024 + col0 + c4;
;       float4 xo = *(const float4*)(xold + idx);
;       v.x = fmaf(coef, v.x, xo.x); v.y = fmaf(coef, v.y, xo.y); v.z = fmaf(coef, v.z, xo.z); v.w = fmaf(coef, v.w, xo.w);
;       *(float4*)(xnew + idx) = v;
;       *(bf16x4*)(xb + idx) = pack4(v.x, v.y, v.z, v.w);
;       float s = row16_sum(v.x * v.x + v.y * v.y + v.z * v.z + v.w * v.w);
;       if ((lane & 15) == 0) atomicAdd(ssqn + row, s);
;     });
; template <int MF, class Epi>
; __device__ __forceinline__ void staged_epilogue(f32x4 (&acc)[MF][4], int row0, int col0, const Epi& epi) {
;     ...
;         for (int j = 0; j < 4; ++j) reg[(mm * 16 + fq * 4 + j) * 68 + n * 16 + fr] = acc[mp * 2 + mm][n][j];
.LBB0_1453:
	s_or_b64 exec, exec, s[0:1]
	v_add_u32_e32 v32, v107, v34
	v_lshl_add_u32 v44, v32, 10, v128
	v_ashrrev_i32_e32 v45, 31, v44
	v_lshl_add_u64 v[46:47], v[44:45], 2, s[12:13]
	ds_read_b128 v[40:43], v98 offset:3264
	v_mov_b32_e32 v35, 0
	v_lshl_add_u64 v[44:45], v[44:45], 1, s[14:15]
	s_waitcnt vmcnt(19) lgkmcnt(0)
	v_mov_b32_e32 v36, v168
	v_mov_b32_e32 v37, v169
	v_mov_b32_e32 v38, v170
	v_mov_b32_e32 v39, v171
	v_pk_add_f32 v[36:37], v[40:41], v[36:37]
	v_pk_add_f32 v[38:39], v[42:43], v[38:39]
	global_store_dwordx4 v[46:47], v[36:39], off
	v_cvt_pk_bf16_f32 v40, v36, v37
	v_cvt_pk_bf16_f32 v41, v38, v39
	v_pk_mul_f32 v[36:37], v[36:37], v[36:37]
	v_pk_mul_f32 v[38:39], v[38:39], v[38:39]
	v_add_f32_e32 v33, v36, v37
	v_add_f32_e32 v33, v38, v33
	v_add_f32_e32 v33, v39, v33
	global_store_dwordx2 v[44:45], v[40:41], off
	s_nop 0
	v_add_f32_dpp v33, v33, v33 quad_perm:[1,0,3,2] row_mask:0xf bank_mask:0xf bound_ctrl:1
	s_nop 1
	v_add_f32_dpp v33, v33, v33 quad_perm:[2,3,0,1] row_mask:0xf bank_mask:0xf bound_ctrl:1
	s_nop 1
	v_add_f32_dpp v33, v33, v33 row_half_mirror row_mask:0xf bank_mask:0xf bound_ctrl:1
	s_nop 1
	v_mov_b32_dpp v35, v33 row_mirror row_mask:0xf bank_mask:0xf
	s_and_saveexec_b64 s[0:1], vcc
	s_cbranch_execz .LBB0_1455
	v_add_f32_e32 v35, v33, v35
	v_ashrrev_i32_e32 v33, 31, v32
	v_lshl_add_u64 v[32:33], v[32:33], 2, s[18:19]
	global_atomic_add_f32 v[32:33], v35, off
.LBB0_1455:
	s_or_b64 exec, exec, s[0:1]
	v_add_u32_e32 v32, v108, v34
	v_lshl_add_u32 v42, v32, 10, v128
	v_ashrrev_i32_e32 v43, 31, v42
	v_lshl_add_u64 v[44:45], v[42:43], 2, s[12:13]
	ds_read_b128 v[38:41], v98 offset:4352
	v_lshl_add_u64 v[42:43], v[42:43], 1, s[14:15]
	s_waitcnt vmcnt(21) lgkmcnt(0)
	v_mov_b32_e32 v34, v172
	v_mov_b32_e32 v35, v173
	v_mov_b32_e32 v36, v174
	v_mov_b32_e32 v37, v175
	v_pk_add_f32 v[34:35], v[38:39], v[34:35]
	v_pk_add_f32 v[36:37], v[40:41], v[36:37]
	global_store_dwordx4 v[44:45], v[34:37], off
	v_cvt_pk_bf16_f32 v38, v34, v35
	v_cvt_pk_bf16_f32 v39, v36, v37
	v_pk_mul_f32 v[34:35], v[34:35], v[34:35]
	v_pk_mul_f32 v[36:37], v[36:37], v[36:37]
	v_add_f32_e32 v33, v34, v35
	v_add_f32_e32 v33, v36, v33
	v_add_f32_e32 v33, v37, v33
	v_mov_b32_e32 v34, 0
	global_store_dwordx2 v[42:43], v[38:39], off
	v_add_f32_dpp v33, v33, v33 quad_perm:[1,0,3,2] row_mask:0xf bank_mask:0xf bound_ctrl:1
	s_nop 1
	v_add_f32_dpp v33, v33, v33 quad_perm:[2,3,0,1] row_mask:0xf bank_mask:0xf bound_ctrl:1
	s_nop 1
	v_add_f32_dpp v33, v33, v33 row_half_mirror row_mask:0xf bank_mask:0xf bound_ctrl:1
	s_nop 1
	v_mov_b32_dpp v34, v33 row_mirror row_mask:0xf bank_mask:0xf
	s_and_saveexec_b64 s[0:1], vcc
	s_cbranch_execz .LBB0_1457
	v_add_f32_e32 v34, v33, v34
	v_ashrrev_i32_e32 v33, 31, v32
	v_lshl_add_u64 v[32:33], v[32:33], 2, s[18:19]
	global_atomic_add_f32 v[32:33], v34, off
.LBB0_1457:
	s_or_b64 exec, exec, s[0:1]
	ds_write2_b32 v131, v24, v28 offset1:16
	ds_write2_b32 v131, v25, v29 offset0:68 offset1:84
	ds_write2_b32 v131, v26, v30 offset0:136 offset1:152
	ds_write2_b32 v131, v27, v31 offset0:204 offset1:220
	ds_write2_b32 v131, v16, v20 offset0:32 offset1:48
	ds_write2_b32 v131, v17, v21 offset0:100 offset1:116
	ds_write2_b32 v131, v18, v22 offset0:168 offset1:184
	ds_write2_b32 v131, v19, v23 offset0:236 offset1:252
	ds_write2_b32 v112, v4, v8 offset0:64 offset1:80
	ds_write2_b32 v112, v5, v9 offset0:132 offset1:148
	ds_write2_b32 v112, v6, v10 offset0:200 offset1:216
	ds_write2_b32 v104, v7, v11 offset0:12 offset1:28
	ds_write2_b32 v112, v0, v12 offset0:96 offset1:112
	ds_write2_b32 v112, v1, v13 offset0:164 offset1:180
	ds_write2_b32 v112, v2, v14 offset0:232 offset1:248
	ds_write2_b32 v104, v3, v15 offset0:44 offset1:60
	v_add_u32_e32 v185, 0x60, v129
	v_add_u32_e32 v184, v130, v185
	v_lshl_add_u32 v176, v184, 10, v128
	v_ashrrev_i32_e32 v177, 31, v176
	v_lshl_add_u64 v[178:179], v[176:177], 2, s[12:13]
	global_load_dwordx4 v[144:147], v[178:179], off
	v_add_u32_e32 v185, 0x60, v129
	v_add_u32_e32 v184, v99, v185
	v_lshl_add_u32 v176, v184, 10, v128
	v_ashrrev_i32_e32 v177, 31, v176
	v_lshl_add_u64 v[178:179], v[176:177], 2, s[12:13]
	global_load_dwordx4 v[148:151], v[178:179], off
	v_add_u32_e32 v185, 0x60, v129
	v_add_u32_e32 v184, v101, v185
	v_lshl_add_u32 v176, v184, 10, v128
	v_ashrrev_i32_e32 v177, 31, v176
	v_lshl_add_u64 v[178:179], v[176:177], 2, s[12:13]
	global_load_dwordx4 v[152:155], v[178:179], off
	v_add_u32_e32 v185, 0x60, v129
	v_add_u32_e32 v184, v103, v185
	v_lshl_add_u32 v176, v184, 10, v128
	v_ashrrev_i32_e32 v177, 31, v176
	v_lshl_add_u64 v[178:179], v[176:177], 2, s[12:13]
	global_load_dwordx4 v[156:159], v[178:179], off
	v_add_u32_e32 v185, 0x60, v129
	v_add_u32_e32 v184, v105, v185
	v_lshl_add_u32 v176, v184, 10, v128
	v_ashrrev_i32_e32 v177, 31, v176
	v_lshl_add_u64 v[178:179], v[176:177], 2, s[12:13]
	global_load_dwordx4 v[160:163], v[178:179], off
	v_add_u32_e32 v185, 0x60, v129
	v_add_u32_e32 v184, v106, v185
	v_lshl_add_u32 v176, v184, 10, v128
	v_ashrrev_i32_e32 v177, 31, v176
	v_lshl_add_u64 v[178:179], v[176:177], 2, s[12:13]
	global_load_dwordx4 v[164:167], v[178:179], off
	v_add_u32_e32 v185, 0x60, v129
	v_add_u32_e32 v184, v107, v185
	v_lshl_add_u32 v176, v184, 10, v128
	v_ashrrev_i32_e32 v177, 31, v176
	v_lshl_add_u64 v[178:179], v[176:177], 2, s[12:13]
	global_load_dwordx4 v[168:171], v[178:179], off
	v_add_u32_e32 v185, 0x60, v129
	v_add_u32_e32 v184, v108, v185
	v_lshl_add_u32 v176, v184, 10, v128
	v_ashrrev_i32_e32 v177, 31, v176
	v_lshl_add_u64 v[178:179], v[176:177], 2, s[12:13]
	global_load_dwordx4 v[172:175], v[178:179], off
	v_add_u32_e32 v2, 0x60, v129
	v_add_u32_e32 v0, v130, v2
	v_lshl_add_u32 v12, v0, 10, v128
	v_ashrrev_i32_e32 v13, 31, v12
	v_lshl_add_u64 v[14:15], v[12:13], 2, s[12:13]
	ds_read_b128 v[8:11], v66
	v_mov_b32_e32 v3, 0
	v_lshl_add_u64 v[12:13], v[12:13], 1, s[14:15]
	s_waitcnt vmcnt(7) lgkmcnt(0)
	v_mov_b32_e32 v4, v144
	v_mov_b32_e32 v5, v145
	v_mov_b32_e32 v6, v146
	v_mov_b32_e32 v7, v147
	v_pk_add_f32 v[4:5], v[8:9], v[4:5]
	v_pk_add_f32 v[6:7], v[10:11], v[6:7]
	global_store_dwordx4 v[14:15], v[4:7], off
	v_cvt_pk_bf16_f32 v8, v4, v5
	v_cvt_pk_bf16_f32 v9, v6, v7
	v_pk_mul_f32 v[4:5], v[4:5], v[4:5]
	v_pk_mul_f32 v[6:7], v[6:7], v[6:7]
	v_add_f32_e32 v1, v4, v5
	v_add_f32_e32 v1, v6, v1
	v_add_f32_e32 v1, v7, v1
	global_store_dwordx2 v[12:13], v[8:9], off
	s_nop 0
	v_add_f32_dpp v1, v1, v1 quad_perm:[1,0,3,2] row_mask:0xf bank_mask:0xf bound_ctrl:1
	s_nop 1
	v_add_f32_dpp v1, v1, v1 quad_perm:[2,3,0,1] row_mask:0xf bank_mask:0xf bound_ctrl:1
	s_nop 1
	v_add_f32_dpp v1, v1, v1 row_half_mirror row_mask:0xf bank_mask:0xf bound_ctrl:1
	s_nop 1
	v_mov_b32_dpp v3, v1 row_mirror row_mask:0xf bank_mask:0xf
	s_and_saveexec_b64 s[0:1], vcc
	s_cbranch_execz .LBB0_1459
	v_add_f32_e32 v3, v1, v3
	v_ashrrev_i32_e32 v1, 31, v0
	v_lshl_add_u64 v[0:1], v[0:1], 2, s[18:19]
	global_atomic_add_f32 v[0:1], v3, off
;   __device__ __forceinline__ void tile(const float* reg, int row0, int col0, int lane) const {
;     rows4(reg, lane, [&](int it, int rr, int c4, float4 v) {
;       int row = row0 + rr, idx = row * 1024 + col0 + c4;
;       float4 xo = *(const float4*)(xold + idx);
;       v.x = fmaf(coef, v.x, xo.x); v.y = fmaf(coef, v.y, xo.y); v.z = fmaf(coef, v.z, xo.z); v.w = fmaf(coef, v.w, xo.w);
;       *(float4*)(xnew + idx) = v;
;       *(bf16x4*)(xb + idx) = pack4(v.x, v.y, v.z, v.w);
;       float s = row16_sum(v.x * v.x + v.y * v.y + v.z * v.z + v.w * v.w);
;       if ((lane & 15) == 0) atomicAdd(ssqn + row, s);
;     });
.LBB0_1459:
	s_or_b64 exec, exec, s[0:1]
	v_add_u32_e32 v0, v99, v2
	v_lshl_add_u32 v12, v0, 10, v128
	v_ashrrev_i32_e32 v13, 31, v12
	v_lshl_add_u64 v[14:15], v[12:13], 2, s[12:13]
	ds_read_b128 v[8:11], v100
	v_mov_b32_e32 v3, 0
	v_lshl_add_u64 v[12:13], v[12:13], 1, s[14:15]
	s_waitcnt vmcnt(9) lgkmcnt(0)
	v_mov_b32_e32 v4, v148
	v_mov_b32_e32 v5, v149
	v_mov_b32_e32 v6, v150
	v_mov_b32_e32 v7, v151
	v_pk_add_f32 v[4:5], v[8:9], v[4:5]
	v_pk_add_f32 v[6:7], v[10:11], v[6:7]
	global_store_dwordx4 v[14:15], v[4:7], off
	v_cvt_pk_bf16_f32 v8, v4, v5
	v_cvt_pk_bf16_f32 v9, v6, v7
	v_pk_mul_f32 v[4:5], v[4:5], v[4:5]
	v_pk_mul_f32 v[6:7], v[6:7], v[6:7]
	v_add_f32_e32 v1, v4, v5
	v_add_f32_e32 v1, v6, v1
	v_add_f32_e32 v1, v7, v1
	global_store_dwordx2 v[12:13], v[8:9], off
	s_nop 0
	v_add_f32_dpp v1, v1, v1 quad_perm:[1,0,3,2] row_mask:0xf bank_mask:0xf bound_ctrl:1
	s_nop 1
	v_add_f32_dpp v1, v1, v1 quad_perm:[2,3,0,1] row_mask:0xf bank_mask:0xf bound_ctrl:1
	s_nop 1
	v_add_f32_dpp v1, v1, v1 row_half_mirror row_mask:0xf bank_mask:0xf bound_ctrl:1
	s_nop 1
	v_mov_b32_dpp v3, v1 row_mirror row_mask:0xf bank_mask:0xf
	s_and_saveexec_b64 s[0:1], vcc
	s_cbranch_execz .LBB0_1461
	v_add_f32_e32 v3, v1, v3
	v_ashrrev_i32_e32 v1, 31, v0
	v_lshl_add_u64 v[0:1], v[0:1], 2, s[18:19]
	global_atomic_add_f32 v[0:1], v3, off
.LBB0_1461:
	s_or_b64 exec, exec, s[0:1]
	v_add_u32_e32 v0, v101, v2
	v_lshl_add_u32 v12, v0, 10, v128
	v_ashrrev_i32_e32 v13, 31, v12
	v_lshl_add_u64 v[14:15], v[12:13], 2, s[12:13]
	ds_read_b128 v[8:11], v102
	v_mov_b32_e32 v3, 0
	v_lshl_add_u64 v[12:13], v[12:13], 1, s[14:15]
	s_waitcnt vmcnt(11) lgkmcnt(0)
	v_mov_b32_e32 v4, v152
	v_mov_b32_e32 v5, v153
	v_mov_b32_e32 v6, v154
	v_mov_b32_e32 v7, v155
	v_pk_add_f32 v[4:5], v[8:9], v[4:5]
	v_pk_add_f32 v[6:7], v[10:11], v[6:7]
	global_store_dwordx4 v[14:15], v[4:7], off
	v_cvt_pk_bf16_f32 v8, v4, v5
	v_cvt_pk_bf16_f32 v9, v6, v7
	v_pk_mul_f32 v[4:5], v[4:5], v[4:5]
	v_pk_mul_f32 v[6:7], v[6:7], v[6:7]
	v_add_f32_e32 v1, v4, v5
	v_add_f32_e32 v1, v6, v1
	v_add_f32_e32 v1, v7, v1
	global_store_dwordx2 v[12:13], v[8:9], off
	s_nop 0
	v_add_f32_dpp v1, v1, v1 quad_perm:[1,0,3,2] row_mask:0xf bank_mask:0xf bound_ctrl:1
	s_nop 1
	v_add_f32_dpp v1, v1, v1 quad_perm:[2,3,0,1] row_mask:0xf bank_mask:0xf bound_ctrl:1
	s_nop 1
	v_add_f32_dpp v1, v1, v1 row_half_mirror row_mask:0xf bank_mask:0xf bound_ctrl:1
	s_nop 1
	v_mov_b32_dpp v3, v1 row_mirror row_mask:0xf bank_mask:0xf
	s_and_saveexec_b64 s[0:1], vcc
	s_cbranch_execz .LBB0_1463
	v_add_f32_e32 v3, v1, v3
	v_ashrrev_i32_e32 v1, 31, v0
	v_lshl_add_u64 v[0:1], v[0:1], 2, s[18:19]
	global_atomic_add_f32 v[0:1], v3, off
.LBB0_1463:
	s_or_b64 exec, exec, s[0:1]
	v_add_u32_e32 v0, v103, v2
	v_lshl_add_u32 v12, v0, 10, v128
	v_ashrrev_i32_e32 v13, 31, v12
	v_lshl_add_u64 v[14:15], v[12:13], 2, s[12:13]
	ds_read_b128 v[8:11], v98
	v_mov_b32_e32 v3, 0
	v_lshl_add_u64 v[12:13], v[12:13], 1, s[14:15]
	s_waitcnt vmcnt(13) lgkmcnt(0)
	v_mov_b32_e32 v4, v156
	v_mov_b32_e32 v5, v157
	v_mov_b32_e32 v6, v158
	v_mov_b32_e32 v7, v159
	v_pk_add_f32 v[4:5], v[8:9], v[4:5]
	v_pk_add_f32 v[6:7], v[10:11], v[6:7]
	global_store_dwordx4 v[14:15], v[4:7], off
	v_cvt_pk_bf16_f32 v8, v4, v5
	v_cvt_pk_bf16_f32 v9, v6, v7
	v_pk_mul_f32 v[4:5], v[4:5], v[4:5]
	v_pk_mul_f32 v[6:7], v[6:7], v[6:7]
	v_add_f32_e32 v1, v4, v5
	v_add_f32_e32 v1, v6, v1
	v_add_f32_e32 v1, v7, v1
	global_store_dwordx2 v[12:13], v[8:9], off
	s_nop 0
	v_add_f32_dpp v1, v1, v1 quad_perm:[1,0,3,2] row_mask:0xf bank_mask:0xf bound_ctrl:1
	s_nop 1
	v_add_f32_dpp v1, v1, v1 quad_perm:[2,3,0,1] row_mask:0xf bank_mask:0xf bound_ctrl:1
	s_nop 1
	v_add_f32_dpp v1, v1, v1 row_half_mirror row_mask:0xf bank_mask:0xf bound_ctrl:1
	s_nop 1
	v_mov_b32_dpp v3, v1 row_mirror row_mask:0xf bank_mask:0xf
	s_and_saveexec_b64 s[0:1], vcc
	s_cbranch_execz .LBB0_1465
	v_add_f32_e32 v3, v1, v3
	v_ashrrev_i32_e32 v1, 31, v0
	v_lshl_add_u64 v[0:1], v[0:1], 2, s[18:19]
	global_atomic_add_f32 v[0:1], v3, off
.LBB0_1465:
	s_or_b64 exec, exec, s[0:1]
	v_add_u32_e32 v0, v105, v2
	v_lshl_add_u32 v12, v0, 10, v128
	v_ashrrev_i32_e32 v13, 31, v12
	v_lshl_add_u64 v[14:15], v[12:13], 2, s[12:13]
	ds_read_b128 v[8:11], v98 offset:1088
	v_mov_b32_e32 v3, 0
	v_lshl_add_u64 v[12:13], v[12:13], 1, s[14:15]
	s_waitcnt vmcnt(15) lgkmcnt(0)
	v_mov_b32_e32 v4, v160
	v_mov_b32_e32 v5, v161
	v_mov_b32_e32 v6, v162
	v_mov_b32_e32 v7, v163
	v_pk_add_f32 v[4:5], v[8:9], v[4:5]
	v_pk_add_f32 v[6:7], v[10:11], v[6:7]
	global_store_dwordx4 v[14:15], v[4:7], off
	v_cvt_pk_bf16_f32 v8, v4, v5
	v_cvt_pk_bf16_f32 v9, v6, v7
	v_pk_mul_f32 v[4:5], v[4:5], v[4:5]
	v_pk_mul_f32 v[6:7], v[6:7], v[6:7]
	v_add_f32_e32 v1, v4, v5
	v_add_f32_e32 v1, v6, v1
	v_add_f32_e32 v1, v7, v1
	global_store_dwordx2 v[12:13], v[8:9], off
	s_nop 0
	v_add_f32_dpp v1, v1, v1 quad_perm:[1,0,3,2] row_mask:0xf bank_mask:0xf bound_ctrl:1
	s_nop 1
	v_add_f32_dpp v1, v1, v1 quad_perm:[2,3,0,1] row_mask:0xf bank_mask:0xf bound_ctrl:1
	s_nop 1
	v_add_f32_dpp v1, v1, v1 row_half_mirror row_mask:0xf bank_mask:0xf bound_ctrl:1
	s_nop 1
	v_mov_b32_dpp v3, v1 row_mirror row_mask:0xf bank_mask:0xf
	s_and_saveexec_b64 s[0:1], vcc
	s_cbranch_execz .LBB0_1467
	v_add_f32_e32 v3, v1, v3
	v_ashrrev_i32_e32 v1, 31, v0
	v_lshl_add_u64 v[0:1], v[0:1], 2, s[18:19]
	global_atomic_add_f32 v[0:1], v3, off
;   __device__ __forceinline__ void tile(const float* reg, int row0, int col0, int lane) const {
;     rows4(reg, lane, [&](int it, int rr, int c4, float4 v) {
;       int row = row0 + rr, idx = row * 1024 + col0 + c4;
;       float4 xo = *(const float4*)(xold + idx);
;       v.x = fmaf(coef, v.x, xo.x); v.y = fmaf(coef, v.y, xo.y); v.z = fmaf(coef, v.z, xo.z); v.w = fmaf(coef, v.w, xo.w);
;       *(float4*)(xnew + idx) = v;
;       *(bf16x4*)(xb + idx) = pack4(v.x, v.y, v.z, v.w);
;       float s = row16_sum(v.x * v.x + v.y * v.y + v.z * v.z + v.w * v.w);
;       if ((lane & 15) == 0) atomicAdd(ssqn + row, s);
;     });
.LBB0_1467:
	s_or_b64 exec, exec, s[0:1]
	v_add_u32_e32 v0, v106, v2
	v_lshl_add_u32 v12, v0, 10, v128
	v_ashrrev_i32_e32 v13, 31, v12
	v_lshl_add_u64 v[14:15], v[12:13], 2, s[12:13]
	ds_read_b128 v[8:11], v98 offset:2176
	v_mov_b32_e32 v3, 0
	v_lshl_add_u64 v[12:13], v[12:13], 1, s[14:15]
	s_waitcnt vmcnt(17) lgkmcnt(0)
	v_mov_b32_e32 v4, v164
	v_mov_b32_e32 v5, v165
	v_mov_b32_e32 v6, v166
	v_mov_b32_e32 v7, v167
	v_pk_add_f32 v[4:5], v[8:9], v[4:5]
	v_pk_add_f32 v[6:7], v[10:11], v[6:7]
	global_store_dwordx4 v[14:15], v[4:7], off
	v_cvt_pk_bf16_f32 v8, v4, v5
	v_cvt_pk_bf16_f32 v9, v6, v7
	v_pk_mul_f32 v[4:5], v[4:5], v[4:5]
	v_pk_mul_f32 v[6:7], v[6:7], v[6:7]
	v_add_f32_e32 v1, v4, v5
	v_add_f32_e32 v1, v6, v1
	v_add_f32_e32 v1, v7, v1
	global_store_dwordx2 v[12:13], v[8:9], off
	s_nop 0
	v_add_f32_dpp v1, v1, v1 quad_perm:[1,0,3,2] row_mask:0xf bank_mask:0xf bound_ctrl:1
	s_nop 1
	v_add_f32_dpp v1, v1, v1 quad_perm:[2,3,0,1] row_mask:0xf bank_mask:0xf bound_ctrl:1
	s_nop 1
	v_add_f32_dpp v1, v1, v1 row_half_mirror row_mask:0xf bank_mask:0xf bound_ctrl:1
	s_nop 1
	v_mov_b32_dpp v3, v1 row_mirror row_mask:0xf bank_mask:0xf
	s_and_saveexec_b64 s[0:1], vcc
	s_cbranch_execz .LBB0_1469
	v_add_f32_e32 v3, v1, v3
	v_ashrrev_i32_e32 v1, 31, v0
	v_lshl_add_u64 v[0:1], v[0:1], 2, s[18:19]
	global_atomic_add_f32 v[0:1], v3, off
.LBB0_1469:
	s_or_b64 exec, exec, s[0:1]
	v_add_u32_e32 v0, v107, v2
	v_lshl_add_u32 v12, v0, 10, v128
	v_ashrrev_i32_e32 v13, 31, v12
	v_lshl_add_u64 v[14:15], v[12:13], 2, s[12:13]
	ds_read_b128 v[8:11], v98 offset:3264
	v_mov_b32_e32 v3, 0
	v_lshl_add_u64 v[12:13], v[12:13], 1, s[14:15]
	s_waitcnt vmcnt(19) lgkmcnt(0)
	v_mov_b32_e32 v4, v168
	v_mov_b32_e32 v5, v169
	v_mov_b32_e32 v6, v170
	v_mov_b32_e32 v7, v171
	v_pk_add_f32 v[4:5], v[8:9], v[4:5]
	v_pk_add_f32 v[6:7], v[10:11], v[6:7]
	global_store_dwordx4 v[14:15], v[4:7], off
	v_cvt_pk_bf16_f32 v8, v4, v5
	v_cvt_pk_bf16_f32 v9, v6, v7
	v_pk_mul_f32 v[4:5], v[4:5], v[4:5]
	v_pk_mul_f32 v[6:7], v[6:7], v[6:7]
	v_add_f32_e32 v1, v4, v5
	v_add_f32_e32 v1, v6, v1
	v_add_f32_e32 v1, v7, v1
	global_store_dwordx2 v[12:13], v[8:9], off
	s_nop 0
	v_add_f32_dpp v1, v1, v1 quad_perm:[1,0,3,2] row_mask:0xf bank_mask:0xf bound_ctrl:1
	s_nop 1
	v_add_f32_dpp v1, v1, v1 quad_perm:[2,3,0,1] row_mask:0xf bank_mask:0xf bound_ctrl:1
	s_nop 1
	v_add_f32_dpp v1, v1, v1 row_half_mirror row_mask:0xf bank_mask:0xf bound_ctrl:1
	s_nop 1
	v_mov_b32_dpp v3, v1 row_mirror row_mask:0xf bank_mask:0xf
	s_and_saveexec_b64 s[0:1], vcc
	s_cbranch_execz .LBB0_1471
	v_add_f32_e32 v3, v1, v3
	v_ashrrev_i32_e32 v1, 31, v0
	v_lshl_add_u64 v[0:1], v[0:1], 2, s[18:19]
	global_atomic_add_f32 v[0:1], v3, off
.LBB0_1471:
	s_or_b64 exec, exec, s[0:1]
	v_add_u32_e32 v0, v108, v2
	v_lshl_add_u32 v10, v0, 10, v128
	v_ashrrev_i32_e32 v11, 31, v10
	v_lshl_add_u64 v[12:13], v[10:11], 2, s[12:13]
	ds_read_b128 v[6:9], v98 offset:4352
	v_lshl_add_u64 v[10:11], v[10:11], 1, s[14:15]
	s_waitcnt vmcnt(21) lgkmcnt(0)
	v_mov_b32_e32 v2, v172
	v_mov_b32_e32 v3, v173
	v_mov_b32_e32 v4, v174
	v_mov_b32_e32 v5, v175
	v_pk_add_f32 v[2:3], v[6:7], v[2:3]
	v_pk_add_f32 v[4:5], v[8:9], v[4:5]
	global_store_dwordx4 v[12:13], v[2:5], off
	v_cvt_pk_bf16_f32 v6, v2, v3
	v_cvt_pk_bf16_f32 v7, v4, v5
	v_pk_mul_f32 v[2:3], v[2:3], v[2:3]
	v_pk_mul_f32 v[4:5], v[4:5], v[4:5]
	v_add_f32_e32 v1, v2, v3
	v_add_f32_e32 v1, v4, v1
	v_add_f32_e32 v1, v5, v1
	v_mov_b32_e32 v2, 0
	global_store_dwordx2 v[10:11], v[6:7], off
	v_add_f32_dpp v1, v1, v1 quad_perm:[1,0,3,2] row_mask:0xf bank_mask:0xf bound_ctrl:1
	s_nop 1
	v_add_f32_dpp v1, v1, v1 quad_perm:[2,3,0,1] row_mask:0xf bank_mask:0xf bound_ctrl:1
	s_nop 1
	v_add_f32_dpp v1, v1, v1 row_half_mirror row_mask:0xf bank_mask:0xf bound_ctrl:1
	s_nop 1
	v_mov_b32_dpp v2, v1 row_mirror row_mask:0xf bank_mask:0xf
	s_and_saveexec_b64 s[0:1], vcc
	s_cbranch_execz .LBB0_1404
	v_add_f32_e32 v2, v1, v2
	v_ashrrev_i32_e32 v1, 31, v0
	v_lshl_add_u64 v[0:1], v[0:1], 2, s[18:19]
	global_atomic_add_f32 v[0:1], v2, off
	s_branch .LBB0_1404

;   __device__ __forceinline__ void tile(const float* reg, int row0, int col0, int lane) const {
;     rows4(reg, lane, [&](int it, int rr, int c4, float4 v) {
;       int row = row0 + rr, idx = row * 1024 + col0 + c4;
;       float4 xo = *(const float4*)(xold + idx);
;       v.x = fmaf(coef, v.x, xo.x); v.y = fmaf(coef, v.y, xo.y); v.z = fmaf(coef, v.z, xo.z); v.w = fmaf(coef, v.w, xo.w);
;       *(float4*)(xnew + idx) = v;
;       *(bf16x4*)(xb + idx) = pack4(v.x, v.y, v.z, v.w);
;       float s = row16_sum(v.x * v.x + v.y * v.y + v.z * v.z + v.w * v.w);
;       if ((lane & 15) == 0) atomicAdd(ssqn + row, s);
;     });
; template <int MF, class Epi>
; __device__ __forceinline__ void staged_epilogue(f32x4 (&acc)[MF][4], int row0, int col0, const Epi& epi) {
;     ...
; #pragma unroll
;   for (int mp = 0; mp < MF / 2; ++mp) {
;     __builtin_amdgcn_sched_barrier(0);
; #pragma unroll
;     for (int mm = 0; mm < 2; ++mm)
; #pragma unroll
;       for (int n = 0; n < 4; ++n)
; #pragma unroll
;         for (int j = 0; j < 4; ++j) reg[(mm * 16 + fq * 4 + j) * 68 + n * 16 + fr] = acc[mp * 2 + mm][n][j];
;     __builtin_amdgcn_fence(__ATOMIC_ACQ_REL, "wavefront");
;     epi.tile(reg, row0 + mp * 32, col0, lane);
.LBB0_1529:
	v_mov_b32_e32 v131, v204
	v_mov_b32_e32 v130, v204
	s_nop 0
	v_lshrrev_b32_e32 v130, 6, v130
	v_mul_lo_u32 v130, v130, s53
	v_add_u32_e32 v136, 0x10000, v130
	v_lshrrev_b32_e32 v130, 2, v131
	v_and_b32_e32 v137, 15, v131
	v_and_b32_e32 v138, 12, v130
	v_bfe_u32 v130, v131, 4, 2
	v_lshlrev_b32_e32 v131, 2, v131
	v_and_b32_e32 v131, 60, v131
	v_lshl_or_b32 v139, v137, 2, v136
	v_lshl_or_b32 v136, v131, 2, v136
	v_add_u32_e32 v128, v131, v128
	v_cmp_eq_u32_e32 vcc, 0, v137
	v_mad_u32_u24 v140, v130, s60, v136
	v_mad_u32_u24 v131, v138, s60, v139
	ds_write2_b32 v131, v120, v124 offset1:16
	ds_write2_b32 v131, v121, v125 offset0:68 offset1:84
	ds_write2_b32 v131, v122, v126 offset0:136 offset1:152
	ds_write2_b32 v131, v123, v127 offset0:204 offset1:220
	ds_write2_b32 v131, v112, v116 offset0:32 offset1:48
	ds_write2_b32 v131, v113, v117 offset0:100 offset1:116
	ds_write2_b32 v131, v114, v118 offset0:168 offset1:184
	ds_write2_b32 v131, v115, v119 offset0:236 offset1:252
	v_add_u32_e32 v112, 0x1000, v131
	ds_write2_b32 v112, v104, v108 offset0:64 offset1:80
	ds_write2_b32 v112, v105, v109 offset0:132 offset1:148
	ds_write2_b32 v112, v106, v110 offset0:200 offset1:216
	v_add_u32_e32 v104, 0x1400, v131
	ds_write2_b32 v104, v107, v111 offset0:12 offset1:28
	ds_write2_b32 v112, v96, v100 offset0:96 offset1:112
	ds_write2_b32 v112, v97, v101 offset0:164 offset1:180
	ds_write2_b32 v112, v98, v102 offset0:232 offset1:248
	ds_write2_b32 v104, v99, v103 offset0:44 offset1:60
	v_add_u32_e32 v184, v130, v129
	v_lshl_add_u32 v176, v184, 10, v128
	v_ashrrev_i32_e32 v177, 31, v176
	v_lshl_add_u64 v[178:179], v[176:177], 2, s[12:13]
	global_load_dwordx4 v[144:147], v[178:179], off
	v_or_b32_e32 v185, 4, v130
	v_add_u32_e32 v184, v185, v129
	v_lshl_add_u32 v176, v184, 10, v128
	v_ashrrev_i32_e32 v177, 31, v176
	v_lshl_add_u64 v[178:179], v[176:177], 2, s[12:13]
	global_load_dwordx4 v[148:151], v[178:179], off
	v_or_b32_e32 v185, 8, v130
	v_add_u32_e32 v184, v185, v129
	v_lshl_add_u32 v176, v184, 10, v128
	v_ashrrev_i32_e32 v177, 31, v176
	v_lshl_add_u64 v[178:179], v[176:177], 2, s[12:13]
	global_load_dwordx4 v[152:155], v[178:179], off
	v_or_b32_e32 v185, 12, v130
	v_add_u32_e32 v184, v185, v129
	v_lshl_add_u32 v176, v184, 10, v128
	v_ashrrev_i32_e32 v177, 31, v176
	v_lshl_add_u64 v[178:179], v[176:177], 2, s[12:13]
	global_load_dwordx4 v[156:159], v[178:179], off
	v_or_b32_e32 v185, 16, v130
	v_add_u32_e32 v184, v185, v129
	v_lshl_add_u32 v176, v184, 10, v128
	v_ashrrev_i32_e32 v177, 31, v176
	v_lshl_add_u64 v[178:179], v[176:177], 2, s[12:13]
	global_load_dwordx4 v[160:163], v[178:179], off
	v_or_b32_e32 v185, 20, v130
	v_add_u32_e32 v184, v185, v129
	v_lshl_add_u32 v176, v184, 10, v128
	v_ashrrev_i32_e32 v177, 31, v176
	v_lshl_add_u64 v[178:179], v[176:177], 2, s[12:13]
	global_load_dwordx4 v[164:167], v[178:179], off
	v_or_b32_e32 v185, 24, v130
	v_add_u32_e32 v184, v185, v129
	v_lshl_add_u32 v176, v184, 10, v128
	v_ashrrev_i32_e32 v177, 31, v176
	v_lshl_add_u64 v[178:179], v[176:177], 2, s[12:13]
	global_load_dwordx4 v[168:171], v[178:179], off
	v_or_b32_e32 v185, 28, v130
	v_add_u32_e32 v184, v185, v129
	v_lshl_add_u32 v176, v184, 10, v128
	v_ashrrev_i32_e32 v177, 31, v176
	v_lshl_add_u64 v[178:179], v[176:177], 2, s[12:13]
	global_load_dwordx4 v[172:175], v[178:179], off
	v_add_u32_e32 v96, v130, v129
	v_lshl_add_u32 v102, v96, 10, v128
	v_ashrrev_i32_e32 v103, 31, v102
	v_lshl_add_u64 v[110:111], v[102:103], 2, s[12:13]
	s_waitcnt vmcnt(7)
	v_mov_b32_e32 v98, v144
	v_mov_b32_e32 v99, v145
	v_mov_b32_e32 v100, v146
	v_mov_b32_e32 v101, v147
	ds_read_b128 v[106:109], v140
	v_lshl_add_u64 v[102:103], v[102:103], 1, s[14:15]
	s_waitcnt lgkmcnt(0)
	v_pk_fma_f32 v[98:99], v[106:107], 0.5, v[98:99] op_sel_hi:[1,0,1]
	v_pk_fma_f32 v[100:101], v[108:109], 0.5, v[100:101] op_sel_hi:[1,0,1]
	global_store_dwordx4 v[110:111], v[98:101], off
	v_cvt_pk_bf16_f32 v106, v98, v99
	v_cvt_pk_bf16_f32 v107, v100, v101
	v_pk_mul_f32 v[98:99], v[98:99], v[98:99]
	v_pk_mul_f32 v[100:101], v[100:101], v[100:101]
	v_add_f32_e32 v97, v98, v99
	v_add_f32_e32 v97, v100, v97
	v_add_f32_e32 v97, v101, v97
	v_mov_b32_e32 v98, 0
	global_store_dwordx2 v[102:103], v[106:107], off
	v_add_f32_dpp v97, v97, v97 quad_perm:[1,0,3,2] row_mask:0xf bank_mask:0xf bound_ctrl:1
	s_nop 1
	v_add_f32_dpp v97, v97, v97 quad_perm:[2,3,0,1] row_mask:0xf bank_mask:0xf bound_ctrl:1
	s_nop 1
	v_add_f32_dpp v97, v97, v97 row_half_mirror row_mask:0xf bank_mask:0xf bound_ctrl:1
	s_nop 1
	v_mov_b32_dpp v98, v97 row_mirror row_mask:0xf bank_mask:0xf
	s_and_saveexec_b64 s[0:1], vcc
	s_cbranch_execz .LBB0_1531
	v_add_f32_e32 v98, v97, v98
	v_ashrrev_i32_e32 v97, 31, v96
	v_lshl_add_u64 v[96:97], v[96:97], 2, s[10:11]
	global_atomic_add_f32 v[96:97], v98, off
.LBB0_1531:
	s_or_b64 exec, exec, s[0:1]
	v_or_b32_e32 v99, 4, v130
	v_add_u32_e32 v96, v99, v129
	v_lshl_add_u32 v102, v96, 10, v128
	v_ashrrev_i32_e32 v103, 31, v102
	v_lshl_add_u64 v[106:107], v[102:103], 2, s[12:13]
	v_mul_u32_u24_e32 v109, 0x110, v130
	v_add_u32_e32 v98, 0x440, v109
	v_add_u32_e32 v100, v136, v98
	ds_read_b128 v[118:121], v100
	v_mov_b32_e32 v101, 0
	v_lshl_add_u64 v[102:103], v[102:103], 1, s[14:15]
	s_waitcnt vmcnt(9) lgkmcnt(0)
	v_mov_b32_e32 v114, v148
	v_mov_b32_e32 v115, v149
	v_mov_b32_e32 v116, v150
	v_mov_b32_e32 v117, v151
	v_pk_fma_f32 v[114:115], v[118:119], 0.5, v[114:115] op_sel_hi:[1,0,1]
	v_pk_fma_f32 v[116:117], v[120:121], 0.5, v[116:117] op_sel_hi:[1,0,1]
	v_pk_mul_f32 v[110:111], v[114:115], v[114:115]
	global_store_dwordx4 v[106:107], v[114:117], off
	v_cvt_pk_bf16_f32 v106, v114, v115
	v_add_f32_e32 v97, v110, v111
	v_pk_mul_f32 v[114:115], v[116:117], v[116:117]
	v_cvt_pk_bf16_f32 v107, v116, v117
	v_add_f32_e32 v97, v114, v97
	v_add_f32_e32 v97, v115, v97
	global_store_dwordx2 v[102:103], v[106:107], off
	s_nop 0
	v_add_f32_dpp v97, v97, v97 quad_perm:[1,0,3,2] row_mask:0xf bank_mask:0xf bound_ctrl:1
	s_nop 1
	v_add_f32_dpp v97, v97, v97 quad_perm:[2,3,0,1] row_mask:0xf bank_mask:0xf bound_ctrl:1
	s_nop 1
	v_add_f32_dpp v97, v97, v97 row_half_mirror row_mask:0xf bank_mask:0xf bound_ctrl:1
	s_nop 1
	v_mov_b32_dpp v101, v97 row_mirror row_mask:0xf bank_mask:0xf
	s_and_saveexec_b64 s[0:1], vcc
	s_cbranch_execz .LBB0_1533
	v_add_f32_e32 v101, v97, v101
	v_ashrrev_i32_e32 v97, 31, v96
	v_lshl_add_u64 v[96:97], v[96:97], 2, s[10:11]
	global_atomic_add_f32 v[96:97], v101, off
;   __device__ __forceinline__ void tile(const float* reg, int row0, int col0, int lane) const {
;     rows4(reg, lane, [&](int it, int rr, int c4, float4 v) {
;       int row = row0 + rr, idx = row * 1024 + col0 + c4;
;       float4 xo = *(const float4*)(xold + idx);
;       v.x = fmaf(coef, v.x, xo.x); v.y = fmaf(coef, v.y, xo.y); v.z = fmaf(coef, v.z, xo.z); v.w = fmaf(coef, v.w, xo.w);
;       *(float4*)(xnew + idx) = v;
;       *(bf16x4*)(xb + idx) = pack4(v.x, v.y, v.z, v.w);
;       float s = row16_sum(v.x * v.x + v.y * v.y + v.z * v.z + v.w * v.w);
;       if ((lane & 15) == 0) atomicAdd(ssqn + row, s);
;     });
.LBB0_1533:
	s_or_b64 exec, exec, s[0:1]
	v_or_b32_e32 v101, 8, v130
	v_add_u32_e32 v96, v101, v129
	v_lshl_add_u32 v106, v96, 10, v128
	v_ashrrev_i32_e32 v107, 31, v106
	v_lshl_add_u64 v[110:111], v[106:107], 2, s[12:13]
	v_add_u32_e32 v98, 0x440, v98
	v_add_u32_e32 v102, v136, v98
	ds_read_b128 v[118:121], v102
	v_mov_b32_e32 v103, 0
	v_lshl_add_u64 v[106:107], v[106:107], 1, s[14:15]
	s_waitcnt vmcnt(11) lgkmcnt(0)
	v_mov_b32_e32 v114, v152
	v_mov_b32_e32 v115, v153
	v_mov_b32_e32 v116, v154
	v_mov_b32_e32 v117, v155
	v_pk_fma_f32 v[114:115], v[118:119], 0.5, v[114:115] op_sel_hi:[1,0,1]
	v_pk_fma_f32 v[116:117], v[120:121], 0.5, v[116:117] op_sel_hi:[1,0,1]
	global_store_dwordx4 v[110:111], v[114:117], off
	v_cvt_pk_bf16_f32 v110, v114, v115
	v_cvt_pk_bf16_f32 v111, v116, v117
	v_pk_mul_f32 v[114:115], v[114:115], v[114:115]
	v_pk_mul_f32 v[116:117], v[116:117], v[116:117]
	v_add_f32_e32 v97, v114, v115
	v_add_f32_e32 v97, v116, v97
	v_add_f32_e32 v97, v117, v97
	global_store_dwordx2 v[106:107], v[110:111], off
	s_nop 0
	v_add_f32_dpp v97, v97, v97 quad_perm:[1,0,3,2] row_mask:0xf bank_mask:0xf bound_ctrl:1
	s_nop 1
	v_add_f32_dpp v97, v97, v97 quad_perm:[2,3,0,1] row_mask:0xf bank_mask:0xf bound_ctrl:1
	s_nop 1
	v_add_f32_dpp v97, v97, v97 row_half_mirror row_mask:0xf bank_mask:0xf bound_ctrl:1
	s_nop 1
	v_mov_b32_dpp v103, v97 row_mirror row_mask:0xf bank_mask:0xf
	s_and_saveexec_b64 s[0:1], vcc
	s_cbranch_execz .LBB0_1535
	v_add_f32_e32 v103, v97, v103
	v_ashrrev_i32_e32 v97, 31, v96
	v_lshl_add_u64 v[96:97], v[96:97], 2, s[10:11]
	global_atomic_add_f32 v[96:97], v103, off
.LBB0_1535:
	s_or_b64 exec, exec, s[0:1]
	v_or_b32_e32 v103, 12, v130
	v_add_u32_e32 v96, v103, v129
	v_lshl_add_u32 v106, v96, 10, v128
	v_ashrrev_i32_e32 v107, 31, v106
	v_lshl_add_u64 v[110:111], v[106:107], 2, s[12:13]
	v_add_u32_e32 v97, 0x440, v98
	v_add_u32_e32 v98, v136, v97
	ds_read_b128 v[118:121], v98
	v_mov_b32_e32 v105, 0
	v_lshl_add_u64 v[106:107], v[106:107], 1, s[14:15]
	s_waitcnt vmcnt(13) lgkmcnt(0)
	v_mov_b32_e32 v114, v156
	v_mov_b32_e32 v115, v157
	v_mov_b32_e32 v116, v158
	v_mov_b32_e32 v117, v159
	v_pk_fma_f32 v[114:115], v[118:119], 0.5, v[114:115] op_sel_hi:[1,0,1]
	v_pk_fma_f32 v[116:117], v[120:121], 0.5, v[116:117] op_sel_hi:[1,0,1]
	global_store_dwordx4 v[110:111], v[114:117], off
	v_cvt_pk_bf16_f32 v110, v114, v115
	v_cvt_pk_bf16_f32 v111, v116, v117
	v_pk_mul_f32 v[114:115], v[114:115], v[114:115]
	v_pk_mul_f32 v[116:117], v[116:117], v[116:117]
	v_add_f32_e32 v97, v114, v115
	v_add_f32_e32 v97, v116, v97
	v_add_f32_e32 v97, v117, v97
	global_store_dwordx2 v[106:107], v[110:111], off
	s_nop 0
	v_add_f32_dpp v97, v97, v97 quad_perm:[1,0,3,2] row_mask:0xf bank_mask:0xf bound_ctrl:1
	s_nop 1
	v_add_f32_dpp v97, v97, v97 quad_perm:[2,3,0,1] row_mask:0xf bank_mask:0xf bound_ctrl:1
	s_nop 1
	v_add_f32_dpp v97, v97, v97 row_half_mirror row_mask:0xf bank_mask:0xf bound_ctrl:1
	s_nop 1
	v_mov_b32_dpp v105, v97 row_mirror row_mask:0xf bank_mask:0xf
	s_and_saveexec_b64 s[0:1], vcc
	s_cbranch_execz .LBB0_1537
	v_add_f32_e32 v105, v97, v105
	v_ashrrev_i32_e32 v97, 31, v96
	v_lshl_add_u64 v[96:97], v[96:97], 2, s[10:11]
	global_atomic_add_f32 v[96:97], v105, off
.LBB0_1537:
	s_or_b64 exec, exec, s[0:1]
	v_or_b32_e32 v105, 16, v130
	v_add_u32_e32 v96, v105, v129
	v_lshl_add_u32 v106, v96, 10, v128
	v_ashrrev_i32_e32 v107, 31, v106
	v_lshl_add_u64 v[110:111], v[106:107], 2, s[12:13]
	ds_read_b128 v[118:121], v98 offset:1088
	v_lshl_add_u64 v[106:107], v[106:107], 1, s[14:15]
	s_waitcnt vmcnt(15) lgkmcnt(0)
	v_mov_b32_e32 v114, v160
	v_mov_b32_e32 v115, v161
	v_mov_b32_e32 v116, v162
	v_mov_b32_e32 v117, v163
	v_pk_fma_f32 v[114:115], v[118:119], 0.5, v[114:115] op_sel_hi:[1,0,1]
	v_pk_fma_f32 v[116:117], v[120:121], 0.5, v[116:117] op_sel_hi:[1,0,1]
	global_store_dwordx4 v[110:111], v[114:117], off
	v_cvt_pk_bf16_f32 v110, v114, v115
	v_cvt_pk_bf16_f32 v111, v116, v117
	v_pk_mul_f32 v[114:115], v[114:115], v[114:115]
	v_pk_mul_f32 v[116:117], v[116:117], v[116:117]
	v_add_f32_e32 v97, v114, v115
	v_add_f32_e32 v97, v116, v97
	v_add_f32_e32 v97, v117, v97
	global_store_dwordx2 v[106:107], v[110:111], off
	v_mov_b32_e32 v106, 0
	v_add_f32_dpp v97, v97, v97 quad_perm:[1,0,3,2] row_mask:0xf bank_mask:0xf bound_ctrl:1
	s_nop 1
	v_add_f32_dpp v97, v97, v97 quad_perm:[2,3,0,1] row_mask:0xf bank_mask:0xf bound_ctrl:1
	s_nop 1
	v_add_f32_dpp v97, v97, v97 row_half_mirror row_mask:0xf bank_mask:0xf bound_ctrl:1
	s_nop 1
	v_mov_b32_dpp v106, v97 row_mirror row_mask:0xf bank_mask:0xf
	s_and_saveexec_b64 s[0:1], vcc
	s_cbranch_execz .LBB0_1539
	v_add_f32_e32 v106, v97, v106
	v_ashrrev_i32_e32 v97, 31, v96
	v_lshl_add_u64 v[96:97], v[96:97], 2, s[10:11]
	global_atomic_add_f32 v[96:97], v106, off
.LBB0_1539:
	s_or_b64 exec, exec, s[0:1]
	v_or_b32_e32 v106, 20, v130
	v_add_u32_e32 v96, v106, v129
	v_lshl_add_u32 v110, v96, 10, v128
	v_ashrrev_i32_e32 v111, 31, v110
	v_lshl_add_u64 v[122:123], v[110:111], 2, s[12:13]
	ds_read_b128 v[118:121], v98 offset:2176
	v_mov_b32_e32 v107, 0
	v_lshl_add_u64 v[110:111], v[110:111], 1, s[14:15]
	s_waitcnt vmcnt(17) lgkmcnt(0)
	v_mov_b32_e32 v114, v164
	v_mov_b32_e32 v115, v165
	v_mov_b32_e32 v116, v166
	v_mov_b32_e32 v117, v167
	v_pk_fma_f32 v[114:115], v[118:119], 0.5, v[114:115] op_sel_hi:[1,0,1]
	v_pk_fma_f32 v[116:117], v[120:121], 0.5, v[116:117] op_sel_hi:[1,0,1]
	global_store_dwordx4 v[122:123], v[114:117], off
	v_cvt_pk_bf16_f32 v118, v114, v115
	v_cvt_pk_bf16_f32 v119, v116, v117
	v_pk_mul_f32 v[114:115], v[114:115], v[114:115]
	v_pk_mul_f32 v[116:117], v[116:117], v[116:117]
	v_add_f32_e32 v97, v114, v115
	v_add_f32_e32 v97, v116, v97
	v_add_f32_e32 v97, v117, v97
	global_store_dwordx2 v[110:111], v[118:119], off
	s_nop 0
	v_add_f32_dpp v97, v97, v97 quad_perm:[1,0,3,2] row_mask:0xf bank_mask:0xf bound_ctrl:1
	s_nop 1
	v_add_f32_dpp v97, v97, v97 quad_perm:[2,3,0,1] row_mask:0xf bank_mask:0xf bound_ctrl:1
	s_nop 1
	v_add_f32_dpp v97, v97, v97 row_half_mirror row_mask:0xf bank_mask:0xf bound_ctrl:1
	s_nop 1
	v_mov_b32_dpp v107, v97 row_mirror row_mask:0xf bank_mask:0xf
	s_and_saveexec_b64 s[0:1], vcc
	s_cbranch_execz .LBB0_1541
	v_add_f32_e32 v107, v97, v107
	v_ashrrev_i32_e32 v97, 31, v96
	v_lshl_add_u64 v[96:97], v[96:97], 2, s[10:11]
	global_atomic_add_f32 v[96:97], v107, off
;   __device__ __forceinline__ void tile(const float* reg, int row0, int col0, int lane) const {
;     rows4(reg, lane, [&](int it, int rr, int c4, float4 v) {
;       int row = row0 + rr, idx = row * 1024 + col0 + c4;
;       float4 xo = *(const float4*)(xold + idx);
;       v.x = fmaf(coef, v.x, xo.x); v.y = fmaf(coef, v.y, xo.y); v.z = fmaf(coef, v.z, xo.z); v.w = fmaf(coef, v.w, xo.w);
;       *(float4*)(xnew + idx) = v;
;       *(bf16x4*)(xb + idx) = pack4(v.x, v.y, v.z, v.w);
;       float s = row16_sum(v.x * v.x + v.y * v.y + v.z * v.z + v.w * v.w);
;       if ((lane & 15) == 0) atomicAdd(ssqn + row, s);
;     });
; template <int MF, class Epi>
; __device__ __forceinline__ void staged_epilogue(f32x4 (&acc)[MF][4], int row0, int col0, const Epi& epi) {
;     ...
; #pragma unroll
;   for (int mp = 0; mp < MF / 2; ++mp) {
;     __builtin_amdgcn_sched_barrier(0);
; #pragma unroll
;     for (int mm = 0; mm < 2; ++mm)
; #pragma unroll
;       for (int n = 0; n < 4; ++n)
; #pragma unroll
;         for (int j = 0; j < 4; ++j) reg[(mm * 16 + fq * 4 + j) * 68 + n * 16 + fr] = acc[mp * 2 + mm][n][j];
;     __builtin_amdgcn_fence(__ATOMIC_ACQ_REL, "wavefront");
;     epi.tile(reg, row0 + mp * 32, col0, lane);
.LBB0_1541:
	s_or_b64 exec, exec, s[0:1]
	v_or_b32_e32 v107, 24, v130
	v_add_u32_e32 v96, v107, v129
	v_lshl_add_u32 v110, v96, 10, v128
	v_ashrrev_i32_e32 v111, 31, v110
	v_lshl_add_u64 v[122:123], v[110:111], 2, s[12:13]
	ds_read_b128 v[118:121], v98 offset:3264
	v_mov_b32_e32 v108, 0
	v_lshl_add_u64 v[110:111], v[110:111], 1, s[14:15]
	s_waitcnt vmcnt(19) lgkmcnt(0)
	v_mov_b32_e32 v114, v168
	v_mov_b32_e32 v115, v169
	v_mov_b32_e32 v116, v170
	v_mov_b32_e32 v117, v171
	v_pk_fma_f32 v[114:115], v[118:119], 0.5, v[114:115] op_sel_hi:[1,0,1]
	v_pk_fma_f32 v[116:117], v[120:121], 0.5, v[116:117] op_sel_hi:[1,0,1]
	global_store_dwordx4 v[122:123], v[114:117], off
	v_cvt_pk_bf16_f32 v118, v114, v115
	v_cvt_pk_bf16_f32 v119, v116, v117
	v_pk_mul_f32 v[114:115], v[114:115], v[114:115]
	v_pk_mul_f32 v[116:117], v[116:117], v[116:117]
	v_add_f32_e32 v97, v114, v115
	v_add_f32_e32 v97, v116, v97
	v_add_f32_e32 v97, v117, v97
	global_store_dwordx2 v[110:111], v[118:119], off
	s_nop 0
	v_add_f32_dpp v97, v97, v97 quad_perm:[1,0,3,2] row_mask:0xf bank_mask:0xf bound_ctrl:1
	s_nop 1
	v_add_f32_dpp v97, v97, v97 quad_perm:[2,3,0,1] row_mask:0xf bank_mask:0xf bound_ctrl:1
	s_nop 1
	v_add_f32_dpp v97, v97, v97 row_half_mirror row_mask:0xf bank_mask:0xf bound_ctrl:1
	s_nop 1
	v_mov_b32_dpp v108, v97 row_mirror row_mask:0xf bank_mask:0xf
	s_and_saveexec_b64 s[0:1], vcc
	s_cbranch_execz .LBB0_1543
	v_add_f32_e32 v108, v97, v108
	v_ashrrev_i32_e32 v97, 31, v96
	v_lshl_add_u64 v[96:97], v[96:97], 2, s[10:11]
	global_atomic_add_f32 v[96:97], v108, off
.LBB0_1543:
	s_or_b64 exec, exec, s[0:1]
	v_or_b32_e32 v108, 28, v130
	v_add_u32_e32 v96, v108, v129
	v_lshl_add_u32 v110, v96, 10, v128
	v_ashrrev_i32_e32 v111, 31, v110
	v_lshl_add_u64 v[122:123], v[110:111], 2, s[12:13]
	ds_read_b128 v[118:121], v98 offset:4352
	v_lshl_add_u64 v[110:111], v[110:111], 1, s[14:15]
	s_waitcnt vmcnt(21) lgkmcnt(0)
	v_mov_b32_e32 v114, v172
	v_mov_b32_e32 v115, v173
	v_mov_b32_e32 v116, v174
	v_mov_b32_e32 v117, v175
	v_pk_fma_f32 v[114:115], v[118:119], 0.5, v[114:115] op_sel_hi:[1,0,1]
	v_pk_fma_f32 v[116:117], v[120:121], 0.5, v[116:117] op_sel_hi:[1,0,1]
	global_store_dwordx4 v[122:123], v[114:117], off
	v_cvt_pk_bf16_f32 v118, v114, v115
	v_cvt_pk_bf16_f32 v119, v116, v117
	v_pk_mul_f32 v[114:115], v[114:115], v[114:115]
	v_pk_mul_f32 v[116:117], v[116:117], v[116:117]
	v_add_f32_e32 v97, v114, v115
	v_add_f32_e32 v97, v116, v97
	v_add_f32_e32 v97, v117, v97
	global_store_dwordx2 v[110:111], v[118:119], off
	v_mov_b32_e32 v110, 0
	v_add_f32_dpp v97, v97, v97 quad_perm:[1,0,3,2] row_mask:0xf bank_mask:0xf bound_ctrl:1
	s_nop 1
	v_add_f32_dpp v97, v97, v97 quad_perm:[2,3,0,1] row_mask:0xf bank_mask:0xf bound_ctrl:1
	s_nop 1
	v_add_f32_dpp v97, v97, v97 row_half_mirror row_mask:0xf bank_mask:0xf bound_ctrl:1
	s_nop 1
	v_mov_b32_dpp v110, v97 row_mirror row_mask:0xf bank_mask:0xf
	s_and_saveexec_b64 s[0:1], vcc
	s_cbranch_execz .LBB0_1545
	v_add_f32_e32 v110, v97, v110
	v_ashrrev_i32_e32 v97, 31, v96
	v_lshl_add_u64 v[96:97], v[96:97], 2, s[10:11]
	global_atomic_add_f32 v[96:97], v110, off
.LBB0_1545:
	s_or_b64 exec, exec, s[0:1]
	ds_write2_b32 v131, v88, v92 offset1:16
	ds_write2_b32 v131, v89, v93 offset0:68 offset1:84
	ds_write2_b32 v131, v90, v94 offset0:136 offset1:152
	ds_write2_b32 v131, v91, v95 offset0:204 offset1:220
	ds_write2_b32 v131, v80, v84 offset0:32 offset1:48
	ds_write2_b32 v131, v81, v85 offset0:100 offset1:116
	ds_write2_b32 v131, v82, v86 offset0:168 offset1:184
	ds_write2_b32 v131, v83, v87 offset0:236 offset1:252
	ds_write2_b32 v112, v72, v76 offset0:64 offset1:80
	ds_write2_b32 v112, v73, v77 offset0:132 offset1:148
	ds_write2_b32 v112, v74, v78 offset0:200 offset1:216
	ds_write2_b32 v104, v75, v79 offset0:12 offset1:28
	ds_write2_b32 v112, v64, v68 offset0:96 offset1:112
	ds_write2_b32 v112, v65, v69 offset0:164 offset1:180
	ds_write2_b32 v112, v66, v70 offset0:232 offset1:248
	ds_write2_b32 v104, v67, v71 offset0:44 offset1:60
	v_add_u32_e32 v185, 32, v129
	v_add_u32_e32 v184, v130, v185
	v_lshl_add_u32 v176, v184, 10, v128
	v_ashrrev_i32_e32 v177, 31, v176
	v_lshl_add_u64 v[178:179], v[176:177], 2, s[12:13]
	global_load_dwordx4 v[144:147], v[178:179], off
	v_add_u32_e32 v185, 32, v129
	v_add_u32_e32 v184, v99, v185
	v_lshl_add_u32 v176, v184, 10, v128
	v_ashrrev_i32_e32 v177, 31, v176
	v_lshl_add_u64 v[178:179], v[176:177], 2, s[12:13]
	global_load_dwordx4 v[148:151], v[178:179], off
	v_add_u32_e32 v185, 32, v129
	v_add_u32_e32 v184, v101, v185
	v_lshl_add_u32 v176, v184, 10, v128
	v_ashrrev_i32_e32 v177, 31, v176
	v_lshl_add_u64 v[178:179], v[176:177], 2, s[12:13]
	global_load_dwordx4 v[152:155], v[178:179], off
	v_add_u32_e32 v185, 32, v129
	v_add_u32_e32 v184, v103, v185
	v_lshl_add_u32 v176, v184, 10, v128
	v_ashrrev_i32_e32 v177, 31, v176
	v_lshl_add_u64 v[178:179], v[176:177], 2, s[12:13]
	global_load_dwordx4 v[156:159], v[178:179], off
	v_add_u32_e32 v185, 32, v129
	v_add_u32_e32 v184, v105, v185
	v_lshl_add_u32 v176, v184, 10, v128
	v_ashrrev_i32_e32 v177, 31, v176
	v_lshl_add_u64 v[178:179], v[176:177], 2, s[12:13]
	global_load_dwordx4 v[160:163], v[178:179], off
	v_add_u32_e32 v185, 32, v129
	v_add_u32_e32 v184, v106, v185
	v_lshl_add_u32 v176, v184, 10, v128
	v_ashrrev_i32_e32 v177, 31, v176
	v_lshl_add_u64 v[178:179], v[176:177], 2, s[12:13]
	global_load_dwordx4 v[164:167], v[178:179], off
	v_add_u32_e32 v185, 32, v129
	v_add_u32_e32 v184, v107, v185
	v_lshl_add_u32 v176, v184, 10, v128
	v_ashrrev_i32_e32 v177, 31, v176
	v_lshl_add_u64 v[178:179], v[176:177], 2, s[12:13]
	global_load_dwordx4 v[168:171], v[178:179], off
	v_add_u32_e32 v185, 32, v129
	v_add_u32_e32 v184, v108, v185
	v_lshl_add_u32 v176, v184, 10, v128
	v_ashrrev_i32_e32 v177, 31, v176
	v_lshl_add_u64 v[178:179], v[176:177], 2, s[12:13]
	global_load_dwordx4 v[172:175], v[178:179], off
	v_add_u32_e32 v67, 32, v129
	v_add_u32_e32 v64, v130, v67
	v_lshl_add_u32 v76, v64, 10, v128
	v_ashrrev_i32_e32 v77, 31, v76
	v_lshl_add_u64 v[78:79], v[76:77], 2, s[12:13]
	v_add_u32_e32 v66, v136, v109
	ds_read_b128 v[72:75], v66
	v_lshl_add_u64 v[76:77], v[76:77], 1, s[14:15]
	s_waitcnt vmcnt(7) lgkmcnt(0)
;   __device__ __forceinline__ void tile(const float* reg, int row0, int col0, int lane) const {
;     rows4(reg, lane, [&](int it, int rr, int c4, float4 v) {
;       int row = row0 + rr, idx = row * 1024 + col0 + c4;
;       float4 xo = *(const float4*)(xold + idx);
;       v.x = fmaf(coef, v.x, xo.x); v.y = fmaf(coef, v.y, xo.y); v.z = fmaf(coef, v.z, xo.z); v.w = fmaf(coef, v.w, xo.w);
;       *(float4*)(xnew + idx) = v;
;       *(bf16x4*)(xb + idx) = pack4(v.x, v.y, v.z, v.w);
;       float s = row16_sum(v.x * v.x + v.y * v.y + v.z * v.z + v.w * v.w);
;       if ((lane & 15) == 0) atomicAdd(ssqn + row, s);
;     });
	v_mov_b32_e32 v68, v144
	v_mov_b32_e32 v69, v145
	v_mov_b32_e32 v70, v146
	v_mov_b32_e32 v71, v147
	v_pk_fma_f32 v[68:69], v[72:73], 0.5, v[68:69] op_sel_hi:[1,0,1]
	v_pk_fma_f32 v[70:71], v[74:75], 0.5, v[70:71] op_sel_hi:[1,0,1]
	global_store_dwordx4 v[78:79], v[68:71], off
	v_cvt_pk_bf16_f32 v72, v68, v69
	v_cvt_pk_bf16_f32 v73, v70, v71
	v_pk_mul_f32 v[68:69], v[68:69], v[68:69]
	v_pk_mul_f32 v[70:71], v[70:71], v[70:71]
	v_add_f32_e32 v65, v68, v69
	v_add_f32_e32 v65, v70, v65
	v_add_f32_e32 v65, v71, v65
	v_mov_b32_e32 v68, 0
	global_store_dwordx2 v[76:77], v[72:73], off
	v_add_f32_dpp v65, v65, v65 quad_perm:[1,0,3,2] row_mask:0xf bank_mask:0xf bound_ctrl:1
	s_nop 1
	v_add_f32_dpp v65, v65, v65 quad_perm:[2,3,0,1] row_mask:0xf bank_mask:0xf bound_ctrl:1
	s_nop 1
	v_add_f32_dpp v65, v65, v65 row_half_mirror row_mask:0xf bank_mask:0xf bound_ctrl:1
	s_nop 1
	v_mov_b32_dpp v68, v65 row_mirror row_mask:0xf bank_mask:0xf
	s_and_saveexec_b64 s[0:1], vcc
	s_cbranch_execz .LBB0_1547
	v_add_f32_e32 v68, v65, v68
	v_ashrrev_i32_e32 v65, 31, v64
	v_lshl_add_u64 v[64:65], v[64:65], 2, s[10:11]
	global_atomic_add_f32 v[64:65], v68, off
.LBB0_1547:
	s_or_b64 exec, exec, s[0:1]
	v_add_u32_e32 v64, v99, v67
	v_lshl_add_u32 v76, v64, 10, v128
	v_ashrrev_i32_e32 v77, 31, v76
	v_lshl_add_u64 v[78:79], v[76:77], 2, s[12:13]
	ds_read_b128 v[72:75], v100
	v_lshl_add_u64 v[76:77], v[76:77], 1, s[14:15]
	s_waitcnt vmcnt(9) lgkmcnt(0)
	v_mov_b32_e32 v68, v148
	v_mov_b32_e32 v69, v149
	v_mov_b32_e32 v70, v150
	v_mov_b32_e32 v71, v151
	v_pk_fma_f32 v[68:69], v[72:73], 0.5, v[68:69] op_sel_hi:[1,0,1]
	v_pk_fma_f32 v[70:71], v[74:75], 0.5, v[70:71] op_sel_hi:[1,0,1]
	global_store_dwordx4 v[78:79], v[68:71], off
	v_cvt_pk_bf16_f32 v72, v68, v69
	v_cvt_pk_bf16_f32 v73, v70, v71
	v_pk_mul_f32 v[68:69], v[68:69], v[68:69]
	v_pk_mul_f32 v[70:71], v[70:71], v[70:71]
	v_add_f32_e32 v65, v68, v69
	v_add_f32_e32 v65, v70, v65
	v_add_f32_e32 v65, v71, v65
	v_mov_b32_e32 v68, 0
	global_store_dwordx2 v[76:77], v[72:73], off
	v_add_f32_dpp v65, v65, v65 quad_perm:[1,0,3,2] row_mask:0xf bank_mask:0xf bound_ctrl:1
	s_nop 1
	v_add_f32_dpp v65, v65, v65 quad_perm:[2,3,0,1] row_mask:0xf bank_mask:0xf bound_ctrl:1
	s_nop 1
	v_add_f32_dpp v65, v65, v65 row_half_mirror row_mask:0xf bank_mask:0xf bound_ctrl:1
	s_nop 1
	v_mov_b32_dpp v68, v65 row_mirror row_mask:0xf bank_mask:0xf
	s_and_saveexec_b64 s[0:1], vcc
	s_cbranch_execz .LBB0_1549
	v_add_f32_e32 v68, v65, v68
	v_ashrrev_i32_e32 v65, 31, v64
	v_lshl_add_u64 v[64:65], v[64:65], 2, s[10:11]
	global_atomic_add_f32 v[64:65], v68, off
.LBB0_1549:
	s_or_b64 exec, exec, s[0:1]
	v_add_u32_e32 v64, v101, v67
	v_lshl_add_u32 v76, v64, 10, v128
	v_ashrrev_i32_e32 v77, 31, v76
	v_lshl_add_u64 v[78:79], v[76:77], 2, s[12:13]
	ds_read_b128 v[72:75], v102
	v_lshl_add_u64 v[76:77], v[76:77], 1, s[14:15]
	s_waitcnt vmcnt(11) lgkmcnt(0)
	v_mov_b32_e32 v68, v152
	v_mov_b32_e32 v69, v153
	v_mov_b32_e32 v70, v154
	v_mov_b32_e32 v71, v155
	v_pk_fma_f32 v[68:69], v[72:73], 0.5, v[68:69] op_sel_hi:[1,0,1]
	v_pk_fma_f32 v[70:71], v[74:75], 0.5, v[70:71] op_sel_hi:[1,0,1]
	global_store_dwordx4 v[78:79], v[68:71], off
	v_cvt_pk_bf16_f32 v72, v68, v69
	v_cvt_pk_bf16_f32 v73, v70, v71
	v_pk_mul_f32 v[68:69], v[68:69], v[68:69]
	v_pk_mul_f32 v[70:71], v[70:71], v[70:71]
	v_add_f32_e32 v65, v68, v69
	v_add_f32_e32 v65, v70, v65
	v_add_f32_e32 v65, v71, v65
	v_mov_b32_e32 v68, 0
	global_store_dwordx2 v[76:77], v[72:73], off
	v_add_f32_dpp v65, v65, v65 quad_perm:[1,0,3,2] row_mask:0xf bank_mask:0xf bound_ctrl:1
	s_nop 1
	v_add_f32_dpp v65, v65, v65 quad_perm:[2,3,0,1] row_mask:0xf bank_mask:0xf bound_ctrl:1
	s_nop 1
	v_add_f32_dpp v65, v65, v65 row_half_mirror row_mask:0xf bank_mask:0xf bound_ctrl:1
	s_nop 1
	v_mov_b32_dpp v68, v65 row_mirror row_mask:0xf bank_mask:0xf
	s_and_saveexec_b64 s[0:1], vcc
	s_cbranch_execz .LBB0_1551
	v_add_f32_e32 v68, v65, v68
	v_ashrrev_i32_e32 v65, 31, v64
	v_lshl_add_u64 v[64:65], v[64:65], 2, s[10:11]
	global_atomic_add_f32 v[64:65], v68, off
.LBB0_1551:
	s_or_b64 exec, exec, s[0:1]
	v_add_u32_e32 v64, v103, v67
	v_lshl_add_u32 v76, v64, 10, v128
	v_ashrrev_i32_e32 v77, 31, v76
	v_lshl_add_u64 v[78:79], v[76:77], 2, s[12:13]
	ds_read_b128 v[72:75], v98
	v_lshl_add_u64 v[76:77], v[76:77], 1, s[14:15]
	s_waitcnt vmcnt(13) lgkmcnt(0)
	v_mov_b32_e32 v68, v156
	v_mov_b32_e32 v69, v157
	v_mov_b32_e32 v70, v158
	v_mov_b32_e32 v71, v159
	v_pk_fma_f32 v[68:69], v[72:73], 0.5, v[68:69] op_sel_hi:[1,0,1]
	v_pk_fma_f32 v[70:71], v[74:75], 0.5, v[70:71] op_sel_hi:[1,0,1]
	global_store_dwordx4 v[78:79], v[68:71], off
	v_cvt_pk_bf16_f32 v72, v68, v69
	v_cvt_pk_bf16_f32 v73, v70, v71
	v_pk_mul_f32 v[68:69], v[68:69], v[68:69]
	v_pk_mul_f32 v[70:71], v[70:71], v[70:71]
	v_add_f32_e32 v65, v68, v69
	v_add_f32_e32 v65, v70, v65
	v_add_f32_e32 v65, v71, v65
	v_mov_b32_e32 v68, 0
	global_store_dwordx2 v[76:77], v[72:73], off
	v_add_f32_dpp v65, v65, v65 quad_perm:[1,0,3,2] row_mask:0xf bank_mask:0xf bound_ctrl:1
	s_nop 1
	v_add_f32_dpp v65, v65, v65 quad_perm:[2,3,0,1] row_mask:0xf bank_mask:0xf bound_ctrl:1
	s_nop 1
	v_add_f32_dpp v65, v65, v65 row_half_mirror row_mask:0xf bank_mask:0xf bound_ctrl:1
	s_nop 1
	v_mov_b32_dpp v68, v65 row_mirror row_mask:0xf bank_mask:0xf
	s_and_saveexec_b64 s[0:1], vcc
	s_cbranch_execz .LBB0_1553
	v_add_f32_e32 v68, v65, v68
	v_ashrrev_i32_e32 v65, 31, v64
	v_lshl_add_u64 v[64:65], v[64:65], 2, s[10:11]
	global_atomic_add_f32 v[64:65], v68, off
;   __device__ __forceinline__ void tile(const float* reg, int row0, int col0, int lane) const {
;     rows4(reg, lane, [&](int it, int rr, int c4, float4 v) {
;       int row = row0 + rr, idx = row * 1024 + col0 + c4;
;       float4 xo = *(const float4*)(xold + idx);
;       v.x = fmaf(coef, v.x, xo.x); v.y = fmaf(coef, v.y, xo.y); v.z = fmaf(coef, v.z, xo.z); v.w = fmaf(coef, v.w, xo.w);
;       *(float4*)(xnew + idx) = v;
;       *(bf16x4*)(xb + idx) = pack4(v.x, v.y, v.z, v.w);
;       float s = row16_sum(v.x * v.x + v.y * v.y + v.z * v.z + v.w * v.w);
;       if ((lane & 15) == 0) atomicAdd(ssqn + row, s);
;     });
.LBB0_1553:
	s_or_b64 exec, exec, s[0:1]
	v_add_u32_e32 v64, v105, v67
	v_lshl_add_u32 v76, v64, 10, v128
	v_ashrrev_i32_e32 v77, 31, v76
	v_lshl_add_u64 v[78:79], v[76:77], 2, s[12:13]
	ds_read_b128 v[72:75], v98 offset:1088
	v_lshl_add_u64 v[76:77], v[76:77], 1, s[14:15]
	s_waitcnt vmcnt(15) lgkmcnt(0)
	v_mov_b32_e32 v68, v160
	v_mov_b32_e32 v69, v161
	v_mov_b32_e32 v70, v162
	v_mov_b32_e32 v71, v163
	v_pk_fma_f32 v[68:69], v[72:73], 0.5, v[68:69] op_sel_hi:[1,0,1]
	v_pk_fma_f32 v[70:71], v[74:75], 0.5, v[70:71] op_sel_hi:[1,0,1]
	global_store_dwordx4 v[78:79], v[68:71], off
	v_cvt_pk_bf16_f32 v72, v68, v69
	v_cvt_pk_bf16_f32 v73, v70, v71
	v_pk_mul_f32 v[68:69], v[68:69], v[68:69]
	v_pk_mul_f32 v[70:71], v[70:71], v[70:71]
	v_add_f32_e32 v65, v68, v69
	v_add_f32_e32 v65, v70, v65
	v_add_f32_e32 v65, v71, v65
	v_mov_b32_e32 v68, 0
	global_store_dwordx2 v[76:77], v[72:73], off
	v_add_f32_dpp v65, v65, v65 quad_perm:[1,0,3,2] row_mask:0xf bank_mask:0xf bound_ctrl:1
	s_nop 1
	v_add_f32_dpp v65, v65, v65 quad_perm:[2,3,0,1] row_mask:0xf bank_mask:0xf bound_ctrl:1
	s_nop 1
	v_add_f32_dpp v65, v65, v65 row_half_mirror row_mask:0xf bank_mask:0xf bound_ctrl:1
	s_nop 1
	v_mov_b32_dpp v68, v65 row_mirror row_mask:0xf bank_mask:0xf
	s_and_saveexec_b64 s[0:1], vcc
	s_cbranch_execz .LBB0_1555
	v_add_f32_e32 v68, v65, v68
	v_ashrrev_i32_e32 v65, 31, v64
	v_lshl_add_u64 v[64:65], v[64:65], 2, s[10:11]
	global_atomic_add_f32 v[64:65], v68, off
.LBB0_1555:
	s_or_b64 exec, exec, s[0:1]
	v_add_u32_e32 v64, v106, v67
	v_lshl_add_u32 v76, v64, 10, v128
	v_ashrrev_i32_e32 v77, 31, v76
	v_lshl_add_u64 v[78:79], v[76:77], 2, s[12:13]
	ds_read_b128 v[72:75], v98 offset:2176
	v_lshl_add_u64 v[76:77], v[76:77], 1, s[14:15]
	s_waitcnt vmcnt(17) lgkmcnt(0)
	v_mov_b32_e32 v68, v164
	v_mov_b32_e32 v69, v165
	v_mov_b32_e32 v70, v166
	v_mov_b32_e32 v71, v167
	v_pk_fma_f32 v[68:69], v[72:73], 0.5, v[68:69] op_sel_hi:[1,0,1]
	v_pk_fma_f32 v[70:71], v[74:75], 0.5, v[70:71] op_sel_hi:[1,0,1]
	global_store_dwordx4 v[78:79], v[68:71], off
	v_cvt_pk_bf16_f32 v72, v68, v69
	v_cvt_pk_bf16_f32 v73, v70, v71
	v_pk_mul_f32 v[68:69], v[68:69], v[68:69]
	v_pk_mul_f32 v[70:71], v[70:71], v[70:71]
	v_add_f32_e32 v65, v68, v69
	v_add_f32_e32 v65, v70, v65
	v_add_f32_e32 v65, v71, v65
	v_mov_b32_e32 v68, 0
	global_store_dwordx2 v[76:77], v[72:73], off
	v_add_f32_dpp v65, v65, v65 quad_perm:[1,0,3,2] row_mask:0xf bank_mask:0xf bound_ctrl:1
	s_nop 1
	v_add_f32_dpp v65, v65, v65 quad_perm:[2,3,0,1] row_mask:0xf bank_mask:0xf bound_ctrl:1
	s_nop 1
	v_add_f32_dpp v65, v65, v65 row_half_mirror row_mask:0xf bank_mask:0xf bound_ctrl:1
	s_nop 1
	v_mov_b32_dpp v68, v65 row_mirror row_mask:0xf bank_mask:0xf
	s_and_saveexec_b64 s[0:1], vcc
	s_cbranch_execz .LBB0_1557
	v_add_f32_e32 v68, v65, v68
	v_ashrrev_i32_e32 v65, 31, v64
	v_lshl_add_u64 v[64:65], v[64:65], 2, s[10:11]
	global_atomic_add_f32 v[64:65], v68, off
.LBB0_1557:
	s_or_b64 exec, exec, s[0:1]
	v_add_u32_e32 v64, v107, v67
	v_lshl_add_u32 v76, v64, 10, v128
	v_ashrrev_i32_e32 v77, 31, v76
	v_lshl_add_u64 v[78:79], v[76:77], 2, s[12:13]
	ds_read_b128 v[72:75], v98 offset:3264
	v_lshl_add_u64 v[76:77], v[76:77], 1, s[14:15]
	s_waitcnt vmcnt(19) lgkmcnt(0)
	v_mov_b32_e32 v68, v168
	v_mov_b32_e32 v69, v169
	v_mov_b32_e32 v70, v170
	v_mov_b32_e32 v71, v171
	v_pk_fma_f32 v[68:69], v[72:73], 0.5, v[68:69] op_sel_hi:[1,0,1]
	v_pk_fma_f32 v[70:71], v[74:75], 0.5, v[70:71] op_sel_hi:[1,0,1]
	global_store_dwordx4 v[78:79], v[68:71], off
	v_cvt_pk_bf16_f32 v72, v68, v69
	v_cvt_pk_bf16_f32 v73, v70, v71
	v_pk_mul_f32 v[68:69], v[68:69], v[68:69]
	v_pk_mul_f32 v[70:71], v[70:71], v[70:71]
	v_add_f32_e32 v65, v68, v69
	v_add_f32_e32 v65, v70, v65
	v_add_f32_e32 v65, v71, v65
	v_mov_b32_e32 v68, 0
	global_store_dwordx2 v[76:77], v[72:73], off
	v_add_f32_dpp v65, v65, v65 quad_perm:[1,0,3,2] row_mask:0xf bank_mask:0xf bound_ctrl:1
	s_nop 1
	v_add_f32_dpp v65, v65, v65 quad_perm:[2,3,0,1] row_mask:0xf bank_mask:0xf bound_ctrl:1
	s_nop 1
	v_add_f32_dpp v65, v65, v65 row_half_mirror row_mask:0xf bank_mask:0xf bound_ctrl:1
	s_nop 1
	v_mov_b32_dpp v68, v65 row_mirror row_mask:0xf bank_mask:0xf
	s_and_saveexec_b64 s[0:1], vcc
	s_cbranch_execz .LBB0_1559
	v_add_f32_e32 v68, v65, v68
	v_ashrrev_i32_e32 v65, 31, v64
	v_lshl_add_u64 v[64:65], v[64:65], 2, s[10:11]
	global_atomic_add_f32 v[64:65], v68, off
.LBB0_1559:
	s_or_b64 exec, exec, s[0:1]
	v_add_u32_e32 v64, v108, v67
	v_lshl_add_u32 v76, v64, 10, v128
	v_ashrrev_i32_e32 v77, 31, v76
	v_lshl_add_u64 v[78:79], v[76:77], 2, s[12:13]
	ds_read_b128 v[72:75], v98 offset:4352
	v_mov_b32_e32 v67, 0
	v_lshl_add_u64 v[76:77], v[76:77], 1, s[14:15]
	s_waitcnt vmcnt(21) lgkmcnt(0)
	v_mov_b32_e32 v68, v172
	v_mov_b32_e32 v69, v173
	v_mov_b32_e32 v70, v174
	v_mov_b32_e32 v71, v175
	v_pk_fma_f32 v[68:69], v[72:73], 0.5, v[68:69] op_sel_hi:[1,0,1]
	v_pk_fma_f32 v[70:71], v[74:75], 0.5, v[70:71] op_sel_hi:[1,0,1]
	global_store_dwordx4 v[78:79], v[68:71], off
	v_cvt_pk_bf16_f32 v72, v68, v69
	v_cvt_pk_bf16_f32 v73, v70, v71
	v_pk_mul_f32 v[68:69], v[68:69], v[68:69]
	v_pk_mul_f32 v[70:71], v[70:71], v[70:71]
	v_add_f32_e32 v65, v68, v69
	v_add_f32_e32 v65, v70, v65
	v_add_f32_e32 v65, v71, v65
	global_store_dwordx2 v[76:77], v[72:73], off
	s_nop 0
	v_add_f32_dpp v65, v65, v65 quad_perm:[1,0,3,2] row_mask:0xf bank_mask:0xf bound_ctrl:1
	s_nop 1
	v_add_f32_dpp v65, v65, v65 quad_perm:[2,3,0,1] row_mask:0xf bank_mask:0xf bound_ctrl:1
	s_nop 1
	v_add_f32_dpp v65, v65, v65 row_half_mirror row_mask:0xf bank_mask:0xf bound_ctrl:1
	s_nop 1
	v_mov_b32_dpp v67, v65 row_mirror row_mask:0xf bank_mask:0xf
	s_and_saveexec_b64 s[0:1], vcc
	s_cbranch_execz .LBB0_1561
	v_add_f32_e32 v67, v65, v67
	v_ashrrev_i32_e32 v65, 31, v64
	v_lshl_add_u64 v[64:65], v[64:65], 2, s[10:11]
	global_atomic_add_f32 v[64:65], v67, off
;   __device__ __forceinline__ void tile(const float* reg, int row0, int col0, int lane) const {
;     rows4(reg, lane, [&](int it, int rr, int c4, float4 v) {
;       int row = row0 + rr, idx = row * 1024 + col0 + c4;
;       float4 xo = *(const float4*)(xold + idx);
;       v.x = fmaf(coef, v.x, xo.x); v.y = fmaf(coef, v.y, xo.y); v.z = fmaf(coef, v.z, xo.z); v.w = fmaf(coef, v.w, xo.w);
;       *(float4*)(xnew + idx) = v;
;       *(bf16x4*)(xb + idx) = pack4(v.x, v.y, v.z, v.w);
;       float s = row16_sum(v.x * v.x + v.y * v.y + v.z * v.z + v.w * v.w);
;       if ((lane & 15) == 0) atomicAdd(ssqn + row, s);
;     });
; template <int MF, class Epi>
; __device__ __forceinline__ void staged_epilogue(f32x4 (&acc)[MF][4], int row0, int col0, const Epi& epi) {
;     ...
; #pragma unroll
;   for (int mp = 0; mp < MF / 2; ++mp) {
;     __builtin_amdgcn_sched_barrier(0);
; #pragma unroll
;     for (int mm = 0; mm < 2; ++mm)
; #pragma unroll
;       for (int n = 0; n < 4; ++n)
; #pragma unroll
;         for (int j = 0; j < 4; ++j) reg[(mm * 16 + fq * 4 + j) * 68 + n * 16 + fr] = acc[mp * 2 + mm][n][j];
;     __builtin_amdgcn_fence(__ATOMIC_ACQ_REL, "wavefront");
;     epi.tile(reg, row0 + mp * 32, col0, lane);
.LBB0_1561:
	s_or_b64 exec, exec, s[0:1]
	ds_write2_b32 v131, v56, v60 offset1:16
	ds_write2_b32 v131, v57, v61 offset0:68 offset1:84
	ds_write2_b32 v131, v58, v62 offset0:136 offset1:152
	ds_write2_b32 v131, v59, v63 offset0:204 offset1:220
	ds_write2_b32 v131, v48, v52 offset0:32 offset1:48
	ds_write2_b32 v131, v49, v53 offset0:100 offset1:116
	ds_write2_b32 v131, v50, v54 offset0:168 offset1:184
	ds_write2_b32 v131, v51, v55 offset0:236 offset1:252
	ds_write2_b32 v112, v40, v44 offset0:64 offset1:80
	ds_write2_b32 v112, v41, v45 offset0:132 offset1:148
	ds_write2_b32 v112, v42, v46 offset0:200 offset1:216
	ds_write2_b32 v104, v43, v47 offset0:12 offset1:28
	ds_write2_b32 v112, v32, v36 offset0:96 offset1:112
	ds_write2_b32 v112, v33, v37 offset0:164 offset1:180
	ds_write2_b32 v112, v34, v38 offset0:232 offset1:248
	ds_write2_b32 v104, v35, v39 offset0:44 offset1:60
	v_add_u32_e32 v185, 64, v129
	v_add_u32_e32 v184, v130, v185
	v_lshl_add_u32 v176, v184, 10, v128
	v_ashrrev_i32_e32 v177, 31, v176
	v_lshl_add_u64 v[178:179], v[176:177], 2, s[12:13]
	global_load_dwordx4 v[144:147], v[178:179], off
	v_add_u32_e32 v185, 64, v129
	v_add_u32_e32 v184, v99, v185
	v_lshl_add_u32 v176, v184, 10, v128
	v_ashrrev_i32_e32 v177, 31, v176
	v_lshl_add_u64 v[178:179], v[176:177], 2, s[12:13]
	global_load_dwordx4 v[148:151], v[178:179], off
	v_add_u32_e32 v185, 64, v129
	v_add_u32_e32 v184, v101, v185
	v_lshl_add_u32 v176, v184, 10, v128
	v_ashrrev_i32_e32 v177, 31, v176
	v_lshl_add_u64 v[178:179], v[176:177], 2, s[12:13]
	global_load_dwordx4 v[152:155], v[178:179], off
	v_add_u32_e32 v185, 64, v129
	v_add_u32_e32 v184, v103, v185
	v_lshl_add_u32 v176, v184, 10, v128
	v_ashrrev_i32_e32 v177, 31, v176
	v_lshl_add_u64 v[178:179], v[176:177], 2, s[12:13]
	global_load_dwordx4 v[156:159], v[178:179], off
	v_add_u32_e32 v185, 64, v129
	v_add_u32_e32 v184, v105, v185
	v_lshl_add_u32 v176, v184, 10, v128
	v_ashrrev_i32_e32 v177, 31, v176
	v_lshl_add_u64 v[178:179], v[176:177], 2, s[12:13]
	global_load_dwordx4 v[160:163], v[178:179], off
	v_add_u32_e32 v185, 64, v129
	v_add_u32_e32 v184, v106, v185
	v_lshl_add_u32 v176, v184, 10, v128
	v_ashrrev_i32_e32 v177, 31, v176
	v_lshl_add_u64 v[178:179], v[176:177], 2, s[12:13]
	global_load_dwordx4 v[164:167], v[178:179], off
	v_add_u32_e32 v185, 64, v129
	v_add_u32_e32 v184, v107, v185
	v_lshl_add_u32 v176, v184, 10, v128
	v_ashrrev_i32_e32 v177, 31, v176
	v_lshl_add_u64 v[178:179], v[176:177], 2, s[12:13]
	global_load_dwordx4 v[168:171], v[178:179], off
	v_add_u32_e32 v185, 64, v129
	v_add_u32_e32 v184, v108, v185
	v_lshl_add_u32 v176, v184, 10, v128
	v_ashrrev_i32_e32 v177, 31, v176
	v_lshl_add_u64 v[178:179], v[176:177], 2, s[12:13]
	global_load_dwordx4 v[172:175], v[178:179], off
	v_add_u32_e32 v34, 64, v129
	v_add_u32_e32 v32, v130, v34
	v_lshl_add_u32 v44, v32, 10, v128
	v_ashrrev_i32_e32 v45, 31, v44
	v_lshl_add_u64 v[46:47], v[44:45], 2, s[12:13]
	ds_read_b128 v[40:43], v66
	v_mov_b32_e32 v35, 0
	v_lshl_add_u64 v[44:45], v[44:45], 1, s[14:15]
	s_waitcnt vmcnt(7) lgkmcnt(0)
	v_mov_b32_e32 v36, v144
	v_mov_b32_e32 v37, v145
	v_mov_b32_e32 v38, v146
	v_mov_b32_e32 v39, v147
	v_pk_fma_f32 v[36:37], v[40:41], 0.5, v[36:37] op_sel_hi:[1,0,1]
	v_pk_fma_f32 v[38:39], v[42:43], 0.5, v[38:39] op_sel_hi:[1,0,1]
	global_store_dwordx4 v[46:47], v[36:39], off
	v_cvt_pk_bf16_f32 v40, v36, v37
	v_cvt_pk_bf16_f32 v41, v38, v39
	v_pk_mul_f32 v[36:37], v[36:37], v[36:37]
	v_pk_mul_f32 v[38:39], v[38:39], v[38:39]
	v_add_f32_e32 v33, v36, v37
	v_add_f32_e32 v33, v38, v33
	v_add_f32_e32 v33, v39, v33
	global_store_dwordx2 v[44:45], v[40:41], off
	s_nop 0
	v_add_f32_dpp v33, v33, v33 quad_perm:[1,0,3,2] row_mask:0xf bank_mask:0xf bound_ctrl:1
	s_nop 1
	v_add_f32_dpp v33, v33, v33 quad_perm:[2,3,0,1] row_mask:0xf bank_mask:0xf bound_ctrl:1
	s_nop 1
	v_add_f32_dpp v33, v33, v33 row_half_mirror row_mask:0xf bank_mask:0xf bound_ctrl:1
	s_nop 1
	v_mov_b32_dpp v35, v33 row_mirror row_mask:0xf bank_mask:0xf
	s_and_saveexec_b64 s[0:1], vcc
	s_cbranch_execz .LBB0_1563
	v_add_f32_e32 v35, v33, v35
	v_ashrrev_i32_e32 v33, 31, v32
	v_lshl_add_u64 v[32:33], v[32:33], 2, s[10:11]
	global_atomic_add_f32 v[32:33], v35, off
.LBB0_1563:
	s_or_b64 exec, exec, s[0:1]
	v_add_u32_e32 v32, v99, v34
	v_lshl_add_u32 v44, v32, 10, v128
	v_ashrrev_i32_e32 v45, 31, v44
	v_lshl_add_u64 v[46:47], v[44:45], 2, s[12:13]
	ds_read_b128 v[40:43], v100
	v_mov_b32_e32 v35, 0
	v_lshl_add_u64 v[44:45], v[44:45], 1, s[14:15]
	s_waitcnt vmcnt(9) lgkmcnt(0)
	v_mov_b32_e32 v36, v148
	v_mov_b32_e32 v37, v149
	v_mov_b32_e32 v38, v150
	v_mov_b32_e32 v39, v151
	v_pk_fma_f32 v[36:37], v[40:41], 0.5, v[36:37] op_sel_hi:[1,0,1]
	v_pk_fma_f32 v[38:39], v[42:43], 0.5, v[38:39] op_sel_hi:[1,0,1]
	global_store_dwordx4 v[46:47], v[36:39], off
	v_cvt_pk_bf16_f32 v40, v36, v37
	v_cvt_pk_bf16_f32 v41, v38, v39
	v_pk_mul_f32 v[36:37], v[36:37], v[36:37]
	v_pk_mul_f32 v[38:39], v[38:39], v[38:39]
	v_add_f32_e32 v33, v36, v37
	v_add_f32_e32 v33, v38, v33
	v_add_f32_e32 v33, v39, v33
	global_store_dwordx2 v[44:45], v[40:41], off
	s_nop 0
	v_add_f32_dpp v33, v33, v33 quad_perm:[1,0,3,2] row_mask:0xf bank_mask:0xf bound_ctrl:1
	s_nop 1
	v_add_f32_dpp v33, v33, v33 quad_perm:[2,3,0,1] row_mask:0xf bank_mask:0xf bound_ctrl:1
	s_nop 1
	v_add_f32_dpp v33, v33, v33 row_half_mirror row_mask:0xf bank_mask:0xf bound_ctrl:1
	s_nop 1
	v_mov_b32_dpp v35, v33 row_mirror row_mask:0xf bank_mask:0xf
	s_and_saveexec_b64 s[0:1], vcc
	s_cbranch_execz .LBB0_1565
	v_add_f32_e32 v35, v33, v35
	v_ashrrev_i32_e32 v33, 31, v32
	v_lshl_add_u64 v[32:33], v[32:33], 2, s[10:11]
	global_atomic_add_f32 v[32:33], v35, off
;   __device__ __forceinline__ void tile(const float* reg, int row0, int col0, int lane) const {
;     rows4(reg, lane, [&](int it, int rr, int c4, float4 v) {
;       int row = row0 + rr, idx = row * 1024 + col0 + c4;
;       float4 xo = *(const float4*)(xold + idx);
;       v.x = fmaf(coef, v.x, xo.x); v.y = fmaf(coef, v.y, xo.y); v.z = fmaf(coef, v.z, xo.z); v.w = fmaf(coef, v.w, xo.w);
;       *(float4*)(xnew + idx) = v;
;       *(bf16x4*)(xb + idx) = pack4(v.x, v.y, v.z, v.w);
;       float s = row16_sum(v.x * v.x + v.y * v.y + v.z * v.z + v.w * v.w);
;       if ((lane & 15) == 0) atomicAdd(ssqn + row, s);
;     });
.LBB0_1565:
	s_or_b64 exec, exec, s[0:1]
	v_add_u32_e32 v32, v101, v34
	v_lshl_add_u32 v44, v32, 10, v128
	v_ashrrev_i32_e32 v45, 31, v44
	v_lshl_add_u64 v[46:47], v[44:45], 2, s[12:13]
	ds_read_b128 v[40:43], v102
	v_mov_b32_e32 v35, 0
	v_lshl_add_u64 v[44:45], v[44:45], 1, s[14:15]
	s_waitcnt vmcnt(11) lgkmcnt(0)
	v_mov_b32_e32 v36, v152
	v_mov_b32_e32 v37, v153
	v_mov_b32_e32 v38, v154
	v_mov_b32_e32 v39, v155
	v_pk_fma_f32 v[36:37], v[40:41], 0.5, v[36:37] op_sel_hi:[1,0,1]
	v_pk_fma_f32 v[38:39], v[42:43], 0.5, v[38:39] op_sel_hi:[1,0,1]
	global_store_dwordx4 v[46:47], v[36:39], off
	v_cvt_pk_bf16_f32 v40, v36, v37
	v_cvt_pk_bf16_f32 v41, v38, v39
	v_pk_mul_f32 v[36:37], v[36:37], v[36:37]
	v_pk_mul_f32 v[38:39], v[38:39], v[38:39]
	v_add_f32_e32 v33, v36, v37
	v_add_f32_e32 v33, v38, v33
	v_add_f32_e32 v33, v39, v33
	global_store_dwordx2 v[44:45], v[40:41], off
	s_nop 0
	v_add_f32_dpp v33, v33, v33 quad_perm:[1,0,3,2] row_mask:0xf bank_mask:0xf bound_ctrl:1
	s_nop 1
	v_add_f32_dpp v33, v33, v33 quad_perm:[2,3,0,1] row_mask:0xf bank_mask:0xf bound_ctrl:1
	s_nop 1
	v_add_f32_dpp v33, v33, v33 row_half_mirror row_mask:0xf bank_mask:0xf bound_ctrl:1
	s_nop 1
	v_mov_b32_dpp v35, v33 row_mirror row_mask:0xf bank_mask:0xf
	s_and_saveexec_b64 s[0:1], vcc
	s_cbranch_execz .LBB0_1567
	v_add_f32_e32 v35, v33, v35
	v_ashrrev_i32_e32 v33, 31, v32
	v_lshl_add_u64 v[32:33], v[32:33], 2, s[10:11]
	global_atomic_add_f32 v[32:33], v35, off
.LBB0_1567:
	s_or_b64 exec, exec, s[0:1]
	v_add_u32_e32 v32, v103, v34
	v_lshl_add_u32 v44, v32, 10, v128
	v_ashrrev_i32_e32 v45, 31, v44
	v_lshl_add_u64 v[46:47], v[44:45], 2, s[12:13]
	ds_read_b128 v[40:43], v98
	v_mov_b32_e32 v35, 0
	v_lshl_add_u64 v[44:45], v[44:45], 1, s[14:15]
	s_waitcnt vmcnt(13) lgkmcnt(0)
	v_mov_b32_e32 v36, v156
	v_mov_b32_e32 v37, v157
	v_mov_b32_e32 v38, v158
	v_mov_b32_e32 v39, v159
	v_pk_fma_f32 v[36:37], v[40:41], 0.5, v[36:37] op_sel_hi:[1,0,1]
	v_pk_fma_f32 v[38:39], v[42:43], 0.5, v[38:39] op_sel_hi:[1,0,1]
	global_store_dwordx4 v[46:47], v[36:39], off
	v_cvt_pk_bf16_f32 v40, v36, v37
	v_cvt_pk_bf16_f32 v41, v38, v39
	v_pk_mul_f32 v[36:37], v[36:37], v[36:37]
	v_pk_mul_f32 v[38:39], v[38:39], v[38:39]
	v_add_f32_e32 v33, v36, v37
	v_add_f32_e32 v33, v38, v33
	v_add_f32_e32 v33, v39, v33
	global_store_dwordx2 v[44:45], v[40:41], off
	s_nop 0
	v_add_f32_dpp v33, v33, v33 quad_perm:[1,0,3,2] row_mask:0xf bank_mask:0xf bound_ctrl:1
	s_nop 1
	v_add_f32_dpp v33, v33, v33 quad_perm:[2,3,0,1] row_mask:0xf bank_mask:0xf bound_ctrl:1
	s_nop 1
	v_add_f32_dpp v33, v33, v33 row_half_mirror row_mask:0xf bank_mask:0xf bound_ctrl:1
	s_nop 1
	v_mov_b32_dpp v35, v33 row_mirror row_mask:0xf bank_mask:0xf
	s_and_saveexec_b64 s[0:1], vcc
	s_cbranch_execz .LBB0_1569
	v_add_f32_e32 v35, v33, v35
	v_ashrrev_i32_e32 v33, 31, v32
	v_lshl_add_u64 v[32:33], v[32:33], 2, s[10:11]
	global_atomic_add_f32 v[32:33], v35, off
.LBB0_1569:
	s_or_b64 exec, exec, s[0:1]
	v_add_u32_e32 v32, v105, v34
	v_lshl_add_u32 v44, v32, 10, v128
	v_ashrrev_i32_e32 v45, 31, v44
	v_lshl_add_u64 v[46:47], v[44:45], 2, s[12:13]
	ds_read_b128 v[40:43], v98 offset:1088
	v_mov_b32_e32 v35, 0
	v_lshl_add_u64 v[44:45], v[44:45], 1, s[14:15]
	s_waitcnt vmcnt(15) lgkmcnt(0)
	v_mov_b32_e32 v36, v160
	v_mov_b32_e32 v37, v161
	v_mov_b32_e32 v38, v162
	v_mov_b32_e32 v39, v163
	v_pk_fma_f32 v[36:37], v[40:41], 0.5, v[36:37] op_sel_hi:[1,0,1]
	v_pk_fma_f32 v[38:39], v[42:43], 0.5, v[38:39] op_sel_hi:[1,0,1]
	global_store_dwordx4 v[46:47], v[36:39], off
	v_cvt_pk_bf16_f32 v40, v36, v37
	v_cvt_pk_bf16_f32 v41, v38, v39
	v_pk_mul_f32 v[36:37], v[36:37], v[36:37]
	v_pk_mul_f32 v[38:39], v[38:39], v[38:39]
	v_add_f32_e32 v33, v36, v37
	v_add_f32_e32 v33, v38, v33
	v_add_f32_e32 v33, v39, v33
	global_store_dwordx2 v[44:45], v[40:41], off
	s_nop 0
	v_add_f32_dpp v33, v33, v33 quad_perm:[1,0,3,2] row_mask:0xf bank_mask:0xf bound_ctrl:1
	s_nop 1
	v_add_f32_dpp v33, v33, v33 quad_perm:[2,3,0,1] row_mask:0xf bank_mask:0xf bound_ctrl:1
	s_nop 1
	v_add_f32_dpp v33, v33, v33 row_half_mirror row_mask:0xf bank_mask:0xf bound_ctrl:1
	s_nop 1
	v_mov_b32_dpp v35, v33 row_mirror row_mask:0xf bank_mask:0xf
	s_and_saveexec_b64 s[0:1], vcc
	s_cbranch_execz .LBB0_1571
	v_add_f32_e32 v35, v33, v35
	v_ashrrev_i32_e32 v33, 31, v32
	v_lshl_add_u64 v[32:33], v[32:33], 2, s[10:11]
	global_atomic_add_f32 v[32:33], v35, off
.LBB0_1571:
	s_or_b64 exec, exec, s[0:1]
	v_add_u32_e32 v32, v106, v34
	v_lshl_add_u32 v44, v32, 10, v128
	v_ashrrev_i32_e32 v45, 31, v44
	v_lshl_add_u64 v[46:47], v[44:45], 2, s[12:13]
	ds_read_b128 v[40:43], v98 offset:2176
	v_mov_b32_e32 v35, 0
	v_lshl_add_u64 v[44:45], v[44:45], 1, s[14:15]
	s_waitcnt vmcnt(17) lgkmcnt(0)
	v_mov_b32_e32 v36, v164
	v_mov_b32_e32 v37, v165
	v_mov_b32_e32 v38, v166
	v_mov_b32_e32 v39, v167
	v_pk_fma_f32 v[36:37], v[40:41], 0.5, v[36:37] op_sel_hi:[1,0,1]
	v_pk_fma_f32 v[38:39], v[42:43], 0.5, v[38:39] op_sel_hi:[1,0,1]
	global_store_dwordx4 v[46:47], v[36:39], off
	v_cvt_pk_bf16_f32 v40, v36, v37
	v_cvt_pk_bf16_f32 v41, v38, v39
	v_pk_mul_f32 v[36:37], v[36:37], v[36:37]
	v_pk_mul_f32 v[38:39], v[38:39], v[38:39]
	v_add_f32_e32 v33, v36, v37
	v_add_f32_e32 v33, v38, v33
	v_add_f32_e32 v33, v39, v33
	global_store_dwordx2 v[44:45], v[40:41], off
	s_nop 0
	v_add_f32_dpp v33, v33, v33 quad_perm:[1,0,3,2] row_mask:0xf bank_mask:0xf bound_ctrl:1
	s_nop 1
	v_add_f32_dpp v33, v33, v33 quad_perm:[2,3,0,1] row_mask:0xf bank_mask:0xf bound_ctrl:1
	s_nop 1
	v_add_f32_dpp v33, v33, v33 row_half_mirror row_mask:0xf bank_mask:0xf bound_ctrl:1
	s_nop 1
	v_mov_b32_dpp v35, v33 row_mirror row_mask:0xf bank_mask:0xf
	s_and_saveexec_b64 s[0:1], vcc
	s_cbranch_execz .LBB0_1573
	v_add_f32_e32 v35, v33, v35
	v_ashrrev_i32_e32 v33, 31, v32
	v_lshl_add_u64 v[32:33], v[32:33], 2, s[10:11]
	global_atomic_add_f32 v[32:33], v35, off
;   __device__ __forceinline__ void tile(const float* reg, int row0, int col0, int lane) const {
;     rows4(reg, lane, [&](int it, int rr, int c4, float4 v) {
;       int row = row0 + rr, idx = row * 1024 + col0 + c4;
;       float4 xo = *(const float4*)(xold + idx);
;       v.x = fmaf(coef, v.x, xo.x); v.y = fmaf(coef, v.y, xo.y); v.z = fmaf(coef, v.z, xo.z); v.w = fmaf(coef, v.w, xo.w);
;       *(float4*)(xnew + idx) = v;
;       *(bf16x4*)(xb + idx) = pack4(v.x, v.y, v.z, v.w);
;       float s = row16_sum(v.x * v.x + v.y * v.y + v.z * v.z + v.w * v.w);
;       if ((lane & 15) == 0) atomicAdd(ssqn + row, s);
;     });
; template <int MF, class Epi>
; __device__ __forceinline__ void staged_epilogue(f32x4 (&acc)[MF][4], int row0, int col0, const Epi& epi) {
;     ...
; #pragma unroll
;   for (int mp = 0; mp < MF / 2; ++mp) {
;     __builtin_amdgcn_sched_barrier(0);
; #pragma unroll
;     for (int mm = 0; mm < 2; ++mm)
; #pragma unroll
;       for (int n = 0; n < 4; ++n)
; #pragma unroll
;         for (int j = 0; j < 4; ++j) reg[(mm * 16 + fq * 4 + j) * 68 + n * 16 + fr] = acc[mp * 2 + mm][n][j];
;     __builtin_amdgcn_fence(__ATOMIC_ACQ_REL, "wavefront");
;     epi.tile(reg, row0 + mp * 32, col0, lane);
.LBB0_1573:
	s_or_b64 exec, exec, s[0:1]
	v_add_u32_e32 v32, v107, v34
	v_lshl_add_u32 v44, v32, 10, v128
	v_ashrrev_i32_e32 v45, 31, v44
	v_lshl_add_u64 v[46:47], v[44:45], 2, s[12:13]
	ds_read_b128 v[40:43], v98 offset:3264
	v_mov_b32_e32 v35, 0
	v_lshl_add_u64 v[44:45], v[44:45], 1, s[14:15]
	s_waitcnt vmcnt(19) lgkmcnt(0)
	v_mov_b32_e32 v36, v168
	v_mov_b32_e32 v37, v169
	v_mov_b32_e32 v38, v170
	v_mov_b32_e32 v39, v171
	v_pk_fma_f32 v[36:37], v[40:41], 0.5, v[36:37] op_sel_hi:[1,0,1]
	v_pk_fma_f32 v[38:39], v[42:43], 0.5, v[38:39] op_sel_hi:[1,0,1]
	global_store_dwordx4 v[46:47], v[36:39], off
	v_cvt_pk_bf16_f32 v40, v36, v37
	v_cvt_pk_bf16_f32 v41, v38, v39
	v_pk_mul_f32 v[36:37], v[36:37], v[36:37]
	v_pk_mul_f32 v[38:39], v[38:39], v[38:39]
	v_add_f32_e32 v33, v36, v37
	v_add_f32_e32 v33, v38, v33
	v_add_f32_e32 v33, v39, v33
	global_store_dwordx2 v[44:45], v[40:41], off
	s_nop 0
	v_add_f32_dpp v33, v33, v33 quad_perm:[1,0,3,2] row_mask:0xf bank_mask:0xf bound_ctrl:1
	s_nop 1
	v_add_f32_dpp v33, v33, v33 quad_perm:[2,3,0,1] row_mask:0xf bank_mask:0xf bound_ctrl:1
	s_nop 1
	v_add_f32_dpp v33, v33, v33 row_half_mirror row_mask:0xf bank_mask:0xf bound_ctrl:1
	s_nop 1
	v_mov_b32_dpp v35, v33 row_mirror row_mask:0xf bank_mask:0xf
	s_and_saveexec_b64 s[0:1], vcc
	s_cbranch_execz .LBB0_1575
	v_add_f32_e32 v35, v33, v35
	v_ashrrev_i32_e32 v33, 31, v32
	v_lshl_add_u64 v[32:33], v[32:33], 2, s[10:11]
	global_atomic_add_f32 v[32:33], v35, off
.LBB0_1575:
	s_or_b64 exec, exec, s[0:1]
	v_add_u32_e32 v32, v108, v34
	v_lshl_add_u32 v42, v32, 10, v128
	v_ashrrev_i32_e32 v43, 31, v42
	v_lshl_add_u64 v[44:45], v[42:43], 2, s[12:13]
	ds_read_b128 v[38:41], v98 offset:4352
	v_lshl_add_u64 v[42:43], v[42:43], 1, s[14:15]
	s_waitcnt vmcnt(21) lgkmcnt(0)
	v_mov_b32_e32 v34, v172
	v_mov_b32_e32 v35, v173
	v_mov_b32_e32 v36, v174
	v_mov_b32_e32 v37, v175
	v_pk_fma_f32 v[34:35], v[38:39], 0.5, v[34:35] op_sel_hi:[1,0,1]
	v_pk_fma_f32 v[36:37], v[40:41], 0.5, v[36:37] op_sel_hi:[1,0,1]
	global_store_dwordx4 v[44:45], v[34:37], off
	v_cvt_pk_bf16_f32 v38, v34, v35
	v_cvt_pk_bf16_f32 v39, v36, v37
	v_pk_mul_f32 v[34:35], v[34:35], v[34:35]
	v_pk_mul_f32 v[36:37], v[36:37], v[36:37]
	v_add_f32_e32 v33, v34, v35
	v_add_f32_e32 v33, v36, v33
	v_add_f32_e32 v33, v37, v33
	v_mov_b32_e32 v34, 0
	global_store_dwordx2 v[42:43], v[38:39], off
	v_add_f32_dpp v33, v33, v33 quad_perm:[1,0,3,2] row_mask:0xf bank_mask:0xf bound_ctrl:1
	s_nop 1
	v_add_f32_dpp v33, v33, v33 quad_perm:[2,3,0,1] row_mask:0xf bank_mask:0xf bound_ctrl:1
	s_nop 1
	v_add_f32_dpp v33, v33, v33 row_half_mirror row_mask:0xf bank_mask:0xf bound_ctrl:1
	s_nop 1
	v_mov_b32_dpp v34, v33 row_mirror row_mask:0xf bank_mask:0xf
	s_and_saveexec_b64 s[0:1], vcc
	s_cbranch_execz .LBB0_1577
	v_add_f32_e32 v34, v33, v34
	v_ashrrev_i32_e32 v33, 31, v32
	v_lshl_add_u64 v[32:33], v[32:33], 2, s[10:11]
	global_atomic_add_f32 v[32:33], v34, off
.LBB0_1577:
	s_or_b64 exec, exec, s[0:1]
	ds_write2_b32 v131, v24, v28 offset1:16
	ds_write2_b32 v131, v25, v29 offset0:68 offset1:84
	ds_write2_b32 v131, v26, v30 offset0:136 offset1:152
	ds_write2_b32 v131, v27, v31 offset0:204 offset1:220
	ds_write2_b32 v131, v16, v20 offset0:32 offset1:48
	ds_write2_b32 v131, v17, v21 offset0:100 offset1:116
	ds_write2_b32 v131, v18, v22 offset0:168 offset1:184
	ds_write2_b32 v131, v19, v23 offset0:236 offset1:252
	ds_write2_b32 v112, v4, v8 offset0:64 offset1:80
	ds_write2_b32 v112, v5, v9 offset0:132 offset1:148
	ds_write2_b32 v112, v6, v10 offset0:200 offset1:216
	ds_write2_b32 v104, v7, v11 offset0:12 offset1:28
	ds_write2_b32 v112, v0, v12 offset0:96 offset1:112
	ds_write2_b32 v112, v1, v13 offset0:164 offset1:180
	ds_write2_b32 v112, v2, v14 offset0:232 offset1:248
	ds_write2_b32 v104, v3, v15 offset0:44 offset1:60
	v_add_u32_e32 v185, 0x60, v129
	v_add_u32_e32 v184, v130, v185
	v_lshl_add_u32 v176, v184, 10, v128
	v_ashrrev_i32_e32 v177, 31, v176
	v_lshl_add_u64 v[178:179], v[176:177], 2, s[12:13]
	global_load_dwordx4 v[144:147], v[178:179], off
	v_add_u32_e32 v185, 0x60, v129
	v_add_u32_e32 v184, v99, v185
	v_lshl_add_u32 v176, v184, 10, v128
	v_ashrrev_i32_e32 v177, 31, v176
	v_lshl_add_u64 v[178:179], v[176:177], 2, s[12:13]
	global_load_dwordx4 v[148:151], v[178:179], off
	v_add_u32_e32 v185, 0x60, v129
	v_add_u32_e32 v184, v101, v185
	v_lshl_add_u32 v176, v184, 10, v128
	v_ashrrev_i32_e32 v177, 31, v176
	v_lshl_add_u64 v[178:179], v[176:177], 2, s[12:13]
	global_load_dwordx4 v[152:155], v[178:179], off
	v_add_u32_e32 v185, 0x60, v129
	v_add_u32_e32 v184, v103, v185
	v_lshl_add_u32 v176, v184, 10, v128
	v_ashrrev_i32_e32 v177, 31, v176
	v_lshl_add_u64 v[178:179], v[176:177], 2, s[12:13]
	global_load_dwordx4 v[156:159], v[178:179], off
	v_add_u32_e32 v185, 0x60, v129
	v_add_u32_e32 v184, v105, v185
	v_lshl_add_u32 v176, v184, 10, v128
	v_ashrrev_i32_e32 v177, 31, v176
	v_lshl_add_u64 v[178:179], v[176:177], 2, s[12:13]
	global_load_dwordx4 v[160:163], v[178:179], off
	v_add_u32_e32 v185, 0x60, v129
	v_add_u32_e32 v184, v106, v185
	v_lshl_add_u32 v176, v184, 10, v128
	v_ashrrev_i32_e32 v177, 31, v176
	v_lshl_add_u64 v[178:179], v[176:177], 2, s[12:13]
	global_load_dwordx4 v[164:167], v[178:179], off
	v_add_u32_e32 v185, 0x60, v129
	v_add_u32_e32 v184, v107, v185
	v_lshl_add_u32 v176, v184, 10, v128
	v_ashrrev_i32_e32 v177, 31, v176
	v_lshl_add_u64 v[178:179], v[176:177], 2, s[12:13]
	global_load_dwordx4 v[168:171], v[178:179], off
	v_add_u32_e32 v185, 0x60, v129
	v_add_u32_e32 v184, v108, v185
	v_lshl_add_u32 v176, v184, 10, v128
	v_ashrrev_i32_e32 v177, 31, v176
	v_lshl_add_u64 v[178:179], v[176:177], 2, s[12:13]
	global_load_dwordx4 v[172:175], v[178:179], off
	v_add_u32_e32 v2, 0x60, v129
	v_add_u32_e32 v0, v130, v2
	v_lshl_add_u32 v12, v0, 10, v128
	v_ashrrev_i32_e32 v13, 31, v12
	v_lshl_add_u64 v[14:15], v[12:13], 2, s[12:13]
	ds_read_b128 v[8:11], v66
	v_mov_b32_e32 v3, 0
	v_lshl_add_u64 v[12:13], v[12:13], 1, s[14:15]
	s_waitcnt vmcnt(7) lgkmcnt(0)
	v_mov_b32_e32 v4, v144
	v_mov_b32_e32 v5, v145
	v_mov_b32_e32 v6, v146
	v_mov_b32_e32 v7, v147
	v_pk_fma_f32 v[4:5], v[8:9], 0.5, v[4:5] op_sel_hi:[1,0,1]
	v_pk_fma_f32 v[6:7], v[10:11], 0.5, v[6:7] op_sel_hi:[1,0,1]
	global_store_dwordx4 v[14:15], v[4:7], off
	v_cvt_pk_bf16_f32 v8, v4, v5
	v_cvt_pk_bf16_f32 v9, v6, v7
	v_pk_mul_f32 v[4:5], v[4:5], v[4:5]
	v_pk_mul_f32 v[6:7], v[6:7], v[6:7]
	v_add_f32_e32 v1, v4, v5
	v_add_f32_e32 v1, v6, v1
	v_add_f32_e32 v1, v7, v1
	global_store_dwordx2 v[12:13], v[8:9], off
	s_nop 0
	v_add_f32_dpp v1, v1, v1 quad_perm:[1,0,3,2] row_mask:0xf bank_mask:0xf bound_ctrl:1
	s_nop 1
	v_add_f32_dpp v1, v1, v1 quad_perm:[2,3,0,1] row_mask:0xf bank_mask:0xf bound_ctrl:1
	s_nop 1
	v_add_f32_dpp v1, v1, v1 row_half_mirror row_mask:0xf bank_mask:0xf bound_ctrl:1
	s_nop 1
	v_mov_b32_dpp v3, v1 row_mirror row_mask:0xf bank_mask:0xf
	s_and_saveexec_b64 s[0:1], vcc
	s_cbranch_execz .LBB0_1579
	v_add_f32_e32 v3, v1, v3
	v_ashrrev_i32_e32 v1, 31, v0
	v_lshl_add_u64 v[0:1], v[0:1], 2, s[10:11]
	global_atomic_add_f32 v[0:1], v3, off
;   __device__ __forceinline__ void tile(const float* reg, int row0, int col0, int lane) const {
;     rows4(reg, lane, [&](int it, int rr, int c4, float4 v) {
;       int row = row0 + rr, idx = row * 1024 + col0 + c4;
;       float4 xo = *(const float4*)(xold + idx);
;       v.x = fmaf(coef, v.x, xo.x); v.y = fmaf(coef, v.y, xo.y); v.z = fmaf(coef, v.z, xo.z); v.w = fmaf(coef, v.w, xo.w);
;       *(float4*)(xnew + idx) = v;
;       *(bf16x4*)(xb + idx) = pack4(v.x, v.y, v.z, v.w);
;       float s = row16_sum(v.x * v.x + v.y * v.y + v.z * v.z + v.w * v.w);
;       if ((lane & 15) == 0) atomicAdd(ssqn + row, s);
;     });
.LBB0_1579:
	s_or_b64 exec, exec, s[0:1]
	v_add_u32_e32 v0, v99, v2
	v_lshl_add_u32 v12, v0, 10, v128
	v_ashrrev_i32_e32 v13, 31, v12
	v_lshl_add_u64 v[14:15], v[12:13], 2, s[12:13]
	ds_read_b128 v[8:11], v100
	v_mov_b32_e32 v3, 0
	v_lshl_add_u64 v[12:13], v[12:13], 1, s[14:15]
	s_waitcnt vmcnt(9) lgkmcnt(0)
	v_mov_b32_e32 v4, v148
	v_mov_b32_e32 v5, v149
	v_mov_b32_e32 v6, v150
	v_mov_b32_e32 v7, v151
	v_pk_fma_f32 v[4:5], v[8:9], 0.5, v[4:5] op_sel_hi:[1,0,1]
	v_pk_fma_f32 v[6:7], v[10:11], 0.5, v[6:7] op_sel_hi:[1,0,1]
	global_store_dwordx4 v[14:15], v[4:7], off
	v_cvt_pk_bf16_f32 v8, v4, v5
	v_cvt_pk_bf16_f32 v9, v6, v7
	v_pk_mul_f32 v[4:5], v[4:5], v[4:5]
	v_pk_mul_f32 v[6:7], v[6:7], v[6:7]
	v_add_f32_e32 v1, v4, v5
	v_add_f32_e32 v1, v6, v1
	v_add_f32_e32 v1, v7, v1
	global_store_dwordx2 v[12:13], v[8:9], off
	s_nop 0
	v_add_f32_dpp v1, v1, v1 quad_perm:[1,0,3,2] row_mask:0xf bank_mask:0xf bound_ctrl:1
	s_nop 1
	v_add_f32_dpp v1, v1, v1 quad_perm:[2,3,0,1] row_mask:0xf bank_mask:0xf bound_ctrl:1
	s_nop 1
	v_add_f32_dpp v1, v1, v1 row_half_mirror row_mask:0xf bank_mask:0xf bound_ctrl:1
	s_nop 1
	v_mov_b32_dpp v3, v1 row_mirror row_mask:0xf bank_mask:0xf
	s_and_saveexec_b64 s[0:1], vcc
	s_cbranch_execz .LBB0_1581
	v_add_f32_e32 v3, v1, v3
	v_ashrrev_i32_e32 v1, 31, v0
	v_lshl_add_u64 v[0:1], v[0:1], 2, s[10:11]
	global_atomic_add_f32 v[0:1], v3, off
.LBB0_1581:
	s_or_b64 exec, exec, s[0:1]
	v_add_u32_e32 v0, v101, v2
	v_lshl_add_u32 v12, v0, 10, v128
	v_ashrrev_i32_e32 v13, 31, v12
	v_lshl_add_u64 v[14:15], v[12:13], 2, s[12:13]
	ds_read_b128 v[8:11], v102
	v_mov_b32_e32 v3, 0
	v_lshl_add_u64 v[12:13], v[12:13], 1, s[14:15]
	s_waitcnt vmcnt(11) lgkmcnt(0)
	v_mov_b32_e32 v4, v152
	v_mov_b32_e32 v5, v153
	v_mov_b32_e32 v6, v154
	v_mov_b32_e32 v7, v155
	v_pk_fma_f32 v[4:5], v[8:9], 0.5, v[4:5] op_sel_hi:[1,0,1]
	v_pk_fma_f32 v[6:7], v[10:11], 0.5, v[6:7] op_sel_hi:[1,0,1]
	global_store_dwordx4 v[14:15], v[4:7], off
	v_cvt_pk_bf16_f32 v8, v4, v5
	v_cvt_pk_bf16_f32 v9, v6, v7
	v_pk_mul_f32 v[4:5], v[4:5], v[4:5]
	v_pk_mul_f32 v[6:7], v[6:7], v[6:7]
	v_add_f32_e32 v1, v4, v5
	v_add_f32_e32 v1, v6, v1
	v_add_f32_e32 v1, v7, v1
	global_store_dwordx2 v[12:13], v[8:9], off
	s_nop 0
	v_add_f32_dpp v1, v1, v1 quad_perm:[1,0,3,2] row_mask:0xf bank_mask:0xf bound_ctrl:1
	s_nop 1
	v_add_f32_dpp v1, v1, v1 quad_perm:[2,3,0,1] row_mask:0xf bank_mask:0xf bound_ctrl:1
	s_nop 1
	v_add_f32_dpp v1, v1, v1 row_half_mirror row_mask:0xf bank_mask:0xf bound_ctrl:1
	s_nop 1
	v_mov_b32_dpp v3, v1 row_mirror row_mask:0xf bank_mask:0xf
	s_and_saveexec_b64 s[0:1], vcc
	s_cbranch_execz .LBB0_1583
	v_add_f32_e32 v3, v1, v3
	v_ashrrev_i32_e32 v1, 31, v0
	v_lshl_add_u64 v[0:1], v[0:1], 2, s[10:11]
	global_atomic_add_f32 v[0:1], v3, off
.LBB0_1583:
	s_or_b64 exec, exec, s[0:1]
	v_add_u32_e32 v0, v103, v2
	v_lshl_add_u32 v12, v0, 10, v128
	v_ashrrev_i32_e32 v13, 31, v12
	v_lshl_add_u64 v[14:15], v[12:13], 2, s[12:13]
	ds_read_b128 v[8:11], v98
	v_mov_b32_e32 v3, 0
	v_lshl_add_u64 v[12:13], v[12:13], 1, s[14:15]
	s_waitcnt vmcnt(13) lgkmcnt(0)
	v_mov_b32_e32 v4, v156
	v_mov_b32_e32 v5, v157
	v_mov_b32_e32 v6, v158
	v_mov_b32_e32 v7, v159
	v_pk_fma_f32 v[4:5], v[8:9], 0.5, v[4:5] op_sel_hi:[1,0,1]
	v_pk_fma_f32 v[6:7], v[10:11], 0.5, v[6:7] op_sel_hi:[1,0,1]
	global_store_dwordx4 v[14:15], v[4:7], off
	v_cvt_pk_bf16_f32 v8, v4, v5
	v_cvt_pk_bf16_f32 v9, v6, v7
	v_pk_mul_f32 v[4:5], v[4:5], v[4:5]
	v_pk_mul_f32 v[6:7], v[6:7], v[6:7]
	v_add_f32_e32 v1, v4, v5
	v_add_f32_e32 v1, v6, v1
	v_add_f32_e32 v1, v7, v1
	global_store_dwordx2 v[12:13], v[8:9], off
	s_nop 0
	v_add_f32_dpp v1, v1, v1 quad_perm:[1,0,3,2] row_mask:0xf bank_mask:0xf bound_ctrl:1
	s_nop 1
	v_add_f32_dpp v1, v1, v1 quad_perm:[2,3,0,1] row_mask:0xf bank_mask:0xf bound_ctrl:1
	s_nop 1
	v_add_f32_dpp v1, v1, v1 row_half_mirror row_mask:0xf bank_mask:0xf bound_ctrl:1
	s_nop 1
	v_mov_b32_dpp v3, v1 row_mirror row_mask:0xf bank_mask:0xf
	s_and_saveexec_b64 s[0:1], vcc
	s_cbranch_execz .LBB0_1585
	v_add_f32_e32 v3, v1, v3
	v_ashrrev_i32_e32 v1, 31, v0
	v_lshl_add_u64 v[0:1], v[0:1], 2, s[10:11]
	global_atomic_add_f32 v[0:1], v3, off
.LBB0_1585:
	s_or_b64 exec, exec, s[0:1]
	v_add_u32_e32 v0, v105, v2
	v_lshl_add_u32 v12, v0, 10, v128
	v_ashrrev_i32_e32 v13, 31, v12
	v_lshl_add_u64 v[14:15], v[12:13], 2, s[12:13]
	ds_read_b128 v[8:11], v98 offset:1088
	v_mov_b32_e32 v3, 0
	v_lshl_add_u64 v[12:13], v[12:13], 1, s[14:15]
	s_waitcnt vmcnt(15) lgkmcnt(0)
	v_mov_b32_e32 v4, v160
	v_mov_b32_e32 v5, v161
	v_mov_b32_e32 v6, v162
	v_mov_b32_e32 v7, v163
	v_pk_fma_f32 v[4:5], v[8:9], 0.5, v[4:5] op_sel_hi:[1,0,1]
	v_pk_fma_f32 v[6:7], v[10:11], 0.5, v[6:7] op_sel_hi:[1,0,1]
	global_store_dwordx4 v[14:15], v[4:7], off
	v_cvt_pk_bf16_f32 v8, v4, v5
	v_cvt_pk_bf16_f32 v9, v6, v7
	v_pk_mul_f32 v[4:5], v[4:5], v[4:5]
	v_pk_mul_f32 v[6:7], v[6:7], v[6:7]
	v_add_f32_e32 v1, v4, v5
	v_add_f32_e32 v1, v6, v1
	v_add_f32_e32 v1, v7, v1
	global_store_dwordx2 v[12:13], v[8:9], off
	s_nop 0
	v_add_f32_dpp v1, v1, v1 quad_perm:[1,0,3,2] row_mask:0xf bank_mask:0xf bound_ctrl:1
	s_nop 1
	v_add_f32_dpp v1, v1, v1 quad_perm:[2,3,0,1] row_mask:0xf bank_mask:0xf bound_ctrl:1
	s_nop 1
	v_add_f32_dpp v1, v1, v1 row_half_mirror row_mask:0xf bank_mask:0xf bound_ctrl:1
	s_nop 1
	v_mov_b32_dpp v3, v1 row_mirror row_mask:0xf bank_mask:0xf
	s_and_saveexec_b64 s[0:1], vcc
	s_cbranch_execz .LBB0_1587
	v_add_f32_e32 v3, v1, v3
	v_ashrrev_i32_e32 v1, 31, v0
	v_lshl_add_u64 v[0:1], v[0:1], 2, s[10:11]
	global_atomic_add_f32 v[0:1], v3, off
;   __device__ __forceinline__ void tile(const float* reg, int row0, int col0, int lane) const {
;     rows4(reg, lane, [&](int it, int rr, int c4, float4 v) {
;       int row = row0 + rr, idx = row * 1024 + col0 + c4;
;       float4 xo = *(const float4*)(xold + idx);
;       v.x = fmaf(coef, v.x, xo.x); v.y = fmaf(coef, v.y, xo.y); v.z = fmaf(coef, v.z, xo.z); v.w = fmaf(coef, v.w, xo.w);
;       *(float4*)(xnew + idx) = v;
;       *(bf16x4*)(xb + idx) = pack4(v.x, v.y, v.z, v.w);
;       float s = row16_sum(v.x * v.x + v.y * v.y + v.z * v.z + v.w * v.w);
;       if ((lane & 15) == 0) atomicAdd(ssqn + row, s);
;     });
.LBB0_1587:
	s_or_b64 exec, exec, s[0:1]
	v_add_u32_e32 v0, v106, v2
	v_lshl_add_u32 v12, v0, 10, v128
	v_ashrrev_i32_e32 v13, 31, v12
	v_lshl_add_u64 v[14:15], v[12:13], 2, s[12:13]
	ds_read_b128 v[8:11], v98 offset:2176
	v_mov_b32_e32 v3, 0
	v_lshl_add_u64 v[12:13], v[12:13], 1, s[14:15]
	s_waitcnt vmcnt(17) lgkmcnt(0)
	v_mov_b32_e32 v4, v164
	v_mov_b32_e32 v5, v165
	v_mov_b32_e32 v6, v166
	v_mov_b32_e32 v7, v167
	v_pk_fma_f32 v[4:5], v[8:9], 0.5, v[4:5] op_sel_hi:[1,0,1]
	v_pk_fma_f32 v[6:7], v[10:11], 0.5, v[6:7] op_sel_hi:[1,0,1]
	global_store_dwordx4 v[14:15], v[4:7], off
	v_cvt_pk_bf16_f32 v8, v4, v5
	v_cvt_pk_bf16_f32 v9, v6, v7
	v_pk_mul_f32 v[4:5], v[4:5], v[4:5]
	v_pk_mul_f32 v[6:7], v[6:7], v[6:7]
	v_add_f32_e32 v1, v4, v5
	v_add_f32_e32 v1, v6, v1
	v_add_f32_e32 v1, v7, v1
	global_store_dwordx2 v[12:13], v[8:9], off
	s_nop 0
	v_add_f32_dpp v1, v1, v1 quad_perm:[1,0,3,2] row_mask:0xf bank_mask:0xf bound_ctrl:1
	s_nop 1
	v_add_f32_dpp v1, v1, v1 quad_perm:[2,3,0,1] row_mask:0xf bank_mask:0xf bound_ctrl:1
	s_nop 1
	v_add_f32_dpp v1, v1, v1 row_half_mirror row_mask:0xf bank_mask:0xf bound_ctrl:1
	s_nop 1
	v_mov_b32_dpp v3, v1 row_mirror row_mask:0xf bank_mask:0xf
	s_and_saveexec_b64 s[0:1], vcc
	s_cbranch_execz .LBB0_1589
	v_add_f32_e32 v3, v1, v3
	v_ashrrev_i32_e32 v1, 31, v0
	v_lshl_add_u64 v[0:1], v[0:1], 2, s[10:11]
	global_atomic_add_f32 v[0:1], v3, off
.LBB0_1589:
	s_or_b64 exec, exec, s[0:1]
	v_add_u32_e32 v0, v107, v2
	v_lshl_add_u32 v12, v0, 10, v128
	v_ashrrev_i32_e32 v13, 31, v12
	v_lshl_add_u64 v[14:15], v[12:13], 2, s[12:13]
	ds_read_b128 v[8:11], v98 offset:3264
	v_mov_b32_e32 v3, 0
	v_lshl_add_u64 v[12:13], v[12:13], 1, s[14:15]
	s_waitcnt vmcnt(19) lgkmcnt(0)
	v_mov_b32_e32 v4, v168
	v_mov_b32_e32 v5, v169
	v_mov_b32_e32 v6, v170
	v_mov_b32_e32 v7, v171
	v_pk_fma_f32 v[4:5], v[8:9], 0.5, v[4:5] op_sel_hi:[1,0,1]
	v_pk_fma_f32 v[6:7], v[10:11], 0.5, v[6:7] op_sel_hi:[1,0,1]
	global_store_dwordx4 v[14:15], v[4:7], off
	v_cvt_pk_bf16_f32 v8, v4, v5
	v_cvt_pk_bf16_f32 v9, v6, v7
	v_pk_mul_f32 v[4:5], v[4:5], v[4:5]
	v_pk_mul_f32 v[6:7], v[6:7], v[6:7]
	v_add_f32_e32 v1, v4, v5
	v_add_f32_e32 v1, v6, v1
	v_add_f32_e32 v1, v7, v1
	global_store_dwordx2 v[12:13], v[8:9], off
	s_nop 0
	v_add_f32_dpp v1, v1, v1 quad_perm:[1,0,3,2] row_mask:0xf bank_mask:0xf bound_ctrl:1
	s_nop 1
	v_add_f32_dpp v1, v1, v1 quad_perm:[2,3,0,1] row_mask:0xf bank_mask:0xf bound_ctrl:1
	s_nop 1
	v_add_f32_dpp v1, v1, v1 row_half_mirror row_mask:0xf bank_mask:0xf bound_ctrl:1
	s_nop 1
	v_mov_b32_dpp v3, v1 row_mirror row_mask:0xf bank_mask:0xf
	s_and_saveexec_b64 s[0:1], vcc
	s_cbranch_execz .LBB0_1591
	v_add_f32_e32 v3, v1, v3
	v_ashrrev_i32_e32 v1, 31, v0
	v_lshl_add_u64 v[0:1], v[0:1], 2, s[10:11]
	global_atomic_add_f32 v[0:1], v3, off
.LBB0_1591:
	s_or_b64 exec, exec, s[0:1]
	v_add_u32_e32 v0, v108, v2
	v_lshl_add_u32 v10, v0, 10, v128
	v_ashrrev_i32_e32 v11, 31, v10
	v_lshl_add_u64 v[12:13], v[10:11], 2, s[12:13]
	ds_read_b128 v[6:9], v98 offset:4352
	v_lshl_add_u64 v[10:11], v[10:11], 1, s[14:15]
	s_waitcnt vmcnt(21) lgkmcnt(0)
	v_mov_b32_e32 v2, v172
	v_mov_b32_e32 v3, v173
	v_mov_b32_e32 v4, v174
	v_mov_b32_e32 v5, v175
	v_pk_fma_f32 v[2:3], v[6:7], 0.5, v[2:3] op_sel_hi:[1,0,1]
	v_pk_fma_f32 v[4:5], v[8:9], 0.5, v[4:5] op_sel_hi:[1,0,1]
	global_store_dwordx4 v[12:13], v[2:5], off
	v_cvt_pk_bf16_f32 v6, v2, v3
	v_cvt_pk_bf16_f32 v7, v4, v5
	v_pk_mul_f32 v[2:3], v[2:3], v[2:3]
	v_pk_mul_f32 v[4:5], v[4:5], v[4:5]
	v_add_f32_e32 v1, v2, v3
	v_add_f32_e32 v1, v4, v1
	v_add_f32_e32 v1, v5, v1
	v_mov_b32_e32 v2, 0
	global_store_dwordx2 v[10:11], v[6:7], off
	v_add_f32_dpp v1, v1, v1 quad_perm:[1,0,3,2] row_mask:0xf bank_mask:0xf bound_ctrl:1
	s_nop 1
	v_add_f32_dpp v1, v1, v1 quad_perm:[2,3,0,1] row_mask:0xf bank_mask:0xf bound_ctrl:1
	s_nop 1
	v_add_f32_dpp v1, v1, v1 row_half_mirror row_mask:0xf bank_mask:0xf bound_ctrl:1
	s_nop 1
	v_mov_b32_dpp v2, v1 row_mirror row_mask:0xf bank_mask:0xf
	s_and_saveexec_b64 s[0:1], vcc
	s_cbranch_execz .LBB0_1524
	v_add_f32_e32 v2, v1, v2
	v_ashrrev_i32_e32 v1, 31, v0
	v_lshl_add_u64 v[0:1], v[0:1], 2, s[10:11]
	global_atomic_add_f32 v[0:1], v2, off
	s_branch .LBB0_1524

;   __device__ __forceinline__ void tile(const float* reg, int row0, int col0, int lane) const {
;     rows4(reg, lane, [&](int it, int rr, int c4, float4 v) {
;       int row = row0 + rr, idx = row * 1024 + col0 + c4;
;       float4 xo = *(const float4*)(xold + idx);
;       v.x = fmaf(coef, v.x, xo.x); v.y = fmaf(coef, v.y, xo.y); v.z = fmaf(coef, v.z, xo.z); v.w = fmaf(coef, v.w, xo.w);
;       *(float4*)(xnew + idx) = v;
;       *(bf16x4*)(xb + idx) = pack4(v.x, v.y, v.z, v.w);
;       float s = row16_sum(v.x * v.x + v.y * v.y + v.z * v.z + v.w * v.w);
;       if ((lane & 15) == 0) atomicAdd(ssqn + row, s);
;     });
; template <int MF, class Epi>
; __device__ __forceinline__ void staged_epilogue(f32x4 (&acc)[MF][4], int row0, int col0, const Epi& epi) {
;     ...
; #pragma unroll
;   for (int mp = 0; mp < MF / 2; ++mp) {
;     __builtin_amdgcn_sched_barrier(0);
; #pragma unroll
;     for (int mm = 0; mm < 2; ++mm)
; #pragma unroll
;       for (int n = 0; n < 4; ++n)
; #pragma unroll
;         for (int j = 0; j < 4; ++j) reg[(mm * 16 + fq * 4 + j) * 68 + n * 16 + fr] = acc[mp * 2 + mm][n][j];
;     __builtin_amdgcn_fence(__ATOMIC_ACQ_REL, "wavefront");
;     epi.tile(reg, row0 + mp * 32, col0, lane);
.LBB0_1759:
	v_mov_b32_e32 v131, v204
	v_mov_b32_e32 v130, v204
	s_nop 0
	v_lshrrev_b32_e32 v130, 6, v130
	v_mul_lo_u32 v130, v130, s61
	v_add_u32_e32 v136, 0x10000, v130
	v_lshrrev_b32_e32 v130, 2, v131
	v_and_b32_e32 v137, 15, v131
	v_and_b32_e32 v138, 12, v130
	v_bfe_u32 v130, v131, 4, 2
	v_lshlrev_b32_e32 v131, 2, v131
	v_and_b32_e32 v131, 60, v131
	v_lshl_or_b32 v139, v137, 2, v136
	v_lshl_or_b32 v136, v131, 2, v136
	v_add_u32_e32 v128, v131, v128
	v_cmp_eq_u32_e32 vcc, 0, v137
	v_mad_u32_u24 v140, v130, s62, v136
	v_mad_u32_u24 v131, v138, s62, v139
	ds_write2_b32 v131, v120, v124 offset1:16
	ds_write2_b32 v131, v121, v125 offset0:68 offset1:84
	ds_write2_b32 v131, v122, v126 offset0:136 offset1:152
	ds_write2_b32 v131, v123, v127 offset0:204 offset1:220
	ds_write2_b32 v131, v112, v116 offset0:32 offset1:48
	ds_write2_b32 v131, v113, v117 offset0:100 offset1:116
	ds_write2_b32 v131, v114, v118 offset0:168 offset1:184
	ds_write2_b32 v131, v115, v119 offset0:236 offset1:252
	v_add_u32_e32 v112, 0x1000, v131
	ds_write2_b32 v112, v104, v108 offset0:64 offset1:80
	ds_write2_b32 v112, v105, v109 offset0:132 offset1:148
	ds_write2_b32 v112, v106, v110 offset0:200 offset1:216
	v_add_u32_e32 v104, 0x1400, v131
	ds_write2_b32 v104, v107, v111 offset0:12 offset1:28
	ds_write2_b32 v112, v96, v100 offset0:96 offset1:112
	ds_write2_b32 v112, v97, v101 offset0:164 offset1:180
	ds_write2_b32 v112, v98, v102 offset0:232 offset1:248
	ds_write2_b32 v104, v99, v103 offset0:44 offset1:60
	v_add_u32_e32 v184, v130, v129
	v_lshl_add_u32 v176, v184, 10, v128
	v_ashrrev_i32_e32 v177, 31, v176
	v_lshl_add_u64 v[178:179], v[176:177], 2, s[12:13]
	global_load_dwordx4 v[144:147], v[178:179], off
	v_or_b32_e32 v185, 4, v130
	v_add_u32_e32 v184, v185, v129
	v_lshl_add_u32 v176, v184, 10, v128
	v_ashrrev_i32_e32 v177, 31, v176
	v_lshl_add_u64 v[178:179], v[176:177], 2, s[12:13]
	global_load_dwordx4 v[148:151], v[178:179], off
	v_or_b32_e32 v185, 8, v130
	v_add_u32_e32 v184, v185, v129
	v_lshl_add_u32 v176, v184, 10, v128
	v_ashrrev_i32_e32 v177, 31, v176
	v_lshl_add_u64 v[178:179], v[176:177], 2, s[12:13]
	global_load_dwordx4 v[152:155], v[178:179], off
	v_or_b32_e32 v185, 12, v130
	v_add_u32_e32 v184, v185, v129
	v_lshl_add_u32 v176, v184, 10, v128
	v_ashrrev_i32_e32 v177, 31, v176
	v_lshl_add_u64 v[178:179], v[176:177], 2, s[12:13]
	global_load_dwordx4 v[156:159], v[178:179], off
	v_or_b32_e32 v185, 16, v130
	v_add_u32_e32 v184, v185, v129
	v_lshl_add_u32 v176, v184, 10, v128
	v_ashrrev_i32_e32 v177, 31, v176
	v_lshl_add_u64 v[178:179], v[176:177], 2, s[12:13]
	global_load_dwordx4 v[160:163], v[178:179], off
	v_or_b32_e32 v185, 20, v130
	v_add_u32_e32 v184, v185, v129
	v_lshl_add_u32 v176, v184, 10, v128
	v_ashrrev_i32_e32 v177, 31, v176
	v_lshl_add_u64 v[178:179], v[176:177], 2, s[12:13]
	global_load_dwordx4 v[164:167], v[178:179], off
	v_or_b32_e32 v185, 24, v130
	v_add_u32_e32 v184, v185, v129
	v_lshl_add_u32 v176, v184, 10, v128
	v_ashrrev_i32_e32 v177, 31, v176
	v_lshl_add_u64 v[178:179], v[176:177], 2, s[12:13]
	global_load_dwordx4 v[168:171], v[178:179], off
	v_or_b32_e32 v185, 28, v130
	v_add_u32_e32 v184, v185, v129
	v_lshl_add_u32 v176, v184, 10, v128
	v_ashrrev_i32_e32 v177, 31, v176
	v_lshl_add_u64 v[178:179], v[176:177], 2, s[12:13]
	global_load_dwordx4 v[172:175], v[178:179], off
	v_add_u32_e32 v96, v130, v129
	v_lshl_add_u32 v102, v96, 10, v128
	v_ashrrev_i32_e32 v103, 31, v102
	v_lshl_add_u64 v[110:111], v[102:103], 2, s[12:13]
	s_waitcnt vmcnt(7)
	v_mov_b32_e32 v98, v144
	v_mov_b32_e32 v99, v145
	v_mov_b32_e32 v100, v146
	v_mov_b32_e32 v101, v147
	ds_read_b128 v[106:109], v140
	v_lshl_add_u64 v[102:103], v[102:103], 1, s[16:17]
	s_waitcnt lgkmcnt(0)
	v_pk_fma_f32 v[98:99], v[106:107], 0.5, v[98:99] op_sel_hi:[1,0,1]
	v_pk_fma_f32 v[100:101], v[108:109], 0.5, v[100:101] op_sel_hi:[1,0,1]
	global_store_dwordx4 v[110:111], v[98:101], off
	v_cvt_pk_bf16_f32 v106, v98, v99
	v_cvt_pk_bf16_f32 v107, v100, v101
	v_pk_mul_f32 v[98:99], v[98:99], v[98:99]
	v_pk_mul_f32 v[100:101], v[100:101], v[100:101]
	v_add_f32_e32 v97, v98, v99
	v_add_f32_e32 v97, v100, v97
	v_add_f32_e32 v97, v101, v97
	v_mov_b32_e32 v98, 0
	global_store_dwordx2 v[102:103], v[106:107], off
	v_add_f32_dpp v97, v97, v97 quad_perm:[1,0,3,2] row_mask:0xf bank_mask:0xf bound_ctrl:1
	s_nop 1
	v_add_f32_dpp v97, v97, v97 quad_perm:[2,3,0,1] row_mask:0xf bank_mask:0xf bound_ctrl:1
	s_nop 1
	v_add_f32_dpp v97, v97, v97 row_half_mirror row_mask:0xf bank_mask:0xf bound_ctrl:1
	s_nop 1
	v_mov_b32_dpp v98, v97 row_mirror row_mask:0xf bank_mask:0xf
	s_and_saveexec_b64 s[0:1], vcc
	s_cbranch_execz .LBB0_1761
	v_add_f32_e32 v98, v97, v98
	v_ashrrev_i32_e32 v97, 31, v96
	v_lshl_add_u64 v[96:97], v[96:97], 2, s[18:19]
	global_atomic_add_f32 v[96:97], v98, off
.LBB0_1761:
	s_or_b64 exec, exec, s[0:1]
	v_or_b32_e32 v99, 4, v130
	v_add_u32_e32 v96, v99, v129
	v_lshl_add_u32 v102, v96, 10, v128
	v_ashrrev_i32_e32 v103, 31, v102
	v_lshl_add_u64 v[106:107], v[102:103], 2, s[12:13]
	v_mul_u32_u24_e32 v109, 0x110, v130
	v_add_u32_e32 v98, 0x440, v109
	v_add_u32_e32 v100, v136, v98
	ds_read_b128 v[118:121], v100
	v_mov_b32_e32 v101, 0
	v_lshl_add_u64 v[102:103], v[102:103], 1, s[16:17]
	s_waitcnt vmcnt(9) lgkmcnt(0)
	v_mov_b32_e32 v114, v148
	v_mov_b32_e32 v115, v149
	v_mov_b32_e32 v116, v150
	v_mov_b32_e32 v117, v151
	v_pk_fma_f32 v[114:115], v[118:119], 0.5, v[114:115] op_sel_hi:[1,0,1]
	v_pk_fma_f32 v[116:117], v[120:121], 0.5, v[116:117] op_sel_hi:[1,0,1]
	v_pk_mul_f32 v[110:111], v[114:115], v[114:115]
	global_store_dwordx4 v[106:107], v[114:117], off
	v_cvt_pk_bf16_f32 v106, v114, v115
	v_add_f32_e32 v97, v110, v111
	v_pk_mul_f32 v[114:115], v[116:117], v[116:117]
	v_cvt_pk_bf16_f32 v107, v116, v117
	v_add_f32_e32 v97, v114, v97
	v_add_f32_e32 v97, v115, v97
	global_store_dwordx2 v[102:103], v[106:107], off
	s_nop 0
	v_add_f32_dpp v97, v97, v97 quad_perm:[1,0,3,2] row_mask:0xf bank_mask:0xf bound_ctrl:1
	s_nop 1
	v_add_f32_dpp v97, v97, v97 quad_perm:[2,3,0,1] row_mask:0xf bank_mask:0xf bound_ctrl:1
	s_nop 1
	v_add_f32_dpp v97, v97, v97 row_half_mirror row_mask:0xf bank_mask:0xf bound_ctrl:1
	s_nop 1
	v_mov_b32_dpp v101, v97 row_mirror row_mask:0xf bank_mask:0xf
	s_and_saveexec_b64 s[0:1], vcc
	s_cbranch_execz .LBB0_1763
	v_add_f32_e32 v101, v97, v101
	v_ashrrev_i32_e32 v97, 31, v96
	v_lshl_add_u64 v[96:97], v[96:97], 2, s[18:19]
	global_atomic_add_f32 v[96:97], v101, off
;   __device__ __forceinline__ void tile(const float* reg, int row0, int col0, int lane) const {
;     rows4(reg, lane, [&](int it, int rr, int c4, float4 v) {
;       int row = row0 + rr, idx = row * 1024 + col0 + c4;
;       float4 xo = *(const float4*)(xold + idx);
;       v.x = fmaf(coef, v.x, xo.x); v.y = fmaf(coef, v.y, xo.y); v.z = fmaf(coef, v.z, xo.z); v.w = fmaf(coef, v.w, xo.w);
;       *(float4*)(xnew + idx) = v;
;       *(bf16x4*)(xb + idx) = pack4(v.x, v.y, v.z, v.w);
;       float s = row16_sum(v.x * v.x + v.y * v.y + v.z * v.z + v.w * v.w);
;       if ((lane & 15) == 0) atomicAdd(ssqn + row, s);
;     });
.LBB0_1763:
	s_or_b64 exec, exec, s[0:1]
	v_or_b32_e32 v101, 8, v130
	v_add_u32_e32 v96, v101, v129
	v_lshl_add_u32 v106, v96, 10, v128
	v_ashrrev_i32_e32 v107, 31, v106
	v_lshl_add_u64 v[110:111], v[106:107], 2, s[12:13]
	v_add_u32_e32 v98, 0x440, v98
	v_add_u32_e32 v102, v136, v98
	ds_read_b128 v[118:121], v102
	v_mov_b32_e32 v103, 0
	v_lshl_add_u64 v[106:107], v[106:107], 1, s[16:17]
	s_waitcnt vmcnt(11) lgkmcnt(0)
	v_mov_b32_e32 v114, v152
	v_mov_b32_e32 v115, v153
	v_mov_b32_e32 v116, v154
	v_mov_b32_e32 v117, v155
	v_pk_fma_f32 v[114:115], v[118:119], 0.5, v[114:115] op_sel_hi:[1,0,1]
	v_pk_fma_f32 v[116:117], v[120:121], 0.5, v[116:117] op_sel_hi:[1,0,1]
	global_store_dwordx4 v[110:111], v[114:117], off
	v_cvt_pk_bf16_f32 v110, v114, v115
	v_cvt_pk_bf16_f32 v111, v116, v117
	v_pk_mul_f32 v[114:115], v[114:115], v[114:115]
	v_pk_mul_f32 v[116:117], v[116:117], v[116:117]
	v_add_f32_e32 v97, v114, v115
	v_add_f32_e32 v97, v116, v97
	v_add_f32_e32 v97, v117, v97
	global_store_dwordx2 v[106:107], v[110:111], off
	s_nop 0
	v_add_f32_dpp v97, v97, v97 quad_perm:[1,0,3,2] row_mask:0xf bank_mask:0xf bound_ctrl:1
	s_nop 1
	v_add_f32_dpp v97, v97, v97 quad_perm:[2,3,0,1] row_mask:0xf bank_mask:0xf bound_ctrl:1
	s_nop 1
	v_add_f32_dpp v97, v97, v97 row_half_mirror row_mask:0xf bank_mask:0xf bound_ctrl:1
	s_nop 1
	v_mov_b32_dpp v103, v97 row_mirror row_mask:0xf bank_mask:0xf
	s_and_saveexec_b64 s[0:1], vcc
	s_cbranch_execz .LBB0_1765
	v_add_f32_e32 v103, v97, v103
	v_ashrrev_i32_e32 v97, 31, v96
	v_lshl_add_u64 v[96:97], v[96:97], 2, s[18:19]
	global_atomic_add_f32 v[96:97], v103, off
.LBB0_1765:
	s_or_b64 exec, exec, s[0:1]
	v_or_b32_e32 v103, 12, v130
	v_add_u32_e32 v96, v103, v129
	v_lshl_add_u32 v106, v96, 10, v128
	v_ashrrev_i32_e32 v107, 31, v106
	v_lshl_add_u64 v[110:111], v[106:107], 2, s[12:13]
	v_add_u32_e32 v97, 0x440, v98
	v_add_u32_e32 v98, v136, v97
	ds_read_b128 v[118:121], v98
	v_mov_b32_e32 v105, 0
	v_lshl_add_u64 v[106:107], v[106:107], 1, s[16:17]
	s_waitcnt vmcnt(13) lgkmcnt(0)
	v_mov_b32_e32 v114, v156
	v_mov_b32_e32 v115, v157
	v_mov_b32_e32 v116, v158
	v_mov_b32_e32 v117, v159
	v_pk_fma_f32 v[114:115], v[118:119], 0.5, v[114:115] op_sel_hi:[1,0,1]
	v_pk_fma_f32 v[116:117], v[120:121], 0.5, v[116:117] op_sel_hi:[1,0,1]
	global_store_dwordx4 v[110:111], v[114:117], off
	v_cvt_pk_bf16_f32 v110, v114, v115
	v_cvt_pk_bf16_f32 v111, v116, v117
	v_pk_mul_f32 v[114:115], v[114:115], v[114:115]
	v_pk_mul_f32 v[116:117], v[116:117], v[116:117]
	v_add_f32_e32 v97, v114, v115
	v_add_f32_e32 v97, v116, v97
	v_add_f32_e32 v97, v117, v97
	global_store_dwordx2 v[106:107], v[110:111], off
	s_nop 0
	v_add_f32_dpp v97, v97, v97 quad_perm:[1,0,3,2] row_mask:0xf bank_mask:0xf bound_ctrl:1
	s_nop 1
	v_add_f32_dpp v97, v97, v97 quad_perm:[2,3,0,1] row_mask:0xf bank_mask:0xf bound_ctrl:1
	s_nop 1
	v_add_f32_dpp v97, v97, v97 row_half_mirror row_mask:0xf bank_mask:0xf bound_ctrl:1
	s_nop 1
	v_mov_b32_dpp v105, v97 row_mirror row_mask:0xf bank_mask:0xf
	s_and_saveexec_b64 s[0:1], vcc
	s_cbranch_execz .LBB0_1767
	v_add_f32_e32 v105, v97, v105
	v_ashrrev_i32_e32 v97, 31, v96
	v_lshl_add_u64 v[96:97], v[96:97], 2, s[18:19]
	global_atomic_add_f32 v[96:97], v105, off
.LBB0_1767:
	s_or_b64 exec, exec, s[0:1]
	v_or_b32_e32 v105, 16, v130
	v_add_u32_e32 v96, v105, v129
	v_lshl_add_u32 v106, v96, 10, v128
	v_ashrrev_i32_e32 v107, 31, v106
	v_lshl_add_u64 v[110:111], v[106:107], 2, s[12:13]
	ds_read_b128 v[118:121], v98 offset:1088
	v_lshl_add_u64 v[106:107], v[106:107], 1, s[16:17]
	s_waitcnt vmcnt(15) lgkmcnt(0)
	v_mov_b32_e32 v114, v160
	v_mov_b32_e32 v115, v161
	v_mov_b32_e32 v116, v162
	v_mov_b32_e32 v117, v163
	v_pk_fma_f32 v[114:115], v[118:119], 0.5, v[114:115] op_sel_hi:[1,0,1]
	v_pk_fma_f32 v[116:117], v[120:121], 0.5, v[116:117] op_sel_hi:[1,0,1]
	global_store_dwordx4 v[110:111], v[114:117], off
	v_cvt_pk_bf16_f32 v110, v114, v115
	v_cvt_pk_bf16_f32 v111, v116, v117
	v_pk_mul_f32 v[114:115], v[114:115], v[114:115]
	v_pk_mul_f32 v[116:117], v[116:117], v[116:117]
	v_add_f32_e32 v97, v114, v115
	v_add_f32_e32 v97, v116, v97
	v_add_f32_e32 v97, v117, v97
	global_store_dwordx2 v[106:107], v[110:111], off
	v_mov_b32_e32 v106, 0
	v_add_f32_dpp v97, v97, v97 quad_perm:[1,0,3,2] row_mask:0xf bank_mask:0xf bound_ctrl:1
	s_nop 1
	v_add_f32_dpp v97, v97, v97 quad_perm:[2,3,0,1] row_mask:0xf bank_mask:0xf bound_ctrl:1
	s_nop 1
	v_add_f32_dpp v97, v97, v97 row_half_mirror row_mask:0xf bank_mask:0xf bound_ctrl:1
	s_nop 1
	v_mov_b32_dpp v106, v97 row_mirror row_mask:0xf bank_mask:0xf
	s_and_saveexec_b64 s[0:1], vcc
	s_cbranch_execz .LBB0_1769
	v_add_f32_e32 v106, v97, v106
	v_ashrrev_i32_e32 v97, 31, v96
	v_lshl_add_u64 v[96:97], v[96:97], 2, s[18:19]
	global_atomic_add_f32 v[96:97], v106, off
.LBB0_1769:
	s_or_b64 exec, exec, s[0:1]
	v_or_b32_e32 v106, 20, v130
	v_add_u32_e32 v96, v106, v129
	v_lshl_add_u32 v110, v96, 10, v128
	v_ashrrev_i32_e32 v111, 31, v110
	v_lshl_add_u64 v[122:123], v[110:111], 2, s[12:13]
	ds_read_b128 v[118:121], v98 offset:2176
	v_mov_b32_e32 v107, 0
	v_lshl_add_u64 v[110:111], v[110:111], 1, s[16:17]
	s_waitcnt vmcnt(17) lgkmcnt(0)
	v_mov_b32_e32 v114, v164
	v_mov_b32_e32 v115, v165
	v_mov_b32_e32 v116, v166
	v_mov_b32_e32 v117, v167
	v_pk_fma_f32 v[114:115], v[118:119], 0.5, v[114:115] op_sel_hi:[1,0,1]
	v_pk_fma_f32 v[116:117], v[120:121], 0.5, v[116:117] op_sel_hi:[1,0,1]
	global_store_dwordx4 v[122:123], v[114:117], off
	v_cvt_pk_bf16_f32 v118, v114, v115
	v_cvt_pk_bf16_f32 v119, v116, v117
	v_pk_mul_f32 v[114:115], v[114:115], v[114:115]
	v_pk_mul_f32 v[116:117], v[116:117], v[116:117]
	v_add_f32_e32 v97, v114, v115
	v_add_f32_e32 v97, v116, v97
	v_add_f32_e32 v97, v117, v97
	global_store_dwordx2 v[110:111], v[118:119], off
	s_nop 0
	v_add_f32_dpp v97, v97, v97 quad_perm:[1,0,3,2] row_mask:0xf bank_mask:0xf bound_ctrl:1
	s_nop 1
	v_add_f32_dpp v97, v97, v97 quad_perm:[2,3,0,1] row_mask:0xf bank_mask:0xf bound_ctrl:1
	s_nop 1
	v_add_f32_dpp v97, v97, v97 row_half_mirror row_mask:0xf bank_mask:0xf bound_ctrl:1
	s_nop 1
	v_mov_b32_dpp v107, v97 row_mirror row_mask:0xf bank_mask:0xf
	s_and_saveexec_b64 s[0:1], vcc
	s_cbranch_execz .LBB0_1771
	v_add_f32_e32 v107, v97, v107
	v_ashrrev_i32_e32 v97, 31, v96
	v_lshl_add_u64 v[96:97], v[96:97], 2, s[18:19]
	global_atomic_add_f32 v[96:97], v107, off
;   __device__ __forceinline__ void tile(const float* reg, int row0, int col0, int lane) const {
;     rows4(reg, lane, [&](int it, int rr, int c4, float4 v) {
;       int row = row0 + rr, idx = row * 1024 + col0 + c4;
;       float4 xo = *(const float4*)(xold + idx);
;       v.x = fmaf(coef, v.x, xo.x); v.y = fmaf(coef, v.y, xo.y); v.z = fmaf(coef, v.z, xo.z); v.w = fmaf(coef, v.w, xo.w);
;       *(float4*)(xnew + idx) = v;
;       *(bf16x4*)(xb + idx) = pack4(v.x, v.y, v.z, v.w);
;       float s = row16_sum(v.x * v.x + v.y * v.y + v.z * v.z + v.w * v.w);
;       if ((lane & 15) == 0) atomicAdd(ssqn + row, s);
;     });
; template <int MF, class Epi>
; __device__ __forceinline__ void staged_epilogue(f32x4 (&acc)[MF][4], int row0, int col0, const Epi& epi) {
;     ...
; #pragma unroll
;   for (int mp = 0; mp < MF / 2; ++mp) {
;     __builtin_amdgcn_sched_barrier(0);
; #pragma unroll
;     for (int mm = 0; mm < 2; ++mm)
; #pragma unroll
;       for (int n = 0; n < 4; ++n)
; #pragma unroll
;         for (int j = 0; j < 4; ++j) reg[(mm * 16 + fq * 4 + j) * 68 + n * 16 + fr] = acc[mp * 2 + mm][n][j];
;     __builtin_amdgcn_fence(__ATOMIC_ACQ_REL, "wavefront");
;     epi.tile(reg, row0 + mp * 32, col0, lane);
.LBB0_1771:
	s_or_b64 exec, exec, s[0:1]
	v_or_b32_e32 v107, 24, v130
	v_add_u32_e32 v96, v107, v129
	v_lshl_add_u32 v110, v96, 10, v128
	v_ashrrev_i32_e32 v111, 31, v110
	v_lshl_add_u64 v[122:123], v[110:111], 2, s[12:13]
	ds_read_b128 v[118:121], v98 offset:3264
	v_mov_b32_e32 v108, 0
	v_lshl_add_u64 v[110:111], v[110:111], 1, s[16:17]
	s_waitcnt vmcnt(19) lgkmcnt(0)
	v_mov_b32_e32 v114, v168
	v_mov_b32_e32 v115, v169
	v_mov_b32_e32 v116, v170
	v_mov_b32_e32 v117, v171
	v_pk_fma_f32 v[114:115], v[118:119], 0.5, v[114:115] op_sel_hi:[1,0,1]
	v_pk_fma_f32 v[116:117], v[120:121], 0.5, v[116:117] op_sel_hi:[1,0,1]
	global_store_dwordx4 v[122:123], v[114:117], off
	v_cvt_pk_bf16_f32 v118, v114, v115
	v_cvt_pk_bf16_f32 v119, v116, v117
	v_pk_mul_f32 v[114:115], v[114:115], v[114:115]
	v_pk_mul_f32 v[116:117], v[116:117], v[116:117]
	v_add_f32_e32 v97, v114, v115
	v_add_f32_e32 v97, v116, v97
	v_add_f32_e32 v97, v117, v97
	global_store_dwordx2 v[110:111], v[118:119], off
	s_nop 0
	v_add_f32_dpp v97, v97, v97 quad_perm:[1,0,3,2] row_mask:0xf bank_mask:0xf bound_ctrl:1
	s_nop 1
	v_add_f32_dpp v97, v97, v97 quad_perm:[2,3,0,1] row_mask:0xf bank_mask:0xf bound_ctrl:1
	s_nop 1
	v_add_f32_dpp v97, v97, v97 row_half_mirror row_mask:0xf bank_mask:0xf bound_ctrl:1
	s_nop 1
	v_mov_b32_dpp v108, v97 row_mirror row_mask:0xf bank_mask:0xf
	s_and_saveexec_b64 s[0:1], vcc
	s_cbranch_execz .LBB0_1773
	v_add_f32_e32 v108, v97, v108
	v_ashrrev_i32_e32 v97, 31, v96
	v_lshl_add_u64 v[96:97], v[96:97], 2, s[18:19]
	global_atomic_add_f32 v[96:97], v108, off
.LBB0_1773:
	s_or_b64 exec, exec, s[0:1]
	v_or_b32_e32 v108, 28, v130
	v_add_u32_e32 v96, v108, v129
	v_lshl_add_u32 v110, v96, 10, v128
	v_ashrrev_i32_e32 v111, 31, v110
	v_lshl_add_u64 v[122:123], v[110:111], 2, s[12:13]
	ds_read_b128 v[118:121], v98 offset:4352
	v_lshl_add_u64 v[110:111], v[110:111], 1, s[16:17]
	s_waitcnt vmcnt(21) lgkmcnt(0)
	v_mov_b32_e32 v114, v172
	v_mov_b32_e32 v115, v173
	v_mov_b32_e32 v116, v174
	v_mov_b32_e32 v117, v175
	v_pk_fma_f32 v[114:115], v[118:119], 0.5, v[114:115] op_sel_hi:[1,0,1]
	v_pk_fma_f32 v[116:117], v[120:121], 0.5, v[116:117] op_sel_hi:[1,0,1]
	global_store_dwordx4 v[122:123], v[114:117], off
	v_cvt_pk_bf16_f32 v118, v114, v115
	v_cvt_pk_bf16_f32 v119, v116, v117
	v_pk_mul_f32 v[114:115], v[114:115], v[114:115]
	v_pk_mul_f32 v[116:117], v[116:117], v[116:117]
	v_add_f32_e32 v97, v114, v115
	v_add_f32_e32 v97, v116, v97
	v_add_f32_e32 v97, v117, v97
	global_store_dwordx2 v[110:111], v[118:119], off
	v_mov_b32_e32 v110, 0
	v_add_f32_dpp v97, v97, v97 quad_perm:[1,0,3,2] row_mask:0xf bank_mask:0xf bound_ctrl:1
	s_nop 1
	v_add_f32_dpp v97, v97, v97 quad_perm:[2,3,0,1] row_mask:0xf bank_mask:0xf bound_ctrl:1
	s_nop 1
	v_add_f32_dpp v97, v97, v97 row_half_mirror row_mask:0xf bank_mask:0xf bound_ctrl:1
	s_nop 1
	v_mov_b32_dpp v110, v97 row_mirror row_mask:0xf bank_mask:0xf
	s_and_saveexec_b64 s[0:1], vcc
	s_cbranch_execz .LBB0_1775
	v_add_f32_e32 v110, v97, v110
	v_ashrrev_i32_e32 v97, 31, v96
	v_lshl_add_u64 v[96:97], v[96:97], 2, s[18:19]
	global_atomic_add_f32 v[96:97], v110, off
.LBB0_1775:
	s_or_b64 exec, exec, s[0:1]
	ds_write2_b32 v131, v88, v92 offset1:16
	ds_write2_b32 v131, v89, v93 offset0:68 offset1:84
	ds_write2_b32 v131, v90, v94 offset0:136 offset1:152
	ds_write2_b32 v131, v91, v95 offset0:204 offset1:220
	ds_write2_b32 v131, v80, v84 offset0:32 offset1:48
	ds_write2_b32 v131, v81, v85 offset0:100 offset1:116
	ds_write2_b32 v131, v82, v86 offset0:168 offset1:184
	ds_write2_b32 v131, v83, v87 offset0:236 offset1:252
	ds_write2_b32 v112, v72, v76 offset0:64 offset1:80
	ds_write2_b32 v112, v73, v77 offset0:132 offset1:148
	ds_write2_b32 v112, v74, v78 offset0:200 offset1:216
	ds_write2_b32 v104, v75, v79 offset0:12 offset1:28
	ds_write2_b32 v112, v64, v68 offset0:96 offset1:112
	ds_write2_b32 v112, v65, v69 offset0:164 offset1:180
	ds_write2_b32 v112, v66, v70 offset0:232 offset1:248
	ds_write2_b32 v104, v67, v71 offset0:44 offset1:60
	v_add_u32_e32 v185, 32, v129
	v_add_u32_e32 v184, v130, v185
	v_lshl_add_u32 v176, v184, 10, v128
	v_ashrrev_i32_e32 v177, 31, v176
	v_lshl_add_u64 v[178:179], v[176:177], 2, s[12:13]
	global_load_dwordx4 v[144:147], v[178:179], off
	v_add_u32_e32 v185, 32, v129
	v_add_u32_e32 v184, v99, v185
	v_lshl_add_u32 v176, v184, 10, v128
	v_ashrrev_i32_e32 v177, 31, v176
	v_lshl_add_u64 v[178:179], v[176:177], 2, s[12:13]
	global_load_dwordx4 v[148:151], v[178:179], off
	v_add_u32_e32 v185, 32, v129
	v_add_u32_e32 v184, v101, v185
	v_lshl_add_u32 v176, v184, 10, v128
	v_ashrrev_i32_e32 v177, 31, v176
	v_lshl_add_u64 v[178:179], v[176:177], 2, s[12:13]
	global_load_dwordx4 v[152:155], v[178:179], off
	v_add_u32_e32 v185, 32, v129
	v_add_u32_e32 v184, v103, v185
	v_lshl_add_u32 v176, v184, 10, v128
	v_ashrrev_i32_e32 v177, 31, v176
	v_lshl_add_u64 v[178:179], v[176:177], 2, s[12:13]
	global_load_dwordx4 v[156:159], v[178:179], off
	v_add_u32_e32 v185, 32, v129
	v_add_u32_e32 v184, v105, v185
	v_lshl_add_u32 v176, v184, 10, v128
	v_ashrrev_i32_e32 v177, 31, v176
	v_lshl_add_u64 v[178:179], v[176:177], 2, s[12:13]
	global_load_dwordx4 v[160:163], v[178:179], off
	v_add_u32_e32 v185, 32, v129
	v_add_u32_e32 v184, v106, v185
	v_lshl_add_u32 v176, v184, 10, v128
	v_ashrrev_i32_e32 v177, 31, v176
	v_lshl_add_u64 v[178:179], v[176:177], 2, s[12:13]
	global_load_dwordx4 v[164:167], v[178:179], off
	v_add_u32_e32 v185, 32, v129
	v_add_u32_e32 v184, v107, v185
	v_lshl_add_u32 v176, v184, 10, v128
	v_ashrrev_i32_e32 v177, 31, v176
	v_lshl_add_u64 v[178:179], v[176:177], 2, s[12:13]
	global_load_dwordx4 v[168:171], v[178:179], off
	v_add_u32_e32 v185, 32, v129
	v_add_u32_e32 v184, v108, v185
	v_lshl_add_u32 v176, v184, 10, v128
	v_ashrrev_i32_e32 v177, 31, v176
	v_lshl_add_u64 v[178:179], v[176:177], 2, s[12:13]
	global_load_dwordx4 v[172:175], v[178:179], off
	v_add_u32_e32 v67, 32, v129
	v_add_u32_e32 v64, v130, v67
	v_lshl_add_u32 v76, v64, 10, v128
	v_ashrrev_i32_e32 v77, 31, v76
	v_lshl_add_u64 v[78:79], v[76:77], 2, s[12:13]
	v_add_u32_e32 v66, v136, v109
	ds_read_b128 v[72:75], v66
	v_lshl_add_u64 v[76:77], v[76:77], 1, s[16:17]
	s_waitcnt vmcnt(7) lgkmcnt(0)
;   __device__ __forceinline__ void tile(const float* reg, int row0, int col0, int lane) const {
;     rows4(reg, lane, [&](int it, int rr, int c4, float4 v) {
;       int row = row0 + rr, idx = row * 1024 + col0 + c4;
;       float4 xo = *(const float4*)(xold + idx);
;       v.x = fmaf(coef, v.x, xo.x); v.y = fmaf(coef, v.y, xo.y); v.z = fmaf(coef, v.z, xo.z); v.w = fmaf(coef, v.w, xo.w);
;       *(float4*)(xnew + idx) = v;
;       *(bf16x4*)(xb + idx) = pack4(v.x, v.y, v.z, v.w);
;       float s = row16_sum(v.x * v.x + v.y * v.y + v.z * v.z + v.w * v.w);
;       if ((lane & 15) == 0) atomicAdd(ssqn + row, s);
;     });
	v_mov_b32_e32 v68, v144
	v_mov_b32_e32 v69, v145
	v_mov_b32_e32 v70, v146
	v_mov_b32_e32 v71, v147
	v_pk_fma_f32 v[68:69], v[72:73], 0.5, v[68:69] op_sel_hi:[1,0,1]
	v_pk_fma_f32 v[70:71], v[74:75], 0.5, v[70:71] op_sel_hi:[1,0,1]
	global_store_dwordx4 v[78:79], v[68:71], off
	v_cvt_pk_bf16_f32 v72, v68, v69
	v_cvt_pk_bf16_f32 v73, v70, v71
	v_pk_mul_f32 v[68:69], v[68:69], v[68:69]
	v_pk_mul_f32 v[70:71], v[70:71], v[70:71]
	v_add_f32_e32 v65, v68, v69
	v_add_f32_e32 v65, v70, v65
	v_add_f32_e32 v65, v71, v65
	v_mov_b32_e32 v68, 0
	global_store_dwordx2 v[76:77], v[72:73], off
	v_add_f32_dpp v65, v65, v65 quad_perm:[1,0,3,2] row_mask:0xf bank_mask:0xf bound_ctrl:1
	s_nop 1
	v_add_f32_dpp v65, v65, v65 quad_perm:[2,3,0,1] row_mask:0xf bank_mask:0xf bound_ctrl:1
	s_nop 1
	v_add_f32_dpp v65, v65, v65 row_half_mirror row_mask:0xf bank_mask:0xf bound_ctrl:1
	s_nop 1
	v_mov_b32_dpp v68, v65 row_mirror row_mask:0xf bank_mask:0xf
	s_and_saveexec_b64 s[0:1], vcc
	s_cbranch_execz .LBB0_1777
	v_add_f32_e32 v68, v65, v68
	v_ashrrev_i32_e32 v65, 31, v64
	v_lshl_add_u64 v[64:65], v[64:65], 2, s[18:19]
	global_atomic_add_f32 v[64:65], v68, off
.LBB0_1777:
	s_or_b64 exec, exec, s[0:1]
	v_add_u32_e32 v64, v99, v67
	v_lshl_add_u32 v76, v64, 10, v128
	v_ashrrev_i32_e32 v77, 31, v76
	v_lshl_add_u64 v[78:79], v[76:77], 2, s[12:13]
	ds_read_b128 v[72:75], v100
	v_lshl_add_u64 v[76:77], v[76:77], 1, s[16:17]
	s_waitcnt vmcnt(9) lgkmcnt(0)
	v_mov_b32_e32 v68, v148
	v_mov_b32_e32 v69, v149
	v_mov_b32_e32 v70, v150
	v_mov_b32_e32 v71, v151
	v_pk_fma_f32 v[68:69], v[72:73], 0.5, v[68:69] op_sel_hi:[1,0,1]
	v_pk_fma_f32 v[70:71], v[74:75], 0.5, v[70:71] op_sel_hi:[1,0,1]
	global_store_dwordx4 v[78:79], v[68:71], off
	v_cvt_pk_bf16_f32 v72, v68, v69
	v_cvt_pk_bf16_f32 v73, v70, v71
	v_pk_mul_f32 v[68:69], v[68:69], v[68:69]
	v_pk_mul_f32 v[70:71], v[70:71], v[70:71]
	v_add_f32_e32 v65, v68, v69
	v_add_f32_e32 v65, v70, v65
	v_add_f32_e32 v65, v71, v65
	v_mov_b32_e32 v68, 0
	global_store_dwordx2 v[76:77], v[72:73], off
	v_add_f32_dpp v65, v65, v65 quad_perm:[1,0,3,2] row_mask:0xf bank_mask:0xf bound_ctrl:1
	s_nop 1
	v_add_f32_dpp v65, v65, v65 quad_perm:[2,3,0,1] row_mask:0xf bank_mask:0xf bound_ctrl:1
	s_nop 1
	v_add_f32_dpp v65, v65, v65 row_half_mirror row_mask:0xf bank_mask:0xf bound_ctrl:1
	s_nop 1
	v_mov_b32_dpp v68, v65 row_mirror row_mask:0xf bank_mask:0xf
	s_and_saveexec_b64 s[0:1], vcc
	s_cbranch_execz .LBB0_1779
	v_add_f32_e32 v68, v65, v68
	v_ashrrev_i32_e32 v65, 31, v64
	v_lshl_add_u64 v[64:65], v[64:65], 2, s[18:19]
	global_atomic_add_f32 v[64:65], v68, off
.LBB0_1779:
	s_or_b64 exec, exec, s[0:1]
	v_add_u32_e32 v64, v101, v67
	v_lshl_add_u32 v76, v64, 10, v128
	v_ashrrev_i32_e32 v77, 31, v76
	v_lshl_add_u64 v[78:79], v[76:77], 2, s[12:13]
	ds_read_b128 v[72:75], v102
	v_lshl_add_u64 v[76:77], v[76:77], 1, s[16:17]
	s_waitcnt vmcnt(11) lgkmcnt(0)
	v_mov_b32_e32 v68, v152
	v_mov_b32_e32 v69, v153
	v_mov_b32_e32 v70, v154
	v_mov_b32_e32 v71, v155
	v_pk_fma_f32 v[68:69], v[72:73], 0.5, v[68:69] op_sel_hi:[1,0,1]
	v_pk_fma_f32 v[70:71], v[74:75], 0.5, v[70:71] op_sel_hi:[1,0,1]
	global_store_dwordx4 v[78:79], v[68:71], off
	v_cvt_pk_bf16_f32 v72, v68, v69
	v_cvt_pk_bf16_f32 v73, v70, v71
	v_pk_mul_f32 v[68:69], v[68:69], v[68:69]
	v_pk_mul_f32 v[70:71], v[70:71], v[70:71]
	v_add_f32_e32 v65, v68, v69
	v_add_f32_e32 v65, v70, v65
	v_add_f32_e32 v65, v71, v65
	v_mov_b32_e32 v68, 0
	global_store_dwordx2 v[76:77], v[72:73], off
	v_add_f32_dpp v65, v65, v65 quad_perm:[1,0,3,2] row_mask:0xf bank_mask:0xf bound_ctrl:1
	s_nop 1
	v_add_f32_dpp v65, v65, v65 quad_perm:[2,3,0,1] row_mask:0xf bank_mask:0xf bound_ctrl:1
	s_nop 1
	v_add_f32_dpp v65, v65, v65 row_half_mirror row_mask:0xf bank_mask:0xf bound_ctrl:1
	s_nop 1
	v_mov_b32_dpp v68, v65 row_mirror row_mask:0xf bank_mask:0xf
	s_and_saveexec_b64 s[0:1], vcc
	s_cbranch_execz .LBB0_1781
	v_add_f32_e32 v68, v65, v68
	v_ashrrev_i32_e32 v65, 31, v64
	v_lshl_add_u64 v[64:65], v[64:65], 2, s[18:19]
	global_atomic_add_f32 v[64:65], v68, off
.LBB0_1781:
	s_or_b64 exec, exec, s[0:1]
	v_add_u32_e32 v64, v103, v67
	v_lshl_add_u32 v76, v64, 10, v128
	v_ashrrev_i32_e32 v77, 31, v76
	v_lshl_add_u64 v[78:79], v[76:77], 2, s[12:13]
	ds_read_b128 v[72:75], v98
	v_lshl_add_u64 v[76:77], v[76:77], 1, s[16:17]
	s_waitcnt vmcnt(13) lgkmcnt(0)
	v_mov_b32_e32 v68, v156
	v_mov_b32_e32 v69, v157
	v_mov_b32_e32 v70, v158
	v_mov_b32_e32 v71, v159
	v_pk_fma_f32 v[68:69], v[72:73], 0.5, v[68:69] op_sel_hi:[1,0,1]
	v_pk_fma_f32 v[70:71], v[74:75], 0.5, v[70:71] op_sel_hi:[1,0,1]
	global_store_dwordx4 v[78:79], v[68:71], off
	v_cvt_pk_bf16_f32 v72, v68, v69
	v_cvt_pk_bf16_f32 v73, v70, v71
	v_pk_mul_f32 v[68:69], v[68:69], v[68:69]
	v_pk_mul_f32 v[70:71], v[70:71], v[70:71]
	v_add_f32_e32 v65, v68, v69
	v_add_f32_e32 v65, v70, v65
	v_add_f32_e32 v65, v71, v65
	v_mov_b32_e32 v68, 0
	global_store_dwordx2 v[76:77], v[72:73], off
	v_add_f32_dpp v65, v65, v65 quad_perm:[1,0,3,2] row_mask:0xf bank_mask:0xf bound_ctrl:1
	s_nop 1
	v_add_f32_dpp v65, v65, v65 quad_perm:[2,3,0,1] row_mask:0xf bank_mask:0xf bound_ctrl:1
	s_nop 1
	v_add_f32_dpp v65, v65, v65 row_half_mirror row_mask:0xf bank_mask:0xf bound_ctrl:1
	s_nop 1
	v_mov_b32_dpp v68, v65 row_mirror row_mask:0xf bank_mask:0xf
	s_and_saveexec_b64 s[0:1], vcc
	s_cbranch_execz .LBB0_1783
	v_add_f32_e32 v68, v65, v68
	v_ashrrev_i32_e32 v65, 31, v64
	v_lshl_add_u64 v[64:65], v[64:65], 2, s[18:19]
	global_atomic_add_f32 v[64:65], v68, off
;   __device__ __forceinline__ void tile(const float* reg, int row0, int col0, int lane) const {
;     rows4(reg, lane, [&](int it, int rr, int c4, float4 v) {
;       int row = row0 + rr, idx = row * 1024 + col0 + c4;
;       float4 xo = *(const float4*)(xold + idx);
;       v.x = fmaf(coef, v.x, xo.x); v.y = fmaf(coef, v.y, xo.y); v.z = fmaf(coef, v.z, xo.z); v.w = fmaf(coef, v.w, xo.w);
;       *(float4*)(xnew + idx) = v;
;       *(bf16x4*)(xb + idx) = pack4(v.x, v.y, v.z, v.w);
;       float s = row16_sum(v.x * v.x + v.y * v.y + v.z * v.z + v.w * v.w);
;       if ((lane & 15) == 0) atomicAdd(ssqn + row, s);
;     });
.LBB0_1783:
	s_or_b64 exec, exec, s[0:1]
	v_add_u32_e32 v64, v105, v67
	v_lshl_add_u32 v76, v64, 10, v128
	v_ashrrev_i32_e32 v77, 31, v76
	v_lshl_add_u64 v[78:79], v[76:77], 2, s[12:13]
	ds_read_b128 v[72:75], v98 offset:1088
	v_lshl_add_u64 v[76:77], v[76:77], 1, s[16:17]
	s_waitcnt vmcnt(15) lgkmcnt(0)
	v_mov_b32_e32 v68, v160
	v_mov_b32_e32 v69, v161
	v_mov_b32_e32 v70, v162
	v_mov_b32_e32 v71, v163
	v_pk_fma_f32 v[68:69], v[72:73], 0.5, v[68:69] op_sel_hi:[1,0,1]
	v_pk_fma_f32 v[70:71], v[74:75], 0.5, v[70:71] op_sel_hi:[1,0,1]
	global_store_dwordx4 v[78:79], v[68:71], off
	v_cvt_pk_bf16_f32 v72, v68, v69
	v_cvt_pk_bf16_f32 v73, v70, v71
	v_pk_mul_f32 v[68:69], v[68:69], v[68:69]
	v_pk_mul_f32 v[70:71], v[70:71], v[70:71]
	v_add_f32_e32 v65, v68, v69
	v_add_f32_e32 v65, v70, v65
	v_add_f32_e32 v65, v71, v65
	v_mov_b32_e32 v68, 0
	global_store_dwordx2 v[76:77], v[72:73], off
	v_add_f32_dpp v65, v65, v65 quad_perm:[1,0,3,2] row_mask:0xf bank_mask:0xf bound_ctrl:1
	s_nop 1
	v_add_f32_dpp v65, v65, v65 quad_perm:[2,3,0,1] row_mask:0xf bank_mask:0xf bound_ctrl:1
	s_nop 1
	v_add_f32_dpp v65, v65, v65 row_half_mirror row_mask:0xf bank_mask:0xf bound_ctrl:1
	s_nop 1
	v_mov_b32_dpp v68, v65 row_mirror row_mask:0xf bank_mask:0xf
	s_and_saveexec_b64 s[0:1], vcc
	s_cbranch_execz .LBB0_1785
	v_add_f32_e32 v68, v65, v68
	v_ashrrev_i32_e32 v65, 31, v64
	v_lshl_add_u64 v[64:65], v[64:65], 2, s[18:19]
	global_atomic_add_f32 v[64:65], v68, off
.LBB0_1785:
	s_or_b64 exec, exec, s[0:1]
	v_add_u32_e32 v64, v106, v67
	v_lshl_add_u32 v76, v64, 10, v128
	v_ashrrev_i32_e32 v77, 31, v76
	v_lshl_add_u64 v[78:79], v[76:77], 2, s[12:13]
	ds_read_b128 v[72:75], v98 offset:2176
	v_lshl_add_u64 v[76:77], v[76:77], 1, s[16:17]
	s_waitcnt vmcnt(17) lgkmcnt(0)
	v_mov_b32_e32 v68, v164
	v_mov_b32_e32 v69, v165
	v_mov_b32_e32 v70, v166
	v_mov_b32_e32 v71, v167
	v_pk_fma_f32 v[68:69], v[72:73], 0.5, v[68:69] op_sel_hi:[1,0,1]
	v_pk_fma_f32 v[70:71], v[74:75], 0.5, v[70:71] op_sel_hi:[1,0,1]
	global_store_dwordx4 v[78:79], v[68:71], off
	v_cvt_pk_bf16_f32 v72, v68, v69
	v_cvt_pk_bf16_f32 v73, v70, v71
	v_pk_mul_f32 v[68:69], v[68:69], v[68:69]
	v_pk_mul_f32 v[70:71], v[70:71], v[70:71]
	v_add_f32_e32 v65, v68, v69
	v_add_f32_e32 v65, v70, v65
	v_add_f32_e32 v65, v71, v65
	v_mov_b32_e32 v68, 0
	global_store_dwordx2 v[76:77], v[72:73], off
	v_add_f32_dpp v65, v65, v65 quad_perm:[1,0,3,2] row_mask:0xf bank_mask:0xf bound_ctrl:1
	s_nop 1
	v_add_f32_dpp v65, v65, v65 quad_perm:[2,3,0,1] row_mask:0xf bank_mask:0xf bound_ctrl:1
	s_nop 1
	v_add_f32_dpp v65, v65, v65 row_half_mirror row_mask:0xf bank_mask:0xf bound_ctrl:1
	s_nop 1
	v_mov_b32_dpp v68, v65 row_mirror row_mask:0xf bank_mask:0xf
	s_and_saveexec_b64 s[0:1], vcc
	s_cbranch_execz .LBB0_1787
	v_add_f32_e32 v68, v65, v68
	v_ashrrev_i32_e32 v65, 31, v64
	v_lshl_add_u64 v[64:65], v[64:65], 2, s[18:19]
	global_atomic_add_f32 v[64:65], v68, off
.LBB0_1787:
	s_or_b64 exec, exec, s[0:1]
	v_add_u32_e32 v64, v107, v67
	v_lshl_add_u32 v76, v64, 10, v128
	v_ashrrev_i32_e32 v77, 31, v76
	v_lshl_add_u64 v[78:79], v[76:77], 2, s[12:13]
	ds_read_b128 v[72:75], v98 offset:3264
	v_lshl_add_u64 v[76:77], v[76:77], 1, s[16:17]
	s_waitcnt vmcnt(19) lgkmcnt(0)
	v_mov_b32_e32 v68, v168
	v_mov_b32_e32 v69, v169
	v_mov_b32_e32 v70, v170
	v_mov_b32_e32 v71, v171
	v_pk_fma_f32 v[68:69], v[72:73], 0.5, v[68:69] op_sel_hi:[1,0,1]
	v_pk_fma_f32 v[70:71], v[74:75], 0.5, v[70:71] op_sel_hi:[1,0,1]
	global_store_dwordx4 v[78:79], v[68:71], off
	v_cvt_pk_bf16_f32 v72, v68, v69
	v_cvt_pk_bf16_f32 v73, v70, v71
	v_pk_mul_f32 v[68:69], v[68:69], v[68:69]
	v_pk_mul_f32 v[70:71], v[70:71], v[70:71]
	v_add_f32_e32 v65, v68, v69
	v_add_f32_e32 v65, v70, v65
	v_add_f32_e32 v65, v71, v65
	v_mov_b32_e32 v68, 0
	global_store_dwordx2 v[76:77], v[72:73], off
	v_add_f32_dpp v65, v65, v65 quad_perm:[1,0,3,2] row_mask:0xf bank_mask:0xf bound_ctrl:1
	s_nop 1
	v_add_f32_dpp v65, v65, v65 quad_perm:[2,3,0,1] row_mask:0xf bank_mask:0xf bound_ctrl:1
	s_nop 1
	v_add_f32_dpp v65, v65, v65 row_half_mirror row_mask:0xf bank_mask:0xf bound_ctrl:1
	s_nop 1
	v_mov_b32_dpp v68, v65 row_mirror row_mask:0xf bank_mask:0xf
	s_and_saveexec_b64 s[0:1], vcc
	s_cbranch_execz .LBB0_1789
	v_add_f32_e32 v68, v65, v68
	v_ashrrev_i32_e32 v65, 31, v64
	v_lshl_add_u64 v[64:65], v[64:65], 2, s[18:19]
	global_atomic_add_f32 v[64:65], v68, off
.LBB0_1789:
	s_or_b64 exec, exec, s[0:1]
	v_add_u32_e32 v64, v108, v67
	v_lshl_add_u32 v76, v64, 10, v128
	v_ashrrev_i32_e32 v77, 31, v76
	v_lshl_add_u64 v[78:79], v[76:77], 2, s[12:13]
	ds_read_b128 v[72:75], v98 offset:4352
	v_mov_b32_e32 v67, 0
	v_lshl_add_u64 v[76:77], v[76:77], 1, s[16:17]
	s_waitcnt vmcnt(21) lgkmcnt(0)
	v_mov_b32_e32 v68, v172
	v_mov_b32_e32 v69, v173
	v_mov_b32_e32 v70, v174
	v_mov_b32_e32 v71, v175
	v_pk_fma_f32 v[68:69], v[72:73], 0.5, v[68:69] op_sel_hi:[1,0,1]
	v_pk_fma_f32 v[70:71], v[74:75], 0.5, v[70:71] op_sel_hi:[1,0,1]
	global_store_dwordx4 v[78:79], v[68:71], off
	v_cvt_pk_bf16_f32 v72, v68, v69
	v_cvt_pk_bf16_f32 v73, v70, v71
	v_pk_mul_f32 v[68:69], v[68:69], v[68:69]
	v_pk_mul_f32 v[70:71], v[70:71], v[70:71]
	v_add_f32_e32 v65, v68, v69
	v_add_f32_e32 v65, v70, v65
	v_add_f32_e32 v65, v71, v65
	global_store_dwordx2 v[76:77], v[72:73], off
	s_nop 0
	v_add_f32_dpp v65, v65, v65 quad_perm:[1,0,3,2] row_mask:0xf bank_mask:0xf bound_ctrl:1
	s_nop 1
	v_add_f32_dpp v65, v65, v65 quad_perm:[2,3,0,1] row_mask:0xf bank_mask:0xf bound_ctrl:1
	s_nop 1
	v_add_f32_dpp v65, v65, v65 row_half_mirror row_mask:0xf bank_mask:0xf bound_ctrl:1
	s_nop 1
	v_mov_b32_dpp v67, v65 row_mirror row_mask:0xf bank_mask:0xf
	s_and_saveexec_b64 s[0:1], vcc
	s_cbranch_execz .LBB0_1791
	v_add_f32_e32 v67, v65, v67
	v_ashrrev_i32_e32 v65, 31, v64
	v_lshl_add_u64 v[64:65], v[64:65], 2, s[18:19]
	global_atomic_add_f32 v[64:65], v67, off
;   __device__ __forceinline__ void tile(const float* reg, int row0, int col0, int lane) const {
;     rows4(reg, lane, [&](int it, int rr, int c4, float4 v) {
;       int row = row0 + rr, idx = row * 1024 + col0 + c4;
;       float4 xo = *(const float4*)(xold + idx);
;       v.x = fmaf(coef, v.x, xo.x); v.y = fmaf(coef, v.y, xo.y); v.z = fmaf(coef, v.z, xo.z); v.w = fmaf(coef, v.w, xo.w);
;       *(float4*)(xnew + idx) = v;
;       *(bf16x4*)(xb + idx) = pack4(v.x, v.y, v.z, v.w);
;       float s = row16_sum(v.x * v.x + v.y * v.y + v.z * v.z + v.w * v.w);
;       if ((lane & 15) == 0) atomicAdd(ssqn + row, s);
;     });
; template <int MF, class Epi>
; __device__ __forceinline__ void staged_epilogue(f32x4 (&acc)[MF][4], int row0, int col0, const Epi& epi) {
;     ...
; #pragma unroll
;   for (int mp = 0; mp < MF / 2; ++mp) {
;     __builtin_amdgcn_sched_barrier(0);
; #pragma unroll
;     for (int mm = 0; mm < 2; ++mm)
; #pragma unroll
;       for (int n = 0; n < 4; ++n)
; #pragma unroll
;         for (int j = 0; j < 4; ++j) reg[(mm * 16 + fq * 4 + j) * 68 + n * 16 + fr] = acc[mp * 2 + mm][n][j];
;     __builtin_amdgcn_fence(__ATOMIC_ACQ_REL, "wavefront");
;     epi.tile(reg, row0 + mp * 32, col0, lane);
.LBB0_1791:
	s_or_b64 exec, exec, s[0:1]
	ds_write2_b32 v131, v56, v60 offset1:16
	ds_write2_b32 v131, v57, v61 offset0:68 offset1:84
	ds_write2_b32 v131, v58, v62 offset0:136 offset1:152
	ds_write2_b32 v131, v59, v63 offset0:204 offset1:220
	ds_write2_b32 v131, v48, v52 offset0:32 offset1:48
	ds_write2_b32 v131, v49, v53 offset0:100 offset1:116
	ds_write2_b32 v131, v50, v54 offset0:168 offset1:184
	ds_write2_b32 v131, v51, v55 offset0:236 offset1:252
	ds_write2_b32 v112, v40, v44 offset0:64 offset1:80
	ds_write2_b32 v112, v41, v45 offset0:132 offset1:148
	ds_write2_b32 v112, v42, v46 offset0:200 offset1:216
	ds_write2_b32 v104, v43, v47 offset0:12 offset1:28
	ds_write2_b32 v112, v32, v36 offset0:96 offset1:112
	ds_write2_b32 v112, v33, v37 offset0:164 offset1:180
	ds_write2_b32 v112, v34, v38 offset0:232 offset1:248
	ds_write2_b32 v104, v35, v39 offset0:44 offset1:60
	v_add_u32_e32 v185, 64, v129
	v_add_u32_e32 v184, v130, v185
	v_lshl_add_u32 v176, v184, 10, v128
	v_ashrrev_i32_e32 v177, 31, v176
	v_lshl_add_u64 v[178:179], v[176:177], 2, s[12:13]
	global_load_dwordx4 v[144:147], v[178:179], off
	v_add_u32_e32 v185, 64, v129
	v_add_u32_e32 v184, v99, v185
	v_lshl_add_u32 v176, v184, 10, v128
	v_ashrrev_i32_e32 v177, 31, v176
	v_lshl_add_u64 v[178:179], v[176:177], 2, s[12:13]
	global_load_dwordx4 v[148:151], v[178:179], off
	v_add_u32_e32 v185, 64, v129
	v_add_u32_e32 v184, v101, v185
	v_lshl_add_u32 v176, v184, 10, v128
	v_ashrrev_i32_e32 v177, 31, v176
	v_lshl_add_u64 v[178:179], v[176:177], 2, s[12:13]
	global_load_dwordx4 v[152:155], v[178:179], off
	v_add_u32_e32 v185, 64, v129
	v_add_u32_e32 v184, v103, v185
	v_lshl_add_u32 v176, v184, 10, v128
	v_ashrrev_i32_e32 v177, 31, v176
	v_lshl_add_u64 v[178:179], v[176:177], 2, s[12:13]
	global_load_dwordx4 v[156:159], v[178:179], off
	v_add_u32_e32 v185, 64, v129
	v_add_u32_e32 v184, v105, v185
	v_lshl_add_u32 v176, v184, 10, v128
	v_ashrrev_i32_e32 v177, 31, v176
	v_lshl_add_u64 v[178:179], v[176:177], 2, s[12:13]
	global_load_dwordx4 v[160:163], v[178:179], off
	v_add_u32_e32 v185, 64, v129
	v_add_u32_e32 v184, v106, v185
	v_lshl_add_u32 v176, v184, 10, v128
	v_ashrrev_i32_e32 v177, 31, v176
	v_lshl_add_u64 v[178:179], v[176:177], 2, s[12:13]
	global_load_dwordx4 v[164:167], v[178:179], off
	v_add_u32_e32 v185, 64, v129
	v_add_u32_e32 v184, v107, v185
	v_lshl_add_u32 v176, v184, 10, v128
	v_ashrrev_i32_e32 v177, 31, v176
	v_lshl_add_u64 v[178:179], v[176:177], 2, s[12:13]
	global_load_dwordx4 v[168:171], v[178:179], off
	v_add_u32_e32 v185, 64, v129
	v_add_u32_e32 v184, v108, v185
	v_lshl_add_u32 v176, v184, 10, v128
	v_ashrrev_i32_e32 v177, 31, v176
	v_lshl_add_u64 v[178:179], v[176:177], 2, s[12:13]
	global_load_dwordx4 v[172:175], v[178:179], off
	v_add_u32_e32 v34, 64, v129
	v_add_u32_e32 v32, v130, v34
	v_lshl_add_u32 v44, v32, 10, v128
	v_ashrrev_i32_e32 v45, 31, v44
	v_lshl_add_u64 v[46:47], v[44:45], 2, s[12:13]
	ds_read_b128 v[40:43], v66
	v_mov_b32_e32 v35, 0
	v_lshl_add_u64 v[44:45], v[44:45], 1, s[16:17]
	s_waitcnt vmcnt(7) lgkmcnt(0)
	v_mov_b32_e32 v36, v144
	v_mov_b32_e32 v37, v145
	v_mov_b32_e32 v38, v146
	v_mov_b32_e32 v39, v147
	v_pk_fma_f32 v[36:37], v[40:41], 0.5, v[36:37] op_sel_hi:[1,0,1]
	v_pk_fma_f32 v[38:39], v[42:43], 0.5, v[38:39] op_sel_hi:[1,0,1]
	global_store_dwordx4 v[46:47], v[36:39], off
	v_cvt_pk_bf16_f32 v40, v36, v37
	v_cvt_pk_bf16_f32 v41, v38, v39
	v_pk_mul_f32 v[36:37], v[36:37], v[36:37]
	v_pk_mul_f32 v[38:39], v[38:39], v[38:39]
	v_add_f32_e32 v33, v36, v37
	v_add_f32_e32 v33, v38, v33
	v_add_f32_e32 v33, v39, v33
	global_store_dwordx2 v[44:45], v[40:41], off
	s_nop 0
	v_add_f32_dpp v33, v33, v33 quad_perm:[1,0,3,2] row_mask:0xf bank_mask:0xf bound_ctrl:1
	s_nop 1
	v_add_f32_dpp v33, v33, v33 quad_perm:[2,3,0,1] row_mask:0xf bank_mask:0xf bound_ctrl:1
	s_nop 1
	v_add_f32_dpp v33, v33, v33 row_half_mirror row_mask:0xf bank_mask:0xf bound_ctrl:1
	s_nop 1
	v_mov_b32_dpp v35, v33 row_mirror row_mask:0xf bank_mask:0xf
	s_and_saveexec_b64 s[0:1], vcc
	s_cbranch_execz .LBB0_1793
	v_add_f32_e32 v35, v33, v35
	v_ashrrev_i32_e32 v33, 31, v32
	v_lshl_add_u64 v[32:33], v[32:33], 2, s[18:19]
	global_atomic_add_f32 v[32:33], v35, off
.LBB0_1793:
	s_or_b64 exec, exec, s[0:1]
	v_add_u32_e32 v32, v99, v34
	v_lshl_add_u32 v44, v32, 10, v128
	v_ashrrev_i32_e32 v45, 31, v44
	v_lshl_add_u64 v[46:47], v[44:45], 2, s[12:13]
	ds_read_b128 v[40:43], v100
	v_mov_b32_e32 v35, 0
	v_lshl_add_u64 v[44:45], v[44:45], 1, s[16:17]
	s_waitcnt vmcnt(9) lgkmcnt(0)
	v_mov_b32_e32 v36, v148
	v_mov_b32_e32 v37, v149
	v_mov_b32_e32 v38, v150
	v_mov_b32_e32 v39, v151
	v_pk_fma_f32 v[36:37], v[40:41], 0.5, v[36:37] op_sel_hi:[1,0,1]
	v_pk_fma_f32 v[38:39], v[42:43], 0.5, v[38:39] op_sel_hi:[1,0,1]
	global_store_dwordx4 v[46:47], v[36:39], off
	v_cvt_pk_bf16_f32 v40, v36, v37
	v_cvt_pk_bf16_f32 v41, v38, v39
	v_pk_mul_f32 v[36:37], v[36:37], v[36:37]
	v_pk_mul_f32 v[38:39], v[38:39], v[38:39]
	v_add_f32_e32 v33, v36, v37
	v_add_f32_e32 v33, v38, v33
	v_add_f32_e32 v33, v39, v33
	global_store_dwordx2 v[44:45], v[40:41], off
	s_nop 0
	v_add_f32_dpp v33, v33, v33 quad_perm:[1,0,3,2] row_mask:0xf bank_mask:0xf bound_ctrl:1
	s_nop 1
	v_add_f32_dpp v33, v33, v33 quad_perm:[2,3,0,1] row_mask:0xf bank_mask:0xf bound_ctrl:1
	s_nop 1
	v_add_f32_dpp v33, v33, v33 row_half_mirror row_mask:0xf bank_mask:0xf bound_ctrl:1
	s_nop 1
	v_mov_b32_dpp v35, v33 row_mirror row_mask:0xf bank_mask:0xf
	s_and_saveexec_b64 s[0:1], vcc
	s_cbranch_execz .LBB0_1795
	v_add_f32_e32 v35, v33, v35
	v_ashrrev_i32_e32 v33, 31, v32
	v_lshl_add_u64 v[32:33], v[32:33], 2, s[18:19]
	global_atomic_add_f32 v[32:33], v35, off
;   __device__ __forceinline__ void tile(const float* reg, int row0, int col0, int lane) const {
;     rows4(reg, lane, [&](int it, int rr, int c4, float4 v) {
;       int row = row0 + rr, idx = row * 1024 + col0 + c4;
;       float4 xo = *(const float4*)(xold + idx);
;       v.x = fmaf(coef, v.x, xo.x); v.y = fmaf(coef, v.y, xo.y); v.z = fmaf(coef, v.z, xo.z); v.w = fmaf(coef, v.w, xo.w);
;       *(float4*)(xnew + idx) = v;
;       *(bf16x4*)(xb + idx) = pack4(v.x, v.y, v.z, v.w);
;       float s = row16_sum(v.x * v.x + v.y * v.y + v.z * v.z + v.w * v.w);
;       if ((lane & 15) == 0) atomicAdd(ssqn + row, s);
;     });
.LBB0_1795:
	s_or_b64 exec, exec, s[0:1]
	v_add_u32_e32 v32, v101, v34
	v_lshl_add_u32 v44, v32, 10, v128
	v_ashrrev_i32_e32 v45, 31, v44
	v_lshl_add_u64 v[46:47], v[44:45], 2, s[12:13]
	ds_read_b128 v[40:43], v102
	v_mov_b32_e32 v35, 0
	v_lshl_add_u64 v[44:45], v[44:45], 1, s[16:17]
	s_waitcnt vmcnt(11) lgkmcnt(0)
	v_mov_b32_e32 v36, v152
	v_mov_b32_e32 v37, v153
	v_mov_b32_e32 v38, v154
	v_mov_b32_e32 v39, v155
	v_pk_fma_f32 v[36:37], v[40:41], 0.5, v[36:37] op_sel_hi:[1,0,1]
	v_pk_fma_f32 v[38:39], v[42:43], 0.5, v[38:39] op_sel_hi:[1,0,1]
	global_store_dwordx4 v[46:47], v[36:39], off
	v_cvt_pk_bf16_f32 v40, v36, v37
	v_cvt_pk_bf16_f32 v41, v38, v39
	v_pk_mul_f32 v[36:37], v[36:37], v[36:37]
	v_pk_mul_f32 v[38:39], v[38:39], v[38:39]
	v_add_f32_e32 v33, v36, v37
	v_add_f32_e32 v33, v38, v33
	v_add_f32_e32 v33, v39, v33
	global_store_dwordx2 v[44:45], v[40:41], off
	s_nop 0
	v_add_f32_dpp v33, v33, v33 quad_perm:[1,0,3,2] row_mask:0xf bank_mask:0xf bound_ctrl:1
	s_nop 1
	v_add_f32_dpp v33, v33, v33 quad_perm:[2,3,0,1] row_mask:0xf bank_mask:0xf bound_ctrl:1
	s_nop 1
	v_add_f32_dpp v33, v33, v33 row_half_mirror row_mask:0xf bank_mask:0xf bound_ctrl:1
	s_nop 1
	v_mov_b32_dpp v35, v33 row_mirror row_mask:0xf bank_mask:0xf
	s_and_saveexec_b64 s[0:1], vcc
	s_cbranch_execz .LBB0_1797
	v_add_f32_e32 v35, v33, v35
	v_ashrrev_i32_e32 v33, 31, v32
	v_lshl_add_u64 v[32:33], v[32:33], 2, s[18:19]
	global_atomic_add_f32 v[32:33], v35, off
.LBB0_1797:
	s_or_b64 exec, exec, s[0:1]
	v_add_u32_e32 v32, v103, v34
	v_lshl_add_u32 v44, v32, 10, v128
	v_ashrrev_i32_e32 v45, 31, v44
	v_lshl_add_u64 v[46:47], v[44:45], 2, s[12:13]
	ds_read_b128 v[40:43], v98
	v_mov_b32_e32 v35, 0
	v_lshl_add_u64 v[44:45], v[44:45], 1, s[16:17]
	s_waitcnt vmcnt(13) lgkmcnt(0)
	v_mov_b32_e32 v36, v156
	v_mov_b32_e32 v37, v157
	v_mov_b32_e32 v38, v158
	v_mov_b32_e32 v39, v159
	v_pk_fma_f32 v[36:37], v[40:41], 0.5, v[36:37] op_sel_hi:[1,0,1]
	v_pk_fma_f32 v[38:39], v[42:43], 0.5, v[38:39] op_sel_hi:[1,0,1]
	global_store_dwordx4 v[46:47], v[36:39], off
	v_cvt_pk_bf16_f32 v40, v36, v37
	v_cvt_pk_bf16_f32 v41, v38, v39
	v_pk_mul_f32 v[36:37], v[36:37], v[36:37]
	v_pk_mul_f32 v[38:39], v[38:39], v[38:39]
	v_add_f32_e32 v33, v36, v37
	v_add_f32_e32 v33, v38, v33
	v_add_f32_e32 v33, v39, v33
	global_store_dwordx2 v[44:45], v[40:41], off
	s_nop 0
	v_add_f32_dpp v33, v33, v33 quad_perm:[1,0,3,2] row_mask:0xf bank_mask:0xf bound_ctrl:1
	s_nop 1
	v_add_f32_dpp v33, v33, v33 quad_perm:[2,3,0,1] row_mask:0xf bank_mask:0xf bound_ctrl:1
	s_nop 1
	v_add_f32_dpp v33, v33, v33 row_half_mirror row_mask:0xf bank_mask:0xf bound_ctrl:1
	s_nop 1
	v_mov_b32_dpp v35, v33 row_mirror row_mask:0xf bank_mask:0xf
	s_and_saveexec_b64 s[0:1], vcc
	s_cbranch_execz .LBB0_1799
	v_add_f32_e32 v35, v33, v35
	v_ashrrev_i32_e32 v33, 31, v32
	v_lshl_add_u64 v[32:33], v[32:33], 2, s[18:19]
	global_atomic_add_f32 v[32:33], v35, off
.LBB0_1799:
	s_or_b64 exec, exec, s[0:1]
	v_add_u32_e32 v32, v105, v34
	v_lshl_add_u32 v44, v32, 10, v128
	v_ashrrev_i32_e32 v45, 31, v44
	v_lshl_add_u64 v[46:47], v[44:45], 2, s[12:13]
	ds_read_b128 v[40:43], v98 offset:1088
	v_mov_b32_e32 v35, 0
	v_lshl_add_u64 v[44:45], v[44:45], 1, s[16:17]
	s_waitcnt vmcnt(15) lgkmcnt(0)
	v_mov_b32_e32 v36, v160
	v_mov_b32_e32 v37, v161
	v_mov_b32_e32 v38, v162
	v_mov_b32_e32 v39, v163
	v_pk_fma_f32 v[36:37], v[40:41], 0.5, v[36:37] op_sel_hi:[1,0,1]
	v_pk_fma_f32 v[38:39], v[42:43], 0.5, v[38:39] op_sel_hi:[1,0,1]
	global_store_dwordx4 v[46:47], v[36:39], off
	v_cvt_pk_bf16_f32 v40, v36, v37
	v_cvt_pk_bf16_f32 v41, v38, v39
	v_pk_mul_f32 v[36:37], v[36:37], v[36:37]
	v_pk_mul_f32 v[38:39], v[38:39], v[38:39]
	v_add_f32_e32 v33, v36, v37
	v_add_f32_e32 v33, v38, v33
	v_add_f32_e32 v33, v39, v33
	global_store_dwordx2 v[44:45], v[40:41], off
	s_nop 0
	v_add_f32_dpp v33, v33, v33 quad_perm:[1,0,3,2] row_mask:0xf bank_mask:0xf bound_ctrl:1
	s_nop 1
	v_add_f32_dpp v33, v33, v33 quad_perm:[2,3,0,1] row_mask:0xf bank_mask:0xf bound_ctrl:1
	s_nop 1
	v_add_f32_dpp v33, v33, v33 row_half_mirror row_mask:0xf bank_mask:0xf bound_ctrl:1
	s_nop 1
	v_mov_b32_dpp v35, v33 row_mirror row_mask:0xf bank_mask:0xf
	s_and_saveexec_b64 s[0:1], vcc
	s_cbranch_execz .LBB0_1801
	v_add_f32_e32 v35, v33, v35
	v_ashrrev_i32_e32 v33, 31, v32
	v_lshl_add_u64 v[32:33], v[32:33], 2, s[18:19]
	global_atomic_add_f32 v[32:33], v35, off
.LBB0_1801:
	s_or_b64 exec, exec, s[0:1]
	v_add_u32_e32 v32, v106, v34
	v_lshl_add_u32 v44, v32, 10, v128
	v_ashrrev_i32_e32 v45, 31, v44
	v_lshl_add_u64 v[46:47], v[44:45], 2, s[12:13]
	ds_read_b128 v[40:43], v98 offset:2176
	v_mov_b32_e32 v35, 0
	v_lshl_add_u64 v[44:45], v[44:45], 1, s[16:17]
	s_waitcnt vmcnt(17) lgkmcnt(0)
	v_mov_b32_e32 v36, v164
	v_mov_b32_e32 v37, v165
	v_mov_b32_e32 v38, v166
	v_mov_b32_e32 v39, v167
	v_pk_fma_f32 v[36:37], v[40:41], 0.5, v[36:37] op_sel_hi:[1,0,1]
	v_pk_fma_f32 v[38:39], v[42:43], 0.5, v[38:39] op_sel_hi:[1,0,1]
	global_store_dwordx4 v[46:47], v[36:39], off
	v_cvt_pk_bf16_f32 v40, v36, v37
	v_cvt_pk_bf16_f32 v41, v38, v39
	v_pk_mul_f32 v[36:37], v[36:37], v[36:37]
	v_pk_mul_f32 v[38:39], v[38:39], v[38:39]
	v_add_f32_e32 v33, v36, v37
	v_add_f32_e32 v33, v38, v33
	v_add_f32_e32 v33, v39, v33
	global_store_dwordx2 v[44:45], v[40:41], off
	s_nop 0
	v_add_f32_dpp v33, v33, v33 quad_perm:[1,0,3,2] row_mask:0xf bank_mask:0xf bound_ctrl:1
	s_nop 1
	v_add_f32_dpp v33, v33, v33 quad_perm:[2,3,0,1] row_mask:0xf bank_mask:0xf bound_ctrl:1
	s_nop 1
	v_add_f32_dpp v33, v33, v33 row_half_mirror row_mask:0xf bank_mask:0xf bound_ctrl:1
	s_nop 1
	v_mov_b32_dpp v35, v33 row_mirror row_mask:0xf bank_mask:0xf
	s_and_saveexec_b64 s[0:1], vcc
	s_cbranch_execz .LBB0_1803
	v_add_f32_e32 v35, v33, v35
	v_ashrrev_i32_e32 v33, 31, v32
	v_lshl_add_u64 v[32:33], v[32:33], 2, s[18:19]
	global_atomic_add_f32 v[32:33], v35, off
;   __device__ __forceinline__ void tile(const float* reg, int row0, int col0, int lane) const {
;     rows4(reg, lane, [&](int it, int rr, int c4, float4 v) {
;       int row = row0 + rr, idx = row * 1024 + col0 + c4;
;       float4 xo = *(const float4*)(xold + idx);
;       v.x = fmaf(coef, v.x, xo.x); v.y = fmaf(coef, v.y, xo.y); v.z = fmaf(coef, v.z, xo.z); v.w = fmaf(coef, v.w, xo.w);
;       *(float4*)(xnew + idx) = v;
;       *(bf16x4*)(xb + idx) = pack4(v.x, v.y, v.z, v.w);
;       float s = row16_sum(v.x * v.x + v.y * v.y + v.z * v.z + v.w * v.w);
;       if ((lane & 15) == 0) atomicAdd(ssqn + row, s);
;     });
; template <int MF, class Epi>
; __device__ __forceinline__ void staged_epilogue(f32x4 (&acc)[MF][4], int row0, int col0, const Epi& epi) {
;     ...
; #pragma unroll
;   for (int mp = 0; mp < MF / 2; ++mp) {
;     __builtin_amdgcn_sched_barrier(0);
; #pragma unroll
;     for (int mm = 0; mm < 2; ++mm)
; #pragma unroll
;       for (int n = 0; n < 4; ++n)
; #pragma unroll
;         for (int j = 0; j < 4; ++j) reg[(mm * 16 + fq * 4 + j) * 68 + n * 16 + fr] = acc[mp * 2 + mm][n][j];
;     __builtin_amdgcn_fence(__ATOMIC_ACQ_REL, "wavefront");
;     epi.tile(reg, row0 + mp * 32, col0, lane);
.LBB0_1803:
	s_or_b64 exec, exec, s[0:1]
	v_add_u32_e32 v32, v107, v34
	v_lshl_add_u32 v44, v32, 10, v128
	v_ashrrev_i32_e32 v45, 31, v44
	v_lshl_add_u64 v[46:47], v[44:45], 2, s[12:13]
	ds_read_b128 v[40:43], v98 offset:3264
	v_mov_b32_e32 v35, 0
	v_lshl_add_u64 v[44:45], v[44:45], 1, s[16:17]
	s_waitcnt vmcnt(19) lgkmcnt(0)
	v_mov_b32_e32 v36, v168
	v_mov_b32_e32 v37, v169
	v_mov_b32_e32 v38, v170
	v_mov_b32_e32 v39, v171
	v_pk_fma_f32 v[36:37], v[40:41], 0.5, v[36:37] op_sel_hi:[1,0,1]
	v_pk_fma_f32 v[38:39], v[42:43], 0.5, v[38:39] op_sel_hi:[1,0,1]
	global_store_dwordx4 v[46:47], v[36:39], off
	v_cvt_pk_bf16_f32 v40, v36, v37
	v_cvt_pk_bf16_f32 v41, v38, v39
	v_pk_mul_f32 v[36:37], v[36:37], v[36:37]
	v_pk_mul_f32 v[38:39], v[38:39], v[38:39]
	v_add_f32_e32 v33, v36, v37
	v_add_f32_e32 v33, v38, v33
	v_add_f32_e32 v33, v39, v33
	global_store_dwordx2 v[44:45], v[40:41], off
	s_nop 0
	v_add_f32_dpp v33, v33, v33 quad_perm:[1,0,3,2] row_mask:0xf bank_mask:0xf bound_ctrl:1
	s_nop 1
	v_add_f32_dpp v33, v33, v33 quad_perm:[2,3,0,1] row_mask:0xf bank_mask:0xf bound_ctrl:1
	s_nop 1
	v_add_f32_dpp v33, v33, v33 row_half_mirror row_mask:0xf bank_mask:0xf bound_ctrl:1
	s_nop 1
	v_mov_b32_dpp v35, v33 row_mirror row_mask:0xf bank_mask:0xf
	s_and_saveexec_b64 s[0:1], vcc
	s_cbranch_execz .LBB0_1805
	v_add_f32_e32 v35, v33, v35
	v_ashrrev_i32_e32 v33, 31, v32
	v_lshl_add_u64 v[32:33], v[32:33], 2, s[18:19]
	global_atomic_add_f32 v[32:33], v35, off
.LBB0_1805:
	s_or_b64 exec, exec, s[0:1]
	v_add_u32_e32 v32, v108, v34
	v_lshl_add_u32 v42, v32, 10, v128
	v_ashrrev_i32_e32 v43, 31, v42
	v_lshl_add_u64 v[44:45], v[42:43], 2, s[12:13]
	ds_read_b128 v[38:41], v98 offset:4352
	v_lshl_add_u64 v[42:43], v[42:43], 1, s[16:17]
	s_waitcnt vmcnt(21) lgkmcnt(0)
	v_mov_b32_e32 v34, v172
	v_mov_b32_e32 v35, v173
	v_mov_b32_e32 v36, v174
	v_mov_b32_e32 v37, v175
	v_pk_fma_f32 v[34:35], v[38:39], 0.5, v[34:35] op_sel_hi:[1,0,1]
	v_pk_fma_f32 v[36:37], v[40:41], 0.5, v[36:37] op_sel_hi:[1,0,1]
	global_store_dwordx4 v[44:45], v[34:37], off
	v_cvt_pk_bf16_f32 v38, v34, v35
	v_cvt_pk_bf16_f32 v39, v36, v37
	v_pk_mul_f32 v[34:35], v[34:35], v[34:35]
	v_pk_mul_f32 v[36:37], v[36:37], v[36:37]
	v_add_f32_e32 v33, v34, v35
	v_add_f32_e32 v33, v36, v33
	v_add_f32_e32 v33, v37, v33
	v_mov_b32_e32 v34, 0
	global_store_dwordx2 v[42:43], v[38:39], off
	v_add_f32_dpp v33, v33, v33 quad_perm:[1,0,3,2] row_mask:0xf bank_mask:0xf bound_ctrl:1
	s_nop 1
	v_add_f32_dpp v33, v33, v33 quad_perm:[2,3,0,1] row_mask:0xf bank_mask:0xf bound_ctrl:1
	s_nop 1
	v_add_f32_dpp v33, v33, v33 row_half_mirror row_mask:0xf bank_mask:0xf bound_ctrl:1
	s_nop 1
	v_mov_b32_dpp v34, v33 row_mirror row_mask:0xf bank_mask:0xf
	s_and_saveexec_b64 s[0:1], vcc
	s_cbranch_execz .LBB0_1807
	v_add_f32_e32 v34, v33, v34
	v_ashrrev_i32_e32 v33, 31, v32
	v_lshl_add_u64 v[32:33], v[32:33], 2, s[18:19]
	global_atomic_add_f32 v[32:33], v34, off
.LBB0_1807:
	s_or_b64 exec, exec, s[0:1]
	ds_write2_b32 v131, v24, v28 offset1:16
	ds_write2_b32 v131, v25, v29 offset0:68 offset1:84
	ds_write2_b32 v131, v26, v30 offset0:136 offset1:152
	ds_write2_b32 v131, v27, v31 offset0:204 offset1:220
	ds_write2_b32 v131, v16, v20 offset0:32 offset1:48
	ds_write2_b32 v131, v17, v21 offset0:100 offset1:116
	ds_write2_b32 v131, v18, v22 offset0:168 offset1:184
	ds_write2_b32 v131, v19, v23 offset0:236 offset1:252
	ds_write2_b32 v112, v4, v8 offset0:64 offset1:80
	ds_write2_b32 v112, v5, v9 offset0:132 offset1:148
	ds_write2_b32 v112, v6, v10 offset0:200 offset1:216
	ds_write2_b32 v104, v7, v11 offset0:12 offset1:28
	ds_write2_b32 v112, v0, v12 offset0:96 offset1:112
	ds_write2_b32 v112, v1, v13 offset0:164 offset1:180
	ds_write2_b32 v112, v2, v14 offset0:232 offset1:248
	ds_write2_b32 v104, v3, v15 offset0:44 offset1:60
	v_add_u32_e32 v185, 0x60, v129
	v_add_u32_e32 v184, v130, v185
	v_lshl_add_u32 v176, v184, 10, v128
	v_ashrrev_i32_e32 v177, 31, v176
	v_lshl_add_u64 v[178:179], v[176:177], 2, s[12:13]
	global_load_dwordx4 v[144:147], v[178:179], off
	v_add_u32_e32 v185, 0x60, v129
	v_add_u32_e32 v184, v99, v185
	v_lshl_add_u32 v176, v184, 10, v128
	v_ashrrev_i32_e32 v177, 31, v176
	v_lshl_add_u64 v[178:179], v[176:177], 2, s[12:13]
	global_load_dwordx4 v[148:151], v[178:179], off
	v_add_u32_e32 v185, 0x60, v129
	v_add_u32_e32 v184, v101, v185
	v_lshl_add_u32 v176, v184, 10, v128
	v_ashrrev_i32_e32 v177, 31, v176
	v_lshl_add_u64 v[178:179], v[176:177], 2, s[12:13]
	global_load_dwordx4 v[152:155], v[178:179], off
	v_add_u32_e32 v185, 0x60, v129
	v_add_u32_e32 v184, v103, v185
	v_lshl_add_u32 v176, v184, 10, v128
	v_ashrrev_i32_e32 v177, 31, v176
	v_lshl_add_u64 v[178:179], v[176:177], 2, s[12:13]
	global_load_dwordx4 v[156:159], v[178:179], off
	v_add_u32_e32 v185, 0x60, v129
	v_add_u32_e32 v184, v105, v185
	v_lshl_add_u32 v176, v184, 10, v128
	v_ashrrev_i32_e32 v177, 31, v176
	v_lshl_add_u64 v[178:179], v[176:177], 2, s[12:13]
	global_load_dwordx4 v[160:163], v[178:179], off
	v_add_u32_e32 v185, 0x60, v129
	v_add_u32_e32 v184, v106, v185
	v_lshl_add_u32 v176, v184, 10, v128
	v_ashrrev_i32_e32 v177, 31, v176
	v_lshl_add_u64 v[178:179], v[176:177], 2, s[12:13]
	global_load_dwordx4 v[164:167], v[178:179], off
	v_add_u32_e32 v185, 0x60, v129
	v_add_u32_e32 v184, v107, v185
	v_lshl_add_u32 v176, v184, 10, v128
	v_ashrrev_i32_e32 v177, 31, v176
	v_lshl_add_u64 v[178:179], v[176:177], 2, s[12:13]
	global_load_dwordx4 v[168:171], v[178:179], off
	v_add_u32_e32 v185, 0x60, v129
	v_add_u32_e32 v184, v108, v185
	v_lshl_add_u32 v176, v184, 10, v128
	v_ashrrev_i32_e32 v177, 31, v176
	v_lshl_add_u64 v[178:179], v[176:177], 2, s[12:13]
	global_load_dwordx4 v[172:175], v[178:179], off
	v_add_u32_e32 v2, 0x60, v129
	v_add_u32_e32 v0, v130, v2
	v_lshl_add_u32 v12, v0, 10, v128
	v_ashrrev_i32_e32 v13, 31, v12
	v_lshl_add_u64 v[14:15], v[12:13], 2, s[12:13]
	ds_read_b128 v[8:11], v66
	v_mov_b32_e32 v3, 0
	v_lshl_add_u64 v[12:13], v[12:13], 1, s[16:17]
	s_waitcnt vmcnt(7) lgkmcnt(0)
	v_mov_b32_e32 v4, v144
	v_mov_b32_e32 v5, v145
	v_mov_b32_e32 v6, v146
	v_mov_b32_e32 v7, v147
	v_pk_fma_f32 v[4:5], v[8:9], 0.5, v[4:5] op_sel_hi:[1,0,1]
	v_pk_fma_f32 v[6:7], v[10:11], 0.5, v[6:7] op_sel_hi:[1,0,1]
	global_store_dwordx4 v[14:15], v[4:7], off
	v_cvt_pk_bf16_f32 v8, v4, v5
	v_cvt_pk_bf16_f32 v9, v6, v7
	v_pk_mul_f32 v[4:5], v[4:5], v[4:5]
	v_pk_mul_f32 v[6:7], v[6:7], v[6:7]
	v_add_f32_e32 v1, v4, v5
	v_add_f32_e32 v1, v6, v1
	v_add_f32_e32 v1, v7, v1
	global_store_dwordx2 v[12:13], v[8:9], off
	s_nop 0
	v_add_f32_dpp v1, v1, v1 quad_perm:[1,0,3,2] row_mask:0xf bank_mask:0xf bound_ctrl:1
	s_nop 1
	v_add_f32_dpp v1, v1, v1 quad_perm:[2,3,0,1] row_mask:0xf bank_mask:0xf bound_ctrl:1
	s_nop 1
	v_add_f32_dpp v1, v1, v1 row_half_mirror row_mask:0xf bank_mask:0xf bound_ctrl:1
	s_nop 1
	v_mov_b32_dpp v3, v1 row_mirror row_mask:0xf bank_mask:0xf
	s_and_saveexec_b64 s[0:1], vcc
	s_cbranch_execz .LBB0_1809
	v_add_f32_e32 v3, v1, v3
	v_ashrrev_i32_e32 v1, 31, v0
	v_lshl_add_u64 v[0:1], v[0:1], 2, s[18:19]
	global_atomic_add_f32 v[0:1], v3, off
;   __device__ __forceinline__ void tile(const float* reg, int row0, int col0, int lane) const {
;     rows4(reg, lane, [&](int it, int rr, int c4, float4 v) {
;       int row = row0 + rr, idx = row * 1024 + col0 + c4;
;       float4 xo = *(const float4*)(xold + idx);
;       v.x = fmaf(coef, v.x, xo.x); v.y = fmaf(coef, v.y, xo.y); v.z = fmaf(coef, v.z, xo.z); v.w = fmaf(coef, v.w, xo.w);
;       *(float4*)(xnew + idx) = v;
;       *(bf16x4*)(xb + idx) = pack4(v.x, v.y, v.z, v.w);
;       float s = row16_sum(v.x * v.x + v.y * v.y + v.z * v.z + v.w * v.w);
;       if ((lane & 15) == 0) atomicAdd(ssqn + row, s);
;     });
.LBB0_1809:
	s_or_b64 exec, exec, s[0:1]
	v_add_u32_e32 v0, v99, v2
	v_lshl_add_u32 v12, v0, 10, v128
	v_ashrrev_i32_e32 v13, 31, v12
	v_lshl_add_u64 v[14:15], v[12:13], 2, s[12:13]
	ds_read_b128 v[8:11], v100
	v_mov_b32_e32 v3, 0
	v_lshl_add_u64 v[12:13], v[12:13], 1, s[16:17]
	s_waitcnt vmcnt(9) lgkmcnt(0)
	v_mov_b32_e32 v4, v148
	v_mov_b32_e32 v5, v149
	v_mov_b32_e32 v6, v150
	v_mov_b32_e32 v7, v151
	v_pk_fma_f32 v[4:5], v[8:9], 0.5, v[4:5] op_sel_hi:[1,0,1]
	v_pk_fma_f32 v[6:7], v[10:11], 0.5, v[6:7] op_sel_hi:[1,0,1]
	global_store_dwordx4 v[14:15], v[4:7], off
	v_cvt_pk_bf16_f32 v8, v4, v5
	v_cvt_pk_bf16_f32 v9, v6, v7
	v_pk_mul_f32 v[4:5], v[4:5], v[4:5]
	v_pk_mul_f32 v[6:7], v[6:7], v[6:7]
	v_add_f32_e32 v1, v4, v5
	v_add_f32_e32 v1, v6, v1
	v_add_f32_e32 v1, v7, v1
	global_store_dwordx2 v[12:13], v[8:9], off
	s_nop 0
	v_add_f32_dpp v1, v1, v1 quad_perm:[1,0,3,2] row_mask:0xf bank_mask:0xf bound_ctrl:1
	s_nop 1
	v_add_f32_dpp v1, v1, v1 quad_perm:[2,3,0,1] row_mask:0xf bank_mask:0xf bound_ctrl:1
	s_nop 1
	v_add_f32_dpp v1, v1, v1 row_half_mirror row_mask:0xf bank_mask:0xf bound_ctrl:1
	s_nop 1
	v_mov_b32_dpp v3, v1 row_mirror row_mask:0xf bank_mask:0xf
	s_and_saveexec_b64 s[0:1], vcc
	s_cbranch_execz .LBB0_1811
	v_add_f32_e32 v3, v1, v3
	v_ashrrev_i32_e32 v1, 31, v0
	v_lshl_add_u64 v[0:1], v[0:1], 2, s[18:19]
	global_atomic_add_f32 v[0:1], v3, off
.LBB0_1811:
	s_or_b64 exec, exec, s[0:1]
	v_add_u32_e32 v0, v101, v2
	v_lshl_add_u32 v12, v0, 10, v128
	v_ashrrev_i32_e32 v13, 31, v12
	v_lshl_add_u64 v[14:15], v[12:13], 2, s[12:13]
	ds_read_b128 v[8:11], v102
	v_mov_b32_e32 v3, 0
	v_lshl_add_u64 v[12:13], v[12:13], 1, s[16:17]
	s_waitcnt vmcnt(11) lgkmcnt(0)
	v_mov_b32_e32 v4, v152
	v_mov_b32_e32 v5, v153
	v_mov_b32_e32 v6, v154
	v_mov_b32_e32 v7, v155
	v_pk_fma_f32 v[4:5], v[8:9], 0.5, v[4:5] op_sel_hi:[1,0,1]
	v_pk_fma_f32 v[6:7], v[10:11], 0.5, v[6:7] op_sel_hi:[1,0,1]
	global_store_dwordx4 v[14:15], v[4:7], off
	v_cvt_pk_bf16_f32 v8, v4, v5
	v_cvt_pk_bf16_f32 v9, v6, v7
	v_pk_mul_f32 v[4:5], v[4:5], v[4:5]
	v_pk_mul_f32 v[6:7], v[6:7], v[6:7]
	v_add_f32_e32 v1, v4, v5
	v_add_f32_e32 v1, v6, v1
	v_add_f32_e32 v1, v7, v1
	global_store_dwordx2 v[12:13], v[8:9], off
	s_nop 0
	v_add_f32_dpp v1, v1, v1 quad_perm:[1,0,3,2] row_mask:0xf bank_mask:0xf bound_ctrl:1
	s_nop 1
	v_add_f32_dpp v1, v1, v1 quad_perm:[2,3,0,1] row_mask:0xf bank_mask:0xf bound_ctrl:1
	s_nop 1
	v_add_f32_dpp v1, v1, v1 row_half_mirror row_mask:0xf bank_mask:0xf bound_ctrl:1
	s_nop 1
	v_mov_b32_dpp v3, v1 row_mirror row_mask:0xf bank_mask:0xf
	s_and_saveexec_b64 s[0:1], vcc
	s_cbranch_execz .LBB0_1813
	v_add_f32_e32 v3, v1, v3
	v_ashrrev_i32_e32 v1, 31, v0
	v_lshl_add_u64 v[0:1], v[0:1], 2, s[18:19]
	global_atomic_add_f32 v[0:1], v3, off
.LBB0_1813:
	s_or_b64 exec, exec, s[0:1]
	v_add_u32_e32 v0, v103, v2
	v_lshl_add_u32 v12, v0, 10, v128
	v_ashrrev_i32_e32 v13, 31, v12
	v_lshl_add_u64 v[14:15], v[12:13], 2, s[12:13]
	ds_read_b128 v[8:11], v98
	v_mov_b32_e32 v3, 0
	v_lshl_add_u64 v[12:13], v[12:13], 1, s[16:17]
	s_waitcnt vmcnt(13) lgkmcnt(0)
	v_mov_b32_e32 v4, v156
	v_mov_b32_e32 v5, v157
	v_mov_b32_e32 v6, v158
	v_mov_b32_e32 v7, v159
	v_pk_fma_f32 v[4:5], v[8:9], 0.5, v[4:5] op_sel_hi:[1,0,1]
	v_pk_fma_f32 v[6:7], v[10:11], 0.5, v[6:7] op_sel_hi:[1,0,1]
	global_store_dwordx4 v[14:15], v[4:7], off
	v_cvt_pk_bf16_f32 v8, v4, v5
	v_cvt_pk_bf16_f32 v9, v6, v7
	v_pk_mul_f32 v[4:5], v[4:5], v[4:5]
	v_pk_mul_f32 v[6:7], v[6:7], v[6:7]
	v_add_f32_e32 v1, v4, v5
	v_add_f32_e32 v1, v6, v1
	v_add_f32_e32 v1, v7, v1
	global_store_dwordx2 v[12:13], v[8:9], off
	s_nop 0
	v_add_f32_dpp v1, v1, v1 quad_perm:[1,0,3,2] row_mask:0xf bank_mask:0xf bound_ctrl:1
	s_nop 1
	v_add_f32_dpp v1, v1, v1 quad_perm:[2,3,0,1] row_mask:0xf bank_mask:0xf bound_ctrl:1
	s_nop 1
	v_add_f32_dpp v1, v1, v1 row_half_mirror row_mask:0xf bank_mask:0xf bound_ctrl:1
	s_nop 1
	v_mov_b32_dpp v3, v1 row_mirror row_mask:0xf bank_mask:0xf
	s_and_saveexec_b64 s[0:1], vcc
	s_cbranch_execz .LBB0_1815
	v_add_f32_e32 v3, v1, v3
	v_ashrrev_i32_e32 v1, 31, v0
	v_lshl_add_u64 v[0:1], v[0:1], 2, s[18:19]
	global_atomic_add_f32 v[0:1], v3, off
.LBB0_1815:
	s_or_b64 exec, exec, s[0:1]
	v_add_u32_e32 v0, v105, v2
	v_lshl_add_u32 v12, v0, 10, v128
	v_ashrrev_i32_e32 v13, 31, v12
	v_lshl_add_u64 v[14:15], v[12:13], 2, s[12:13]
	ds_read_b128 v[8:11], v98 offset:1088
	v_mov_b32_e32 v3, 0
	v_lshl_add_u64 v[12:13], v[12:13], 1, s[16:17]
	s_waitcnt vmcnt(15) lgkmcnt(0)
	v_mov_b32_e32 v4, v160
	v_mov_b32_e32 v5, v161
	v_mov_b32_e32 v6, v162
	v_mov_b32_e32 v7, v163
	v_pk_fma_f32 v[4:5], v[8:9], 0.5, v[4:5] op_sel_hi:[1,0,1]
	v_pk_fma_f32 v[6:7], v[10:11], 0.5, v[6:7] op_sel_hi:[1,0,1]
	global_store_dwordx4 v[14:15], v[4:7], off
	v_cvt_pk_bf16_f32 v8, v4, v5
	v_cvt_pk_bf16_f32 v9, v6, v7
	v_pk_mul_f32 v[4:5], v[4:5], v[4:5]
	v_pk_mul_f32 v[6:7], v[6:7], v[6:7]
	v_add_f32_e32 v1, v4, v5
	v_add_f32_e32 v1, v6, v1
	v_add_f32_e32 v1, v7, v1
	global_store_dwordx2 v[12:13], v[8:9], off
	s_nop 0
	v_add_f32_dpp v1, v1, v1 quad_perm:[1,0,3,2] row_mask:0xf bank_mask:0xf bound_ctrl:1
	s_nop 1
	v_add_f32_dpp v1, v1, v1 quad_perm:[2,3,0,1] row_mask:0xf bank_mask:0xf bound_ctrl:1
	s_nop 1
	v_add_f32_dpp v1, v1, v1 row_half_mirror row_mask:0xf bank_mask:0xf bound_ctrl:1
	s_nop 1
	v_mov_b32_dpp v3, v1 row_mirror row_mask:0xf bank_mask:0xf
	s_and_saveexec_b64 s[0:1], vcc
	s_cbranch_execz .LBB0_1817
	v_add_f32_e32 v3, v1, v3
	v_ashrrev_i32_e32 v1, 31, v0
	v_lshl_add_u64 v[0:1], v[0:1], 2, s[18:19]
	global_atomic_add_f32 v[0:1], v3, off
;   __device__ __forceinline__ void tile(const float* reg, int row0, int col0, int lane) const {
;     rows4(reg, lane, [&](int it, int rr, int c4, float4 v) {
;       int row = row0 + rr, idx = row * 1024 + col0 + c4;
;       float4 xo = *(const float4*)(xold + idx);
;       v.x = fmaf(coef, v.x, xo.x); v.y = fmaf(coef, v.y, xo.y); v.z = fmaf(coef, v.z, xo.z); v.w = fmaf(coef, v.w, xo.w);
;       *(float4*)(xnew + idx) = v;
;       *(bf16x4*)(xb + idx) = pack4(v.x, v.y, v.z, v.w);
;       float s = row16_sum(v.x * v.x + v.y * v.y + v.z * v.z + v.w * v.w);
;       if ((lane & 15) == 0) atomicAdd(ssqn + row, s);
;     });
.LBB0_1817:
	s_or_b64 exec, exec, s[0:1]
	v_add_u32_e32 v0, v106, v2
	v_lshl_add_u32 v12, v0, 10, v128
	v_ashrrev_i32_e32 v13, 31, v12
	v_lshl_add_u64 v[14:15], v[12:13], 2, s[12:13]
	ds_read_b128 v[8:11], v98 offset:2176
	v_mov_b32_e32 v3, 0
	v_lshl_add_u64 v[12:13], v[12:13], 1, s[16:17]
	s_waitcnt vmcnt(17) lgkmcnt(0)
	v_mov_b32_e32 v4, v164
	v_mov_b32_e32 v5, v165
	v_mov_b32_e32 v6, v166
	v_mov_b32_e32 v7, v167
	v_pk_fma_f32 v[4:5], v[8:9], 0.5, v[4:5] op_sel_hi:[1,0,1]
	v_pk_fma_f32 v[6:7], v[10:11], 0.5, v[6:7] op_sel_hi:[1,0,1]
	global_store_dwordx4 v[14:15], v[4:7], off
	v_cvt_pk_bf16_f32 v8, v4, v5
	v_cvt_pk_bf16_f32 v9, v6, v7
	v_pk_mul_f32 v[4:5], v[4:5], v[4:5]
	v_pk_mul_f32 v[6:7], v[6:7], v[6:7]
	v_add_f32_e32 v1, v4, v5
	v_add_f32_e32 v1, v6, v1
	v_add_f32_e32 v1, v7, v1
	global_store_dwordx2 v[12:13], v[8:9], off
	s_nop 0
	v_add_f32_dpp v1, v1, v1 quad_perm:[1,0,3,2] row_mask:0xf bank_mask:0xf bound_ctrl:1
	s_nop 1
	v_add_f32_dpp v1, v1, v1 quad_perm:[2,3,0,1] row_mask:0xf bank_mask:0xf bound_ctrl:1
	s_nop 1
	v_add_f32_dpp v1, v1, v1 row_half_mirror row_mask:0xf bank_mask:0xf bound_ctrl:1
	s_nop 1
	v_mov_b32_dpp v3, v1 row_mirror row_mask:0xf bank_mask:0xf
	s_and_saveexec_b64 s[0:1], vcc
	s_cbranch_execz .LBB0_1819
	v_add_f32_e32 v3, v1, v3
	v_ashrrev_i32_e32 v1, 31, v0
	v_lshl_add_u64 v[0:1], v[0:1], 2, s[18:19]
	global_atomic_add_f32 v[0:1], v3, off
.LBB0_1819:
	s_or_b64 exec, exec, s[0:1]
	v_add_u32_e32 v0, v107, v2
	v_lshl_add_u32 v12, v0, 10, v128
	v_ashrrev_i32_e32 v13, 31, v12
	v_lshl_add_u64 v[14:15], v[12:13], 2, s[12:13]
	ds_read_b128 v[8:11], v98 offset:3264
	v_mov_b32_e32 v3, 0
	v_lshl_add_u64 v[12:13], v[12:13], 1, s[16:17]
	s_waitcnt vmcnt(19) lgkmcnt(0)
	v_mov_b32_e32 v4, v168
	v_mov_b32_e32 v5, v169
	v_mov_b32_e32 v6, v170
	v_mov_b32_e32 v7, v171
	v_pk_fma_f32 v[4:5], v[8:9], 0.5, v[4:5] op_sel_hi:[1,0,1]
	v_pk_fma_f32 v[6:7], v[10:11], 0.5, v[6:7] op_sel_hi:[1,0,1]
	global_store_dwordx4 v[14:15], v[4:7], off
	v_cvt_pk_bf16_f32 v8, v4, v5
	v_cvt_pk_bf16_f32 v9, v6, v7
	v_pk_mul_f32 v[4:5], v[4:5], v[4:5]
	v_pk_mul_f32 v[6:7], v[6:7], v[6:7]
	v_add_f32_e32 v1, v4, v5
	v_add_f32_e32 v1, v6, v1
	v_add_f32_e32 v1, v7, v1
	global_store_dwordx2 v[12:13], v[8:9], off
	s_nop 0
	v_add_f32_dpp v1, v1, v1 quad_perm:[1,0,3,2] row_mask:0xf bank_mask:0xf bound_ctrl:1
	s_nop 1
	v_add_f32_dpp v1, v1, v1 quad_perm:[2,3,0,1] row_mask:0xf bank_mask:0xf bound_ctrl:1
	s_nop 1
	v_add_f32_dpp v1, v1, v1 row_half_mirror row_mask:0xf bank_mask:0xf bound_ctrl:1
	s_nop 1
	v_mov_b32_dpp v3, v1 row_mirror row_mask:0xf bank_mask:0xf
	s_and_saveexec_b64 s[0:1], vcc
	s_cbranch_execz .LBB0_1821
	v_add_f32_e32 v3, v1, v3
	v_ashrrev_i32_e32 v1, 31, v0
	v_lshl_add_u64 v[0:1], v[0:1], 2, s[18:19]
	global_atomic_add_f32 v[0:1], v3, off
.LBB0_1821:
	s_or_b64 exec, exec, s[0:1]
	v_add_u32_e32 v0, v108, v2
	v_lshl_add_u32 v10, v0, 10, v128
	v_ashrrev_i32_e32 v11, 31, v10
	v_lshl_add_u64 v[12:13], v[10:11], 2, s[12:13]
	ds_read_b128 v[6:9], v98 offset:4352
	v_lshl_add_u64 v[10:11], v[10:11], 1, s[16:17]
	s_waitcnt vmcnt(21) lgkmcnt(0)
	v_mov_b32_e32 v2, v172
	v_mov_b32_e32 v3, v173
	v_mov_b32_e32 v4, v174
	v_mov_b32_e32 v5, v175
	v_pk_fma_f32 v[2:3], v[6:7], 0.5, v[2:3] op_sel_hi:[1,0,1]
	v_pk_fma_f32 v[4:5], v[8:9], 0.5, v[4:5] op_sel_hi:[1,0,1]
	global_store_dwordx4 v[12:13], v[2:5], off
	v_cvt_pk_bf16_f32 v6, v2, v3
	v_cvt_pk_bf16_f32 v7, v4, v5
	v_pk_mul_f32 v[2:3], v[2:3], v[2:3]
	v_pk_mul_f32 v[4:5], v[4:5], v[4:5]
	v_add_f32_e32 v1, v2, v3
	v_add_f32_e32 v1, v4, v1
	v_add_f32_e32 v1, v5, v1
	v_mov_b32_e32 v2, 0
	global_store_dwordx2 v[10:11], v[6:7], off
	v_add_f32_dpp v1, v1, v1 quad_perm:[1,0,3,2] row_mask:0xf bank_mask:0xf bound_ctrl:1
	s_nop 1
	v_add_f32_dpp v1, v1, v1 quad_perm:[2,3,0,1] row_mask:0xf bank_mask:0xf bound_ctrl:1
	s_nop 1
	v_add_f32_dpp v1, v1, v1 row_half_mirror row_mask:0xf bank_mask:0xf bound_ctrl:1
	s_nop 1
	v_mov_b32_dpp v2, v1 row_mirror row_mask:0xf bank_mask:0xf
	s_and_saveexec_b64 s[0:1], vcc
	s_cbranch_execz .LBB0_1754
	v_add_f32_e32 v2, v1, v2
	v_ashrrev_i32_e32 v1, 31, v0
	v_lshl_add_u64 v[0:1], v[0:1], 2, s[18:19]
	global_atomic_add_f32 v[0:1], v2, off
	s_branch .LBB0_1754

;   __device__ __forceinline__ void tile(const float* reg, int row0, int col0, int lane) const {
;     rows4(reg, lane, [&](int it, int rr, int c4, float4 v) {
;       int row = row0 + rr, idx = row * 1024 + col0 + c4;
;       float4 xo = *(const float4*)(xold + idx);
;       v.x = fmaf(coef, v.x, xo.x); v.y = fmaf(coef, v.y, xo.y); v.z = fmaf(coef, v.z, xo.z); v.w = fmaf(coef, v.w, xo.w);
;       *(float4*)(xnew + idx) = v;
;       *(bf16x4*)(xb + idx) = pack4(v.x, v.y, v.z, v.w);
;       float s = row16_sum(v.x * v.x + v.y * v.y + v.z * v.z + v.w * v.w);
;       if ((lane & 15) == 0) atomicAdd(ssqn + row, s);
;     });
; template <int MF, class Epi>
; __device__ __forceinline__ void staged_epilogue(f32x4 (&acc)[MF][4], int row0, int col0, const Epi& epi) {
;   const int lane = tidx() & 63, wid = tidx() >> 6, fr = lane & 15, fq = lane >> 4;
;   float* reg = (float*)(g_shm + 65536 + wid * 8704);
; #pragma unroll
;   for (int mp = 0; mp < MF / 2; ++mp) {
;     __builtin_amdgcn_sched_barrier(0);
; #pragma unroll
;     for (int mm = 0; mm < 2; ++mm)
; #pragma unroll
;       for (int n = 0; n < 4; ++n)
; #pragma unroll
;         for (int j = 0; j < 4; ++j) reg[(mm * 16 + fq * 4 + j) * 68 + n * 16 + fr] = acc[mp * 2 + mm][n][j];
;     __builtin_amdgcn_fence(__ATOMIC_ACQ_REL, "wavefront");
;     epi.tile(reg, row0 + mp * 32, col0, lane);
.LBB0_3048:
	v_mov_b32_e32 v131, v204
	v_mov_b32_e32 v130, v204
	s_nop 0
	v_lshrrev_b32_e32 v130, 6, v130
	v_mul_lo_u32 v130, v130, s55
	v_add_u32_e32 v135, 0x10000, v130
	v_lshrrev_b32_e32 v130, 2, v131
	v_and_b32_e32 v136, 15, v131
	v_and_b32_e32 v137, 12, v130
	v_bfe_u32 v130, v131, 4, 2
	v_lshlrev_b32_e32 v131, 2, v131
	v_and_b32_e32 v131, 60, v131
	v_lshl_or_b32 v138, v136, 2, v135
	v_lshl_or_b32 v135, v131, 2, v135
	v_add_u32_e32 v128, v131, v128
	v_cmp_eq_u32_e32 vcc, 0, v136
	v_mad_u32_u24 v139, v130, s56, v135
	v_mad_u32_u24 v131, v137, s56, v138
	ds_write2_b32 v131, v120, v124 offset1:16
	ds_write2_b32 v131, v121, v125 offset0:68 offset1:84
	ds_write2_b32 v131, v122, v126 offset0:136 offset1:152
	ds_write2_b32 v131, v123, v127 offset0:204 offset1:220
	ds_write2_b32 v131, v112, v116 offset0:32 offset1:48
	ds_write2_b32 v131, v113, v117 offset0:100 offset1:116
	ds_write2_b32 v131, v114, v118 offset0:168 offset1:184
	ds_write2_b32 v131, v115, v119 offset0:236 offset1:252
	v_add_u32_e32 v112, 0x1000, v131
	ds_write2_b32 v112, v104, v108 offset0:64 offset1:80
	ds_write2_b32 v112, v105, v109 offset0:132 offset1:148
	ds_write2_b32 v112, v106, v110 offset0:200 offset1:216
	v_add_u32_e32 v104, 0x1400, v131
	ds_write2_b32 v104, v107, v111 offset0:12 offset1:28
	ds_write2_b32 v112, v96, v100 offset0:96 offset1:112
	ds_write2_b32 v112, v97, v101 offset0:164 offset1:180
	ds_write2_b32 v112, v98, v102 offset0:232 offset1:248
	ds_write2_b32 v104, v99, v103 offset0:44 offset1:60
	v_add_u32_e32 v184, v130, v129
	v_lshl_add_u32 v176, v184, 10, v128
	v_ashrrev_i32_e32 v177, 31, v176
	v_lshl_add_u64 v[178:179], v[176:177], 2, s[12:13]
	global_load_dwordx4 v[144:147], v[178:179], off
	v_or_b32_e32 v185, 4, v130
	v_add_u32_e32 v184, v185, v129
	v_lshl_add_u32 v176, v184, 10, v128
	v_ashrrev_i32_e32 v177, 31, v176
	v_lshl_add_u64 v[178:179], v[176:177], 2, s[12:13]
	global_load_dwordx4 v[148:151], v[178:179], off
	v_or_b32_e32 v185, 8, v130
	v_add_u32_e32 v184, v185, v129
	v_lshl_add_u32 v176, v184, 10, v128
	v_ashrrev_i32_e32 v177, 31, v176
	v_lshl_add_u64 v[178:179], v[176:177], 2, s[12:13]
	global_load_dwordx4 v[152:155], v[178:179], off
	v_or_b32_e32 v185, 12, v130
	v_add_u32_e32 v184, v185, v129
	v_lshl_add_u32 v176, v184, 10, v128
	v_ashrrev_i32_e32 v177, 31, v176
	v_lshl_add_u64 v[178:179], v[176:177], 2, s[12:13]
	global_load_dwordx4 v[156:159], v[178:179], off
	v_or_b32_e32 v185, 16, v130
	v_add_u32_e32 v184, v185, v129
	v_lshl_add_u32 v176, v184, 10, v128
	v_ashrrev_i32_e32 v177, 31, v176
	v_lshl_add_u64 v[178:179], v[176:177], 2, s[12:13]
	global_load_dwordx4 v[160:163], v[178:179], off
	v_or_b32_e32 v185, 20, v130
	v_add_u32_e32 v184, v185, v129
	v_lshl_add_u32 v176, v184, 10, v128
	v_ashrrev_i32_e32 v177, 31, v176
	v_lshl_add_u64 v[178:179], v[176:177], 2, s[12:13]
	global_load_dwordx4 v[164:167], v[178:179], off
	v_or_b32_e32 v185, 24, v130
	v_add_u32_e32 v184, v185, v129
	v_lshl_add_u32 v176, v184, 10, v128
	v_ashrrev_i32_e32 v177, 31, v176
	v_lshl_add_u64 v[178:179], v[176:177], 2, s[12:13]
	global_load_dwordx4 v[168:171], v[178:179], off
	v_or_b32_e32 v185, 28, v130
	v_add_u32_e32 v184, v185, v129
	v_lshl_add_u32 v176, v184, 10, v128
	v_ashrrev_i32_e32 v177, 31, v176
	v_lshl_add_u64 v[178:179], v[176:177], 2, s[12:13]
	global_load_dwordx4 v[172:175], v[178:179], off
	v_add_u32_e32 v96, v130, v129
	v_lshl_add_u32 v102, v96, 10, v128
	v_ashrrev_i32_e32 v103, 31, v102
	v_lshl_add_u64 v[110:111], v[102:103], 2, s[12:13]
	s_waitcnt vmcnt(7)
	v_mov_b32_e32 v98, v144
	v_mov_b32_e32 v99, v145
	v_mov_b32_e32 v100, v146
	v_mov_b32_e32 v101, v147
	ds_read_b128 v[106:109], v139
	v_lshl_add_u64 v[102:103], v[102:103], 1, s[20:21]
	s_waitcnt lgkmcnt(0)
	v_pk_add_f32 v[98:99], v[106:107], v[98:99]
	v_pk_add_f32 v[100:101], v[108:109], v[100:101]
	global_store_dwordx4 v[110:111], v[98:101], off
	v_cvt_pk_bf16_f32 v106, v98, v99
	v_cvt_pk_bf16_f32 v107, v100, v101
	v_pk_mul_f32 v[98:99], v[98:99], v[98:99]
	v_pk_mul_f32 v[100:101], v[100:101], v[100:101]
	v_add_f32_e32 v97, v98, v99
	v_add_f32_e32 v97, v100, v97
	v_add_f32_e32 v97, v101, v97
	v_mov_b32_e32 v98, 0
	global_store_dwordx2 v[102:103], v[106:107], off
	v_add_f32_dpp v97, v97, v97 quad_perm:[1,0,3,2] row_mask:0xf bank_mask:0xf bound_ctrl:1
	s_nop 1
	v_add_f32_dpp v97, v97, v97 quad_perm:[2,3,0,1] row_mask:0xf bank_mask:0xf bound_ctrl:1
	s_nop 1
	v_add_f32_dpp v97, v97, v97 row_half_mirror row_mask:0xf bank_mask:0xf bound_ctrl:1
	s_nop 1
	v_mov_b32_dpp v98, v97 row_mirror row_mask:0xf bank_mask:0xf
	s_and_saveexec_b64 s[0:1], vcc
	s_cbranch_execz .LBB0_3050
	v_add_f32_e32 v98, v97, v98
	v_ashrrev_i32_e32 v97, 31, v96
	v_lshl_add_u64 v[96:97], v[96:97], 2, s[22:23]
	global_atomic_add_f32 v[96:97], v98, off
.LBB0_3050:
	s_or_b64 exec, exec, s[0:1]
	v_or_b32_e32 v99, 4, v130
	v_add_u32_e32 v96, v99, v129
	v_lshl_add_u32 v102, v96, 10, v128
	v_ashrrev_i32_e32 v103, 31, v102
	v_lshl_add_u64 v[106:107], v[102:103], 2, s[12:13]
	v_mul_u32_u24_e32 v109, 0x110, v130
	v_add_u32_e32 v98, 0x440, v109
	v_add_u32_e32 v100, v135, v98
	ds_read_b128 v[118:121], v100
	v_mov_b32_e32 v101, 0
	v_lshl_add_u64 v[102:103], v[102:103], 1, s[20:21]
	s_waitcnt vmcnt(9) lgkmcnt(0)
	v_mov_b32_e32 v114, v148
	v_mov_b32_e32 v115, v149
	v_mov_b32_e32 v116, v150
	v_mov_b32_e32 v117, v151
	v_pk_add_f32 v[114:115], v[118:119], v[114:115]
	v_pk_add_f32 v[116:117], v[120:121], v[116:117]
	v_pk_mul_f32 v[110:111], v[114:115], v[114:115]
	global_store_dwordx4 v[106:107], v[114:117], off
	v_cvt_pk_bf16_f32 v106, v114, v115
	v_add_f32_e32 v97, v110, v111
	v_pk_mul_f32 v[114:115], v[116:117], v[116:117]
	v_cvt_pk_bf16_f32 v107, v116, v117
	v_add_f32_e32 v97, v114, v97
	v_add_f32_e32 v97, v115, v97
	global_store_dwordx2 v[102:103], v[106:107], off
	s_nop 0
	v_add_f32_dpp v97, v97, v97 quad_perm:[1,0,3,2] row_mask:0xf bank_mask:0xf bound_ctrl:1
	s_nop 1
	v_add_f32_dpp v97, v97, v97 quad_perm:[2,3,0,1] row_mask:0xf bank_mask:0xf bound_ctrl:1
	s_nop 1
	v_add_f32_dpp v97, v97, v97 row_half_mirror row_mask:0xf bank_mask:0xf bound_ctrl:1
	s_nop 1
	v_mov_b32_dpp v101, v97 row_mirror row_mask:0xf bank_mask:0xf
	s_and_saveexec_b64 s[0:1], vcc
	s_cbranch_execz .LBB0_3052
	v_add_f32_e32 v101, v97, v101
	v_ashrrev_i32_e32 v97, 31, v96
	v_lshl_add_u64 v[96:97], v[96:97], 2, s[22:23]
	global_atomic_add_f32 v[96:97], v101, off
;   __device__ __forceinline__ void tile(const float* reg, int row0, int col0, int lane) const {
;     rows4(reg, lane, [&](int it, int rr, int c4, float4 v) {
;       int row = row0 + rr, idx = row * 1024 + col0 + c4;
;       float4 xo = *(const float4*)(xold + idx);
;       v.x = fmaf(coef, v.x, xo.x); v.y = fmaf(coef, v.y, xo.y); v.z = fmaf(coef, v.z, xo.z); v.w = fmaf(coef, v.w, xo.w);
;       *(float4*)(xnew + idx) = v;
;       *(bf16x4*)(xb + idx) = pack4(v.x, v.y, v.z, v.w);
;       float s = row16_sum(v.x * v.x + v.y * v.y + v.z * v.z + v.w * v.w);
;       if ((lane & 15) == 0) atomicAdd(ssqn + row, s);
;     });
.LBB0_3052:
	s_or_b64 exec, exec, s[0:1]
	v_or_b32_e32 v101, 8, v130
	v_add_u32_e32 v96, v101, v129
	v_lshl_add_u32 v106, v96, 10, v128
	v_ashrrev_i32_e32 v107, 31, v106
	v_lshl_add_u64 v[110:111], v[106:107], 2, s[12:13]
	v_add_u32_e32 v98, 0x440, v98
	v_add_u32_e32 v102, v135, v98
	ds_read_b128 v[118:121], v102
	v_mov_b32_e32 v103, 0
	v_lshl_add_u64 v[106:107], v[106:107], 1, s[20:21]
	s_waitcnt vmcnt(11) lgkmcnt(0)
	v_mov_b32_e32 v114, v152
	v_mov_b32_e32 v115, v153
	v_mov_b32_e32 v116, v154
	v_mov_b32_e32 v117, v155
	v_pk_add_f32 v[114:115], v[118:119], v[114:115]
	v_pk_add_f32 v[116:117], v[120:121], v[116:117]
	global_store_dwordx4 v[110:111], v[114:117], off
	v_cvt_pk_bf16_f32 v110, v114, v115
	v_cvt_pk_bf16_f32 v111, v116, v117
	v_pk_mul_f32 v[114:115], v[114:115], v[114:115]
	v_pk_mul_f32 v[116:117], v[116:117], v[116:117]
	v_add_f32_e32 v97, v114, v115
	v_add_f32_e32 v97, v116, v97
	v_add_f32_e32 v97, v117, v97
	global_store_dwordx2 v[106:107], v[110:111], off
	s_nop 0
	v_add_f32_dpp v97, v97, v97 quad_perm:[1,0,3,2] row_mask:0xf bank_mask:0xf bound_ctrl:1
	s_nop 1
	v_add_f32_dpp v97, v97, v97 quad_perm:[2,3,0,1] row_mask:0xf bank_mask:0xf bound_ctrl:1
	s_nop 1
	v_add_f32_dpp v97, v97, v97 row_half_mirror row_mask:0xf bank_mask:0xf bound_ctrl:1
	s_nop 1
	v_mov_b32_dpp v103, v97 row_mirror row_mask:0xf bank_mask:0xf
	s_and_saveexec_b64 s[0:1], vcc
	s_cbranch_execz .LBB0_3054
	v_add_f32_e32 v103, v97, v103
	v_ashrrev_i32_e32 v97, 31, v96
	v_lshl_add_u64 v[96:97], v[96:97], 2, s[22:23]
	global_atomic_add_f32 v[96:97], v103, off
.LBB0_3054:
	s_or_b64 exec, exec, s[0:1]
	v_or_b32_e32 v103, 12, v130
	v_add_u32_e32 v96, v103, v129
	v_lshl_add_u32 v106, v96, 10, v128
	v_ashrrev_i32_e32 v107, 31, v106
	v_lshl_add_u64 v[110:111], v[106:107], 2, s[12:13]
	v_add_u32_e32 v97, 0x440, v98
	v_add_u32_e32 v98, v135, v97
	ds_read_b128 v[118:121], v98
	v_mov_b32_e32 v105, 0
	v_lshl_add_u64 v[106:107], v[106:107], 1, s[20:21]
	s_waitcnt vmcnt(13) lgkmcnt(0)
	v_mov_b32_e32 v114, v156
	v_mov_b32_e32 v115, v157
	v_mov_b32_e32 v116, v158
	v_mov_b32_e32 v117, v159
	v_pk_add_f32 v[114:115], v[118:119], v[114:115]
	v_pk_add_f32 v[116:117], v[120:121], v[116:117]
	global_store_dwordx4 v[110:111], v[114:117], off
	v_cvt_pk_bf16_f32 v110, v114, v115
	v_cvt_pk_bf16_f32 v111, v116, v117
	v_pk_mul_f32 v[114:115], v[114:115], v[114:115]
	v_pk_mul_f32 v[116:117], v[116:117], v[116:117]
	v_add_f32_e32 v97, v114, v115
	v_add_f32_e32 v97, v116, v97
	v_add_f32_e32 v97, v117, v97
	global_store_dwordx2 v[106:107], v[110:111], off
	s_nop 0
	v_add_f32_dpp v97, v97, v97 quad_perm:[1,0,3,2] row_mask:0xf bank_mask:0xf bound_ctrl:1
	s_nop 1
	v_add_f32_dpp v97, v97, v97 quad_perm:[2,3,0,1] row_mask:0xf bank_mask:0xf bound_ctrl:1
	s_nop 1
	v_add_f32_dpp v97, v97, v97 row_half_mirror row_mask:0xf bank_mask:0xf bound_ctrl:1
	s_nop 1
	v_mov_b32_dpp v105, v97 row_mirror row_mask:0xf bank_mask:0xf
	s_and_saveexec_b64 s[0:1], vcc
	s_cbranch_execz .LBB0_3056
	v_add_f32_e32 v105, v97, v105
	v_ashrrev_i32_e32 v97, 31, v96
	v_lshl_add_u64 v[96:97], v[96:97], 2, s[22:23]
	global_atomic_add_f32 v[96:97], v105, off
.LBB0_3056:
	s_or_b64 exec, exec, s[0:1]
	v_or_b32_e32 v105, 16, v130
	v_add_u32_e32 v96, v105, v129
	v_lshl_add_u32 v106, v96, 10, v128
	v_ashrrev_i32_e32 v107, 31, v106
	v_lshl_add_u64 v[110:111], v[106:107], 2, s[12:13]
	ds_read_b128 v[118:121], v98 offset:1088
	v_lshl_add_u64 v[106:107], v[106:107], 1, s[20:21]
	s_waitcnt vmcnt(15) lgkmcnt(0)
	v_mov_b32_e32 v114, v160
	v_mov_b32_e32 v115, v161
	v_mov_b32_e32 v116, v162
	v_mov_b32_e32 v117, v163
	v_pk_add_f32 v[114:115], v[118:119], v[114:115]
	v_pk_add_f32 v[116:117], v[120:121], v[116:117]
	global_store_dwordx4 v[110:111], v[114:117], off
	v_cvt_pk_bf16_f32 v110, v114, v115
	v_cvt_pk_bf16_f32 v111, v116, v117
	v_pk_mul_f32 v[114:115], v[114:115], v[114:115]
	v_pk_mul_f32 v[116:117], v[116:117], v[116:117]
	v_add_f32_e32 v97, v114, v115
	v_add_f32_e32 v97, v116, v97
	v_add_f32_e32 v97, v117, v97
	global_store_dwordx2 v[106:107], v[110:111], off
	v_mov_b32_e32 v106, 0
	v_add_f32_dpp v97, v97, v97 quad_perm:[1,0,3,2] row_mask:0xf bank_mask:0xf bound_ctrl:1
	s_nop 1
	v_add_f32_dpp v97, v97, v97 quad_perm:[2,3,0,1] row_mask:0xf bank_mask:0xf bound_ctrl:1
	s_nop 1
	v_add_f32_dpp v97, v97, v97 row_half_mirror row_mask:0xf bank_mask:0xf bound_ctrl:1
	s_nop 1
	v_mov_b32_dpp v106, v97 row_mirror row_mask:0xf bank_mask:0xf
	s_and_saveexec_b64 s[0:1], vcc
	s_cbranch_execz .LBB0_3058
	v_add_f32_e32 v106, v97, v106
	v_ashrrev_i32_e32 v97, 31, v96
	v_lshl_add_u64 v[96:97], v[96:97], 2, s[22:23]
	global_atomic_add_f32 v[96:97], v106, off
.LBB0_3058:
	s_or_b64 exec, exec, s[0:1]
	v_or_b32_e32 v106, 20, v130
	v_add_u32_e32 v96, v106, v129
	v_lshl_add_u32 v110, v96, 10, v128
	v_ashrrev_i32_e32 v111, 31, v110
	v_lshl_add_u64 v[122:123], v[110:111], 2, s[12:13]
	ds_read_b128 v[118:121], v98 offset:2176
	v_mov_b32_e32 v107, 0
	v_lshl_add_u64 v[110:111], v[110:111], 1, s[20:21]
	s_waitcnt vmcnt(17) lgkmcnt(0)
	v_mov_b32_e32 v114, v164
	v_mov_b32_e32 v115, v165
	v_mov_b32_e32 v116, v166
	v_mov_b32_e32 v117, v167
	v_pk_add_f32 v[114:115], v[118:119], v[114:115]
	v_pk_add_f32 v[116:117], v[120:121], v[116:117]
	global_store_dwordx4 v[122:123], v[114:117], off
	v_cvt_pk_bf16_f32 v118, v114, v115
	v_cvt_pk_bf16_f32 v119, v116, v117
	v_pk_mul_f32 v[114:115], v[114:115], v[114:115]
	v_pk_mul_f32 v[116:117], v[116:117], v[116:117]
	v_add_f32_e32 v97, v114, v115
	v_add_f32_e32 v97, v116, v97
	v_add_f32_e32 v97, v117, v97
	global_store_dwordx2 v[110:111], v[118:119], off
	s_nop 0
	v_add_f32_dpp v97, v97, v97 quad_perm:[1,0,3,2] row_mask:0xf bank_mask:0xf bound_ctrl:1
	s_nop 1
	v_add_f32_dpp v97, v97, v97 quad_perm:[2,3,0,1] row_mask:0xf bank_mask:0xf bound_ctrl:1
	s_nop 1
	v_add_f32_dpp v97, v97, v97 row_half_mirror row_mask:0xf bank_mask:0xf bound_ctrl:1
	s_nop 1
	v_mov_b32_dpp v107, v97 row_mirror row_mask:0xf bank_mask:0xf
	s_and_saveexec_b64 s[0:1], vcc
	s_cbranch_execz .LBB0_3060
	v_add_f32_e32 v107, v97, v107
	v_ashrrev_i32_e32 v97, 31, v96
	v_lshl_add_u64 v[96:97], v[96:97], 2, s[22:23]
	global_atomic_add_f32 v[96:97], v107, off
;   __device__ __forceinline__ void tile(const float* reg, int row0, int col0, int lane) const {
;     rows4(reg, lane, [&](int it, int rr, int c4, float4 v) {
;       int row = row0 + rr, idx = row * 1024 + col0 + c4;
;       float4 xo = *(const float4*)(xold + idx);
;       v.x = fmaf(coef, v.x, xo.x); v.y = fmaf(coef, v.y, xo.y); v.z = fmaf(coef, v.z, xo.z); v.w = fmaf(coef, v.w, xo.w);
;       *(float4*)(xnew + idx) = v;
;       *(bf16x4*)(xb + idx) = pack4(v.x, v.y, v.z, v.w);
;       float s = row16_sum(v.x * v.x + v.y * v.y + v.z * v.z + v.w * v.w);
;       if ((lane & 15) == 0) atomicAdd(ssqn + row, s);
;     });
; template <int MF, class Epi>
; __device__ __forceinline__ void staged_epilogue(f32x4 (&acc)[MF][4], int row0, int col0, const Epi& epi) {
;   const int lane = tidx() & 63, wid = tidx() >> 6, fr = lane & 15, fq = lane >> 4;
;   float* reg = (float*)(g_shm + 65536 + wid * 8704);
; #pragma unroll
;   for (int mp = 0; mp < MF / 2; ++mp) {
;     __builtin_amdgcn_sched_barrier(0);
; #pragma unroll
;     for (int mm = 0; mm < 2; ++mm)
; #pragma unroll
;       for (int n = 0; n < 4; ++n)
; #pragma unroll
;         for (int j = 0; j < 4; ++j) reg[(mm * 16 + fq * 4 + j) * 68 + n * 16 + fr] = acc[mp * 2 + mm][n][j];
;     __builtin_amdgcn_fence(__ATOMIC_ACQ_REL, "wavefront");
;     epi.tile(reg, row0 + mp * 32, col0, lane);
.LBB0_3060:
	s_or_b64 exec, exec, s[0:1]
	v_or_b32_e32 v107, 24, v130
	v_add_u32_e32 v96, v107, v129
	v_lshl_add_u32 v110, v96, 10, v128
	v_ashrrev_i32_e32 v111, 31, v110
	v_lshl_add_u64 v[122:123], v[110:111], 2, s[12:13]
	ds_read_b128 v[118:121], v98 offset:3264
	v_mov_b32_e32 v108, 0
	v_lshl_add_u64 v[110:111], v[110:111], 1, s[20:21]
	s_waitcnt vmcnt(19) lgkmcnt(0)
	v_mov_b32_e32 v114, v168
	v_mov_b32_e32 v115, v169
	v_mov_b32_e32 v116, v170
	v_mov_b32_e32 v117, v171
	v_pk_add_f32 v[114:115], v[118:119], v[114:115]
	v_pk_add_f32 v[116:117], v[120:121], v[116:117]
	global_store_dwordx4 v[122:123], v[114:117], off
	v_cvt_pk_bf16_f32 v118, v114, v115
	v_cvt_pk_bf16_f32 v119, v116, v117
	v_pk_mul_f32 v[114:115], v[114:115], v[114:115]
	v_pk_mul_f32 v[116:117], v[116:117], v[116:117]
	v_add_f32_e32 v97, v114, v115
	v_add_f32_e32 v97, v116, v97
	v_add_f32_e32 v97, v117, v97
	global_store_dwordx2 v[110:111], v[118:119], off
	s_nop 0
	v_add_f32_dpp v97, v97, v97 quad_perm:[1,0,3,2] row_mask:0xf bank_mask:0xf bound_ctrl:1
	s_nop 1
	v_add_f32_dpp v97, v97, v97 quad_perm:[2,3,0,1] row_mask:0xf bank_mask:0xf bound_ctrl:1
	s_nop 1
	v_add_f32_dpp v97, v97, v97 row_half_mirror row_mask:0xf bank_mask:0xf bound_ctrl:1
	s_nop 1
	v_mov_b32_dpp v108, v97 row_mirror row_mask:0xf bank_mask:0xf
	s_and_saveexec_b64 s[0:1], vcc
	s_cbranch_execz .LBB0_3062
	v_add_f32_e32 v108, v97, v108
	v_ashrrev_i32_e32 v97, 31, v96
	v_lshl_add_u64 v[96:97], v[96:97], 2, s[22:23]
	global_atomic_add_f32 v[96:97], v108, off
.LBB0_3062:
	s_or_b64 exec, exec, s[0:1]
	v_or_b32_e32 v108, 28, v130
	v_add_u32_e32 v96, v108, v129
	v_lshl_add_u32 v110, v96, 10, v128
	v_ashrrev_i32_e32 v111, 31, v110
	v_lshl_add_u64 v[122:123], v[110:111], 2, s[12:13]
	ds_read_b128 v[118:121], v98 offset:4352
	v_lshl_add_u64 v[110:111], v[110:111], 1, s[20:21]
	s_waitcnt vmcnt(21) lgkmcnt(0)
	v_mov_b32_e32 v114, v172
	v_mov_b32_e32 v115, v173
	v_mov_b32_e32 v116, v174
	v_mov_b32_e32 v117, v175
	v_pk_add_f32 v[114:115], v[118:119], v[114:115]
	v_pk_add_f32 v[116:117], v[120:121], v[116:117]
	global_store_dwordx4 v[122:123], v[114:117], off
	v_cvt_pk_bf16_f32 v118, v114, v115
	v_cvt_pk_bf16_f32 v119, v116, v117
	v_pk_mul_f32 v[114:115], v[114:115], v[114:115]
	v_pk_mul_f32 v[116:117], v[116:117], v[116:117]
	v_add_f32_e32 v97, v114, v115
	v_add_f32_e32 v97, v116, v97
	v_add_f32_e32 v97, v117, v97
	global_store_dwordx2 v[110:111], v[118:119], off
	v_mov_b32_e32 v110, 0
	v_add_f32_dpp v97, v97, v97 quad_perm:[1,0,3,2] row_mask:0xf bank_mask:0xf bound_ctrl:1
	s_nop 1
	v_add_f32_dpp v97, v97, v97 quad_perm:[2,3,0,1] row_mask:0xf bank_mask:0xf bound_ctrl:1
	s_nop 1
	v_add_f32_dpp v97, v97, v97 row_half_mirror row_mask:0xf bank_mask:0xf bound_ctrl:1
	s_nop 1
	v_mov_b32_dpp v110, v97 row_mirror row_mask:0xf bank_mask:0xf
	s_and_saveexec_b64 s[0:1], vcc
	s_cbranch_execz .LBB0_3064
	v_add_f32_e32 v110, v97, v110
	v_ashrrev_i32_e32 v97, 31, v96
	v_lshl_add_u64 v[96:97], v[96:97], 2, s[22:23]
	global_atomic_add_f32 v[96:97], v110, off
.LBB0_3064:
	s_or_b64 exec, exec, s[0:1]
	ds_write2_b32 v131, v88, v92 offset1:16
	ds_write2_b32 v131, v89, v93 offset0:68 offset1:84
	ds_write2_b32 v131, v90, v94 offset0:136 offset1:152
	ds_write2_b32 v131, v91, v95 offset0:204 offset1:220
	ds_write2_b32 v131, v80, v84 offset0:32 offset1:48
	ds_write2_b32 v131, v81, v85 offset0:100 offset1:116
	ds_write2_b32 v131, v82, v86 offset0:168 offset1:184
	ds_write2_b32 v131, v83, v87 offset0:236 offset1:252
	ds_write2_b32 v112, v72, v76 offset0:64 offset1:80
	ds_write2_b32 v112, v73, v77 offset0:132 offset1:148
	ds_write2_b32 v112, v74, v78 offset0:200 offset1:216
	ds_write2_b32 v104, v75, v79 offset0:12 offset1:28
	ds_write2_b32 v112, v64, v68 offset0:96 offset1:112
	ds_write2_b32 v112, v65, v69 offset0:164 offset1:180
	ds_write2_b32 v112, v66, v70 offset0:232 offset1:248
	ds_write2_b32 v104, v67, v71 offset0:44 offset1:60
	v_add_u32_e32 v185, 32, v129
	v_add_u32_e32 v184, v130, v185
	v_lshl_add_u32 v176, v184, 10, v128
	v_ashrrev_i32_e32 v177, 31, v176
	v_lshl_add_u64 v[178:179], v[176:177], 2, s[12:13]
	global_load_dwordx4 v[144:147], v[178:179], off
	v_add_u32_e32 v185, 32, v129
	v_add_u32_e32 v184, v99, v185
	v_lshl_add_u32 v176, v184, 10, v128
	v_ashrrev_i32_e32 v177, 31, v176
	v_lshl_add_u64 v[178:179], v[176:177], 2, s[12:13]
	global_load_dwordx4 v[148:151], v[178:179], off
	v_add_u32_e32 v185, 32, v129
	v_add_u32_e32 v184, v101, v185
	v_lshl_add_u32 v176, v184, 10, v128
	v_ashrrev_i32_e32 v177, 31, v176
	v_lshl_add_u64 v[178:179], v[176:177], 2, s[12:13]
	global_load_dwordx4 v[152:155], v[178:179], off
	v_add_u32_e32 v185, 32, v129
	v_add_u32_e32 v184, v103, v185
	v_lshl_add_u32 v176, v184, 10, v128
	v_ashrrev_i32_e32 v177, 31, v176
	v_lshl_add_u64 v[178:179], v[176:177], 2, s[12:13]
	global_load_dwordx4 v[156:159], v[178:179], off
	v_add_u32_e32 v185, 32, v129
	v_add_u32_e32 v184, v105, v185
	v_lshl_add_u32 v176, v184, 10, v128
	v_ashrrev_i32_e32 v177, 31, v176
	v_lshl_add_u64 v[178:179], v[176:177], 2, s[12:13]
	global_load_dwordx4 v[160:163], v[178:179], off
	v_add_u32_e32 v185, 32, v129
	v_add_u32_e32 v184, v106, v185
	v_lshl_add_u32 v176, v184, 10, v128
	v_ashrrev_i32_e32 v177, 31, v176
	v_lshl_add_u64 v[178:179], v[176:177], 2, s[12:13]
	global_load_dwordx4 v[164:167], v[178:179], off
	v_add_u32_e32 v185, 32, v129
	v_add_u32_e32 v184, v107, v185
	v_lshl_add_u32 v176, v184, 10, v128
	v_ashrrev_i32_e32 v177, 31, v176
	v_lshl_add_u64 v[178:179], v[176:177], 2, s[12:13]
	global_load_dwordx4 v[168:171], v[178:179], off
	v_add_u32_e32 v185, 32, v129
	v_add_u32_e32 v184, v108, v185
	v_lshl_add_u32 v176, v184, 10, v128
	v_ashrrev_i32_e32 v177, 31, v176
	v_lshl_add_u64 v[178:179], v[176:177], 2, s[12:13]
	global_load_dwordx4 v[172:175], v[178:179], off
	v_add_u32_e32 v67, 32, v129
	v_add_u32_e32 v64, v130, v67
	v_lshl_add_u32 v76, v64, 10, v128
	v_ashrrev_i32_e32 v77, 31, v76
	v_lshl_add_u64 v[78:79], v[76:77], 2, s[12:13]
	v_add_u32_e32 v66, v135, v109
	ds_read_b128 v[72:75], v66
	v_lshl_add_u64 v[76:77], v[76:77], 1, s[20:21]
	s_waitcnt vmcnt(7) lgkmcnt(0)
	v_mov_b32_e32 v68, v144
	v_mov_b32_e32 v69, v145
	v_mov_b32_e32 v70, v146
	v_mov_b32_e32 v71, v147
	v_pk_add_f32 v[68:69], v[72:73], v[68:69]
	v_pk_add_f32 v[70:71], v[74:75], v[70:71]
	global_store_dwordx4 v[78:79], v[68:71], off
	v_cvt_pk_bf16_f32 v72, v68, v69
	v_cvt_pk_bf16_f32 v73, v70, v71
	v_pk_mul_f32 v[68:69], v[68:69], v[68:69]
	v_pk_mul_f32 v[70:71], v[70:71], v[70:71]
	v_add_f32_e32 v65, v68, v69
	v_add_f32_e32 v65, v70, v65
	v_add_f32_e32 v65, v71, v65
	v_mov_b32_e32 v68, 0
	global_store_dwordx2 v[76:77], v[72:73], off
	v_add_f32_dpp v65, v65, v65 quad_perm:[1,0,3,2] row_mask:0xf bank_mask:0xf bound_ctrl:1
	s_nop 1
	v_add_f32_dpp v65, v65, v65 quad_perm:[2,3,0,1] row_mask:0xf bank_mask:0xf bound_ctrl:1
	s_nop 1
	v_add_f32_dpp v65, v65, v65 row_half_mirror row_mask:0xf bank_mask:0xf bound_ctrl:1
	s_nop 1
	v_mov_b32_dpp v68, v65 row_mirror row_mask:0xf bank_mask:0xf
	s_and_saveexec_b64 s[0:1], vcc
	s_cbranch_execz .LBB0_3066
;   __device__ __forceinline__ void tile(const float* reg, int row0, int col0, int lane) const {
;     rows4(reg, lane, [&](int it, int rr, int c4, float4 v) {
;       int row = row0 + rr, idx = row * 1024 + col0 + c4;
;       float4 xo = *(const float4*)(xold + idx);
;       v.x = fmaf(coef, v.x, xo.x); v.y = fmaf(coef, v.y, xo.y); v.z = fmaf(coef, v.z, xo.z); v.w = fmaf(coef, v.w, xo.w);
;       *(float4*)(xnew + idx) = v;
;       *(bf16x4*)(xb + idx) = pack4(v.x, v.y, v.z, v.w);
;       float s = row16_sum(v.x * v.x + v.y * v.y + v.z * v.z + v.w * v.w);
;       if ((lane & 15) == 0) atomicAdd(ssqn + row, s);
;     });
	v_add_f32_e32 v68, v65, v68
	v_ashrrev_i32_e32 v65, 31, v64
	v_lshl_add_u64 v[64:65], v[64:65], 2, s[22:23]
	global_atomic_add_f32 v[64:65], v68, off
.LBB0_3066:
	s_or_b64 exec, exec, s[0:1]
	v_add_u32_e32 v64, v99, v67
	v_lshl_add_u32 v76, v64, 10, v128
	v_ashrrev_i32_e32 v77, 31, v76
	v_lshl_add_u64 v[78:79], v[76:77], 2, s[12:13]
	ds_read_b128 v[72:75], v100
	v_lshl_add_u64 v[76:77], v[76:77], 1, s[20:21]
	s_waitcnt vmcnt(9) lgkmcnt(0)
	v_mov_b32_e32 v68, v148
	v_mov_b32_e32 v69, v149
	v_mov_b32_e32 v70, v150
	v_mov_b32_e32 v71, v151
	v_pk_add_f32 v[68:69], v[72:73], v[68:69]
	v_pk_add_f32 v[70:71], v[74:75], v[70:71]
	global_store_dwordx4 v[78:79], v[68:71], off
	v_cvt_pk_bf16_f32 v72, v68, v69
	v_cvt_pk_bf16_f32 v73, v70, v71
	v_pk_mul_f32 v[68:69], v[68:69], v[68:69]
	v_pk_mul_f32 v[70:71], v[70:71], v[70:71]
	v_add_f32_e32 v65, v68, v69
	v_add_f32_e32 v65, v70, v65
	v_add_f32_e32 v65, v71, v65
	v_mov_b32_e32 v68, 0
	global_store_dwordx2 v[76:77], v[72:73], off
	v_add_f32_dpp v65, v65, v65 quad_perm:[1,0,3,2] row_mask:0xf bank_mask:0xf bound_ctrl:1
	s_nop 1
	v_add_f32_dpp v65, v65, v65 quad_perm:[2,3,0,1] row_mask:0xf bank_mask:0xf bound_ctrl:1
	s_nop 1
	v_add_f32_dpp v65, v65, v65 row_half_mirror row_mask:0xf bank_mask:0xf bound_ctrl:1
	s_nop 1
	v_mov_b32_dpp v68, v65 row_mirror row_mask:0xf bank_mask:0xf
	s_and_saveexec_b64 s[0:1], vcc
	s_cbranch_execz .LBB0_3068
	v_add_f32_e32 v68, v65, v68
	v_ashrrev_i32_e32 v65, 31, v64
	v_lshl_add_u64 v[64:65], v[64:65], 2, s[22:23]
	global_atomic_add_f32 v[64:65], v68, off
.LBB0_3068:
	s_or_b64 exec, exec, s[0:1]
	v_add_u32_e32 v64, v101, v67
	v_lshl_add_u32 v76, v64, 10, v128
	v_ashrrev_i32_e32 v77, 31, v76
	v_lshl_add_u64 v[78:79], v[76:77], 2, s[12:13]
	ds_read_b128 v[72:75], v102
	v_lshl_add_u64 v[76:77], v[76:77], 1, s[20:21]
	s_waitcnt vmcnt(11) lgkmcnt(0)
	v_mov_b32_e32 v68, v152
	v_mov_b32_e32 v69, v153
	v_mov_b32_e32 v70, v154
	v_mov_b32_e32 v71, v155
	v_pk_add_f32 v[68:69], v[72:73], v[68:69]
	v_pk_add_f32 v[70:71], v[74:75], v[70:71]
	global_store_dwordx4 v[78:79], v[68:71], off
	v_cvt_pk_bf16_f32 v72, v68, v69
	v_cvt_pk_bf16_f32 v73, v70, v71
	v_pk_mul_f32 v[68:69], v[68:69], v[68:69]
	v_pk_mul_f32 v[70:71], v[70:71], v[70:71]
	v_add_f32_e32 v65, v68, v69
	v_add_f32_e32 v65, v70, v65
	v_add_f32_e32 v65, v71, v65
	v_mov_b32_e32 v68, 0
	global_store_dwordx2 v[76:77], v[72:73], off
	v_add_f32_dpp v65, v65, v65 quad_perm:[1,0,3,2] row_mask:0xf bank_mask:0xf bound_ctrl:1
	s_nop 1
	v_add_f32_dpp v65, v65, v65 quad_perm:[2,3,0,1] row_mask:0xf bank_mask:0xf bound_ctrl:1
	s_nop 1
	v_add_f32_dpp v65, v65, v65 row_half_mirror row_mask:0xf bank_mask:0xf bound_ctrl:1
	s_nop 1
	v_mov_b32_dpp v68, v65 row_mirror row_mask:0xf bank_mask:0xf
	s_and_saveexec_b64 s[0:1], vcc
	s_cbranch_execz .LBB0_3070
	v_add_f32_e32 v68, v65, v68
	v_ashrrev_i32_e32 v65, 31, v64
	v_lshl_add_u64 v[64:65], v[64:65], 2, s[22:23]
	global_atomic_add_f32 v[64:65], v68, off
.LBB0_3070:
	s_or_b64 exec, exec, s[0:1]
	v_add_u32_e32 v64, v103, v67
	v_lshl_add_u32 v76, v64, 10, v128
	v_ashrrev_i32_e32 v77, 31, v76
	v_lshl_add_u64 v[78:79], v[76:77], 2, s[12:13]
	ds_read_b128 v[72:75], v98
	v_lshl_add_u64 v[76:77], v[76:77], 1, s[20:21]
	s_waitcnt vmcnt(13) lgkmcnt(0)
	v_mov_b32_e32 v68, v156
	v_mov_b32_e32 v69, v157
	v_mov_b32_e32 v70, v158
	v_mov_b32_e32 v71, v159
	v_pk_add_f32 v[68:69], v[72:73], v[68:69]
	v_pk_add_f32 v[70:71], v[74:75], v[70:71]
	global_store_dwordx4 v[78:79], v[68:71], off
	v_cvt_pk_bf16_f32 v72, v68, v69
	v_cvt_pk_bf16_f32 v73, v70, v71
	v_pk_mul_f32 v[68:69], v[68:69], v[68:69]
	v_pk_mul_f32 v[70:71], v[70:71], v[70:71]
	v_add_f32_e32 v65, v68, v69
	v_add_f32_e32 v65, v70, v65
	v_add_f32_e32 v65, v71, v65
	v_mov_b32_e32 v68, 0
	global_store_dwordx2 v[76:77], v[72:73], off
	v_add_f32_dpp v65, v65, v65 quad_perm:[1,0,3,2] row_mask:0xf bank_mask:0xf bound_ctrl:1
	s_nop 1
	v_add_f32_dpp v65, v65, v65 quad_perm:[2,3,0,1] row_mask:0xf bank_mask:0xf bound_ctrl:1
	s_nop 1
	v_add_f32_dpp v65, v65, v65 row_half_mirror row_mask:0xf bank_mask:0xf bound_ctrl:1
	s_nop 1
	v_mov_b32_dpp v68, v65 row_mirror row_mask:0xf bank_mask:0xf
	s_and_saveexec_b64 s[0:1], vcc
	s_cbranch_execz .LBB0_3072
	v_add_f32_e32 v68, v65, v68
	v_ashrrev_i32_e32 v65, 31, v64
	v_lshl_add_u64 v[64:65], v[64:65], 2, s[22:23]
	global_atomic_add_f32 v[64:65], v68, off
.LBB0_3072:
	s_or_b64 exec, exec, s[0:1]
	v_add_u32_e32 v64, v105, v67
	v_lshl_add_u32 v76, v64, 10, v128
	v_ashrrev_i32_e32 v77, 31, v76
	v_lshl_add_u64 v[78:79], v[76:77], 2, s[12:13]
	ds_read_b128 v[72:75], v98 offset:1088
	v_lshl_add_u64 v[76:77], v[76:77], 1, s[20:21]
	s_waitcnt vmcnt(15) lgkmcnt(0)
	v_mov_b32_e32 v68, v160
	v_mov_b32_e32 v69, v161
	v_mov_b32_e32 v70, v162
	v_mov_b32_e32 v71, v163
	v_pk_add_f32 v[68:69], v[72:73], v[68:69]
	v_pk_add_f32 v[70:71], v[74:75], v[70:71]
	global_store_dwordx4 v[78:79], v[68:71], off
	v_cvt_pk_bf16_f32 v72, v68, v69
	v_cvt_pk_bf16_f32 v73, v70, v71
	v_pk_mul_f32 v[68:69], v[68:69], v[68:69]
	v_pk_mul_f32 v[70:71], v[70:71], v[70:71]
	v_add_f32_e32 v65, v68, v69
	v_add_f32_e32 v65, v70, v65
	v_add_f32_e32 v65, v71, v65
	v_mov_b32_e32 v68, 0
	global_store_dwordx2 v[76:77], v[72:73], off
	v_add_f32_dpp v65, v65, v65 quad_perm:[1,0,3,2] row_mask:0xf bank_mask:0xf bound_ctrl:1
	s_nop 1
	v_add_f32_dpp v65, v65, v65 quad_perm:[2,3,0,1] row_mask:0xf bank_mask:0xf bound_ctrl:1
	s_nop 1
	v_add_f32_dpp v65, v65, v65 row_half_mirror row_mask:0xf bank_mask:0xf bound_ctrl:1
	s_nop 1
	v_mov_b32_dpp v68, v65 row_mirror row_mask:0xf bank_mask:0xf
	s_and_saveexec_b64 s[0:1], vcc
	s_cbranch_execz .LBB0_3074
	v_add_f32_e32 v68, v65, v68
	v_ashrrev_i32_e32 v65, 31, v64
	v_lshl_add_u64 v[64:65], v[64:65], 2, s[22:23]
	global_atomic_add_f32 v[64:65], v68, off
;   __device__ __forceinline__ void tile(const float* reg, int row0, int col0, int lane) const {
;     rows4(reg, lane, [&](int it, int rr, int c4, float4 v) {
;       int row = row0 + rr, idx = row * 1024 + col0 + c4;
;       float4 xo = *(const float4*)(xold + idx);
;       v.x = fmaf(coef, v.x, xo.x); v.y = fmaf(coef, v.y, xo.y); v.z = fmaf(coef, v.z, xo.z); v.w = fmaf(coef, v.w, xo.w);
;       *(float4*)(xnew + idx) = v;
;       *(bf16x4*)(xb + idx) = pack4(v.x, v.y, v.z, v.w);
;       float s = row16_sum(v.x * v.x + v.y * v.y + v.z * v.z + v.w * v.w);
;       if ((lane & 15) == 0) atomicAdd(ssqn + row, s);
;     });
.LBB0_3074:
	s_or_b64 exec, exec, s[0:1]
	v_add_u32_e32 v64, v106, v67
	v_lshl_add_u32 v76, v64, 10, v128
	v_ashrrev_i32_e32 v77, 31, v76
	v_lshl_add_u64 v[78:79], v[76:77], 2, s[12:13]
	ds_read_b128 v[72:75], v98 offset:2176
	v_lshl_add_u64 v[76:77], v[76:77], 1, s[20:21]
	s_waitcnt vmcnt(17) lgkmcnt(0)
	v_mov_b32_e32 v68, v164
	v_mov_b32_e32 v69, v165
	v_mov_b32_e32 v70, v166
	v_mov_b32_e32 v71, v167
	v_pk_add_f32 v[68:69], v[72:73], v[68:69]
	v_pk_add_f32 v[70:71], v[74:75], v[70:71]
	global_store_dwordx4 v[78:79], v[68:71], off
	v_cvt_pk_bf16_f32 v72, v68, v69
	v_cvt_pk_bf16_f32 v73, v70, v71
	v_pk_mul_f32 v[68:69], v[68:69], v[68:69]
	v_pk_mul_f32 v[70:71], v[70:71], v[70:71]
	v_add_f32_e32 v65, v68, v69
	v_add_f32_e32 v65, v70, v65
	v_add_f32_e32 v65, v71, v65
	v_mov_b32_e32 v68, 0
	global_store_dwordx2 v[76:77], v[72:73], off
	v_add_f32_dpp v65, v65, v65 quad_perm:[1,0,3,2] row_mask:0xf bank_mask:0xf bound_ctrl:1
	s_nop 1
	v_add_f32_dpp v65, v65, v65 quad_perm:[2,3,0,1] row_mask:0xf bank_mask:0xf bound_ctrl:1
	s_nop 1
	v_add_f32_dpp v65, v65, v65 row_half_mirror row_mask:0xf bank_mask:0xf bound_ctrl:1
	s_nop 1
	v_mov_b32_dpp v68, v65 row_mirror row_mask:0xf bank_mask:0xf
	s_and_saveexec_b64 s[0:1], vcc
	s_cbranch_execz .LBB0_3076
	v_add_f32_e32 v68, v65, v68
	v_ashrrev_i32_e32 v65, 31, v64
	v_lshl_add_u64 v[64:65], v[64:65], 2, s[22:23]
	global_atomic_add_f32 v[64:65], v68, off
.LBB0_3076:
	s_or_b64 exec, exec, s[0:1]
	v_add_u32_e32 v64, v107, v67
	v_lshl_add_u32 v76, v64, 10, v128
	v_ashrrev_i32_e32 v77, 31, v76
	v_lshl_add_u64 v[78:79], v[76:77], 2, s[12:13]
	ds_read_b128 v[72:75], v98 offset:3264
	v_lshl_add_u64 v[76:77], v[76:77], 1, s[20:21]
	s_waitcnt vmcnt(19) lgkmcnt(0)
	v_mov_b32_e32 v68, v168
	v_mov_b32_e32 v69, v169
	v_mov_b32_e32 v70, v170
	v_mov_b32_e32 v71, v171
	v_pk_add_f32 v[68:69], v[72:73], v[68:69]
	v_pk_add_f32 v[70:71], v[74:75], v[70:71]
	global_store_dwordx4 v[78:79], v[68:71], off
	v_cvt_pk_bf16_f32 v72, v68, v69
	v_cvt_pk_bf16_f32 v73, v70, v71
	v_pk_mul_f32 v[68:69], v[68:69], v[68:69]
	v_pk_mul_f32 v[70:71], v[70:71], v[70:71]
	v_add_f32_e32 v65, v68, v69
	v_add_f32_e32 v65, v70, v65
	v_add_f32_e32 v65, v71, v65
	v_mov_b32_e32 v68, 0
	global_store_dwordx2 v[76:77], v[72:73], off
	v_add_f32_dpp v65, v65, v65 quad_perm:[1,0,3,2] row_mask:0xf bank_mask:0xf bound_ctrl:1
	s_nop 1
	v_add_f32_dpp v65, v65, v65 quad_perm:[2,3,0,1] row_mask:0xf bank_mask:0xf bound_ctrl:1
	s_nop 1
	v_add_f32_dpp v65, v65, v65 row_half_mirror row_mask:0xf bank_mask:0xf bound_ctrl:1
	s_nop 1
	v_mov_b32_dpp v68, v65 row_mirror row_mask:0xf bank_mask:0xf
	s_and_saveexec_b64 s[0:1], vcc
	s_cbranch_execz .LBB0_3078
	v_add_f32_e32 v68, v65, v68
	v_ashrrev_i32_e32 v65, 31, v64
	v_lshl_add_u64 v[64:65], v[64:65], 2, s[22:23]
	global_atomic_add_f32 v[64:65], v68, off
.LBB0_3078:
	s_or_b64 exec, exec, s[0:1]
	v_add_u32_e32 v64, v108, v67
	v_lshl_add_u32 v76, v64, 10, v128
	v_ashrrev_i32_e32 v77, 31, v76
	v_lshl_add_u64 v[78:79], v[76:77], 2, s[12:13]
	ds_read_b128 v[72:75], v98 offset:4352
	v_mov_b32_e32 v67, 0
	v_lshl_add_u64 v[76:77], v[76:77], 1, s[20:21]
	s_waitcnt vmcnt(21) lgkmcnt(0)
	v_mov_b32_e32 v68, v172
	v_mov_b32_e32 v69, v173
	v_mov_b32_e32 v70, v174
	v_mov_b32_e32 v71, v175
	v_pk_add_f32 v[68:69], v[72:73], v[68:69]
	v_pk_add_f32 v[70:71], v[74:75], v[70:71]
	global_store_dwordx4 v[78:79], v[68:71], off
	v_cvt_pk_bf16_f32 v72, v68, v69
	v_cvt_pk_bf16_f32 v73, v70, v71
	v_pk_mul_f32 v[68:69], v[68:69], v[68:69]
	v_pk_mul_f32 v[70:71], v[70:71], v[70:71]
	v_add_f32_e32 v65, v68, v69
	v_add_f32_e32 v65, v70, v65
	v_add_f32_e32 v65, v71, v65
	global_store_dwordx2 v[76:77], v[72:73], off
	s_nop 0
	v_add_f32_dpp v65, v65, v65 quad_perm:[1,0,3,2] row_mask:0xf bank_mask:0xf bound_ctrl:1
	s_nop 1
	v_add_f32_dpp v65, v65, v65 quad_perm:[2,3,0,1] row_mask:0xf bank_mask:0xf bound_ctrl:1
	s_nop 1
	v_add_f32_dpp v65, v65, v65 row_half_mirror row_mask:0xf bank_mask:0xf bound_ctrl:1
	s_nop 1
	v_mov_b32_dpp v67, v65 row_mirror row_mask:0xf bank_mask:0xf
	s_and_saveexec_b64 s[0:1], vcc
	s_cbranch_execz .LBB0_3080
	v_add_f32_e32 v67, v65, v67
	v_ashrrev_i32_e32 v65, 31, v64
	v_lshl_add_u64 v[64:65], v[64:65], 2, s[22:23]
	global_atomic_add_f32 v[64:65], v67, off
;   __device__ __forceinline__ void tile(const float* reg, int row0, int col0, int lane) const {
;     rows4(reg, lane, [&](int it, int rr, int c4, float4 v) {
;       int row = row0 + rr, idx = row * 1024 + col0 + c4;
;       float4 xo = *(const float4*)(xold + idx);
;       v.x = fmaf(coef, v.x, xo.x); v.y = fmaf(coef, v.y, xo.y); v.z = fmaf(coef, v.z, xo.z); v.w = fmaf(coef, v.w, xo.w);
;       *(float4*)(xnew + idx) = v;
;       *(bf16x4*)(xb + idx) = pack4(v.x, v.y, v.z, v.w);
;       float s = row16_sum(v.x * v.x + v.y * v.y + v.z * v.z + v.w * v.w);
;       if ((lane & 15) == 0) atomicAdd(ssqn + row, s);
;     });
; template <int MF, class Epi>
; __device__ __forceinline__ void staged_epilogue(f32x4 (&acc)[MF][4], int row0, int col0, const Epi& epi) {
;   const int lane = tidx() & 63, wid = tidx() >> 6, fr = lane & 15, fq = lane >> 4;
;   float* reg = (float*)(g_shm + 65536 + wid * 8704);
; #pragma unroll
;   for (int mp = 0; mp < MF / 2; ++mp) {
;     __builtin_amdgcn_sched_barrier(0);
; #pragma unroll
;     for (int mm = 0; mm < 2; ++mm)
; #pragma unroll
;       for (int n = 0; n < 4; ++n)
; #pragma unroll
;         for (int j = 0; j < 4; ++j) reg[(mm * 16 + fq * 4 + j) * 68 + n * 16 + fr] = acc[mp * 2 + mm][n][j];
;     __builtin_amdgcn_fence(__ATOMIC_ACQ_REL, "wavefront");
;     epi.tile(reg, row0 + mp * 32, col0, lane);
.LBB0_3080:
	s_or_b64 exec, exec, s[0:1]
	ds_write2_b32 v131, v56, v60 offset1:16
	ds_write2_b32 v131, v57, v61 offset0:68 offset1:84
	ds_write2_b32 v131, v58, v62 offset0:136 offset1:152
	ds_write2_b32 v131, v59, v63 offset0:204 offset1:220
	ds_write2_b32 v131, v48, v52 offset0:32 offset1:48
	ds_write2_b32 v131, v49, v53 offset0:100 offset1:116
	ds_write2_b32 v131, v50, v54 offset0:168 offset1:184
	ds_write2_b32 v131, v51, v55 offset0:236 offset1:252
	ds_write2_b32 v112, v40, v44 offset0:64 offset1:80
	ds_write2_b32 v112, v41, v45 offset0:132 offset1:148
	ds_write2_b32 v112, v42, v46 offset0:200 offset1:216
	ds_write2_b32 v104, v43, v47 offset0:12 offset1:28
	ds_write2_b32 v112, v32, v36 offset0:96 offset1:112
	ds_write2_b32 v112, v33, v37 offset0:164 offset1:180
	ds_write2_b32 v112, v34, v38 offset0:232 offset1:248
	ds_write2_b32 v104, v35, v39 offset0:44 offset1:60
	v_add_u32_e32 v185, 64, v129
	v_add_u32_e32 v184, v130, v185
	v_lshl_add_u32 v176, v184, 10, v128
	v_ashrrev_i32_e32 v177, 31, v176
	v_lshl_add_u64 v[178:179], v[176:177], 2, s[12:13]
	global_load_dwordx4 v[144:147], v[178:179], off
	v_add_u32_e32 v185, 64, v129
	v_add_u32_e32 v184, v99, v185
	v_lshl_add_u32 v176, v184, 10, v128
	v_ashrrev_i32_e32 v177, 31, v176
	v_lshl_add_u64 v[178:179], v[176:177], 2, s[12:13]
	global_load_dwordx4 v[148:151], v[178:179], off
	v_add_u32_e32 v185, 64, v129
	v_add_u32_e32 v184, v101, v185
	v_lshl_add_u32 v176, v184, 10, v128
	v_ashrrev_i32_e32 v177, 31, v176
	v_lshl_add_u64 v[178:179], v[176:177], 2, s[12:13]
	global_load_dwordx4 v[152:155], v[178:179], off
	v_add_u32_e32 v185, 64, v129
	v_add_u32_e32 v184, v103, v185
	v_lshl_add_u32 v176, v184, 10, v128
	v_ashrrev_i32_e32 v177, 31, v176
	v_lshl_add_u64 v[178:179], v[176:177], 2, s[12:13]
	global_load_dwordx4 v[156:159], v[178:179], off
	v_add_u32_e32 v185, 64, v129
	v_add_u32_e32 v184, v105, v185
	v_lshl_add_u32 v176, v184, 10, v128
	v_ashrrev_i32_e32 v177, 31, v176
	v_lshl_add_u64 v[178:179], v[176:177], 2, s[12:13]
	global_load_dwordx4 v[160:163], v[178:179], off
	v_add_u32_e32 v185, 64, v129
	v_add_u32_e32 v184, v106, v185
	v_lshl_add_u32 v176, v184, 10, v128
	v_ashrrev_i32_e32 v177, 31, v176
	v_lshl_add_u64 v[178:179], v[176:177], 2, s[12:13]
	global_load_dwordx4 v[164:167], v[178:179], off
	v_add_u32_e32 v185, 64, v129
	v_add_u32_e32 v184, v107, v185
	v_lshl_add_u32 v176, v184, 10, v128
	v_ashrrev_i32_e32 v177, 31, v176
	v_lshl_add_u64 v[178:179], v[176:177], 2, s[12:13]
	global_load_dwordx4 v[168:171], v[178:179], off
	v_add_u32_e32 v185, 64, v129
	v_add_u32_e32 v184, v108, v185
	v_lshl_add_u32 v176, v184, 10, v128
	v_ashrrev_i32_e32 v177, 31, v176
	v_lshl_add_u64 v[178:179], v[176:177], 2, s[12:13]
	global_load_dwordx4 v[172:175], v[178:179], off
	v_add_u32_e32 v34, 64, v129
	v_add_u32_e32 v32, v130, v34
	v_lshl_add_u32 v44, v32, 10, v128
	v_ashrrev_i32_e32 v45, 31, v44
	v_lshl_add_u64 v[46:47], v[44:45], 2, s[12:13]
	ds_read_b128 v[40:43], v66
	v_mov_b32_e32 v35, 0
	v_lshl_add_u64 v[44:45], v[44:45], 1, s[20:21]
	s_waitcnt vmcnt(7) lgkmcnt(0)
	v_mov_b32_e32 v36, v144
	v_mov_b32_e32 v37, v145
	v_mov_b32_e32 v38, v146
	v_mov_b32_e32 v39, v147
	v_pk_add_f32 v[36:37], v[40:41], v[36:37]
	v_pk_add_f32 v[38:39], v[42:43], v[38:39]
	global_store_dwordx4 v[46:47], v[36:39], off
	v_cvt_pk_bf16_f32 v40, v36, v37
	v_cvt_pk_bf16_f32 v41, v38, v39
	v_pk_mul_f32 v[36:37], v[36:37], v[36:37]
	v_pk_mul_f32 v[38:39], v[38:39], v[38:39]
	v_add_f32_e32 v33, v36, v37
	v_add_f32_e32 v33, v38, v33
	v_add_f32_e32 v33, v39, v33
	global_store_dwordx2 v[44:45], v[40:41], off
	s_nop 0
	v_add_f32_dpp v33, v33, v33 quad_perm:[1,0,3,2] row_mask:0xf bank_mask:0xf bound_ctrl:1
	s_nop 1
	v_add_f32_dpp v33, v33, v33 quad_perm:[2,3,0,1] row_mask:0xf bank_mask:0xf bound_ctrl:1
	s_nop 1
	v_add_f32_dpp v33, v33, v33 row_half_mirror row_mask:0xf bank_mask:0xf bound_ctrl:1
	s_nop 1
	v_mov_b32_dpp v35, v33 row_mirror row_mask:0xf bank_mask:0xf
	s_and_saveexec_b64 s[0:1], vcc
	s_cbranch_execz .LBB0_3082
	v_add_f32_e32 v35, v33, v35
	v_ashrrev_i32_e32 v33, 31, v32
	v_lshl_add_u64 v[32:33], v[32:33], 2, s[22:23]
	global_atomic_add_f32 v[32:33], v35, off
.LBB0_3082:
	s_or_b64 exec, exec, s[0:1]
	v_add_u32_e32 v32, v99, v34
	v_lshl_add_u32 v44, v32, 10, v128
	v_ashrrev_i32_e32 v45, 31, v44
	v_lshl_add_u64 v[46:47], v[44:45], 2, s[12:13]
	ds_read_b128 v[40:43], v100
	v_mov_b32_e32 v35, 0
	v_lshl_add_u64 v[44:45], v[44:45], 1, s[20:21]
	s_waitcnt vmcnt(9) lgkmcnt(0)
	v_mov_b32_e32 v36, v148
	v_mov_b32_e32 v37, v149
	v_mov_b32_e32 v38, v150
	v_mov_b32_e32 v39, v151
	v_pk_add_f32 v[36:37], v[40:41], v[36:37]
	v_pk_add_f32 v[38:39], v[42:43], v[38:39]
	global_store_dwordx4 v[46:47], v[36:39], off
	v_cvt_pk_bf16_f32 v40, v36, v37
	v_cvt_pk_bf16_f32 v41, v38, v39
	v_pk_mul_f32 v[36:37], v[36:37], v[36:37]
	v_pk_mul_f32 v[38:39], v[38:39], v[38:39]
	v_add_f32_e32 v33, v36, v37
	v_add_f32_e32 v33, v38, v33
	v_add_f32_e32 v33, v39, v33
	global_store_dwordx2 v[44:45], v[40:41], off
	s_nop 0
	v_add_f32_dpp v33, v33, v33 quad_perm:[1,0,3,2] row_mask:0xf bank_mask:0xf bound_ctrl:1
	s_nop 1
	v_add_f32_dpp v33, v33, v33 quad_perm:[2,3,0,1] row_mask:0xf bank_mask:0xf bound_ctrl:1
	s_nop 1
	v_add_f32_dpp v33, v33, v33 row_half_mirror row_mask:0xf bank_mask:0xf bound_ctrl:1
	s_nop 1
	v_mov_b32_dpp v35, v33 row_mirror row_mask:0xf bank_mask:0xf
	s_and_saveexec_b64 s[0:1], vcc
	s_cbranch_execz .LBB0_3084
	v_add_f32_e32 v35, v33, v35
	v_ashrrev_i32_e32 v33, 31, v32
	v_lshl_add_u64 v[32:33], v[32:33], 2, s[22:23]
	global_atomic_add_f32 v[32:33], v35, off
;   __device__ __forceinline__ void tile(const float* reg, int row0, int col0, int lane) const {
;     rows4(reg, lane, [&](int it, int rr, int c4, float4 v) {
;       int row = row0 + rr, idx = row * 1024 + col0 + c4;
;       float4 xo = *(const float4*)(xold + idx);
;       v.x = fmaf(coef, v.x, xo.x); v.y = fmaf(coef, v.y, xo.y); v.z = fmaf(coef, v.z, xo.z); v.w = fmaf(coef, v.w, xo.w);
;       *(float4*)(xnew + idx) = v;
;       *(bf16x4*)(xb + idx) = pack4(v.x, v.y, v.z, v.w);
;       float s = row16_sum(v.x * v.x + v.y * v.y + v.z * v.z + v.w * v.w);
;       if ((lane & 15) == 0) atomicAdd(ssqn + row, s);
;     });
.LBB0_3084:
	s_or_b64 exec, exec, s[0:1]
	v_add_u32_e32 v32, v101, v34
	v_lshl_add_u32 v44, v32, 10, v128
	v_ashrrev_i32_e32 v45, 31, v44
	v_lshl_add_u64 v[46:47], v[44:45], 2, s[12:13]
	ds_read_b128 v[40:43], v102
	v_mov_b32_e32 v35, 0
	v_lshl_add_u64 v[44:45], v[44:45], 1, s[20:21]
	s_waitcnt vmcnt(11) lgkmcnt(0)
	v_mov_b32_e32 v36, v152
	v_mov_b32_e32 v37, v153
	v_mov_b32_e32 v38, v154
	v_mov_b32_e32 v39, v155
	v_pk_add_f32 v[36:37], v[40:41], v[36:37]
	v_pk_add_f32 v[38:39], v[42:43], v[38:39]
	global_store_dwordx4 v[46:47], v[36:39], off
	v_cvt_pk_bf16_f32 v40, v36, v37
	v_cvt_pk_bf16_f32 v41, v38, v39
	v_pk_mul_f32 v[36:37], v[36:37], v[36:37]
	v_pk_mul_f32 v[38:39], v[38:39], v[38:39]
	v_add_f32_e32 v33, v36, v37
	v_add_f32_e32 v33, v38, v33
	v_add_f32_e32 v33, v39, v33
	global_store_dwordx2 v[44:45], v[40:41], off
	s_nop 0
	v_add_f32_dpp v33, v33, v33 quad_perm:[1,0,3,2] row_mask:0xf bank_mask:0xf bound_ctrl:1
	s_nop 1
	v_add_f32_dpp v33, v33, v33 quad_perm:[2,3,0,1] row_mask:0xf bank_mask:0xf bound_ctrl:1
	s_nop 1
	v_add_f32_dpp v33, v33, v33 row_half_mirror row_mask:0xf bank_mask:0xf bound_ctrl:1
	s_nop 1
	v_mov_b32_dpp v35, v33 row_mirror row_mask:0xf bank_mask:0xf
	s_and_saveexec_b64 s[0:1], vcc
	s_cbranch_execz .LBB0_3086
	v_add_f32_e32 v35, v33, v35
	v_ashrrev_i32_e32 v33, 31, v32
	v_lshl_add_u64 v[32:33], v[32:33], 2, s[22:23]
	global_atomic_add_f32 v[32:33], v35, off
.LBB0_3086:
	s_or_b64 exec, exec, s[0:1]
	v_add_u32_e32 v32, v103, v34
	v_lshl_add_u32 v44, v32, 10, v128
	v_ashrrev_i32_e32 v45, 31, v44
	v_lshl_add_u64 v[46:47], v[44:45], 2, s[12:13]
	ds_read_b128 v[40:43], v98
	v_mov_b32_e32 v35, 0
	v_lshl_add_u64 v[44:45], v[44:45], 1, s[20:21]
	s_waitcnt vmcnt(13) lgkmcnt(0)
	v_mov_b32_e32 v36, v156
	v_mov_b32_e32 v37, v157
	v_mov_b32_e32 v38, v158
	v_mov_b32_e32 v39, v159
	v_pk_add_f32 v[36:37], v[40:41], v[36:37]
	v_pk_add_f32 v[38:39], v[42:43], v[38:39]
	global_store_dwordx4 v[46:47], v[36:39], off
	v_cvt_pk_bf16_f32 v40, v36, v37
	v_cvt_pk_bf16_f32 v41, v38, v39
	v_pk_mul_f32 v[36:37], v[36:37], v[36:37]
	v_pk_mul_f32 v[38:39], v[38:39], v[38:39]
	v_add_f32_e32 v33, v36, v37
	v_add_f32_e32 v33, v38, v33
	v_add_f32_e32 v33, v39, v33
	global_store_dwordx2 v[44:45], v[40:41], off
	s_nop 0
	v_add_f32_dpp v33, v33, v33 quad_perm:[1,0,3,2] row_mask:0xf bank_mask:0xf bound_ctrl:1
	s_nop 1
	v_add_f32_dpp v33, v33, v33 quad_perm:[2,3,0,1] row_mask:0xf bank_mask:0xf bound_ctrl:1
	s_nop 1
	v_add_f32_dpp v33, v33, v33 row_half_mirror row_mask:0xf bank_mask:0xf bound_ctrl:1
	s_nop 1
	v_mov_b32_dpp v35, v33 row_mirror row_mask:0xf bank_mask:0xf
	s_and_saveexec_b64 s[0:1], vcc
	s_cbranch_execz .LBB0_3088
	v_add_f32_e32 v35, v33, v35
	v_ashrrev_i32_e32 v33, 31, v32
	v_lshl_add_u64 v[32:33], v[32:33], 2, s[22:23]
	global_atomic_add_f32 v[32:33], v35, off
.LBB0_3088:
	s_or_b64 exec, exec, s[0:1]
	v_add_u32_e32 v32, v105, v34
	v_lshl_add_u32 v44, v32, 10, v128
	v_ashrrev_i32_e32 v45, 31, v44
	v_lshl_add_u64 v[46:47], v[44:45], 2, s[12:13]
	ds_read_b128 v[40:43], v98 offset:1088
	v_mov_b32_e32 v35, 0
	v_lshl_add_u64 v[44:45], v[44:45], 1, s[20:21]
	s_waitcnt vmcnt(15) lgkmcnt(0)
	v_mov_b32_e32 v36, v160
	v_mov_b32_e32 v37, v161
	v_mov_b32_e32 v38, v162
	v_mov_b32_e32 v39, v163
	v_pk_add_f32 v[36:37], v[40:41], v[36:37]
	v_pk_add_f32 v[38:39], v[42:43], v[38:39]
	global_store_dwordx4 v[46:47], v[36:39], off
	v_cvt_pk_bf16_f32 v40, v36, v37
	v_cvt_pk_bf16_f32 v41, v38, v39
	v_pk_mul_f32 v[36:37], v[36:37], v[36:37]
	v_pk_mul_f32 v[38:39], v[38:39], v[38:39]
	v_add_f32_e32 v33, v36, v37
	v_add_f32_e32 v33, v38, v33
	v_add_f32_e32 v33, v39, v33
	global_store_dwordx2 v[44:45], v[40:41], off
	s_nop 0
	v_add_f32_dpp v33, v33, v33 quad_perm:[1,0,3,2] row_mask:0xf bank_mask:0xf bound_ctrl:1
	s_nop 1
	v_add_f32_dpp v33, v33, v33 quad_perm:[2,3,0,1] row_mask:0xf bank_mask:0xf bound_ctrl:1
	s_nop 1
	v_add_f32_dpp v33, v33, v33 row_half_mirror row_mask:0xf bank_mask:0xf bound_ctrl:1
	s_nop 1
	v_mov_b32_dpp v35, v33 row_mirror row_mask:0xf bank_mask:0xf
	s_and_saveexec_b64 s[0:1], vcc
	s_cbranch_execz .LBB0_3090
	v_add_f32_e32 v35, v33, v35
	v_ashrrev_i32_e32 v33, 31, v32
	v_lshl_add_u64 v[32:33], v[32:33], 2, s[22:23]
	global_atomic_add_f32 v[32:33], v35, off
.LBB0_3090:
	s_or_b64 exec, exec, s[0:1]
	v_add_u32_e32 v32, v106, v34
	v_lshl_add_u32 v44, v32, 10, v128
	v_ashrrev_i32_e32 v45, 31, v44
	v_lshl_add_u64 v[46:47], v[44:45], 2, s[12:13]
	ds_read_b128 v[40:43], v98 offset:2176
	v_mov_b32_e32 v35, 0
	v_lshl_add_u64 v[44:45], v[44:45], 1, s[20:21]
	s_waitcnt vmcnt(17) lgkmcnt(0)
	v_mov_b32_e32 v36, v164
	v_mov_b32_e32 v37, v165
	v_mov_b32_e32 v38, v166
	v_mov_b32_e32 v39, v167
	v_pk_add_f32 v[36:37], v[40:41], v[36:37]
	v_pk_add_f32 v[38:39], v[42:43], v[38:39]
	global_store_dwordx4 v[46:47], v[36:39], off
	v_cvt_pk_bf16_f32 v40, v36, v37
	v_cvt_pk_bf16_f32 v41, v38, v39
	v_pk_mul_f32 v[36:37], v[36:37], v[36:37]
	v_pk_mul_f32 v[38:39], v[38:39], v[38:39]
	v_add_f32_e32 v33, v36, v37
	v_add_f32_e32 v33, v38, v33
	v_add_f32_e32 v33, v39, v33
	global_store_dwordx2 v[44:45], v[40:41], off
	s_nop 0
	v_add_f32_dpp v33, v33, v33 quad_perm:[1,0,3,2] row_mask:0xf bank_mask:0xf bound_ctrl:1
	s_nop 1
	v_add_f32_dpp v33, v33, v33 quad_perm:[2,3,0,1] row_mask:0xf bank_mask:0xf bound_ctrl:1
	s_nop 1
	v_add_f32_dpp v33, v33, v33 row_half_mirror row_mask:0xf bank_mask:0xf bound_ctrl:1
	s_nop 1
	v_mov_b32_dpp v35, v33 row_mirror row_mask:0xf bank_mask:0xf
	s_and_saveexec_b64 s[0:1], vcc
	s_cbranch_execz .LBB0_3092
	v_add_f32_e32 v35, v33, v35
	v_ashrrev_i32_e32 v33, 31, v32
	v_lshl_add_u64 v[32:33], v[32:33], 2, s[22:23]
	global_atomic_add_f32 v[32:33], v35, off
;   __device__ __forceinline__ void tile(const float* reg, int row0, int col0, int lane) const {
;     rows4(reg, lane, [&](int it, int rr, int c4, float4 v) {
;       int row = row0 + rr, idx = row * 1024 + col0 + c4;
;       float4 xo = *(const float4*)(xold + idx);
;       v.x = fmaf(coef, v.x, xo.x); v.y = fmaf(coef, v.y, xo.y); v.z = fmaf(coef, v.z, xo.z); v.w = fmaf(coef, v.w, xo.w);
;       *(float4*)(xnew + idx) = v;
;       *(bf16x4*)(xb + idx) = pack4(v.x, v.y, v.z, v.w);
;       float s = row16_sum(v.x * v.x + v.y * v.y + v.z * v.z + v.w * v.w);
;       if ((lane & 15) == 0) atomicAdd(ssqn + row, s);
;     });
; template <int MF, class Epi>
; __device__ __forceinline__ void staged_epilogue(f32x4 (&acc)[MF][4], int row0, int col0, const Epi& epi) {
;   const int lane = tidx() & 63, wid = tidx() >> 6, fr = lane & 15, fq = lane >> 4;
;   float* reg = (float*)(g_shm + 65536 + wid * 8704);
; #pragma unroll
;   for (int mp = 0; mp < MF / 2; ++mp) {
;     __builtin_amdgcn_sched_barrier(0);
; #pragma unroll
;     for (int mm = 0; mm < 2; ++mm)
; #pragma unroll
;       for (int n = 0; n < 4; ++n)
; #pragma unroll
;         for (int j = 0; j < 4; ++j) reg[(mm * 16 + fq * 4 + j) * 68 + n * 16 + fr] = acc[mp * 2 + mm][n][j];
;     __builtin_amdgcn_fence(__ATOMIC_ACQ_REL, "wavefront");
;     epi.tile(reg, row0 + mp * 32, col0, lane);
.LBB0_3092:
	s_or_b64 exec, exec, s[0:1]
	v_add_u32_e32 v32, v107, v34
	v_lshl_add_u32 v44, v32, 10, v128
	v_ashrrev_i32_e32 v45, 31, v44
	v_lshl_add_u64 v[46:47], v[44:45], 2, s[12:13]
	ds_read_b128 v[40:43], v98 offset:3264
	v_mov_b32_e32 v35, 0
	v_lshl_add_u64 v[44:45], v[44:45], 1, s[20:21]
	s_waitcnt vmcnt(19) lgkmcnt(0)
	v_mov_b32_e32 v36, v168
	v_mov_b32_e32 v37, v169
	v_mov_b32_e32 v38, v170
	v_mov_b32_e32 v39, v171
	v_pk_add_f32 v[36:37], v[40:41], v[36:37]
	v_pk_add_f32 v[38:39], v[42:43], v[38:39]
	global_store_dwordx4 v[46:47], v[36:39], off
	v_cvt_pk_bf16_f32 v40, v36, v37
	v_cvt_pk_bf16_f32 v41, v38, v39
	v_pk_mul_f32 v[36:37], v[36:37], v[36:37]
	v_pk_mul_f32 v[38:39], v[38:39], v[38:39]
	v_add_f32_e32 v33, v36, v37
	v_add_f32_e32 v33, v38, v33
	v_add_f32_e32 v33, v39, v33
	global_store_dwordx2 v[44:45], v[40:41], off
	s_nop 0
	v_add_f32_dpp v33, v33, v33 quad_perm:[1,0,3,2] row_mask:0xf bank_mask:0xf bound_ctrl:1
	s_nop 1
	v_add_f32_dpp v33, v33, v33 quad_perm:[2,3,0,1] row_mask:0xf bank_mask:0xf bound_ctrl:1
	s_nop 1
	v_add_f32_dpp v33, v33, v33 row_half_mirror row_mask:0xf bank_mask:0xf bound_ctrl:1
	s_nop 1
	v_mov_b32_dpp v35, v33 row_mirror row_mask:0xf bank_mask:0xf
	s_and_saveexec_b64 s[0:1], vcc
	s_cbranch_execz .LBB0_3094
	v_add_f32_e32 v35, v33, v35
	v_ashrrev_i32_e32 v33, 31, v32
	v_lshl_add_u64 v[32:33], v[32:33], 2, s[22:23]
	global_atomic_add_f32 v[32:33], v35, off
.LBB0_3094:
	s_or_b64 exec, exec, s[0:1]
	v_add_u32_e32 v32, v108, v34
	v_lshl_add_u32 v42, v32, 10, v128
	v_ashrrev_i32_e32 v43, 31, v42
	v_lshl_add_u64 v[44:45], v[42:43], 2, s[12:13]
	ds_read_b128 v[38:41], v98 offset:4352
	v_lshl_add_u64 v[42:43], v[42:43], 1, s[20:21]
	s_waitcnt vmcnt(21) lgkmcnt(0)
	v_mov_b32_e32 v34, v172
	v_mov_b32_e32 v35, v173
	v_mov_b32_e32 v36, v174
	v_mov_b32_e32 v37, v175
	v_pk_add_f32 v[34:35], v[38:39], v[34:35]
	v_pk_add_f32 v[36:37], v[40:41], v[36:37]
	global_store_dwordx4 v[44:45], v[34:37], off
	v_cvt_pk_bf16_f32 v38, v34, v35
	v_cvt_pk_bf16_f32 v39, v36, v37
	v_pk_mul_f32 v[34:35], v[34:35], v[34:35]
	v_pk_mul_f32 v[36:37], v[36:37], v[36:37]
	v_add_f32_e32 v33, v34, v35
	v_add_f32_e32 v33, v36, v33
	v_add_f32_e32 v33, v37, v33
	v_mov_b32_e32 v34, 0
	global_store_dwordx2 v[42:43], v[38:39], off
	v_add_f32_dpp v33, v33, v33 quad_perm:[1,0,3,2] row_mask:0xf bank_mask:0xf bound_ctrl:1
	s_nop 1
	v_add_f32_dpp v33, v33, v33 quad_perm:[2,3,0,1] row_mask:0xf bank_mask:0xf bound_ctrl:1
	s_nop 1
	v_add_f32_dpp v33, v33, v33 row_half_mirror row_mask:0xf bank_mask:0xf bound_ctrl:1
	s_nop 1
	v_mov_b32_dpp v34, v33 row_mirror row_mask:0xf bank_mask:0xf
	s_and_saveexec_b64 s[0:1], vcc
	s_cbranch_execz .LBB0_3096
	v_add_f32_e32 v34, v33, v34
	v_ashrrev_i32_e32 v33, 31, v32
	v_lshl_add_u64 v[32:33], v[32:33], 2, s[22:23]
	global_atomic_add_f32 v[32:33], v34, off
.LBB0_3096:
	s_or_b64 exec, exec, s[0:1]
	ds_write2_b32 v131, v24, v28 offset1:16
	ds_write2_b32 v131, v25, v29 offset0:68 offset1:84
	ds_write2_b32 v131, v26, v30 offset0:136 offset1:152
	ds_write2_b32 v131, v27, v31 offset0:204 offset1:220
	ds_write2_b32 v131, v16, v20 offset0:32 offset1:48
	ds_write2_b32 v131, v17, v21 offset0:100 offset1:116
	ds_write2_b32 v131, v18, v22 offset0:168 offset1:184
	ds_write2_b32 v131, v19, v23 offset0:236 offset1:252
	ds_write2_b32 v112, v4, v8 offset0:64 offset1:80
	ds_write2_b32 v112, v5, v9 offset0:132 offset1:148
	ds_write2_b32 v112, v6, v10 offset0:200 offset1:216
	ds_write2_b32 v104, v7, v11 offset0:12 offset1:28
	ds_write2_b32 v112, v0, v12 offset0:96 offset1:112
	ds_write2_b32 v112, v1, v13 offset0:164 offset1:180
	ds_write2_b32 v112, v2, v14 offset0:232 offset1:248
	ds_write2_b32 v104, v3, v15 offset0:44 offset1:60
	v_add_u32_e32 v185, 0x60, v129
	v_add_u32_e32 v184, v130, v185
	v_lshl_add_u32 v176, v184, 10, v128
	v_ashrrev_i32_e32 v177, 31, v176
	v_lshl_add_u64 v[178:179], v[176:177], 2, s[12:13]
	global_load_dwordx4 v[144:147], v[178:179], off
	v_add_u32_e32 v185, 0x60, v129
	v_add_u32_e32 v184, v99, v185
	v_lshl_add_u32 v176, v184, 10, v128
	v_ashrrev_i32_e32 v177, 31, v176
	v_lshl_add_u64 v[178:179], v[176:177], 2, s[12:13]
	global_load_dwordx4 v[148:151], v[178:179], off
	v_add_u32_e32 v185, 0x60, v129
	v_add_u32_e32 v184, v101, v185
	v_lshl_add_u32 v176, v184, 10, v128
	v_ashrrev_i32_e32 v177, 31, v176
	v_lshl_add_u64 v[178:179], v[176:177], 2, s[12:13]
	global_load_dwordx4 v[152:155], v[178:179], off
	v_add_u32_e32 v185, 0x60, v129
	v_add_u32_e32 v184, v103, v185
	v_lshl_add_u32 v176, v184, 10, v128
	v_ashrrev_i32_e32 v177, 31, v176
	v_lshl_add_u64 v[178:179], v[176:177], 2, s[12:13]
	global_load_dwordx4 v[156:159], v[178:179], off
	v_add_u32_e32 v185, 0x60, v129
	v_add_u32_e32 v184, v105, v185
	v_lshl_add_u32 v176, v184, 10, v128
	v_ashrrev_i32_e32 v177, 31, v176
	v_lshl_add_u64 v[178:179], v[176:177], 2, s[12:13]
	global_load_dwordx4 v[160:163], v[178:179], off
	v_add_u32_e32 v185, 0x60, v129
	v_add_u32_e32 v184, v106, v185
	v_lshl_add_u32 v176, v184, 10, v128
	v_ashrrev_i32_e32 v177, 31, v176
	v_lshl_add_u64 v[178:179], v[176:177], 2, s[12:13]
	global_load_dwordx4 v[164:167], v[178:179], off
	v_add_u32_e32 v185, 0x60, v129
	v_add_u32_e32 v184, v107, v185
	v_lshl_add_u32 v176, v184, 10, v128
	v_ashrrev_i32_e32 v177, 31, v176
	v_lshl_add_u64 v[178:179], v[176:177], 2, s[12:13]
	global_load_dwordx4 v[168:171], v[178:179], off
	v_add_u32_e32 v185, 0x60, v129
	v_add_u32_e32 v184, v108, v185
	v_lshl_add_u32 v176, v184, 10, v128
	v_ashrrev_i32_e32 v177, 31, v176
	v_lshl_add_u64 v[178:179], v[176:177], 2, s[12:13]
	global_load_dwordx4 v[172:175], v[178:179], off
	v_add_u32_e32 v2, 0x60, v129
	v_add_u32_e32 v0, v130, v2
	v_lshl_add_u32 v12, v0, 10, v128
	v_ashrrev_i32_e32 v13, 31, v12
	v_lshl_add_u64 v[14:15], v[12:13], 2, s[12:13]
	ds_read_b128 v[8:11], v66
	v_mov_b32_e32 v3, 0
	v_lshl_add_u64 v[12:13], v[12:13], 1, s[20:21]
	s_waitcnt vmcnt(7) lgkmcnt(0)
	v_mov_b32_e32 v4, v144
	v_mov_b32_e32 v5, v145
	v_mov_b32_e32 v6, v146
	v_mov_b32_e32 v7, v147
	v_pk_add_f32 v[4:5], v[8:9], v[4:5]
	v_pk_add_f32 v[6:7], v[10:11], v[6:7]
	global_store_dwordx4 v[14:15], v[4:7], off
	v_cvt_pk_bf16_f32 v8, v4, v5
	v_cvt_pk_bf16_f32 v9, v6, v7
	v_pk_mul_f32 v[4:5], v[4:5], v[4:5]
	v_pk_mul_f32 v[6:7], v[6:7], v[6:7]
	v_add_f32_e32 v1, v4, v5
	v_add_f32_e32 v1, v6, v1
	v_add_f32_e32 v1, v7, v1
	global_store_dwordx2 v[12:13], v[8:9], off
	s_nop 0
	v_add_f32_dpp v1, v1, v1 quad_perm:[1,0,3,2] row_mask:0xf bank_mask:0xf bound_ctrl:1
	s_nop 1
	v_add_f32_dpp v1, v1, v1 quad_perm:[2,3,0,1] row_mask:0xf bank_mask:0xf bound_ctrl:1
	s_nop 1
	v_add_f32_dpp v1, v1, v1 row_half_mirror row_mask:0xf bank_mask:0xf bound_ctrl:1
	s_nop 1
	v_mov_b32_dpp v3, v1 row_mirror row_mask:0xf bank_mask:0xf
	s_and_saveexec_b64 s[0:1], vcc
	s_cbranch_execz .LBB0_3098
	v_add_f32_e32 v3, v1, v3
	v_ashrrev_i32_e32 v1, 31, v0
	v_lshl_add_u64 v[0:1], v[0:1], 2, s[22:23]
	global_atomic_add_f32 v[0:1], v3, off
;   __device__ __forceinline__ void tile(const float* reg, int row0, int col0, int lane) const {
;     rows4(reg, lane, [&](int it, int rr, int c4, float4 v) {
;       int row = row0 + rr, idx = row * 1024 + col0 + c4;
;       float4 xo = *(const float4*)(xold + idx);
;       v.x = fmaf(coef, v.x, xo.x); v.y = fmaf(coef, v.y, xo.y); v.z = fmaf(coef, v.z, xo.z); v.w = fmaf(coef, v.w, xo.w);
;       *(float4*)(xnew + idx) = v;
;       *(bf16x4*)(xb + idx) = pack4(v.x, v.y, v.z, v.w);
;       float s = row16_sum(v.x * v.x + v.y * v.y + v.z * v.z + v.w * v.w);
;       if ((lane & 15) == 0) atomicAdd(ssqn + row, s);
;     });
.LBB0_3098:
	s_or_b64 exec, exec, s[0:1]
	v_add_u32_e32 v0, v99, v2
	v_lshl_add_u32 v12, v0, 10, v128
	v_ashrrev_i32_e32 v13, 31, v12
	v_lshl_add_u64 v[14:15], v[12:13], 2, s[12:13]
	ds_read_b128 v[8:11], v100
	v_mov_b32_e32 v3, 0
	v_lshl_add_u64 v[12:13], v[12:13], 1, s[20:21]
	s_waitcnt vmcnt(9) lgkmcnt(0)
	v_mov_b32_e32 v4, v148
	v_mov_b32_e32 v5, v149
	v_mov_b32_e32 v6, v150
	v_mov_b32_e32 v7, v151
	v_pk_add_f32 v[4:5], v[8:9], v[4:5]
	v_pk_add_f32 v[6:7], v[10:11], v[6:7]
	global_store_dwordx4 v[14:15], v[4:7], off
	v_cvt_pk_bf16_f32 v8, v4, v5
	v_cvt_pk_bf16_f32 v9, v6, v7
	v_pk_mul_f32 v[4:5], v[4:5], v[4:5]
	v_pk_mul_f32 v[6:7], v[6:7], v[6:7]
	v_add_f32_e32 v1, v4, v5
	v_add_f32_e32 v1, v6, v1
	v_add_f32_e32 v1, v7, v1
	global_store_dwordx2 v[12:13], v[8:9], off
	s_nop 0
	v_add_f32_dpp v1, v1, v1 quad_perm:[1,0,3,2] row_mask:0xf bank_mask:0xf bound_ctrl:1
	s_nop 1
	v_add_f32_dpp v1, v1, v1 quad_perm:[2,3,0,1] row_mask:0xf bank_mask:0xf bound_ctrl:1
	s_nop 1
	v_add_f32_dpp v1, v1, v1 row_half_mirror row_mask:0xf bank_mask:0xf bound_ctrl:1
	s_nop 1
	v_mov_b32_dpp v3, v1 row_mirror row_mask:0xf bank_mask:0xf
	s_and_saveexec_b64 s[0:1], vcc
	s_cbranch_execz .LBB0_3100
	v_add_f32_e32 v3, v1, v3
	v_ashrrev_i32_e32 v1, 31, v0
	v_lshl_add_u64 v[0:1], v[0:1], 2, s[22:23]
	global_atomic_add_f32 v[0:1], v3, off
.LBB0_3100:
	s_or_b64 exec, exec, s[0:1]
	v_add_u32_e32 v0, v101, v2
	v_lshl_add_u32 v12, v0, 10, v128
	v_ashrrev_i32_e32 v13, 31, v12
	v_lshl_add_u64 v[14:15], v[12:13], 2, s[12:13]
	ds_read_b128 v[8:11], v102
	v_mov_b32_e32 v3, 0
	v_lshl_add_u64 v[12:13], v[12:13], 1, s[20:21]
	s_waitcnt vmcnt(11) lgkmcnt(0)
	v_mov_b32_e32 v4, v152
	v_mov_b32_e32 v5, v153
	v_mov_b32_e32 v6, v154
	v_mov_b32_e32 v7, v155
	v_pk_add_f32 v[4:5], v[8:9], v[4:5]
	v_pk_add_f32 v[6:7], v[10:11], v[6:7]
	global_store_dwordx4 v[14:15], v[4:7], off
	v_cvt_pk_bf16_f32 v8, v4, v5
	v_cvt_pk_bf16_f32 v9, v6, v7
	v_pk_mul_f32 v[4:5], v[4:5], v[4:5]
	v_pk_mul_f32 v[6:7], v[6:7], v[6:7]
	v_add_f32_e32 v1, v4, v5
	v_add_f32_e32 v1, v6, v1
	v_add_f32_e32 v1, v7, v1
	global_store_dwordx2 v[12:13], v[8:9], off
	s_nop 0
	v_add_f32_dpp v1, v1, v1 quad_perm:[1,0,3,2] row_mask:0xf bank_mask:0xf bound_ctrl:1
	s_nop 1
	v_add_f32_dpp v1, v1, v1 quad_perm:[2,3,0,1] row_mask:0xf bank_mask:0xf bound_ctrl:1
	s_nop 1
	v_add_f32_dpp v1, v1, v1 row_half_mirror row_mask:0xf bank_mask:0xf bound_ctrl:1
	s_nop 1
	v_mov_b32_dpp v3, v1 row_mirror row_mask:0xf bank_mask:0xf
	s_and_saveexec_b64 s[0:1], vcc
	s_cbranch_execz .LBB0_3102
	v_add_f32_e32 v3, v1, v3
	v_ashrrev_i32_e32 v1, 31, v0
	v_lshl_add_u64 v[0:1], v[0:1], 2, s[22:23]
	global_atomic_add_f32 v[0:1], v3, off
.LBB0_3102:
	s_or_b64 exec, exec, s[0:1]
	v_add_u32_e32 v0, v103, v2
	v_lshl_add_u32 v12, v0, 10, v128
	v_ashrrev_i32_e32 v13, 31, v12
	v_lshl_add_u64 v[14:15], v[12:13], 2, s[12:13]
	ds_read_b128 v[8:11], v98
	v_mov_b32_e32 v3, 0
	v_lshl_add_u64 v[12:13], v[12:13], 1, s[20:21]
	s_waitcnt vmcnt(13) lgkmcnt(0)
	v_mov_b32_e32 v4, v156
	v_mov_b32_e32 v5, v157
	v_mov_b32_e32 v6, v158
	v_mov_b32_e32 v7, v159
	v_pk_add_f32 v[4:5], v[8:9], v[4:5]
	v_pk_add_f32 v[6:7], v[10:11], v[6:7]
	global_store_dwordx4 v[14:15], v[4:7], off
	v_cvt_pk_bf16_f32 v8, v4, v5
	v_cvt_pk_bf16_f32 v9, v6, v7
	v_pk_mul_f32 v[4:5], v[4:5], v[4:5]
	v_pk_mul_f32 v[6:7], v[6:7], v[6:7]
	v_add_f32_e32 v1, v4, v5
	v_add_f32_e32 v1, v6, v1
	v_add_f32_e32 v1, v7, v1
	global_store_dwordx2 v[12:13], v[8:9], off
	s_nop 0
	v_add_f32_dpp v1, v1, v1 quad_perm:[1,0,3,2] row_mask:0xf bank_mask:0xf bound_ctrl:1
	s_nop 1
	v_add_f32_dpp v1, v1, v1 quad_perm:[2,3,0,1] row_mask:0xf bank_mask:0xf bound_ctrl:1
	s_nop 1
	v_add_f32_dpp v1, v1, v1 row_half_mirror row_mask:0xf bank_mask:0xf bound_ctrl:1
	s_nop 1
	v_mov_b32_dpp v3, v1 row_mirror row_mask:0xf bank_mask:0xf
	s_and_saveexec_b64 s[0:1], vcc
	s_cbranch_execz .LBB0_3104
	v_add_f32_e32 v3, v1, v3
	v_ashrrev_i32_e32 v1, 31, v0
	v_lshl_add_u64 v[0:1], v[0:1], 2, s[22:23]
	global_atomic_add_f32 v[0:1], v3, off
.LBB0_3104:
	s_or_b64 exec, exec, s[0:1]
	v_add_u32_e32 v0, v105, v2
	v_lshl_add_u32 v12, v0, 10, v128
	v_ashrrev_i32_e32 v13, 31, v12
	v_lshl_add_u64 v[14:15], v[12:13], 2, s[12:13]
	ds_read_b128 v[8:11], v98 offset:1088
	v_mov_b32_e32 v3, 0
	v_lshl_add_u64 v[12:13], v[12:13], 1, s[20:21]
	s_waitcnt vmcnt(15) lgkmcnt(0)
	v_mov_b32_e32 v4, v160
	v_mov_b32_e32 v5, v161
	v_mov_b32_e32 v6, v162
	v_mov_b32_e32 v7, v163
	v_pk_add_f32 v[4:5], v[8:9], v[4:5]
	v_pk_add_f32 v[6:7], v[10:11], v[6:7]
	global_store_dwordx4 v[14:15], v[4:7], off
	v_cvt_pk_bf16_f32 v8, v4, v5
	v_cvt_pk_bf16_f32 v9, v6, v7
	v_pk_mul_f32 v[4:5], v[4:5], v[4:5]
	v_pk_mul_f32 v[6:7], v[6:7], v[6:7]
	v_add_f32_e32 v1, v4, v5
	v_add_f32_e32 v1, v6, v1
	v_add_f32_e32 v1, v7, v1
	global_store_dwordx2 v[12:13], v[8:9], off
	s_nop 0
	v_add_f32_dpp v1, v1, v1 quad_perm:[1,0,3,2] row_mask:0xf bank_mask:0xf bound_ctrl:1
	s_nop 1
	v_add_f32_dpp v1, v1, v1 quad_perm:[2,3,0,1] row_mask:0xf bank_mask:0xf bound_ctrl:1
	s_nop 1
	v_add_f32_dpp v1, v1, v1 row_half_mirror row_mask:0xf bank_mask:0xf bound_ctrl:1
	s_nop 1
	v_mov_b32_dpp v3, v1 row_mirror row_mask:0xf bank_mask:0xf
	s_and_saveexec_b64 s[0:1], vcc
	s_cbranch_execz .LBB0_3106
	v_add_f32_e32 v3, v1, v3
	v_ashrrev_i32_e32 v1, 31, v0
	v_lshl_add_u64 v[0:1], v[0:1], 2, s[22:23]
	global_atomic_add_f32 v[0:1], v3, off
;   __device__ __forceinline__ void tile(const float* reg, int row0, int col0, int lane) const {
;     rows4(reg, lane, [&](int it, int rr, int c4, float4 v) {
;       int row = row0 + rr, idx = row * 1024 + col0 + c4;
;       float4 xo = *(const float4*)(xold + idx);
;       v.x = fmaf(coef, v.x, xo.x); v.y = fmaf(coef, v.y, xo.y); v.z = fmaf(coef, v.z, xo.z); v.w = fmaf(coef, v.w, xo.w);
;       *(float4*)(xnew + idx) = v;
;       *(bf16x4*)(xb + idx) = pack4(v.x, v.y, v.z, v.w);
;       float s = row16_sum(v.x * v.x + v.y * v.y + v.z * v.z + v.w * v.w);
;       if ((lane & 15) == 0) atomicAdd(ssqn + row, s);
;     });
.LBB0_3106:
	s_or_b64 exec, exec, s[0:1]
	v_add_u32_e32 v0, v106, v2
	v_lshl_add_u32 v12, v0, 10, v128
	v_ashrrev_i32_e32 v13, 31, v12
	v_lshl_add_u64 v[14:15], v[12:13], 2, s[12:13]
	ds_read_b128 v[8:11], v98 offset:2176
	v_mov_b32_e32 v3, 0
	v_lshl_add_u64 v[12:13], v[12:13], 1, s[20:21]
	s_waitcnt vmcnt(17) lgkmcnt(0)
	v_mov_b32_e32 v4, v164
	v_mov_b32_e32 v5, v165
	v_mov_b32_e32 v6, v166
	v_mov_b32_e32 v7, v167
	v_pk_add_f32 v[4:5], v[8:9], v[4:5]
	v_pk_add_f32 v[6:7], v[10:11], v[6:7]
	global_store_dwordx4 v[14:15], v[4:7], off
	v_cvt_pk_bf16_f32 v8, v4, v5
	v_cvt_pk_bf16_f32 v9, v6, v7
	v_pk_mul_f32 v[4:5], v[4:5], v[4:5]
	v_pk_mul_f32 v[6:7], v[6:7], v[6:7]
	v_add_f32_e32 v1, v4, v5
	v_add_f32_e32 v1, v6, v1
	v_add_f32_e32 v1, v7, v1
	global_store_dwordx2 v[12:13], v[8:9], off
	s_nop 0
	v_add_f32_dpp v1, v1, v1 quad_perm:[1,0,3,2] row_mask:0xf bank_mask:0xf bound_ctrl:1
	s_nop 1
	v_add_f32_dpp v1, v1, v1 quad_perm:[2,3,0,1] row_mask:0xf bank_mask:0xf bound_ctrl:1
	s_nop 1
	v_add_f32_dpp v1, v1, v1 row_half_mirror row_mask:0xf bank_mask:0xf bound_ctrl:1
	s_nop 1
	v_mov_b32_dpp v3, v1 row_mirror row_mask:0xf bank_mask:0xf
	s_and_saveexec_b64 s[0:1], vcc
	s_cbranch_execz .LBB0_3108
	v_add_f32_e32 v3, v1, v3
	v_ashrrev_i32_e32 v1, 31, v0
	v_lshl_add_u64 v[0:1], v[0:1], 2, s[22:23]
	global_atomic_add_f32 v[0:1], v3, off
.LBB0_3108:
	s_or_b64 exec, exec, s[0:1]
	v_add_u32_e32 v0, v107, v2
	v_lshl_add_u32 v12, v0, 10, v128
	v_ashrrev_i32_e32 v13, 31, v12
	v_lshl_add_u64 v[14:15], v[12:13], 2, s[12:13]
	ds_read_b128 v[8:11], v98 offset:3264
	v_mov_b32_e32 v3, 0
	v_lshl_add_u64 v[12:13], v[12:13], 1, s[20:21]
	s_waitcnt vmcnt(19) lgkmcnt(0)
	v_mov_b32_e32 v4, v168
	v_mov_b32_e32 v5, v169
	v_mov_b32_e32 v6, v170
	v_mov_b32_e32 v7, v171
	v_pk_add_f32 v[4:5], v[8:9], v[4:5]
	v_pk_add_f32 v[6:7], v[10:11], v[6:7]
	global_store_dwordx4 v[14:15], v[4:7], off
	v_cvt_pk_bf16_f32 v8, v4, v5
	v_cvt_pk_bf16_f32 v9, v6, v7
	v_pk_mul_f32 v[4:5], v[4:5], v[4:5]
	v_pk_mul_f32 v[6:7], v[6:7], v[6:7]
	v_add_f32_e32 v1, v4, v5
	v_add_f32_e32 v1, v6, v1
	v_add_f32_e32 v1, v7, v1
	global_store_dwordx2 v[12:13], v[8:9], off
	s_nop 0
	v_add_f32_dpp v1, v1, v1 quad_perm:[1,0,3,2] row_mask:0xf bank_mask:0xf bound_ctrl:1
	s_nop 1
	v_add_f32_dpp v1, v1, v1 quad_perm:[2,3,0,1] row_mask:0xf bank_mask:0xf bound_ctrl:1
	s_nop 1
	v_add_f32_dpp v1, v1, v1 row_half_mirror row_mask:0xf bank_mask:0xf bound_ctrl:1
	s_nop 1
	v_mov_b32_dpp v3, v1 row_mirror row_mask:0xf bank_mask:0xf
	s_and_saveexec_b64 s[0:1], vcc
	s_cbranch_execz .LBB0_3110
	v_add_f32_e32 v3, v1, v3
	v_ashrrev_i32_e32 v1, 31, v0
	v_lshl_add_u64 v[0:1], v[0:1], 2, s[22:23]
	global_atomic_add_f32 v[0:1], v3, off
.LBB0_3110:
	s_or_b64 exec, exec, s[0:1]
	v_add_u32_e32 v0, v108, v2
	v_lshl_add_u32 v10, v0, 10, v128
	v_ashrrev_i32_e32 v11, 31, v10
	v_lshl_add_u64 v[12:13], v[10:11], 2, s[12:13]
	ds_read_b128 v[6:9], v98 offset:4352
	v_lshl_add_u64 v[10:11], v[10:11], 1, s[20:21]
	s_waitcnt vmcnt(21) lgkmcnt(0)
	v_mov_b32_e32 v2, v172
	v_mov_b32_e32 v3, v173
	v_mov_b32_e32 v4, v174
	v_mov_b32_e32 v5, v175
	v_pk_add_f32 v[2:3], v[6:7], v[2:3]
	v_pk_add_f32 v[4:5], v[8:9], v[4:5]
	global_store_dwordx4 v[12:13], v[2:5], off
	v_cvt_pk_bf16_f32 v6, v2, v3
	v_cvt_pk_bf16_f32 v7, v4, v5
	v_pk_mul_f32 v[2:3], v[2:3], v[2:3]
	v_pk_mul_f32 v[4:5], v[4:5], v[4:5]
	v_add_f32_e32 v1, v2, v3
	v_add_f32_e32 v1, v4, v1
	v_add_f32_e32 v1, v5, v1
	v_mov_b32_e32 v2, 0
	global_store_dwordx2 v[10:11], v[6:7], off
	v_add_f32_dpp v1, v1, v1 quad_perm:[1,0,3,2] row_mask:0xf bank_mask:0xf bound_ctrl:1
	s_nop 1
	v_add_f32_dpp v1, v1, v1 quad_perm:[2,3,0,1] row_mask:0xf bank_mask:0xf bound_ctrl:1
	s_nop 1
	v_add_f32_dpp v1, v1, v1 row_half_mirror row_mask:0xf bank_mask:0xf bound_ctrl:1
	s_nop 1
	v_mov_b32_dpp v2, v1 row_mirror row_mask:0xf bank_mask:0xf
	s_and_saveexec_b64 s[0:1], vcc
	s_cbranch_execz .LBB0_3043
	v_add_f32_e32 v2, v1, v2
	v_ashrrev_i32_e32 v1, 31, v0
	v_lshl_add_u64 v[0:1], v[0:1], 2, s[22:23]
	global_atomic_add_f32 v[0:1], v2, off
	s_branch .LBB0_3043

;   __device__ __forceinline__ void tile(const float* reg, int row0, int col0, int lane) const {
;     rows4(reg, lane, [&](int it, int rr, int c4, float4 v) {
;       int row = row0 + rr, idx = row * 1024 + col0 + c4;
;       float4 xo = *(const float4*)(xold + idx);
;       v.x = fmaf(coef, v.x, xo.x); v.y = fmaf(coef, v.y, xo.y); v.z = fmaf(coef, v.z, xo.z); v.w = fmaf(coef, v.w, xo.w);
;       *(float4*)(xnew + idx) = v;
;       *(bf16x4*)(xb + idx) = pack4(v.x, v.y, v.z, v.w);
;       float s = row16_sum(v.x * v.x + v.y * v.y + v.z * v.z + v.w * v.w);
;       if ((lane & 15) == 0) atomicAdd(ssqn + row, s);
;     });
; template <int MF, class Epi>
; __device__ __forceinline__ void staged_epilogue(f32x4 (&acc)[MF][4], int row0, int col0, const Epi& epi) {
;   const int lane = tidx() & 63, wid = tidx() >> 6, fr = lane & 15, fq = lane >> 4;
;   float* reg = (float*)(g_shm + 65536 + wid * 8704);
; #pragma unroll
;   for (int mp = 0; mp < MF / 2; ++mp) {
;     __builtin_amdgcn_sched_barrier(0);
; #pragma unroll
;     for (int mm = 0; mm < 2; ++mm)
; #pragma unroll
;       for (int n = 0; n < 4; ++n)
; #pragma unroll
;         for (int j = 0; j < 4; ++j) reg[(mm * 16 + fq * 4 + j) * 68 + n * 16 + fr] = acc[mp * 2 + mm][n][j];
;     __builtin_amdgcn_fence(__ATOMIC_ACQ_REL, "wavefront");
;     epi.tile(reg, row0 + mp * 32, col0, lane);
.LBB0_3166:
	v_mov_b32_e32 v131, v204
	v_mov_b32_e32 v130, v204
	s_nop 0
	v_lshrrev_b32_e32 v130, 6, v130
	v_mul_lo_u32 v130, v130, s47
	v_add_u32_e32 v136, 0x10000, v130
	v_lshrrev_b32_e32 v130, 2, v131
	v_and_b32_e32 v137, 15, v131
	v_and_b32_e32 v138, 12, v130
	v_bfe_u32 v130, v131, 4, 2
	v_lshlrev_b32_e32 v131, 2, v131
	v_and_b32_e32 v131, 60, v131
	v_lshl_or_b32 v139, v137, 2, v136
	v_lshl_or_b32 v136, v131, 2, v136
	v_add_u32_e32 v128, v131, v128
	v_cmp_eq_u32_e32 vcc, 0, v137
	v_mad_u32_u24 v140, v130, s50, v136
	v_mad_u32_u24 v131, v138, s50, v139
	ds_write2_b32 v131, v120, v124 offset1:16
	ds_write2_b32 v131, v121, v125 offset0:68 offset1:84
	ds_write2_b32 v131, v122, v126 offset0:136 offset1:152
	ds_write2_b32 v131, v123, v127 offset0:204 offset1:220
	ds_write2_b32 v131, v112, v116 offset0:32 offset1:48
	ds_write2_b32 v131, v113, v117 offset0:100 offset1:116
	ds_write2_b32 v131, v114, v118 offset0:168 offset1:184
	ds_write2_b32 v131, v115, v119 offset0:236 offset1:252
	v_add_u32_e32 v112, 0x1000, v131
	ds_write2_b32 v112, v104, v108 offset0:64 offset1:80
	ds_write2_b32 v112, v105, v109 offset0:132 offset1:148
	ds_write2_b32 v112, v106, v110 offset0:200 offset1:216
	v_add_u32_e32 v104, 0x1400, v131
	ds_write2_b32 v104, v107, v111 offset0:12 offset1:28
	ds_write2_b32 v112, v96, v100 offset0:96 offset1:112
	ds_write2_b32 v112, v97, v101 offset0:164 offset1:180
	ds_write2_b32 v112, v98, v102 offset0:232 offset1:248
	ds_write2_b32 v104, v99, v103 offset0:44 offset1:60
	v_add_u32_e32 v184, v130, v129
	v_lshl_add_u32 v176, v184, 10, v128
	v_ashrrev_i32_e32 v177, 31, v176
	v_lshl_add_u64 v[178:179], v[176:177], 2, s[8:9]
	global_load_dwordx4 v[144:147], v[178:179], off
	v_or_b32_e32 v185, 4, v130
	v_add_u32_e32 v184, v185, v129
	v_lshl_add_u32 v176, v184, 10, v128
	v_ashrrev_i32_e32 v177, 31, v176
	v_lshl_add_u64 v[178:179], v[176:177], 2, s[8:9]
	global_load_dwordx4 v[148:151], v[178:179], off
	v_or_b32_e32 v185, 8, v130
	v_add_u32_e32 v184, v185, v129
	v_lshl_add_u32 v176, v184, 10, v128
	v_ashrrev_i32_e32 v177, 31, v176
	v_lshl_add_u64 v[178:179], v[176:177], 2, s[8:9]
	global_load_dwordx4 v[152:155], v[178:179], off
	v_or_b32_e32 v185, 12, v130
	v_add_u32_e32 v184, v185, v129
	v_lshl_add_u32 v176, v184, 10, v128
	v_ashrrev_i32_e32 v177, 31, v176
	v_lshl_add_u64 v[178:179], v[176:177], 2, s[8:9]
	global_load_dwordx4 v[156:159], v[178:179], off
	v_or_b32_e32 v185, 16, v130
	v_add_u32_e32 v184, v185, v129
	v_lshl_add_u32 v176, v184, 10, v128
	v_ashrrev_i32_e32 v177, 31, v176
	v_lshl_add_u64 v[178:179], v[176:177], 2, s[8:9]
	global_load_dwordx4 v[160:163], v[178:179], off
	v_or_b32_e32 v185, 20, v130
	v_add_u32_e32 v184, v185, v129
	v_lshl_add_u32 v176, v184, 10, v128
	v_ashrrev_i32_e32 v177, 31, v176
	v_lshl_add_u64 v[178:179], v[176:177], 2, s[8:9]
	global_load_dwordx4 v[164:167], v[178:179], off
	v_or_b32_e32 v185, 24, v130
	v_add_u32_e32 v184, v185, v129
	v_lshl_add_u32 v176, v184, 10, v128
	v_ashrrev_i32_e32 v177, 31, v176
	v_lshl_add_u64 v[178:179], v[176:177], 2, s[8:9]
	global_load_dwordx4 v[168:171], v[178:179], off
	v_or_b32_e32 v185, 28, v130
	v_add_u32_e32 v184, v185, v129
	v_lshl_add_u32 v176, v184, 10, v128
	v_ashrrev_i32_e32 v177, 31, v176
	v_lshl_add_u64 v[178:179], v[176:177], 2, s[8:9]
	global_load_dwordx4 v[172:175], v[178:179], off
	v_add_u32_e32 v96, v130, v129
	v_lshl_add_u32 v102, v96, 10, v128
	v_ashrrev_i32_e32 v103, 31, v102
	v_lshl_add_u64 v[110:111], v[102:103], 2, s[8:9]
	s_waitcnt vmcnt(7)
	v_mov_b32_e32 v98, v144
	v_mov_b32_e32 v99, v145
	v_mov_b32_e32 v100, v146
	v_mov_b32_e32 v101, v147
	ds_read_b128 v[106:109], v140
	v_lshl_add_u64 v[102:103], v[102:103], 1, s[6:7]
	s_waitcnt lgkmcnt(0)
	v_pk_fma_f32 v[98:99], v[106:107], 0.5, v[98:99] op_sel_hi:[1,0,1]
	v_pk_fma_f32 v[100:101], v[108:109], 0.5, v[100:101] op_sel_hi:[1,0,1]
	global_store_dwordx4 v[110:111], v[98:101], off
	v_cvt_pk_bf16_f32 v106, v98, v99
	v_cvt_pk_bf16_f32 v107, v100, v101
	v_pk_mul_f32 v[98:99], v[98:99], v[98:99]
	v_pk_mul_f32 v[100:101], v[100:101], v[100:101]
	v_add_f32_e32 v97, v98, v99
	v_add_f32_e32 v97, v100, v97
	v_add_f32_e32 v97, v101, v97
	v_mov_b32_e32 v98, 0
	global_store_dwordx2 v[102:103], v[106:107], off
	v_add_f32_dpp v97, v97, v97 quad_perm:[1,0,3,2] row_mask:0xf bank_mask:0xf bound_ctrl:1
	s_nop 1
	v_add_f32_dpp v97, v97, v97 quad_perm:[2,3,0,1] row_mask:0xf bank_mask:0xf bound_ctrl:1
	s_nop 1
	v_add_f32_dpp v97, v97, v97 row_half_mirror row_mask:0xf bank_mask:0xf bound_ctrl:1
	s_nop 1
	v_mov_b32_dpp v98, v97 row_mirror row_mask:0xf bank_mask:0xf
	s_and_saveexec_b64 s[0:1], vcc
	s_cbranch_execz .LBB0_3168
	v_add_f32_e32 v98, v97, v98
	v_ashrrev_i32_e32 v97, 31, v96
	v_lshl_add_u64 v[96:97], v[96:97], 2, s[12:13]
	global_atomic_add_f32 v[96:97], v98, off
.LBB0_3168:
	s_or_b64 exec, exec, s[0:1]
	v_or_b32_e32 v99, 4, v130
	v_add_u32_e32 v96, v99, v129
	v_lshl_add_u32 v102, v96, 10, v128
	v_ashrrev_i32_e32 v103, 31, v102
	v_lshl_add_u64 v[106:107], v[102:103], 2, s[8:9]
	v_mul_u32_u24_e32 v109, 0x110, v130
	v_add_u32_e32 v98, 0x440, v109
	v_add_u32_e32 v100, v136, v98
	ds_read_b128 v[118:121], v100
	v_mov_b32_e32 v101, 0
	v_lshl_add_u64 v[102:103], v[102:103], 1, s[6:7]
	s_waitcnt vmcnt(9) lgkmcnt(0)
	v_mov_b32_e32 v114, v148
	v_mov_b32_e32 v115, v149
	v_mov_b32_e32 v116, v150
	v_mov_b32_e32 v117, v151
	v_pk_fma_f32 v[114:115], v[118:119], 0.5, v[114:115] op_sel_hi:[1,0,1]
	v_pk_fma_f32 v[116:117], v[120:121], 0.5, v[116:117] op_sel_hi:[1,0,1]
	v_pk_mul_f32 v[110:111], v[114:115], v[114:115]
	global_store_dwordx4 v[106:107], v[114:117], off
	v_cvt_pk_bf16_f32 v106, v114, v115
	v_add_f32_e32 v97, v110, v111
	v_pk_mul_f32 v[114:115], v[116:117], v[116:117]
	v_cvt_pk_bf16_f32 v107, v116, v117
	v_add_f32_e32 v97, v114, v97
	v_add_f32_e32 v97, v115, v97
	global_store_dwordx2 v[102:103], v[106:107], off
	s_nop 0
	v_add_f32_dpp v97, v97, v97 quad_perm:[1,0,3,2] row_mask:0xf bank_mask:0xf bound_ctrl:1
	s_nop 1
	v_add_f32_dpp v97, v97, v97 quad_perm:[2,3,0,1] row_mask:0xf bank_mask:0xf bound_ctrl:1
	s_nop 1
	v_add_f32_dpp v97, v97, v97 row_half_mirror row_mask:0xf bank_mask:0xf bound_ctrl:1
	s_nop 1
	v_mov_b32_dpp v101, v97 row_mirror row_mask:0xf bank_mask:0xf
	s_and_saveexec_b64 s[0:1], vcc
	s_cbranch_execz .LBB0_3170
	v_add_f32_e32 v101, v97, v101
	v_ashrrev_i32_e32 v97, 31, v96
	v_lshl_add_u64 v[96:97], v[96:97], 2, s[12:13]
	global_atomic_add_f32 v[96:97], v101, off
;   __device__ __forceinline__ void tile(const float* reg, int row0, int col0, int lane) const {
;     rows4(reg, lane, [&](int it, int rr, int c4, float4 v) {
;       int row = row0 + rr, idx = row * 1024 + col0 + c4;
;       float4 xo = *(const float4*)(xold + idx);
;       v.x = fmaf(coef, v.x, xo.x); v.y = fmaf(coef, v.y, xo.y); v.z = fmaf(coef, v.z, xo.z); v.w = fmaf(coef, v.w, xo.w);
;       *(float4*)(xnew + idx) = v;
;       *(bf16x4*)(xb + idx) = pack4(v.x, v.y, v.z, v.w);
;       float s = row16_sum(v.x * v.x + v.y * v.y + v.z * v.z + v.w * v.w);
;       if ((lane & 15) == 0) atomicAdd(ssqn + row, s);
;     });
.LBB0_3170:
	s_or_b64 exec, exec, s[0:1]
	v_or_b32_e32 v101, 8, v130
	v_add_u32_e32 v96, v101, v129
	v_lshl_add_u32 v106, v96, 10, v128
	v_ashrrev_i32_e32 v107, 31, v106
	v_lshl_add_u64 v[110:111], v[106:107], 2, s[8:9]
	v_add_u32_e32 v98, 0x440, v98
	v_add_u32_e32 v102, v136, v98
	ds_read_b128 v[118:121], v102
	v_mov_b32_e32 v103, 0
	v_lshl_add_u64 v[106:107], v[106:107], 1, s[6:7]
	s_waitcnt vmcnt(11) lgkmcnt(0)
	v_mov_b32_e32 v114, v152
	v_mov_b32_e32 v115, v153
	v_mov_b32_e32 v116, v154
	v_mov_b32_e32 v117, v155
	v_pk_fma_f32 v[114:115], v[118:119], 0.5, v[114:115] op_sel_hi:[1,0,1]
	v_pk_fma_f32 v[116:117], v[120:121], 0.5, v[116:117] op_sel_hi:[1,0,1]
	global_store_dwordx4 v[110:111], v[114:117], off
	v_cvt_pk_bf16_f32 v110, v114, v115
	v_cvt_pk_bf16_f32 v111, v116, v117
	v_pk_mul_f32 v[114:115], v[114:115], v[114:115]
	v_pk_mul_f32 v[116:117], v[116:117], v[116:117]
	v_add_f32_e32 v97, v114, v115
	v_add_f32_e32 v97, v116, v97
	v_add_f32_e32 v97, v117, v97
	global_store_dwordx2 v[106:107], v[110:111], off
	s_nop 0
	v_add_f32_dpp v97, v97, v97 quad_perm:[1,0,3,2] row_mask:0xf bank_mask:0xf bound_ctrl:1
	s_nop 1
	v_add_f32_dpp v97, v97, v97 quad_perm:[2,3,0,1] row_mask:0xf bank_mask:0xf bound_ctrl:1
	s_nop 1
	v_add_f32_dpp v97, v97, v97 row_half_mirror row_mask:0xf bank_mask:0xf bound_ctrl:1
	s_nop 1
	v_mov_b32_dpp v103, v97 row_mirror row_mask:0xf bank_mask:0xf
	s_and_saveexec_b64 s[0:1], vcc
	s_cbranch_execz .LBB0_3172
	v_add_f32_e32 v103, v97, v103
	v_ashrrev_i32_e32 v97, 31, v96
	v_lshl_add_u64 v[96:97], v[96:97], 2, s[12:13]
	global_atomic_add_f32 v[96:97], v103, off
.LBB0_3172:
	s_or_b64 exec, exec, s[0:1]
	v_or_b32_e32 v103, 12, v130
	v_add_u32_e32 v96, v103, v129
	v_lshl_add_u32 v106, v96, 10, v128
	v_ashrrev_i32_e32 v107, 31, v106
	v_lshl_add_u64 v[110:111], v[106:107], 2, s[8:9]
	v_add_u32_e32 v97, 0x440, v98
	v_add_u32_e32 v98, v136, v97
	ds_read_b128 v[118:121], v98
	v_mov_b32_e32 v105, 0
	v_lshl_add_u64 v[106:107], v[106:107], 1, s[6:7]
	s_waitcnt vmcnt(13) lgkmcnt(0)
	v_mov_b32_e32 v114, v156
	v_mov_b32_e32 v115, v157
	v_mov_b32_e32 v116, v158
	v_mov_b32_e32 v117, v159
	v_pk_fma_f32 v[114:115], v[118:119], 0.5, v[114:115] op_sel_hi:[1,0,1]
	v_pk_fma_f32 v[116:117], v[120:121], 0.5, v[116:117] op_sel_hi:[1,0,1]
	global_store_dwordx4 v[110:111], v[114:117], off
	v_cvt_pk_bf16_f32 v110, v114, v115
	v_cvt_pk_bf16_f32 v111, v116, v117
	v_pk_mul_f32 v[114:115], v[114:115], v[114:115]
	v_pk_mul_f32 v[116:117], v[116:117], v[116:117]
	v_add_f32_e32 v97, v114, v115
	v_add_f32_e32 v97, v116, v97
	v_add_f32_e32 v97, v117, v97
	global_store_dwordx2 v[106:107], v[110:111], off
	s_nop 0
	v_add_f32_dpp v97, v97, v97 quad_perm:[1,0,3,2] row_mask:0xf bank_mask:0xf bound_ctrl:1
	s_nop 1
	v_add_f32_dpp v97, v97, v97 quad_perm:[2,3,0,1] row_mask:0xf bank_mask:0xf bound_ctrl:1
	s_nop 1
	v_add_f32_dpp v97, v97, v97 row_half_mirror row_mask:0xf bank_mask:0xf bound_ctrl:1
	s_nop 1
	v_mov_b32_dpp v105, v97 row_mirror row_mask:0xf bank_mask:0xf
	s_and_saveexec_b64 s[0:1], vcc
	s_cbranch_execz .LBB0_3174
	v_add_f32_e32 v105, v97, v105
	v_ashrrev_i32_e32 v97, 31, v96
	v_lshl_add_u64 v[96:97], v[96:97], 2, s[12:13]
	global_atomic_add_f32 v[96:97], v105, off
.LBB0_3174:
	s_or_b64 exec, exec, s[0:1]
	v_or_b32_e32 v105, 16, v130
	v_add_u32_e32 v96, v105, v129
	v_lshl_add_u32 v106, v96, 10, v128
	v_ashrrev_i32_e32 v107, 31, v106
	v_lshl_add_u64 v[110:111], v[106:107], 2, s[8:9]
	ds_read_b128 v[118:121], v98 offset:1088
	v_lshl_add_u64 v[106:107], v[106:107], 1, s[6:7]
	s_waitcnt vmcnt(15) lgkmcnt(0)
	v_mov_b32_e32 v114, v160
	v_mov_b32_e32 v115, v161
	v_mov_b32_e32 v116, v162
	v_mov_b32_e32 v117, v163
	v_pk_fma_f32 v[114:115], v[118:119], 0.5, v[114:115] op_sel_hi:[1,0,1]
	v_pk_fma_f32 v[116:117], v[120:121], 0.5, v[116:117] op_sel_hi:[1,0,1]
	global_store_dwordx4 v[110:111], v[114:117], off
	v_cvt_pk_bf16_f32 v110, v114, v115
	v_cvt_pk_bf16_f32 v111, v116, v117
	v_pk_mul_f32 v[114:115], v[114:115], v[114:115]
	v_pk_mul_f32 v[116:117], v[116:117], v[116:117]
	v_add_f32_e32 v97, v114, v115
	v_add_f32_e32 v97, v116, v97
	v_add_f32_e32 v97, v117, v97
	global_store_dwordx2 v[106:107], v[110:111], off
	v_mov_b32_e32 v106, 0
	v_add_f32_dpp v97, v97, v97 quad_perm:[1,0,3,2] row_mask:0xf bank_mask:0xf bound_ctrl:1
	s_nop 1
	v_add_f32_dpp v97, v97, v97 quad_perm:[2,3,0,1] row_mask:0xf bank_mask:0xf bound_ctrl:1
	s_nop 1
	v_add_f32_dpp v97, v97, v97 row_half_mirror row_mask:0xf bank_mask:0xf bound_ctrl:1
	s_nop 1
	v_mov_b32_dpp v106, v97 row_mirror row_mask:0xf bank_mask:0xf
	s_and_saveexec_b64 s[0:1], vcc
	s_cbranch_execz .LBB0_3176
	v_add_f32_e32 v106, v97, v106
	v_ashrrev_i32_e32 v97, 31, v96
	v_lshl_add_u64 v[96:97], v[96:97], 2, s[12:13]
	global_atomic_add_f32 v[96:97], v106, off
.LBB0_3176:
	s_or_b64 exec, exec, s[0:1]
	v_or_b32_e32 v106, 20, v130
	v_add_u32_e32 v96, v106, v129
	v_lshl_add_u32 v110, v96, 10, v128
	v_ashrrev_i32_e32 v111, 31, v110
	v_lshl_add_u64 v[122:123], v[110:111], 2, s[8:9]
	ds_read_b128 v[118:121], v98 offset:2176
	v_mov_b32_e32 v107, 0
	v_lshl_add_u64 v[110:111], v[110:111], 1, s[6:7]
	s_waitcnt vmcnt(17) lgkmcnt(0)
	v_mov_b32_e32 v114, v164
	v_mov_b32_e32 v115, v165
	v_mov_b32_e32 v116, v166
	v_mov_b32_e32 v117, v167
	v_pk_fma_f32 v[114:115], v[118:119], 0.5, v[114:115] op_sel_hi:[1,0,1]
	v_pk_fma_f32 v[116:117], v[120:121], 0.5, v[116:117] op_sel_hi:[1,0,1]
	global_store_dwordx4 v[122:123], v[114:117], off
	v_cvt_pk_bf16_f32 v118, v114, v115
	v_cvt_pk_bf16_f32 v119, v116, v117
	v_pk_mul_f32 v[114:115], v[114:115], v[114:115]
	v_pk_mul_f32 v[116:117], v[116:117], v[116:117]
	v_add_f32_e32 v97, v114, v115
	v_add_f32_e32 v97, v116, v97
	v_add_f32_e32 v97, v117, v97
	global_store_dwordx2 v[110:111], v[118:119], off
	s_nop 0
	v_add_f32_dpp v97, v97, v97 quad_perm:[1,0,3,2] row_mask:0xf bank_mask:0xf bound_ctrl:1
	s_nop 1
	v_add_f32_dpp v97, v97, v97 quad_perm:[2,3,0,1] row_mask:0xf bank_mask:0xf bound_ctrl:1
	s_nop 1
	v_add_f32_dpp v97, v97, v97 row_half_mirror row_mask:0xf bank_mask:0xf bound_ctrl:1
	s_nop 1
	v_mov_b32_dpp v107, v97 row_mirror row_mask:0xf bank_mask:0xf
	s_and_saveexec_b64 s[0:1], vcc
	s_cbranch_execz .LBB0_3178
	v_add_f32_e32 v107, v97, v107
	v_ashrrev_i32_e32 v97, 31, v96
	v_lshl_add_u64 v[96:97], v[96:97], 2, s[12:13]
	global_atomic_add_f32 v[96:97], v107, off
;   __device__ __forceinline__ void tile(const float* reg, int row0, int col0, int lane) const {
;     rows4(reg, lane, [&](int it, int rr, int c4, float4 v) {
;       int row = row0 + rr, idx = row * 1024 + col0 + c4;
;       float4 xo = *(const float4*)(xold + idx);
;       v.x = fmaf(coef, v.x, xo.x); v.y = fmaf(coef, v.y, xo.y); v.z = fmaf(coef, v.z, xo.z); v.w = fmaf(coef, v.w, xo.w);
;       *(float4*)(xnew + idx) = v;
;       *(bf16x4*)(xb + idx) = pack4(v.x, v.y, v.z, v.w);
;       float s = row16_sum(v.x * v.x + v.y * v.y + v.z * v.z + v.w * v.w);
;       if ((lane & 15) == 0) atomicAdd(ssqn + row, s);
;     });
; template <int MF, class Epi>
; __device__ __forceinline__ void staged_epilogue(f32x4 (&acc)[MF][4], int row0, int col0, const Epi& epi) {
;   const int lane = tidx() & 63, wid = tidx() >> 6, fr = lane & 15, fq = lane >> 4;
;   float* reg = (float*)(g_shm + 65536 + wid * 8704);
; #pragma unroll
;   for (int mp = 0; mp < MF / 2; ++mp) {
;     __builtin_amdgcn_sched_barrier(0);
; #pragma unroll
;     for (int mm = 0; mm < 2; ++mm)
; #pragma unroll
;       for (int n = 0; n < 4; ++n)
; #pragma unroll
;         for (int j = 0; j < 4; ++j) reg[(mm * 16 + fq * 4 + j) * 68 + n * 16 + fr] = acc[mp * 2 + mm][n][j];
;     __builtin_amdgcn_fence(__ATOMIC_ACQ_REL, "wavefront");
;     epi.tile(reg, row0 + mp * 32, col0, lane);
.LBB0_3178:
	s_or_b64 exec, exec, s[0:1]
	v_or_b32_e32 v107, 24, v130
	v_add_u32_e32 v96, v107, v129
	v_lshl_add_u32 v110, v96, 10, v128
	v_ashrrev_i32_e32 v111, 31, v110
	v_lshl_add_u64 v[122:123], v[110:111], 2, s[8:9]
	ds_read_b128 v[118:121], v98 offset:3264
	v_mov_b32_e32 v108, 0
	v_lshl_add_u64 v[110:111], v[110:111], 1, s[6:7]
	s_waitcnt vmcnt(19) lgkmcnt(0)
	v_mov_b32_e32 v114, v168
	v_mov_b32_e32 v115, v169
	v_mov_b32_e32 v116, v170
	v_mov_b32_e32 v117, v171
	v_pk_fma_f32 v[114:115], v[118:119], 0.5, v[114:115] op_sel_hi:[1,0,1]
	v_pk_fma_f32 v[116:117], v[120:121], 0.5, v[116:117] op_sel_hi:[1,0,1]
	global_store_dwordx4 v[122:123], v[114:117], off
	v_cvt_pk_bf16_f32 v118, v114, v115
	v_cvt_pk_bf16_f32 v119, v116, v117
	v_pk_mul_f32 v[114:115], v[114:115], v[114:115]
	v_pk_mul_f32 v[116:117], v[116:117], v[116:117]
	v_add_f32_e32 v97, v114, v115
	v_add_f32_e32 v97, v116, v97
	v_add_f32_e32 v97, v117, v97
	global_store_dwordx2 v[110:111], v[118:119], off
	s_nop 0
	v_add_f32_dpp v97, v97, v97 quad_perm:[1,0,3,2] row_mask:0xf bank_mask:0xf bound_ctrl:1
	s_nop 1
	v_add_f32_dpp v97, v97, v97 quad_perm:[2,3,0,1] row_mask:0xf bank_mask:0xf bound_ctrl:1
	s_nop 1
	v_add_f32_dpp v97, v97, v97 row_half_mirror row_mask:0xf bank_mask:0xf bound_ctrl:1
	s_nop 1
	v_mov_b32_dpp v108, v97 row_mirror row_mask:0xf bank_mask:0xf
	s_and_saveexec_b64 s[0:1], vcc
	s_cbranch_execz .LBB0_3180
	v_add_f32_e32 v108, v97, v108
	v_ashrrev_i32_e32 v97, 31, v96
	v_lshl_add_u64 v[96:97], v[96:97], 2, s[12:13]
	global_atomic_add_f32 v[96:97], v108, off
.LBB0_3180:
	s_or_b64 exec, exec, s[0:1]
	v_or_b32_e32 v108, 28, v130
	v_add_u32_e32 v96, v108, v129
	v_lshl_add_u32 v110, v96, 10, v128
	v_ashrrev_i32_e32 v111, 31, v110
	v_lshl_add_u64 v[122:123], v[110:111], 2, s[8:9]
	ds_read_b128 v[118:121], v98 offset:4352
	v_lshl_add_u64 v[110:111], v[110:111], 1, s[6:7]
	s_waitcnt vmcnt(21) lgkmcnt(0)
	v_mov_b32_e32 v114, v172
	v_mov_b32_e32 v115, v173
	v_mov_b32_e32 v116, v174
	v_mov_b32_e32 v117, v175
	v_pk_fma_f32 v[114:115], v[118:119], 0.5, v[114:115] op_sel_hi:[1,0,1]
	v_pk_fma_f32 v[116:117], v[120:121], 0.5, v[116:117] op_sel_hi:[1,0,1]
	global_store_dwordx4 v[122:123], v[114:117], off
	v_cvt_pk_bf16_f32 v118, v114, v115
	v_cvt_pk_bf16_f32 v119, v116, v117
	v_pk_mul_f32 v[114:115], v[114:115], v[114:115]
	v_pk_mul_f32 v[116:117], v[116:117], v[116:117]
	v_add_f32_e32 v97, v114, v115
	v_add_f32_e32 v97, v116, v97
	v_add_f32_e32 v97, v117, v97
	global_store_dwordx2 v[110:111], v[118:119], off
	v_mov_b32_e32 v110, 0
	v_add_f32_dpp v97, v97, v97 quad_perm:[1,0,3,2] row_mask:0xf bank_mask:0xf bound_ctrl:1
	s_nop 1
	v_add_f32_dpp v97, v97, v97 quad_perm:[2,3,0,1] row_mask:0xf bank_mask:0xf bound_ctrl:1
	s_nop 1
	v_add_f32_dpp v97, v97, v97 row_half_mirror row_mask:0xf bank_mask:0xf bound_ctrl:1
	s_nop 1
	v_mov_b32_dpp v110, v97 row_mirror row_mask:0xf bank_mask:0xf
	s_and_saveexec_b64 s[0:1], vcc
	s_cbranch_execz .LBB0_3182
	v_add_f32_e32 v110, v97, v110
	v_ashrrev_i32_e32 v97, 31, v96
	v_lshl_add_u64 v[96:97], v[96:97], 2, s[12:13]
	global_atomic_add_f32 v[96:97], v110, off
.LBB0_3182:
	s_or_b64 exec, exec, s[0:1]
	ds_write2_b32 v131, v88, v92 offset1:16
	ds_write2_b32 v131, v89, v93 offset0:68 offset1:84
	ds_write2_b32 v131, v90, v94 offset0:136 offset1:152
	ds_write2_b32 v131, v91, v95 offset0:204 offset1:220
	ds_write2_b32 v131, v80, v84 offset0:32 offset1:48
	ds_write2_b32 v131, v81, v85 offset0:100 offset1:116
	ds_write2_b32 v131, v82, v86 offset0:168 offset1:184
	ds_write2_b32 v131, v83, v87 offset0:236 offset1:252
	ds_write2_b32 v112, v72, v76 offset0:64 offset1:80
	ds_write2_b32 v112, v73, v77 offset0:132 offset1:148
	ds_write2_b32 v112, v74, v78 offset0:200 offset1:216
	ds_write2_b32 v104, v75, v79 offset0:12 offset1:28
	ds_write2_b32 v112, v64, v68 offset0:96 offset1:112
	ds_write2_b32 v112, v65, v69 offset0:164 offset1:180
	ds_write2_b32 v112, v66, v70 offset0:232 offset1:248
	ds_write2_b32 v104, v67, v71 offset0:44 offset1:60
	v_add_u32_e32 v185, 32, v129
	v_add_u32_e32 v184, v130, v185
	v_lshl_add_u32 v176, v184, 10, v128
	v_ashrrev_i32_e32 v177, 31, v176
	v_lshl_add_u64 v[178:179], v[176:177], 2, s[8:9]
	global_load_dwordx4 v[144:147], v[178:179], off
	v_add_u32_e32 v185, 32, v129
	v_add_u32_e32 v184, v99, v185
	v_lshl_add_u32 v176, v184, 10, v128
	v_ashrrev_i32_e32 v177, 31, v176
	v_lshl_add_u64 v[178:179], v[176:177], 2, s[8:9]
	global_load_dwordx4 v[148:151], v[178:179], off
	v_add_u32_e32 v185, 32, v129
	v_add_u32_e32 v184, v101, v185
	v_lshl_add_u32 v176, v184, 10, v128
	v_ashrrev_i32_e32 v177, 31, v176
	v_lshl_add_u64 v[178:179], v[176:177], 2, s[8:9]
	global_load_dwordx4 v[152:155], v[178:179], off
	v_add_u32_e32 v185, 32, v129
	v_add_u32_e32 v184, v103, v185
	v_lshl_add_u32 v176, v184, 10, v128
	v_ashrrev_i32_e32 v177, 31, v176
	v_lshl_add_u64 v[178:179], v[176:177], 2, s[8:9]
	global_load_dwordx4 v[156:159], v[178:179], off
	v_add_u32_e32 v185, 32, v129
	v_add_u32_e32 v184, v105, v185
	v_lshl_add_u32 v176, v184, 10, v128
	v_ashrrev_i32_e32 v177, 31, v176
	v_lshl_add_u64 v[178:179], v[176:177], 2, s[8:9]
	global_load_dwordx4 v[160:163], v[178:179], off
	v_add_u32_e32 v185, 32, v129
	v_add_u32_e32 v184, v106, v185
	v_lshl_add_u32 v176, v184, 10, v128
	v_ashrrev_i32_e32 v177, 31, v176
	v_lshl_add_u64 v[178:179], v[176:177], 2, s[8:9]
	global_load_dwordx4 v[164:167], v[178:179], off
	v_add_u32_e32 v185, 32, v129
	v_add_u32_e32 v184, v107, v185
	v_lshl_add_u32 v176, v184, 10, v128
	v_ashrrev_i32_e32 v177, 31, v176
	v_lshl_add_u64 v[178:179], v[176:177], 2, s[8:9]
	global_load_dwordx4 v[168:171], v[178:179], off
	v_add_u32_e32 v185, 32, v129
	v_add_u32_e32 v184, v108, v185
	v_lshl_add_u32 v176, v184, 10, v128
	v_ashrrev_i32_e32 v177, 31, v176
	v_lshl_add_u64 v[178:179], v[176:177], 2, s[8:9]
	global_load_dwordx4 v[172:175], v[178:179], off
	v_add_u32_e32 v67, 32, v129
	v_add_u32_e32 v64, v130, v67
	v_lshl_add_u32 v76, v64, 10, v128
	v_ashrrev_i32_e32 v77, 31, v76
	v_lshl_add_u64 v[78:79], v[76:77], 2, s[8:9]
	v_add_u32_e32 v66, v136, v109
	ds_read_b128 v[72:75], v66
	v_lshl_add_u64 v[76:77], v[76:77], 1, s[6:7]
	s_waitcnt vmcnt(7) lgkmcnt(0)
;   __device__ __forceinline__ void tile(const float* reg, int row0, int col0, int lane) const {
;     rows4(reg, lane, [&](int it, int rr, int c4, float4 v) {
;       int row = row0 + rr, idx = row * 1024 + col0 + c4;
;       float4 xo = *(const float4*)(xold + idx);
;       v.x = fmaf(coef, v.x, xo.x); v.y = fmaf(coef, v.y, xo.y); v.z = fmaf(coef, v.z, xo.z); v.w = fmaf(coef, v.w, xo.w);
;       *(float4*)(xnew + idx) = v;
;       *(bf16x4*)(xb + idx) = pack4(v.x, v.y, v.z, v.w);
;       float s = row16_sum(v.x * v.x + v.y * v.y + v.z * v.z + v.w * v.w);
;       if ((lane & 15) == 0) atomicAdd(ssqn + row, s);
;     });
	v_mov_b32_e32 v68, v144
	v_mov_b32_e32 v69, v145
	v_mov_b32_e32 v70, v146
	v_mov_b32_e32 v71, v147
	v_pk_fma_f32 v[68:69], v[72:73], 0.5, v[68:69] op_sel_hi:[1,0,1]
	v_pk_fma_f32 v[70:71], v[74:75], 0.5, v[70:71] op_sel_hi:[1,0,1]
	global_store_dwordx4 v[78:79], v[68:71], off
	v_cvt_pk_bf16_f32 v72, v68, v69
	v_cvt_pk_bf16_f32 v73, v70, v71
	v_pk_mul_f32 v[68:69], v[68:69], v[68:69]
	v_pk_mul_f32 v[70:71], v[70:71], v[70:71]
	v_add_f32_e32 v65, v68, v69
	v_add_f32_e32 v65, v70, v65
	v_add_f32_e32 v65, v71, v65
	v_mov_b32_e32 v68, 0
	global_store_dwordx2 v[76:77], v[72:73], off
	v_add_f32_dpp v65, v65, v65 quad_perm:[1,0,3,2] row_mask:0xf bank_mask:0xf bound_ctrl:1
	s_nop 1
	v_add_f32_dpp v65, v65, v65 quad_perm:[2,3,0,1] row_mask:0xf bank_mask:0xf bound_ctrl:1
	s_nop 1
	v_add_f32_dpp v65, v65, v65 row_half_mirror row_mask:0xf bank_mask:0xf bound_ctrl:1
	s_nop 1
	v_mov_b32_dpp v68, v65 row_mirror row_mask:0xf bank_mask:0xf
	s_and_saveexec_b64 s[0:1], vcc
	s_cbranch_execz .LBB0_3184
	v_add_f32_e32 v68, v65, v68
	v_ashrrev_i32_e32 v65, 31, v64
	v_lshl_add_u64 v[64:65], v[64:65], 2, s[12:13]
	global_atomic_add_f32 v[64:65], v68, off
.LBB0_3184:
	s_or_b64 exec, exec, s[0:1]
	v_add_u32_e32 v64, v99, v67
	v_lshl_add_u32 v76, v64, 10, v128
	v_ashrrev_i32_e32 v77, 31, v76
	v_lshl_add_u64 v[78:79], v[76:77], 2, s[8:9]
	ds_read_b128 v[72:75], v100
	v_lshl_add_u64 v[76:77], v[76:77], 1, s[6:7]
	s_waitcnt vmcnt(9) lgkmcnt(0)
	v_mov_b32_e32 v68, v148
	v_mov_b32_e32 v69, v149
	v_mov_b32_e32 v70, v150
	v_mov_b32_e32 v71, v151
	v_pk_fma_f32 v[68:69], v[72:73], 0.5, v[68:69] op_sel_hi:[1,0,1]
	v_pk_fma_f32 v[70:71], v[74:75], 0.5, v[70:71] op_sel_hi:[1,0,1]
	global_store_dwordx4 v[78:79], v[68:71], off
	v_cvt_pk_bf16_f32 v72, v68, v69
	v_cvt_pk_bf16_f32 v73, v70, v71
	v_pk_mul_f32 v[68:69], v[68:69], v[68:69]
	v_pk_mul_f32 v[70:71], v[70:71], v[70:71]
	v_add_f32_e32 v65, v68, v69
	v_add_f32_e32 v65, v70, v65
	v_add_f32_e32 v65, v71, v65
	v_mov_b32_e32 v68, 0
	global_store_dwordx2 v[76:77], v[72:73], off
	v_add_f32_dpp v65, v65, v65 quad_perm:[1,0,3,2] row_mask:0xf bank_mask:0xf bound_ctrl:1
	s_nop 1
	v_add_f32_dpp v65, v65, v65 quad_perm:[2,3,0,1] row_mask:0xf bank_mask:0xf bound_ctrl:1
	s_nop 1
	v_add_f32_dpp v65, v65, v65 row_half_mirror row_mask:0xf bank_mask:0xf bound_ctrl:1
	s_nop 1
	v_mov_b32_dpp v68, v65 row_mirror row_mask:0xf bank_mask:0xf
	s_and_saveexec_b64 s[0:1], vcc
	s_cbranch_execz .LBB0_3186
	v_add_f32_e32 v68, v65, v68
	v_ashrrev_i32_e32 v65, 31, v64
	v_lshl_add_u64 v[64:65], v[64:65], 2, s[12:13]
	global_atomic_add_f32 v[64:65], v68, off
.LBB0_3186:
	s_or_b64 exec, exec, s[0:1]
	v_add_u32_e32 v64, v101, v67
	v_lshl_add_u32 v76, v64, 10, v128
	v_ashrrev_i32_e32 v77, 31, v76
	v_lshl_add_u64 v[78:79], v[76:77], 2, s[8:9]
	ds_read_b128 v[72:75], v102
	v_lshl_add_u64 v[76:77], v[76:77], 1, s[6:7]
	s_waitcnt vmcnt(11) lgkmcnt(0)
	v_mov_b32_e32 v68, v152
	v_mov_b32_e32 v69, v153
	v_mov_b32_e32 v70, v154
	v_mov_b32_e32 v71, v155
	v_pk_fma_f32 v[68:69], v[72:73], 0.5, v[68:69] op_sel_hi:[1,0,1]
	v_pk_fma_f32 v[70:71], v[74:75], 0.5, v[70:71] op_sel_hi:[1,0,1]
	global_store_dwordx4 v[78:79], v[68:71], off
	v_cvt_pk_bf16_f32 v72, v68, v69
	v_cvt_pk_bf16_f32 v73, v70, v71
	v_pk_mul_f32 v[68:69], v[68:69], v[68:69]
	v_pk_mul_f32 v[70:71], v[70:71], v[70:71]
	v_add_f32_e32 v65, v68, v69
	v_add_f32_e32 v65, v70, v65
	v_add_f32_e32 v65, v71, v65
	v_mov_b32_e32 v68, 0
	global_store_dwordx2 v[76:77], v[72:73], off
	v_add_f32_dpp v65, v65, v65 quad_perm:[1,0,3,2] row_mask:0xf bank_mask:0xf bound_ctrl:1
	s_nop 1
	v_add_f32_dpp v65, v65, v65 quad_perm:[2,3,0,1] row_mask:0xf bank_mask:0xf bound_ctrl:1
	s_nop 1
	v_add_f32_dpp v65, v65, v65 row_half_mirror row_mask:0xf bank_mask:0xf bound_ctrl:1
	s_nop 1
	v_mov_b32_dpp v68, v65 row_mirror row_mask:0xf bank_mask:0xf
	s_and_saveexec_b64 s[0:1], vcc
	s_cbranch_execz .LBB0_3188
	v_add_f32_e32 v68, v65, v68
	v_ashrrev_i32_e32 v65, 31, v64
	v_lshl_add_u64 v[64:65], v[64:65], 2, s[12:13]
	global_atomic_add_f32 v[64:65], v68, off
.LBB0_3188:
	s_or_b64 exec, exec, s[0:1]
	v_add_u32_e32 v64, v103, v67
	v_lshl_add_u32 v76, v64, 10, v128
	v_ashrrev_i32_e32 v77, 31, v76
	v_lshl_add_u64 v[78:79], v[76:77], 2, s[8:9]
	ds_read_b128 v[72:75], v98
	v_lshl_add_u64 v[76:77], v[76:77], 1, s[6:7]
	s_waitcnt vmcnt(13) lgkmcnt(0)
	v_mov_b32_e32 v68, v156
	v_mov_b32_e32 v69, v157
	v_mov_b32_e32 v70, v158
	v_mov_b32_e32 v71, v159
	v_pk_fma_f32 v[68:69], v[72:73], 0.5, v[68:69] op_sel_hi:[1,0,1]
	v_pk_fma_f32 v[70:71], v[74:75], 0.5, v[70:71] op_sel_hi:[1,0,1]
	global_store_dwordx4 v[78:79], v[68:71], off
	v_cvt_pk_bf16_f32 v72, v68, v69
	v_cvt_pk_bf16_f32 v73, v70, v71
	v_pk_mul_f32 v[68:69], v[68:69], v[68:69]
	v_pk_mul_f32 v[70:71], v[70:71], v[70:71]
	v_add_f32_e32 v65, v68, v69
	v_add_f32_e32 v65, v70, v65
	v_add_f32_e32 v65, v71, v65
	v_mov_b32_e32 v68, 0
	global_store_dwordx2 v[76:77], v[72:73], off
	v_add_f32_dpp v65, v65, v65 quad_perm:[1,0,3,2] row_mask:0xf bank_mask:0xf bound_ctrl:1
	s_nop 1
	v_add_f32_dpp v65, v65, v65 quad_perm:[2,3,0,1] row_mask:0xf bank_mask:0xf bound_ctrl:1
	s_nop 1
	v_add_f32_dpp v65, v65, v65 row_half_mirror row_mask:0xf bank_mask:0xf bound_ctrl:1
	s_nop 1
	v_mov_b32_dpp v68, v65 row_mirror row_mask:0xf bank_mask:0xf
	s_and_saveexec_b64 s[0:1], vcc
	s_cbranch_execz .LBB0_3190
	v_add_f32_e32 v68, v65, v68
	v_ashrrev_i32_e32 v65, 31, v64
	v_lshl_add_u64 v[64:65], v[64:65], 2, s[12:13]
	global_atomic_add_f32 v[64:65], v68, off
;   __device__ __forceinline__ void tile(const float* reg, int row0, int col0, int lane) const {
;     rows4(reg, lane, [&](int it, int rr, int c4, float4 v) {
;       int row = row0 + rr, idx = row * 1024 + col0 + c4;
;       float4 xo = *(const float4*)(xold + idx);
;       v.x = fmaf(coef, v.x, xo.x); v.y = fmaf(coef, v.y, xo.y); v.z = fmaf(coef, v.z, xo.z); v.w = fmaf(coef, v.w, xo.w);
;       *(float4*)(xnew + idx) = v;
;       *(bf16x4*)(xb + idx) = pack4(v.x, v.y, v.z, v.w);
;       float s = row16_sum(v.x * v.x + v.y * v.y + v.z * v.z + v.w * v.w);
;       if ((lane & 15) == 0) atomicAdd(ssqn + row, s);
;     });
.LBB0_3190:
	s_or_b64 exec, exec, s[0:1]
	v_add_u32_e32 v64, v105, v67
	v_lshl_add_u32 v76, v64, 10, v128
	v_ashrrev_i32_e32 v77, 31, v76
	v_lshl_add_u64 v[78:79], v[76:77], 2, s[8:9]
	ds_read_b128 v[72:75], v98 offset:1088
	v_lshl_add_u64 v[76:77], v[76:77], 1, s[6:7]
	s_waitcnt vmcnt(15) lgkmcnt(0)
	v_mov_b32_e32 v68, v160
	v_mov_b32_e32 v69, v161
	v_mov_b32_e32 v70, v162
	v_mov_b32_e32 v71, v163
	v_pk_fma_f32 v[68:69], v[72:73], 0.5, v[68:69] op_sel_hi:[1,0,1]
	v_pk_fma_f32 v[70:71], v[74:75], 0.5, v[70:71] op_sel_hi:[1,0,1]
	global_store_dwordx4 v[78:79], v[68:71], off
	v_cvt_pk_bf16_f32 v72, v68, v69
	v_cvt_pk_bf16_f32 v73, v70, v71
	v_pk_mul_f32 v[68:69], v[68:69], v[68:69]
	v_pk_mul_f32 v[70:71], v[70:71], v[70:71]
	v_add_f32_e32 v65, v68, v69
	v_add_f32_e32 v65, v70, v65
	v_add_f32_e32 v65, v71, v65
	v_mov_b32_e32 v68, 0
	global_store_dwordx2 v[76:77], v[72:73], off
	v_add_f32_dpp v65, v65, v65 quad_perm:[1,0,3,2] row_mask:0xf bank_mask:0xf bound_ctrl:1
	s_nop 1
	v_add_f32_dpp v65, v65, v65 quad_perm:[2,3,0,1] row_mask:0xf bank_mask:0xf bound_ctrl:1
	s_nop 1
	v_add_f32_dpp v65, v65, v65 row_half_mirror row_mask:0xf bank_mask:0xf bound_ctrl:1
	s_nop 1
	v_mov_b32_dpp v68, v65 row_mirror row_mask:0xf bank_mask:0xf
	s_and_saveexec_b64 s[0:1], vcc
	s_cbranch_execz .LBB0_3192
	v_add_f32_e32 v68, v65, v68
	v_ashrrev_i32_e32 v65, 31, v64
	v_lshl_add_u64 v[64:65], v[64:65], 2, s[12:13]
	global_atomic_add_f32 v[64:65], v68, off
.LBB0_3192:
	s_or_b64 exec, exec, s[0:1]
	v_add_u32_e32 v64, v106, v67
	v_lshl_add_u32 v76, v64, 10, v128
	v_ashrrev_i32_e32 v77, 31, v76
	v_lshl_add_u64 v[78:79], v[76:77], 2, s[8:9]
	ds_read_b128 v[72:75], v98 offset:2176
	v_lshl_add_u64 v[76:77], v[76:77], 1, s[6:7]
	s_waitcnt vmcnt(17) lgkmcnt(0)
	v_mov_b32_e32 v68, v164
	v_mov_b32_e32 v69, v165
	v_mov_b32_e32 v70, v166
	v_mov_b32_e32 v71, v167
	v_pk_fma_f32 v[68:69], v[72:73], 0.5, v[68:69] op_sel_hi:[1,0,1]
	v_pk_fma_f32 v[70:71], v[74:75], 0.5, v[70:71] op_sel_hi:[1,0,1]
	global_store_dwordx4 v[78:79], v[68:71], off
	v_cvt_pk_bf16_f32 v72, v68, v69
	v_cvt_pk_bf16_f32 v73, v70, v71
	v_pk_mul_f32 v[68:69], v[68:69], v[68:69]
	v_pk_mul_f32 v[70:71], v[70:71], v[70:71]
	v_add_f32_e32 v65, v68, v69
	v_add_f32_e32 v65, v70, v65
	v_add_f32_e32 v65, v71, v65
	v_mov_b32_e32 v68, 0
	global_store_dwordx2 v[76:77], v[72:73], off
	v_add_f32_dpp v65, v65, v65 quad_perm:[1,0,3,2] row_mask:0xf bank_mask:0xf bound_ctrl:1
	s_nop 1
	v_add_f32_dpp v65, v65, v65 quad_perm:[2,3,0,1] row_mask:0xf bank_mask:0xf bound_ctrl:1
	s_nop 1
	v_add_f32_dpp v65, v65, v65 row_half_mirror row_mask:0xf bank_mask:0xf bound_ctrl:1
	s_nop 1
	v_mov_b32_dpp v68, v65 row_mirror row_mask:0xf bank_mask:0xf
	s_and_saveexec_b64 s[0:1], vcc
	s_cbranch_execz .LBB0_3194
	v_add_f32_e32 v68, v65, v68
	v_ashrrev_i32_e32 v65, 31, v64
	v_lshl_add_u64 v[64:65], v[64:65], 2, s[12:13]
	global_atomic_add_f32 v[64:65], v68, off
.LBB0_3194:
	s_or_b64 exec, exec, s[0:1]
	v_add_u32_e32 v64, v107, v67
	v_lshl_add_u32 v76, v64, 10, v128
	v_ashrrev_i32_e32 v77, 31, v76
	v_lshl_add_u64 v[78:79], v[76:77], 2, s[8:9]
	ds_read_b128 v[72:75], v98 offset:3264
	v_lshl_add_u64 v[76:77], v[76:77], 1, s[6:7]
	s_waitcnt vmcnt(19) lgkmcnt(0)
	v_mov_b32_e32 v68, v168
	v_mov_b32_e32 v69, v169
	v_mov_b32_e32 v70, v170
	v_mov_b32_e32 v71, v171
	v_pk_fma_f32 v[68:69], v[72:73], 0.5, v[68:69] op_sel_hi:[1,0,1]
	v_pk_fma_f32 v[70:71], v[74:75], 0.5, v[70:71] op_sel_hi:[1,0,1]
	global_store_dwordx4 v[78:79], v[68:71], off
	v_cvt_pk_bf16_f32 v72, v68, v69
	v_cvt_pk_bf16_f32 v73, v70, v71
	v_pk_mul_f32 v[68:69], v[68:69], v[68:69]
	v_pk_mul_f32 v[70:71], v[70:71], v[70:71]
	v_add_f32_e32 v65, v68, v69
	v_add_f32_e32 v65, v70, v65
	v_add_f32_e32 v65, v71, v65
	v_mov_b32_e32 v68, 0
	global_store_dwordx2 v[76:77], v[72:73], off
	v_add_f32_dpp v65, v65, v65 quad_perm:[1,0,3,2] row_mask:0xf bank_mask:0xf bound_ctrl:1
	s_nop 1
	v_add_f32_dpp v65, v65, v65 quad_perm:[2,3,0,1] row_mask:0xf bank_mask:0xf bound_ctrl:1
	s_nop 1
	v_add_f32_dpp v65, v65, v65 row_half_mirror row_mask:0xf bank_mask:0xf bound_ctrl:1
	s_nop 1
	v_mov_b32_dpp v68, v65 row_mirror row_mask:0xf bank_mask:0xf
	s_and_saveexec_b64 s[0:1], vcc
	s_cbranch_execz .LBB0_3196
	v_add_f32_e32 v68, v65, v68
	v_ashrrev_i32_e32 v65, 31, v64
	v_lshl_add_u64 v[64:65], v[64:65], 2, s[12:13]
	global_atomic_add_f32 v[64:65], v68, off
.LBB0_3196:
	s_or_b64 exec, exec, s[0:1]
	v_add_u32_e32 v64, v108, v67
	v_lshl_add_u32 v76, v64, 10, v128
	v_ashrrev_i32_e32 v77, 31, v76
	v_lshl_add_u64 v[78:79], v[76:77], 2, s[8:9]
	ds_read_b128 v[72:75], v98 offset:4352
	v_mov_b32_e32 v67, 0
	v_lshl_add_u64 v[76:77], v[76:77], 1, s[6:7]
	s_waitcnt vmcnt(21) lgkmcnt(0)
	v_mov_b32_e32 v68, v172
	v_mov_b32_e32 v69, v173
	v_mov_b32_e32 v70, v174
	v_mov_b32_e32 v71, v175
	v_pk_fma_f32 v[68:69], v[72:73], 0.5, v[68:69] op_sel_hi:[1,0,1]
	v_pk_fma_f32 v[70:71], v[74:75], 0.5, v[70:71] op_sel_hi:[1,0,1]
	global_store_dwordx4 v[78:79], v[68:71], off
	v_cvt_pk_bf16_f32 v72, v68, v69
	v_cvt_pk_bf16_f32 v73, v70, v71
	v_pk_mul_f32 v[68:69], v[68:69], v[68:69]
	v_pk_mul_f32 v[70:71], v[70:71], v[70:71]
	v_add_f32_e32 v65, v68, v69
	v_add_f32_e32 v65, v70, v65
	v_add_f32_e32 v65, v71, v65
	global_store_dwordx2 v[76:77], v[72:73], off
	s_nop 0
	v_add_f32_dpp v65, v65, v65 quad_perm:[1,0,3,2] row_mask:0xf bank_mask:0xf bound_ctrl:1
	s_nop 1
	v_add_f32_dpp v65, v65, v65 quad_perm:[2,3,0,1] row_mask:0xf bank_mask:0xf bound_ctrl:1
	s_nop 1
	v_add_f32_dpp v65, v65, v65 row_half_mirror row_mask:0xf bank_mask:0xf bound_ctrl:1
	s_nop 1
	v_mov_b32_dpp v67, v65 row_mirror row_mask:0xf bank_mask:0xf
	s_and_saveexec_b64 s[0:1], vcc
	s_cbranch_execz .LBB0_3198
	v_add_f32_e32 v67, v65, v67
	v_ashrrev_i32_e32 v65, 31, v64
	v_lshl_add_u64 v[64:65], v[64:65], 2, s[12:13]
	global_atomic_add_f32 v[64:65], v67, off
;   __device__ __forceinline__ void tile(const float* reg, int row0, int col0, int lane) const {
;     rows4(reg, lane, [&](int it, int rr, int c4, float4 v) {
;       int row = row0 + rr, idx = row * 1024 + col0 + c4;
;       float4 xo = *(const float4*)(xold + idx);
;       v.x = fmaf(coef, v.x, xo.x); v.y = fmaf(coef, v.y, xo.y); v.z = fmaf(coef, v.z, xo.z); v.w = fmaf(coef, v.w, xo.w);
;       *(float4*)(xnew + idx) = v;
;       *(bf16x4*)(xb + idx) = pack4(v.x, v.y, v.z, v.w);
;       float s = row16_sum(v.x * v.x + v.y * v.y + v.z * v.z + v.w * v.w);
;       if ((lane & 15) == 0) atomicAdd(ssqn + row, s);
;     });
; template <int MF, class Epi>
; __device__ __forceinline__ void staged_epilogue(f32x4 (&acc)[MF][4], int row0, int col0, const Epi& epi) {
;   const int lane = tidx() & 63, wid = tidx() >> 6, fr = lane & 15, fq = lane >> 4;
;   float* reg = (float*)(g_shm + 65536 + wid * 8704);
; #pragma unroll
;   for (int mp = 0; mp < MF / 2; ++mp) {
;     __builtin_amdgcn_sched_barrier(0);
; #pragma unroll
;     for (int mm = 0; mm < 2; ++mm)
; #pragma unroll
;       for (int n = 0; n < 4; ++n)
; #pragma unroll
;         for (int j = 0; j < 4; ++j) reg[(mm * 16 + fq * 4 + j) * 68 + n * 16 + fr] = acc[mp * 2 + mm][n][j];
;     __builtin_amdgcn_fence(__ATOMIC_ACQ_REL, "wavefront");
;     epi.tile(reg, row0 + mp * 32, col0, lane);
.LBB0_3198:
	s_or_b64 exec, exec, s[0:1]
	ds_write2_b32 v131, v56, v60 offset1:16
	ds_write2_b32 v131, v57, v61 offset0:68 offset1:84
	ds_write2_b32 v131, v58, v62 offset0:136 offset1:152
	ds_write2_b32 v131, v59, v63 offset0:204 offset1:220
	ds_write2_b32 v131, v48, v52 offset0:32 offset1:48
	ds_write2_b32 v131, v49, v53 offset0:100 offset1:116
	ds_write2_b32 v131, v50, v54 offset0:168 offset1:184
	ds_write2_b32 v131, v51, v55 offset0:236 offset1:252
	ds_write2_b32 v112, v40, v44 offset0:64 offset1:80
	ds_write2_b32 v112, v41, v45 offset0:132 offset1:148
	ds_write2_b32 v112, v42, v46 offset0:200 offset1:216
	ds_write2_b32 v104, v43, v47 offset0:12 offset1:28
	ds_write2_b32 v112, v32, v36 offset0:96 offset1:112
	ds_write2_b32 v112, v33, v37 offset0:164 offset1:180
	ds_write2_b32 v112, v34, v38 offset0:232 offset1:248
	ds_write2_b32 v104, v35, v39 offset0:44 offset1:60
	v_add_u32_e32 v185, 64, v129
	v_add_u32_e32 v184, v130, v185
	v_lshl_add_u32 v176, v184, 10, v128
	v_ashrrev_i32_e32 v177, 31, v176
	v_lshl_add_u64 v[178:179], v[176:177], 2, s[8:9]
	global_load_dwordx4 v[144:147], v[178:179], off
	v_add_u32_e32 v185, 64, v129
	v_add_u32_e32 v184, v99, v185
	v_lshl_add_u32 v176, v184, 10, v128
	v_ashrrev_i32_e32 v177, 31, v176
	v_lshl_add_u64 v[178:179], v[176:177], 2, s[8:9]
	global_load_dwordx4 v[148:151], v[178:179], off
	v_add_u32_e32 v185, 64, v129
	v_add_u32_e32 v184, v101, v185
	v_lshl_add_u32 v176, v184, 10, v128
	v_ashrrev_i32_e32 v177, 31, v176
	v_lshl_add_u64 v[178:179], v[176:177], 2, s[8:9]
	global_load_dwordx4 v[152:155], v[178:179], off
	v_add_u32_e32 v185, 64, v129
	v_add_u32_e32 v184, v103, v185
	v_lshl_add_u32 v176, v184, 10, v128
	v_ashrrev_i32_e32 v177, 31, v176
	v_lshl_add_u64 v[178:179], v[176:177], 2, s[8:9]
	global_load_dwordx4 v[156:159], v[178:179], off
	v_add_u32_e32 v185, 64, v129
	v_add_u32_e32 v184, v105, v185
	v_lshl_add_u32 v176, v184, 10, v128
	v_ashrrev_i32_e32 v177, 31, v176
	v_lshl_add_u64 v[178:179], v[176:177], 2, s[8:9]
	global_load_dwordx4 v[160:163], v[178:179], off
	v_add_u32_e32 v185, 64, v129
	v_add_u32_e32 v184, v106, v185
	v_lshl_add_u32 v176, v184, 10, v128
	v_ashrrev_i32_e32 v177, 31, v176
	v_lshl_add_u64 v[178:179], v[176:177], 2, s[8:9]
	global_load_dwordx4 v[164:167], v[178:179], off
	v_add_u32_e32 v185, 64, v129
	v_add_u32_e32 v184, v107, v185
	v_lshl_add_u32 v176, v184, 10, v128
	v_ashrrev_i32_e32 v177, 31, v176
	v_lshl_add_u64 v[178:179], v[176:177], 2, s[8:9]
	global_load_dwordx4 v[168:171], v[178:179], off
	v_add_u32_e32 v185, 64, v129
	v_add_u32_e32 v184, v108, v185
	v_lshl_add_u32 v176, v184, 10, v128
	v_ashrrev_i32_e32 v177, 31, v176
	v_lshl_add_u64 v[178:179], v[176:177], 2, s[8:9]
	global_load_dwordx4 v[172:175], v[178:179], off
	v_add_u32_e32 v34, 64, v129
	v_add_u32_e32 v32, v130, v34
	v_lshl_add_u32 v44, v32, 10, v128
	v_ashrrev_i32_e32 v45, 31, v44
	v_lshl_add_u64 v[46:47], v[44:45], 2, s[8:9]
	ds_read_b128 v[40:43], v66
	v_mov_b32_e32 v35, 0
	v_lshl_add_u64 v[44:45], v[44:45], 1, s[6:7]
	s_waitcnt vmcnt(7) lgkmcnt(0)
	v_mov_b32_e32 v36, v144
	v_mov_b32_e32 v37, v145
	v_mov_b32_e32 v38, v146
	v_mov_b32_e32 v39, v147
	v_pk_fma_f32 v[36:37], v[40:41], 0.5, v[36:37] op_sel_hi:[1,0,1]
	v_pk_fma_f32 v[38:39], v[42:43], 0.5, v[38:39] op_sel_hi:[1,0,1]
	global_store_dwordx4 v[46:47], v[36:39], off
	v_cvt_pk_bf16_f32 v40, v36, v37
	v_cvt_pk_bf16_f32 v41, v38, v39
	v_pk_mul_f32 v[36:37], v[36:37], v[36:37]
	v_pk_mul_f32 v[38:39], v[38:39], v[38:39]
	v_add_f32_e32 v33, v36, v37
	v_add_f32_e32 v33, v38, v33
	v_add_f32_e32 v33, v39, v33
	global_store_dwordx2 v[44:45], v[40:41], off
	s_nop 0
	v_add_f32_dpp v33, v33, v33 quad_perm:[1,0,3,2] row_mask:0xf bank_mask:0xf bound_ctrl:1
	s_nop 1
	v_add_f32_dpp v33, v33, v33 quad_perm:[2,3,0,1] row_mask:0xf bank_mask:0xf bound_ctrl:1
	s_nop 1
	v_add_f32_dpp v33, v33, v33 row_half_mirror row_mask:0xf bank_mask:0xf bound_ctrl:1
	s_nop 1
	v_mov_b32_dpp v35, v33 row_mirror row_mask:0xf bank_mask:0xf
	s_and_saveexec_b64 s[0:1], vcc
	s_cbranch_execz .LBB0_3200
	v_add_f32_e32 v35, v33, v35
	v_ashrrev_i32_e32 v33, 31, v32
	v_lshl_add_u64 v[32:33], v[32:33], 2, s[12:13]
	global_atomic_add_f32 v[32:33], v35, off
.LBB0_3200:
	s_or_b64 exec, exec, s[0:1]
	v_add_u32_e32 v32, v99, v34
	v_lshl_add_u32 v44, v32, 10, v128
	v_ashrrev_i32_e32 v45, 31, v44
	v_lshl_add_u64 v[46:47], v[44:45], 2, s[8:9]
	ds_read_b128 v[40:43], v100
	v_mov_b32_e32 v35, 0
	v_lshl_add_u64 v[44:45], v[44:45], 1, s[6:7]
	s_waitcnt vmcnt(9) lgkmcnt(0)
	v_mov_b32_e32 v36, v148
	v_mov_b32_e32 v37, v149
	v_mov_b32_e32 v38, v150
	v_mov_b32_e32 v39, v151
	v_pk_fma_f32 v[36:37], v[40:41], 0.5, v[36:37] op_sel_hi:[1,0,1]
	v_pk_fma_f32 v[38:39], v[42:43], 0.5, v[38:39] op_sel_hi:[1,0,1]
	global_store_dwordx4 v[46:47], v[36:39], off
	v_cvt_pk_bf16_f32 v40, v36, v37
	v_cvt_pk_bf16_f32 v41, v38, v39
	v_pk_mul_f32 v[36:37], v[36:37], v[36:37]
	v_pk_mul_f32 v[38:39], v[38:39], v[38:39]
	v_add_f32_e32 v33, v36, v37
	v_add_f32_e32 v33, v38, v33
	v_add_f32_e32 v33, v39, v33
	global_store_dwordx2 v[44:45], v[40:41], off
	s_nop 0
	v_add_f32_dpp v33, v33, v33 quad_perm:[1,0,3,2] row_mask:0xf bank_mask:0xf bound_ctrl:1
	s_nop 1
	v_add_f32_dpp v33, v33, v33 quad_perm:[2,3,0,1] row_mask:0xf bank_mask:0xf bound_ctrl:1
	s_nop 1
	v_add_f32_dpp v33, v33, v33 row_half_mirror row_mask:0xf bank_mask:0xf bound_ctrl:1
	s_nop 1
	v_mov_b32_dpp v35, v33 row_mirror row_mask:0xf bank_mask:0xf
	s_and_saveexec_b64 s[0:1], vcc
	s_cbranch_execz .LBB0_3202
	v_add_f32_e32 v35, v33, v35
	v_ashrrev_i32_e32 v33, 31, v32
	v_lshl_add_u64 v[32:33], v[32:33], 2, s[12:13]
	global_atomic_add_f32 v[32:33], v35, off
;   __device__ __forceinline__ void tile(const float* reg, int row0, int col0, int lane) const {
;     rows4(reg, lane, [&](int it, int rr, int c4, float4 v) {
;       int row = row0 + rr, idx = row * 1024 + col0 + c4;
;       float4 xo = *(const float4*)(xold + idx);
;       v.x = fmaf(coef, v.x, xo.x); v.y = fmaf(coef, v.y, xo.y); v.z = fmaf(coef, v.z, xo.z); v.w = fmaf(coef, v.w, xo.w);
;       *(float4*)(xnew + idx) = v;
;       *(bf16x4*)(xb + idx) = pack4(v.x, v.y, v.z, v.w);
;       float s = row16_sum(v.x * v.x + v.y * v.y + v.z * v.z + v.w * v.w);
;       if ((lane & 15) == 0) atomicAdd(ssqn + row, s);
;     });
.LBB0_3202:
	s_or_b64 exec, exec, s[0:1]
	v_add_u32_e32 v32, v101, v34
	v_lshl_add_u32 v44, v32, 10, v128
	v_ashrrev_i32_e32 v45, 31, v44
	v_lshl_add_u64 v[46:47], v[44:45], 2, s[8:9]
	ds_read_b128 v[40:43], v102
	v_mov_b32_e32 v35, 0
	v_lshl_add_u64 v[44:45], v[44:45], 1, s[6:7]
	s_waitcnt vmcnt(11) lgkmcnt(0)
	v_mov_b32_e32 v36, v152
	v_mov_b32_e32 v37, v153
	v_mov_b32_e32 v38, v154
	v_mov_b32_e32 v39, v155
	v_pk_fma_f32 v[36:37], v[40:41], 0.5, v[36:37] op_sel_hi:[1,0,1]
	v_pk_fma_f32 v[38:39], v[42:43], 0.5, v[38:39] op_sel_hi:[1,0,1]
	global_store_dwordx4 v[46:47], v[36:39], off
	v_cvt_pk_bf16_f32 v40, v36, v37
	v_cvt_pk_bf16_f32 v41, v38, v39
	v_pk_mul_f32 v[36:37], v[36:37], v[36:37]
	v_pk_mul_f32 v[38:39], v[38:39], v[38:39]
	v_add_f32_e32 v33, v36, v37
	v_add_f32_e32 v33, v38, v33
	v_add_f32_e32 v33, v39, v33
	global_store_dwordx2 v[44:45], v[40:41], off
	s_nop 0
	v_add_f32_dpp v33, v33, v33 quad_perm:[1,0,3,2] row_mask:0xf bank_mask:0xf bound_ctrl:1
	s_nop 1
	v_add_f32_dpp v33, v33, v33 quad_perm:[2,3,0,1] row_mask:0xf bank_mask:0xf bound_ctrl:1
	s_nop 1
	v_add_f32_dpp v33, v33, v33 row_half_mirror row_mask:0xf bank_mask:0xf bound_ctrl:1
	s_nop 1
	v_mov_b32_dpp v35, v33 row_mirror row_mask:0xf bank_mask:0xf
	s_and_saveexec_b64 s[0:1], vcc
	s_cbranch_execz .LBB0_3204
	v_add_f32_e32 v35, v33, v35
	v_ashrrev_i32_e32 v33, 31, v32
	v_lshl_add_u64 v[32:33], v[32:33], 2, s[12:13]
	global_atomic_add_f32 v[32:33], v35, off
.LBB0_3204:
	s_or_b64 exec, exec, s[0:1]
	v_add_u32_e32 v32, v103, v34
	v_lshl_add_u32 v44, v32, 10, v128
	v_ashrrev_i32_e32 v45, 31, v44
	v_lshl_add_u64 v[46:47], v[44:45], 2, s[8:9]
	ds_read_b128 v[40:43], v98
	v_mov_b32_e32 v35, 0
	v_lshl_add_u64 v[44:45], v[44:45], 1, s[6:7]
	s_waitcnt vmcnt(13) lgkmcnt(0)
	v_mov_b32_e32 v36, v156
	v_mov_b32_e32 v37, v157
	v_mov_b32_e32 v38, v158
	v_mov_b32_e32 v39, v159
	v_pk_fma_f32 v[36:37], v[40:41], 0.5, v[36:37] op_sel_hi:[1,0,1]
	v_pk_fma_f32 v[38:39], v[42:43], 0.5, v[38:39] op_sel_hi:[1,0,1]
	global_store_dwordx4 v[46:47], v[36:39], off
	v_cvt_pk_bf16_f32 v40, v36, v37
	v_cvt_pk_bf16_f32 v41, v38, v39
	v_pk_mul_f32 v[36:37], v[36:37], v[36:37]
	v_pk_mul_f32 v[38:39], v[38:39], v[38:39]
	v_add_f32_e32 v33, v36, v37
	v_add_f32_e32 v33, v38, v33
	v_add_f32_e32 v33, v39, v33
	global_store_dwordx2 v[44:45], v[40:41], off
	s_nop 0
	v_add_f32_dpp v33, v33, v33 quad_perm:[1,0,3,2] row_mask:0xf bank_mask:0xf bound_ctrl:1
	s_nop 1
	v_add_f32_dpp v33, v33, v33 quad_perm:[2,3,0,1] row_mask:0xf bank_mask:0xf bound_ctrl:1
	s_nop 1
	v_add_f32_dpp v33, v33, v33 row_half_mirror row_mask:0xf bank_mask:0xf bound_ctrl:1
	s_nop 1
	v_mov_b32_dpp v35, v33 row_mirror row_mask:0xf bank_mask:0xf
	s_and_saveexec_b64 s[0:1], vcc
	s_cbranch_execz .LBB0_3206
	v_add_f32_e32 v35, v33, v35
	v_ashrrev_i32_e32 v33, 31, v32
	v_lshl_add_u64 v[32:33], v[32:33], 2, s[12:13]
	global_atomic_add_f32 v[32:33], v35, off
.LBB0_3206:
	s_or_b64 exec, exec, s[0:1]
	v_add_u32_e32 v32, v105, v34
	v_lshl_add_u32 v44, v32, 10, v128
	v_ashrrev_i32_e32 v45, 31, v44
	v_lshl_add_u64 v[46:47], v[44:45], 2, s[8:9]
	ds_read_b128 v[40:43], v98 offset:1088
	v_mov_b32_e32 v35, 0
	v_lshl_add_u64 v[44:45], v[44:45], 1, s[6:7]
	s_waitcnt vmcnt(15) lgkmcnt(0)
	v_mov_b32_e32 v36, v160
	v_mov_b32_e32 v37, v161
	v_mov_b32_e32 v38, v162
	v_mov_b32_e32 v39, v163
	v_pk_fma_f32 v[36:37], v[40:41], 0.5, v[36:37] op_sel_hi:[1,0,1]
	v_pk_fma_f32 v[38:39], v[42:43], 0.5, v[38:39] op_sel_hi:[1,0,1]
	global_store_dwordx4 v[46:47], v[36:39], off
	v_cvt_pk_bf16_f32 v40, v36, v37
	v_cvt_pk_bf16_f32 v41, v38, v39
	v_pk_mul_f32 v[36:37], v[36:37], v[36:37]
	v_pk_mul_f32 v[38:39], v[38:39], v[38:39]
	v_add_f32_e32 v33, v36, v37
	v_add_f32_e32 v33, v38, v33
	v_add_f32_e32 v33, v39, v33
	global_store_dwordx2 v[44:45], v[40:41], off
	s_nop 0
	v_add_f32_dpp v33, v33, v33 quad_perm:[1,0,3,2] row_mask:0xf bank_mask:0xf bound_ctrl:1
	s_nop 1
	v_add_f32_dpp v33, v33, v33 quad_perm:[2,3,0,1] row_mask:0xf bank_mask:0xf bound_ctrl:1
	s_nop 1
	v_add_f32_dpp v33, v33, v33 row_half_mirror row_mask:0xf bank_mask:0xf bound_ctrl:1
	s_nop 1
	v_mov_b32_dpp v35, v33 row_mirror row_mask:0xf bank_mask:0xf
	s_and_saveexec_b64 s[0:1], vcc
	s_cbranch_execz .LBB0_3208
	v_add_f32_e32 v35, v33, v35
	v_ashrrev_i32_e32 v33, 31, v32
	v_lshl_add_u64 v[32:33], v[32:33], 2, s[12:13]
	global_atomic_add_f32 v[32:33], v35, off
.LBB0_3208:
	s_or_b64 exec, exec, s[0:1]
	v_add_u32_e32 v32, v106, v34
	v_lshl_add_u32 v44, v32, 10, v128
	v_ashrrev_i32_e32 v45, 31, v44
	v_lshl_add_u64 v[46:47], v[44:45], 2, s[8:9]
	ds_read_b128 v[40:43], v98 offset:2176
	v_mov_b32_e32 v35, 0
	v_lshl_add_u64 v[44:45], v[44:45], 1, s[6:7]
	s_waitcnt vmcnt(17) lgkmcnt(0)
	v_mov_b32_e32 v36, v164
	v_mov_b32_e32 v37, v165
	v_mov_b32_e32 v38, v166
	v_mov_b32_e32 v39, v167
	v_pk_fma_f32 v[36:37], v[40:41], 0.5, v[36:37] op_sel_hi:[1,0,1]
	v_pk_fma_f32 v[38:39], v[42:43], 0.5, v[38:39] op_sel_hi:[1,0,1]
	global_store_dwordx4 v[46:47], v[36:39], off
	v_cvt_pk_bf16_f32 v40, v36, v37
	v_cvt_pk_bf16_f32 v41, v38, v39
	v_pk_mul_f32 v[36:37], v[36:37], v[36:37]
	v_pk_mul_f32 v[38:39], v[38:39], v[38:39]
	v_add_f32_e32 v33, v36, v37
	v_add_f32_e32 v33, v38, v33
	v_add_f32_e32 v33, v39, v33
	global_store_dwordx2 v[44:45], v[40:41], off
	s_nop 0
	v_add_f32_dpp v33, v33, v33 quad_perm:[1,0,3,2] row_mask:0xf bank_mask:0xf bound_ctrl:1
	s_nop 1
	v_add_f32_dpp v33, v33, v33 quad_perm:[2,3,0,1] row_mask:0xf bank_mask:0xf bound_ctrl:1
	s_nop 1
	v_add_f32_dpp v33, v33, v33 row_half_mirror row_mask:0xf bank_mask:0xf bound_ctrl:1
	s_nop 1
	v_mov_b32_dpp v35, v33 row_mirror row_mask:0xf bank_mask:0xf
	s_and_saveexec_b64 s[0:1], vcc
	s_cbranch_execz .LBB0_3210
	v_add_f32_e32 v35, v33, v35
	v_ashrrev_i32_e32 v33, 31, v32
	v_lshl_add_u64 v[32:33], v[32:33], 2, s[12:13]
	global_atomic_add_f32 v[32:33], v35, off
;   __device__ __forceinline__ void tile(const float* reg, int row0, int col0, int lane) const {
;     rows4(reg, lane, [&](int it, int rr, int c4, float4 v) {
;       int row = row0 + rr, idx = row * 1024 + col0 + c4;
;       float4 xo = *(const float4*)(xold + idx);
;       v.x = fmaf(coef, v.x, xo.x); v.y = fmaf(coef, v.y, xo.y); v.z = fmaf(coef, v.z, xo.z); v.w = fmaf(coef, v.w, xo.w);
;       *(float4*)(xnew + idx) = v;
;       *(bf16x4*)(xb + idx) = pack4(v.x, v.y, v.z, v.w);
;       float s = row16_sum(v.x * v.x + v.y * v.y + v.z * v.z + v.w * v.w);
;       if ((lane & 15) == 0) atomicAdd(ssqn + row, s);
;     });
; template <int MF, class Epi>
; __device__ __forceinline__ void staged_epilogue(f32x4 (&acc)[MF][4], int row0, int col0, const Epi& epi) {
;   const int lane = tidx() & 63, wid = tidx() >> 6, fr = lane & 15, fq = lane >> 4;
;   float* reg = (float*)(g_shm + 65536 + wid * 8704);
; #pragma unroll
;   for (int mp = 0; mp < MF / 2; ++mp) {
;     __builtin_amdgcn_sched_barrier(0);
; #pragma unroll
;     for (int mm = 0; mm < 2; ++mm)
; #pragma unroll
;       for (int n = 0; n < 4; ++n)
; #pragma unroll
;         for (int j = 0; j < 4; ++j) reg[(mm * 16 + fq * 4 + j) * 68 + n * 16 + fr] = acc[mp * 2 + mm][n][j];
;     __builtin_amdgcn_fence(__ATOMIC_ACQ_REL, "wavefront");
;     epi.tile(reg, row0 + mp * 32, col0, lane);
.LBB0_3210:
	s_or_b64 exec, exec, s[0:1]
	v_add_u32_e32 v32, v107, v34
	v_lshl_add_u32 v44, v32, 10, v128
	v_ashrrev_i32_e32 v45, 31, v44
	v_lshl_add_u64 v[46:47], v[44:45], 2, s[8:9]
	ds_read_b128 v[40:43], v98 offset:3264
	v_mov_b32_e32 v35, 0
	v_lshl_add_u64 v[44:45], v[44:45], 1, s[6:7]
	s_waitcnt vmcnt(19) lgkmcnt(0)
	v_mov_b32_e32 v36, v168
	v_mov_b32_e32 v37, v169
	v_mov_b32_e32 v38, v170
	v_mov_b32_e32 v39, v171
	v_pk_fma_f32 v[36:37], v[40:41], 0.5, v[36:37] op_sel_hi:[1,0,1]
	v_pk_fma_f32 v[38:39], v[42:43], 0.5, v[38:39] op_sel_hi:[1,0,1]
	global_store_dwordx4 v[46:47], v[36:39], off
	v_cvt_pk_bf16_f32 v40, v36, v37
	v_cvt_pk_bf16_f32 v41, v38, v39
	v_pk_mul_f32 v[36:37], v[36:37], v[36:37]
	v_pk_mul_f32 v[38:39], v[38:39], v[38:39]
	v_add_f32_e32 v33, v36, v37
	v_add_f32_e32 v33, v38, v33
	v_add_f32_e32 v33, v39, v33
	global_store_dwordx2 v[44:45], v[40:41], off
	s_nop 0
	v_add_f32_dpp v33, v33, v33 quad_perm:[1,0,3,2] row_mask:0xf bank_mask:0xf bound_ctrl:1
	s_nop 1
	v_add_f32_dpp v33, v33, v33 quad_perm:[2,3,0,1] row_mask:0xf bank_mask:0xf bound_ctrl:1
	s_nop 1
	v_add_f32_dpp v33, v33, v33 row_half_mirror row_mask:0xf bank_mask:0xf bound_ctrl:1
	s_nop 1
	v_mov_b32_dpp v35, v33 row_mirror row_mask:0xf bank_mask:0xf
	s_and_saveexec_b64 s[0:1], vcc
	s_cbranch_execz .LBB0_3212
	v_add_f32_e32 v35, v33, v35
	v_ashrrev_i32_e32 v33, 31, v32
	v_lshl_add_u64 v[32:33], v[32:33], 2, s[12:13]
	global_atomic_add_f32 v[32:33], v35, off
.LBB0_3212:
	s_or_b64 exec, exec, s[0:1]
	v_add_u32_e32 v32, v108, v34
	v_lshl_add_u32 v42, v32, 10, v128
	v_ashrrev_i32_e32 v43, 31, v42
	v_lshl_add_u64 v[44:45], v[42:43], 2, s[8:9]
	ds_read_b128 v[38:41], v98 offset:4352
	v_lshl_add_u64 v[42:43], v[42:43], 1, s[6:7]
	s_waitcnt vmcnt(21) lgkmcnt(0)
	v_mov_b32_e32 v34, v172
	v_mov_b32_e32 v35, v173
	v_mov_b32_e32 v36, v174
	v_mov_b32_e32 v37, v175
	v_pk_fma_f32 v[34:35], v[38:39], 0.5, v[34:35] op_sel_hi:[1,0,1]
	v_pk_fma_f32 v[36:37], v[40:41], 0.5, v[36:37] op_sel_hi:[1,0,1]
	global_store_dwordx4 v[44:45], v[34:37], off
	v_cvt_pk_bf16_f32 v38, v34, v35
	v_cvt_pk_bf16_f32 v39, v36, v37
	v_pk_mul_f32 v[34:35], v[34:35], v[34:35]
	v_pk_mul_f32 v[36:37], v[36:37], v[36:37]
	v_add_f32_e32 v33, v34, v35
	v_add_f32_e32 v33, v36, v33
	v_add_f32_e32 v33, v37, v33
	v_mov_b32_e32 v34, 0
	global_store_dwordx2 v[42:43], v[38:39], off
	v_add_f32_dpp v33, v33, v33 quad_perm:[1,0,3,2] row_mask:0xf bank_mask:0xf bound_ctrl:1
	s_nop 1
	v_add_f32_dpp v33, v33, v33 quad_perm:[2,3,0,1] row_mask:0xf bank_mask:0xf bound_ctrl:1
	s_nop 1
	v_add_f32_dpp v33, v33, v33 row_half_mirror row_mask:0xf bank_mask:0xf bound_ctrl:1
	s_nop 1
	v_mov_b32_dpp v34, v33 row_mirror row_mask:0xf bank_mask:0xf
	s_and_saveexec_b64 s[0:1], vcc
	s_cbranch_execz .LBB0_3214
	v_add_f32_e32 v34, v33, v34
	v_ashrrev_i32_e32 v33, 31, v32
	v_lshl_add_u64 v[32:33], v[32:33], 2, s[12:13]
	global_atomic_add_f32 v[32:33], v34, off
.LBB0_3214:
	s_or_b64 exec, exec, s[0:1]
	ds_write2_b32 v131, v24, v28 offset1:16
	ds_write2_b32 v131, v25, v29 offset0:68 offset1:84
	ds_write2_b32 v131, v26, v30 offset0:136 offset1:152
	ds_write2_b32 v131, v27, v31 offset0:204 offset1:220
	ds_write2_b32 v131, v16, v20 offset0:32 offset1:48
	ds_write2_b32 v131, v17, v21 offset0:100 offset1:116
	ds_write2_b32 v131, v18, v22 offset0:168 offset1:184
	ds_write2_b32 v131, v19, v23 offset0:236 offset1:252
	ds_write2_b32 v112, v4, v8 offset0:64 offset1:80
	ds_write2_b32 v112, v5, v9 offset0:132 offset1:148
	ds_write2_b32 v112, v6, v10 offset0:200 offset1:216
	ds_write2_b32 v104, v7, v11 offset0:12 offset1:28
	ds_write2_b32 v112, v0, v12 offset0:96 offset1:112
	ds_write2_b32 v112, v1, v13 offset0:164 offset1:180
	ds_write2_b32 v112, v2, v14 offset0:232 offset1:248
	ds_write2_b32 v104, v3, v15 offset0:44 offset1:60
	v_add_u32_e32 v185, 0x60, v129
	v_add_u32_e32 v184, v130, v185
	v_lshl_add_u32 v176, v184, 10, v128
	v_ashrrev_i32_e32 v177, 31, v176
	v_lshl_add_u64 v[178:179], v[176:177], 2, s[8:9]
	global_load_dwordx4 v[144:147], v[178:179], off
	v_add_u32_e32 v185, 0x60, v129
	v_add_u32_e32 v184, v99, v185
	v_lshl_add_u32 v176, v184, 10, v128
	v_ashrrev_i32_e32 v177, 31, v176
	v_lshl_add_u64 v[178:179], v[176:177], 2, s[8:9]
	global_load_dwordx4 v[148:151], v[178:179], off
	v_add_u32_e32 v185, 0x60, v129
	v_add_u32_e32 v184, v101, v185
	v_lshl_add_u32 v176, v184, 10, v128
	v_ashrrev_i32_e32 v177, 31, v176
	v_lshl_add_u64 v[178:179], v[176:177], 2, s[8:9]
	global_load_dwordx4 v[152:155], v[178:179], off
	v_add_u32_e32 v185, 0x60, v129
	v_add_u32_e32 v184, v103, v185
	v_lshl_add_u32 v176, v184, 10, v128
	v_ashrrev_i32_e32 v177, 31, v176
	v_lshl_add_u64 v[178:179], v[176:177], 2, s[8:9]
	global_load_dwordx4 v[156:159], v[178:179], off
	v_add_u32_e32 v185, 0x60, v129
	v_add_u32_e32 v184, v105, v185
	v_lshl_add_u32 v176, v184, 10, v128
	v_ashrrev_i32_e32 v177, 31, v176
	v_lshl_add_u64 v[178:179], v[176:177], 2, s[8:9]
	global_load_dwordx4 v[160:163], v[178:179], off
	v_add_u32_e32 v185, 0x60, v129
	v_add_u32_e32 v184, v106, v185
	v_lshl_add_u32 v176, v184, 10, v128
	v_ashrrev_i32_e32 v177, 31, v176
	v_lshl_add_u64 v[178:179], v[176:177], 2, s[8:9]
	global_load_dwordx4 v[164:167], v[178:179], off
	v_add_u32_e32 v185, 0x60, v129
	v_add_u32_e32 v184, v107, v185
	v_lshl_add_u32 v176, v184, 10, v128
	v_ashrrev_i32_e32 v177, 31, v176
	v_lshl_add_u64 v[178:179], v[176:177], 2, s[8:9]
	global_load_dwordx4 v[168:171], v[178:179], off
	v_add_u32_e32 v185, 0x60, v129
	v_add_u32_e32 v184, v108, v185
	v_lshl_add_u32 v176, v184, 10, v128
	v_ashrrev_i32_e32 v177, 31, v176
	v_lshl_add_u64 v[178:179], v[176:177], 2, s[8:9]
	global_load_dwordx4 v[172:175], v[178:179], off
	v_add_u32_e32 v2, 0x60, v129
	v_add_u32_e32 v0, v130, v2
	v_lshl_add_u32 v12, v0, 10, v128
	v_ashrrev_i32_e32 v13, 31, v12
	v_lshl_add_u64 v[14:15], v[12:13], 2, s[8:9]
	ds_read_b128 v[8:11], v66
	v_mov_b32_e32 v3, 0
	v_lshl_add_u64 v[12:13], v[12:13], 1, s[6:7]
	s_waitcnt vmcnt(7) lgkmcnt(0)
	v_mov_b32_e32 v4, v144
	v_mov_b32_e32 v5, v145
	v_mov_b32_e32 v6, v146
	v_mov_b32_e32 v7, v147
	v_pk_fma_f32 v[4:5], v[8:9], 0.5, v[4:5] op_sel_hi:[1,0,1]
	v_pk_fma_f32 v[6:7], v[10:11], 0.5, v[6:7] op_sel_hi:[1,0,1]
	global_store_dwordx4 v[14:15], v[4:7], off
	v_cvt_pk_bf16_f32 v8, v4, v5
	v_cvt_pk_bf16_f32 v9, v6, v7
	v_pk_mul_f32 v[4:5], v[4:5], v[4:5]
	v_pk_mul_f32 v[6:7], v[6:7], v[6:7]
	v_add_f32_e32 v1, v4, v5
	v_add_f32_e32 v1, v6, v1
	v_add_f32_e32 v1, v7, v1
	global_store_dwordx2 v[12:13], v[8:9], off
	s_nop 0
	v_add_f32_dpp v1, v1, v1 quad_perm:[1,0,3,2] row_mask:0xf bank_mask:0xf bound_ctrl:1
	s_nop 1
	v_add_f32_dpp v1, v1, v1 quad_perm:[2,3,0,1] row_mask:0xf bank_mask:0xf bound_ctrl:1
	s_nop 1
	v_add_f32_dpp v1, v1, v1 row_half_mirror row_mask:0xf bank_mask:0xf bound_ctrl:1
	s_nop 1
	v_mov_b32_dpp v3, v1 row_mirror row_mask:0xf bank_mask:0xf
	s_and_saveexec_b64 s[0:1], vcc
	s_cbranch_execz .LBB0_3216
	v_add_f32_e32 v3, v1, v3
	v_ashrrev_i32_e32 v1, 31, v0
	v_lshl_add_u64 v[0:1], v[0:1], 2, s[12:13]
	global_atomic_add_f32 v[0:1], v3, off
;   __device__ __forceinline__ void tile(const float* reg, int row0, int col0, int lane) const {
;     rows4(reg, lane, [&](int it, int rr, int c4, float4 v) {
;       int row = row0 + rr, idx = row * 1024 + col0 + c4;
;       float4 xo = *(const float4*)(xold + idx);
;       v.x = fmaf(coef, v.x, xo.x); v.y = fmaf(coef, v.y, xo.y); v.z = fmaf(coef, v.z, xo.z); v.w = fmaf(coef, v.w, xo.w);
;       *(float4*)(xnew + idx) = v;
;       *(bf16x4*)(xb + idx) = pack4(v.x, v.y, v.z, v.w);
;       float s = row16_sum(v.x * v.x + v.y * v.y + v.z * v.z + v.w * v.w);
;       if ((lane & 15) == 0) atomicAdd(ssqn + row, s);
;     });
.LBB0_3216:
	s_or_b64 exec, exec, s[0:1]
	v_add_u32_e32 v0, v99, v2
	v_lshl_add_u32 v12, v0, 10, v128
	v_ashrrev_i32_e32 v13, 31, v12
	v_lshl_add_u64 v[14:15], v[12:13], 2, s[8:9]
	ds_read_b128 v[8:11], v100
	v_mov_b32_e32 v3, 0
	v_lshl_add_u64 v[12:13], v[12:13], 1, s[6:7]
	s_waitcnt vmcnt(9) lgkmcnt(0)
	v_mov_b32_e32 v4, v148
	v_mov_b32_e32 v5, v149
	v_mov_b32_e32 v6, v150
	v_mov_b32_e32 v7, v151
	v_pk_fma_f32 v[4:5], v[8:9], 0.5, v[4:5] op_sel_hi:[1,0,1]
	v_pk_fma_f32 v[6:7], v[10:11], 0.5, v[6:7] op_sel_hi:[1,0,1]
	global_store_dwordx4 v[14:15], v[4:7], off
	v_cvt_pk_bf16_f32 v8, v4, v5
	v_cvt_pk_bf16_f32 v9, v6, v7
	v_pk_mul_f32 v[4:5], v[4:5], v[4:5]
	v_pk_mul_f32 v[6:7], v[6:7], v[6:7]
	v_add_f32_e32 v1, v4, v5
	v_add_f32_e32 v1, v6, v1
	v_add_f32_e32 v1, v7, v1
	global_store_dwordx2 v[12:13], v[8:9], off
	s_nop 0
	v_add_f32_dpp v1, v1, v1 quad_perm:[1,0,3,2] row_mask:0xf bank_mask:0xf bound_ctrl:1
	s_nop 1
	v_add_f32_dpp v1, v1, v1 quad_perm:[2,3,0,1] row_mask:0xf bank_mask:0xf bound_ctrl:1
	s_nop 1
	v_add_f32_dpp v1, v1, v1 row_half_mirror row_mask:0xf bank_mask:0xf bound_ctrl:1
	s_nop 1
	v_mov_b32_dpp v3, v1 row_mirror row_mask:0xf bank_mask:0xf
	s_and_saveexec_b64 s[0:1], vcc
	s_cbranch_execz .LBB0_3218
	v_add_f32_e32 v3, v1, v3
	v_ashrrev_i32_e32 v1, 31, v0
	v_lshl_add_u64 v[0:1], v[0:1], 2, s[12:13]
	global_atomic_add_f32 v[0:1], v3, off
.LBB0_3218:
	s_or_b64 exec, exec, s[0:1]
	v_add_u32_e32 v0, v101, v2
	v_lshl_add_u32 v12, v0, 10, v128
	v_ashrrev_i32_e32 v13, 31, v12
	v_lshl_add_u64 v[14:15], v[12:13], 2, s[8:9]
	ds_read_b128 v[8:11], v102
	v_mov_b32_e32 v3, 0
	v_lshl_add_u64 v[12:13], v[12:13], 1, s[6:7]
	s_waitcnt vmcnt(11) lgkmcnt(0)
	v_mov_b32_e32 v4, v152
	v_mov_b32_e32 v5, v153
	v_mov_b32_e32 v6, v154
	v_mov_b32_e32 v7, v155
	v_pk_fma_f32 v[4:5], v[8:9], 0.5, v[4:5] op_sel_hi:[1,0,1]
	v_pk_fma_f32 v[6:7], v[10:11], 0.5, v[6:7] op_sel_hi:[1,0,1]
	global_store_dwordx4 v[14:15], v[4:7], off
	v_cvt_pk_bf16_f32 v8, v4, v5
	v_cvt_pk_bf16_f32 v9, v6, v7
	v_pk_mul_f32 v[4:5], v[4:5], v[4:5]
	v_pk_mul_f32 v[6:7], v[6:7], v[6:7]
	v_add_f32_e32 v1, v4, v5
	v_add_f32_e32 v1, v6, v1
	v_add_f32_e32 v1, v7, v1
	global_store_dwordx2 v[12:13], v[8:9], off
	s_nop 0
	v_add_f32_dpp v1, v1, v1 quad_perm:[1,0,3,2] row_mask:0xf bank_mask:0xf bound_ctrl:1
	s_nop 1
	v_add_f32_dpp v1, v1, v1 quad_perm:[2,3,0,1] row_mask:0xf bank_mask:0xf bound_ctrl:1
	s_nop 1
	v_add_f32_dpp v1, v1, v1 row_half_mirror row_mask:0xf bank_mask:0xf bound_ctrl:1
	s_nop 1
	v_mov_b32_dpp v3, v1 row_mirror row_mask:0xf bank_mask:0xf
	s_and_saveexec_b64 s[0:1], vcc
	s_cbranch_execz .LBB0_3220
	v_add_f32_e32 v3, v1, v3
	v_ashrrev_i32_e32 v1, 31, v0
	v_lshl_add_u64 v[0:1], v[0:1], 2, s[12:13]
	global_atomic_add_f32 v[0:1], v3, off
.LBB0_3220:
	s_or_b64 exec, exec, s[0:1]
	v_add_u32_e32 v0, v103, v2
	v_lshl_add_u32 v12, v0, 10, v128
	v_ashrrev_i32_e32 v13, 31, v12
	v_lshl_add_u64 v[14:15], v[12:13], 2, s[8:9]
	ds_read_b128 v[8:11], v98
	v_mov_b32_e32 v3, 0
	v_lshl_add_u64 v[12:13], v[12:13], 1, s[6:7]
	s_waitcnt vmcnt(13) lgkmcnt(0)
	v_mov_b32_e32 v4, v156
	v_mov_b32_e32 v5, v157
	v_mov_b32_e32 v6, v158
	v_mov_b32_e32 v7, v159
	v_pk_fma_f32 v[4:5], v[8:9], 0.5, v[4:5] op_sel_hi:[1,0,1]
	v_pk_fma_f32 v[6:7], v[10:11], 0.5, v[6:7] op_sel_hi:[1,0,1]
	global_store_dwordx4 v[14:15], v[4:7], off
	v_cvt_pk_bf16_f32 v8, v4, v5
	v_cvt_pk_bf16_f32 v9, v6, v7
	v_pk_mul_f32 v[4:5], v[4:5], v[4:5]
	v_pk_mul_f32 v[6:7], v[6:7], v[6:7]
	v_add_f32_e32 v1, v4, v5
	v_add_f32_e32 v1, v6, v1
	v_add_f32_e32 v1, v7, v1
	global_store_dwordx2 v[12:13], v[8:9], off
	s_nop 0
	v_add_f32_dpp v1, v1, v1 quad_perm:[1,0,3,2] row_mask:0xf bank_mask:0xf bound_ctrl:1
	s_nop 1
	v_add_f32_dpp v1, v1, v1 quad_perm:[2,3,0,1] row_mask:0xf bank_mask:0xf bound_ctrl:1
	s_nop 1
	v_add_f32_dpp v1, v1, v1 row_half_mirror row_mask:0xf bank_mask:0xf bound_ctrl:1
	s_nop 1
	v_mov_b32_dpp v3, v1 row_mirror row_mask:0xf bank_mask:0xf
	s_and_saveexec_b64 s[0:1], vcc
	s_cbranch_execz .LBB0_3222
	v_add_f32_e32 v3, v1, v3
	v_ashrrev_i32_e32 v1, 31, v0
	v_lshl_add_u64 v[0:1], v[0:1], 2, s[12:13]
	global_atomic_add_f32 v[0:1], v3, off
.LBB0_3222:
	s_or_b64 exec, exec, s[0:1]
	v_add_u32_e32 v0, v105, v2
	v_lshl_add_u32 v12, v0, 10, v128
	v_ashrrev_i32_e32 v13, 31, v12
	v_lshl_add_u64 v[14:15], v[12:13], 2, s[8:9]
	ds_read_b128 v[8:11], v98 offset:1088
	v_mov_b32_e32 v3, 0
	v_lshl_add_u64 v[12:13], v[12:13], 1, s[6:7]
	s_waitcnt vmcnt(15) lgkmcnt(0)
	v_mov_b32_e32 v4, v160
	v_mov_b32_e32 v5, v161
	v_mov_b32_e32 v6, v162
	v_mov_b32_e32 v7, v163
	v_pk_fma_f32 v[4:5], v[8:9], 0.5, v[4:5] op_sel_hi:[1,0,1]
	v_pk_fma_f32 v[6:7], v[10:11], 0.5, v[6:7] op_sel_hi:[1,0,1]
	global_store_dwordx4 v[14:15], v[4:7], off
	v_cvt_pk_bf16_f32 v8, v4, v5
	v_cvt_pk_bf16_f32 v9, v6, v7
	v_pk_mul_f32 v[4:5], v[4:5], v[4:5]
	v_pk_mul_f32 v[6:7], v[6:7], v[6:7]
	v_add_f32_e32 v1, v4, v5
	v_add_f32_e32 v1, v6, v1
	v_add_f32_e32 v1, v7, v1
	global_store_dwordx2 v[12:13], v[8:9], off
	s_nop 0
	v_add_f32_dpp v1, v1, v1 quad_perm:[1,0,3,2] row_mask:0xf bank_mask:0xf bound_ctrl:1
	s_nop 1
	v_add_f32_dpp v1, v1, v1 quad_perm:[2,3,0,1] row_mask:0xf bank_mask:0xf bound_ctrl:1
	s_nop 1
	v_add_f32_dpp v1, v1, v1 row_half_mirror row_mask:0xf bank_mask:0xf bound_ctrl:1
	s_nop 1
	v_mov_b32_dpp v3, v1 row_mirror row_mask:0xf bank_mask:0xf
	s_and_saveexec_b64 s[0:1], vcc
	s_cbranch_execz .LBB0_3224
	v_add_f32_e32 v3, v1, v3
	v_ashrrev_i32_e32 v1, 31, v0
	v_lshl_add_u64 v[0:1], v[0:1], 2, s[12:13]
	global_atomic_add_f32 v[0:1], v3, off
; template <class F> __device__ __forceinline__ void rows4(const float* reg, int lane, F f) {
; #pragma unroll
;   for (int it = 0; it < 8; ++it) {
;     if ((it & 3) == 0) __builtin_amdgcn_sched_barrier(0);
;     int rr = it * 4 + (lane >> 4), c4 = (lane & 15) * 4;
;     float4 v = *(const float4*)(reg + rr * 68 + c4);
;     f(it, rr, c4, v);
;   }
;   __device__ __forceinline__ void tile(const float* reg, int row0, int col0, int lane) const {
;     rows4(reg, lane, [&](int it, int rr, int c4, float4 v) {
;       int row = row0 + rr, idx = row * 1024 + col0 + c4;
;       float4 xo = *(const float4*)(xold + idx);
;       v.x = fmaf(coef, v.x, xo.x); v.y = fmaf(coef, v.y, xo.y); v.z = fmaf(coef, v.z, xo.z); v.w = fmaf(coef, v.w, xo.w);
;       *(float4*)(xnew + idx) = v;
;       *(bf16x4*)(xb + idx) = pack4(v.x, v.y, v.z, v.w);
;       float s = row16_sum(v.x * v.x + v.y * v.y + v.z * v.z + v.w * v.w);
;       if ((lane & 15) == 0) atomicAdd(ssqn + row, s);
;     });
;   }
.LBB0_3224:
	s_or_b64 exec, exec, s[0:1]
	v_add_u32_e32 v0, v106, v2
	v_lshl_add_u32 v12, v0, 10, v128
	v_ashrrev_i32_e32 v13, 31, v12
	v_lshl_add_u64 v[14:15], v[12:13], 2, s[8:9]
	ds_read_b128 v[8:11], v98 offset:2176
	v_mov_b32_e32 v3, 0
	v_lshl_add_u64 v[12:13], v[12:13], 1, s[6:7]
	s_waitcnt vmcnt(17) lgkmcnt(0)
	v_mov_b32_e32 v4, v164
	v_mov_b32_e32 v5, v165
	v_mov_b32_e32 v6, v166
	v_mov_b32_e32 v7, v167
	v_pk_fma_f32 v[4:5], v[8:9], 0.5, v[4:5] op_sel_hi:[1,0,1]
	v_pk_fma_f32 v[6:7], v[10:11], 0.5, v[6:7] op_sel_hi:[1,0,1]
	global_store_dwordx4 v[14:15], v[4:7], off
	v_cvt_pk_bf16_f32 v8, v4, v5
	v_cvt_pk_bf16_f32 v9, v6, v7
	v_pk_mul_f32 v[4:5], v[4:5], v[4:5]
	v_pk_mul_f32 v[6:7], v[6:7], v[6:7]
	v_add_f32_e32 v1, v4, v5
	v_add_f32_e32 v1, v6, v1
	v_add_f32_e32 v1, v7, v1
	global_store_dwordx2 v[12:13], v[8:9], off
	s_nop 0
	v_add_f32_dpp v1, v1, v1 quad_perm:[1,0,3,2] row_mask:0xf bank_mask:0xf bound_ctrl:1
	s_nop 1
	v_add_f32_dpp v1, v1, v1 quad_perm:[2,3,0,1] row_mask:0xf bank_mask:0xf bound_ctrl:1
	s_nop 1
	v_add_f32_dpp v1, v1, v1 row_half_mirror row_mask:0xf bank_mask:0xf bound_ctrl:1
	s_nop 1
	v_mov_b32_dpp v3, v1 row_mirror row_mask:0xf bank_mask:0xf
	s_and_saveexec_b64 s[0:1], vcc
	s_cbranch_execz .LBB0_3226
	v_add_f32_e32 v3, v1, v3
	v_ashrrev_i32_e32 v1, 31, v0
	v_lshl_add_u64 v[0:1], v[0:1], 2, s[12:13]
	global_atomic_add_f32 v[0:1], v3, off
.LBB0_3226:
	s_or_b64 exec, exec, s[0:1]
	v_add_u32_e32 v0, v107, v2
	v_lshl_add_u32 v12, v0, 10, v128
	v_ashrrev_i32_e32 v13, 31, v12
	v_lshl_add_u64 v[14:15], v[12:13], 2, s[8:9]
	ds_read_b128 v[8:11], v98 offset:3264
	v_mov_b32_e32 v3, 0
	v_lshl_add_u64 v[12:13], v[12:13], 1, s[6:7]
	s_waitcnt vmcnt(19) lgkmcnt(0)
	v_mov_b32_e32 v4, v168
	v_mov_b32_e32 v5, v169
	v_mov_b32_e32 v6, v170
	v_mov_b32_e32 v7, v171
	v_pk_fma_f32 v[4:5], v[8:9], 0.5, v[4:5] op_sel_hi:[1,0,1]
	v_pk_fma_f32 v[6:7], v[10:11], 0.5, v[6:7] op_sel_hi:[1,0,1]
	global_store_dwordx4 v[14:15], v[4:7], off
	v_cvt_pk_bf16_f32 v8, v4, v5
	v_cvt_pk_bf16_f32 v9, v6, v7
	v_pk_mul_f32 v[4:5], v[4:5], v[4:5]
	v_pk_mul_f32 v[6:7], v[6:7], v[6:7]
	v_add_f32_e32 v1, v4, v5
	v_add_f32_e32 v1, v6, v1
	v_add_f32_e32 v1, v7, v1
	global_store_dwordx2 v[12:13], v[8:9], off
	s_nop 0
	v_add_f32_dpp v1, v1, v1 quad_perm:[1,0,3,2] row_mask:0xf bank_mask:0xf bound_ctrl:1
	s_nop 1
	v_add_f32_dpp v1, v1, v1 quad_perm:[2,3,0,1] row_mask:0xf bank_mask:0xf bound_ctrl:1
	s_nop 1
	v_add_f32_dpp v1, v1, v1 row_half_mirror row_mask:0xf bank_mask:0xf bound_ctrl:1
	s_nop 1
	v_mov_b32_dpp v3, v1 row_mirror row_mask:0xf bank_mask:0xf
	s_and_saveexec_b64 s[0:1], vcc
	s_cbranch_execz .LBB0_3228
	v_add_f32_e32 v3, v1, v3
	v_ashrrev_i32_e32 v1, 31, v0
	v_lshl_add_u64 v[0:1], v[0:1], 2, s[12:13]
	global_atomic_add_f32 v[0:1], v3, off
.LBB0_3228:
	s_or_b64 exec, exec, s[0:1]
	v_add_u32_e32 v0, v108, v2
	v_lshl_add_u32 v10, v0, 10, v128
	v_ashrrev_i32_e32 v11, 31, v10
	v_lshl_add_u64 v[12:13], v[10:11], 2, s[8:9]
	ds_read_b128 v[6:9], v98 offset:4352
	v_lshl_add_u64 v[10:11], v[10:11], 1, s[6:7]
	s_waitcnt vmcnt(21) lgkmcnt(0)
	v_mov_b32_e32 v2, v172
	v_mov_b32_e32 v3, v173
	v_mov_b32_e32 v4, v174
	v_mov_b32_e32 v5, v175
	v_pk_fma_f32 v[2:3], v[6:7], 0.5, v[2:3] op_sel_hi:[1,0,1]
	v_pk_fma_f32 v[4:5], v[8:9], 0.5, v[4:5] op_sel_hi:[1,0,1]
	global_store_dwordx4 v[12:13], v[2:5], off
	v_cvt_pk_bf16_f32 v6, v2, v3
	v_cvt_pk_bf16_f32 v7, v4, v5
	v_pk_mul_f32 v[2:3], v[2:3], v[2:3]
	v_pk_mul_f32 v[4:5], v[4:5], v[4:5]
	v_add_f32_e32 v1, v2, v3
	v_add_f32_e32 v1, v4, v1
	v_add_f32_e32 v1, v5, v1
	v_mov_b32_e32 v2, 0
	global_store_dwordx2 v[10:11], v[6:7], off
	v_add_f32_dpp v1, v1, v1 quad_perm:[1,0,3,2] row_mask:0xf bank_mask:0xf bound_ctrl:1
	s_nop 1
	v_add_f32_dpp v1, v1, v1 quad_perm:[2,3,0,1] row_mask:0xf bank_mask:0xf bound_ctrl:1
	s_nop 1
	v_add_f32_dpp v1, v1, v1 row_half_mirror row_mask:0xf bank_mask:0xf bound_ctrl:1
	s_nop 1
	v_mov_b32_dpp v2, v1 row_mirror row_mask:0xf bank_mask:0xf
	s_and_saveexec_b64 s[0:1], vcc
	s_cbranch_execz .LBB0_3161
	v_add_f32_e32 v2, v1, v2
	v_ashrrev_i32_e32 v1, 31, v0
	v_lshl_add_u64 v[0:1], v[0:1], 2, s[12:13]
	global_atomic_add_f32 v[0:1], v2, off
	s_branch .LBB0_3161
